# residual epilogue f32 Y stores: 128 contiguous bytes per row per store (DPP row_ror:8 exchange on top of the permlane16/32 exchange)
# speedup vs baseline: 1.0043x; 1.0038x over previous
; __device__ __forceinline__ float xsum16(float v) { const auto r = __builtin_amdgcn_permlane16_swap(__float_as_uint(v), __float_as_uint(v), false, false); return __uint_as_float(r[0]) + __uint_as_float(r[1]); }
; __device__ __forceinline__ float xsum32(float v) { const auto r = __builtin_amdgcn_permlane32_swap(__float_as_uint(v), __float_as_uint(v), false, false); return __uint_as_float(r[0]) + __uint_as_float(r[1]); }
; __device__ __forceinline__ void row_stats4(const float* st, int rowb, int fq, float (&mu)[4], float (&rs)[4]) {
;     f32x4 a[4], b[4];
; #pragma unroll
;     for (int m = 0; m < 4; ++m) { const f32x4* p = (const f32x4*)(st + (size_t)(rowb + m * 16) * 32 + fq * 8); a[m] = p[0]; b[m] = p[1]; }
; #pragma unroll
;     for (int m = 0; m < 4; ++m) { float s1 = (a[m][0] + a[m][2]) + (b[m][0] + b[m][2]), s2 = (a[m][1] + a[m][3]) + (b[m][1] + b[m][3]);
;         s1 = xsum32(xsum16(s1)); s2 = xsum32(xsum16(s2));
;         const float mm = s1 * (1.0f / 1024.0f); mu[m] = mm; rs[m] = rsqrtf(fmaxf(s2 * (1.0f / 1024.0f) - mm * mm, 0.f) + LN_EPS_); }
;     asm volatile("" ::: "memory");
; }
;     __device__ __forceinline__ void operator()(const f32x4 (&acc)[2][2][4][2], const pg8::Unit& u, int wr, int wc, int fr, int fq) const {
;     ...
;         for (int ai = 0; ai < 2; ++ai) { float mu4[4], rs4[4]; row_stats4(stp, row0 + ai * 128, fq, mu4, rs4);
; #pragma unroll
;             for (int m = 0; m < 4; ++m) { const int row = row0 + ai * 128 + m * 16; const float mu = mu4[m], rs = rs4[m];
;                 f32x4 yv[2][2], gq[2][2], bq_[2][2];
; #pragma unroll
;                 for (int bj = 0; bj < 2; ++bj)
; #pragma unroll
;                     for (int n = 0; n < 2; ++n) { yv[bj][n] = *(const f32x4*)(Yin + (size_t)row * D_ + col0 + bj * 128 + 4 * n); gq[bj][n] = *(const f32x4*)(g + col0 + bj * 128 + 4 * n); bq_[bj][n] = *(const f32x4*)(b + col0 + bj * 128 + 4 * n); }
.LBB0_372:
	s_lshl_b32 s3, s3, 8
	s_add_i32 s3, s3, s53
	v_or_b32_e32 v158, s3, v182
	v_ashrrev_i32_e32 v159, 31, v158
	v_lshlrev_b64 v[130:131], 7, v[158:159]
	v_lshl_add_u64 v[136:137], v[146:147], 0, v[130:131]
	v_or_b32_e32 v180, 16, v158
	global_load_dwordx4 v[132:135], v[136:137], off
	global_load_dwordx4 v[166:169], v[136:137], off offset:16
	v_ashrrev_i32_e32 v181, 31, v180
	v_lshlrev_b64 v[172:173], 7, v[180:181]
	v_lshl_add_u64 v[136:137], v[146:147], 0, v[172:173]
	global_load_dwordx4 v[174:177], v[136:137], off
	global_load_dwordx4 v[186:189], v[136:137], off offset:16
	v_or_b32_e32 v170, 32, v158
	v_ashrrev_i32_e32 v171, 31, v170
	v_lshlrev_b64 v[164:165], 7, v[170:171]
	v_lshl_add_u64 v[136:137], v[146:147], 0, v[164:165]
	global_load_dwordx4 v[190:193], v[136:137], off
	global_load_dwordx4 v[196:199], v[136:137], off offset:16
	v_or_b32_e32 v162, 48, v158
	v_ashrrev_i32_e32 v163, 31, v162
	v_lshlrev_b64 v[160:161], 7, v[162:163]
	v_lshl_add_u64 v[204:205], v[146:147], 0, v[160:161]
	global_load_dwordx4 v[200:203], v[204:205], off
	s_nop 0
	global_load_dwordx4 v[204:207], v[204:205], off offset:16
	s_lshl_b32 s16, s2, 8
	s_lshl_b32 s17, s2, 3
	s_or_b32 s2, s16, s54
	v_or_b32_e32 v152, s2, v183
	v_ashrrev_i32_e32 v153, 31, v152
	v_lshlrev_b64 v[136:137], 12, v[158:159]
	v_lshlrev_b64 v[152:153], 2, v[152:153]
	v_lshl_add_u64 v[178:179], s[12:13], 0, v[136:137]
	v_lshl_add_u64 v[178:179], v[178:179], 0, v[152:153]
	v_lshl_add_u64 v[154:155], s[8:9], 0, v[152:153]
	v_lshl_add_u64 v[156:157], s[10:11], 0, v[152:153]
	global_load_dwordx4 v[208:211], v[178:179], off offset:16
	global_load_dwordx4 v[212:215], v[178:179], off
	global_load_dwordx4 v[216:219], v[154:155], off offset:16
	global_load_dwordx4 v[220:223], v[154:155], off
	global_load_dwordx4 v[234:237], v[156:157], off offset:16
	global_load_dwordx4 v[238:241], v[156:157], off
	s_mov_b32 s16, 0x3a800000
	s_mov_b32 s18, 0x3fd744fd
	s_load_dwordx16 s[60:75], s[34:35], 0x38
	s_or_b32 s24, s17, s57
	v_bitop3_b32 v194, s2, 56, v183 bitop3:0xc8
	s_ashr_i32 s40, s2, 6
	s_ashr_i32 s25, s24, 31
	s_waitcnt lgkmcnt(0)
	v_lshl_add_u64 v[136:137], s[74:75], 0, v[136:137]
	v_lshl_add_u64 v[136:137], v[136:137], 0, v[152:153]
	s_ashr_i32 s41, s40, 31
	s_waitcnt vmcnt(0)
	v_mov_b32_e32 v224, v132
	v_mov_b32_e32 v225, v166
	v_mov_b32_e32 v228, v134
	v_mov_b32_e32 v229, v168
	v_mov_b32_e32 v166, v133
	v_mov_b32_e32 v168, v135
	v_pk_add_f32 v[132:133], v[224:225], v[228:229]
	v_pk_add_f32 v[134:135], v[166:167], v[168:169]
	v_pk_add_f32 v[132:133], v[132:133], v[132:133] op_sel:[0,1] op_sel_hi:[1,0]
	v_pk_add_f32 v[134:135], v[134:135], v[134:135] op_sel:[0,1] op_sel_hi:[1,0]
	v_mov_b32_e32 v166, v174
	v_mov_b32_e32 v167, v186
	v_mov_b32_e32 v168, v176
	v_mov_b32_e32 v169, v188
	v_mov_b32_e32 v0, v132
	v_mov_b32_e32 v133, v134
	v_pk_add_f32 v[166:167], v[166:167], v[168:169]
	v_permlane16_swap_b32_e32 v132, v0
	v_permlane16_swap_b32_e32 v134, v133
	v_mov_b32_e32 v186, v175
	v_mov_b32_e32 v188, v177
	v_pk_add_f32 v[166:167], v[166:167], v[166:167] op_sel:[0,1] op_sel_hi:[1,0]
	v_add_f32_e32 v177, v132, v0
	v_add_f32_e32 v176, v134, v133
	v_pk_add_f32 v[168:169], v[186:187], v[188:189]
	v_mov_b32_e32 v135, v166
	v_mov_b32_e32 v187, v177
	v_mov_b32_e32 v186, v176
	v_permlane16_swap_b32_e32 v166, v135
	v_permlane32_swap_b32_e32 v177, v187
	v_permlane32_swap_b32_e32 v176, v186
	v_add_f32_e32 v133, v166, v135
	v_pk_add_f32 v[166:167], v[176:177], v[186:187]
	v_pk_add_f32 v[168:169], v[168:169], v[168:169] op_sel:[0,1] op_sel_hi:[1,0]
	v_pk_mul_f32 v[224:225], v[166:167], s[16:17] op_sel_hi:[1,0]
	v_mov_b32_e32 v159, v168
	v_fma_f32 v0, -v225, v225, v224
	v_max_f32_e32 v0, 0, v0
	v_permlane16_swap_b32_e32 v168, v159
	v_add_f32_e32 v0, 0x3727c5ac, v0
	s_mov_b32 s16, 0x800000
	v_add_f32_e32 v132, v168, v159
	v_mul_f32_e32 v159, 0x4b800000, v0
	v_cmp_gt_f32_e32 vcc, s16, v0
	v_mov_b32_e32 v174, v190
	v_mov_b32_e32 v175, v196
	v_cndmask_b32_e32 v0, v0, v159, vcc
	v_rsq_f32_e32 v0, v0
	v_mov_b32_e32 v166, v192
	v_mov_b32_e32 v167, v198
	v_pk_add_f32 v[166:167], v[174:175], v[166:167]
	v_mul_f32_e32 v159, 0x45800000, v0
	v_pk_add_f32 v[166:167], v[166:167], v[166:167] op_sel:[0,1] op_sel_hi:[1,0]
	v_mov_b32_e32 v196, v191
	v_mov_b32_e32 v198, v193
	v_cndmask_b32_e32 v0, v0, v159, vcc
	v_pk_add_f32 v[168:169], v[196:197], v[198:199]
	v_mov_b32_e32 v159, v166
	v_pk_add_f32 v[168:169], v[168:169], v[168:169] op_sel:[0,1] op_sel_hi:[1,0]
	s_nop 0
	v_permlane16_swap_b32_e32 v166, v159
	v_add_f32_e32 v175, v166, v159
	v_mov_b32_e32 v159, v168
	s_nop 1
	v_permlane16_swap_b32_e32 v168, v159
	global_load_dwordx4 v[186:189], v[178:179], off offset:528
	global_load_dwordx4 v[190:193], v[178:179], off offset:512
	v_add_f32_e32 v174, v168, v159
	v_mov_b32_e32 v166, v200
	v_mov_b32_e32 v167, v204
	v_mov_b32_e32 v168, v202
	v_mov_b32_e32 v169, v206
	v_mov_b32_e32 v204, v201
	v_mov_b32_e32 v206, v203
	v_pk_add_f32 v[166:167], v[166:167], v[168:169]
	v_pk_add_f32 v[168:169], v[204:205], v[206:207]
	global_load_dwordx4 v[196:199], v[154:155], off offset:528
	global_load_dwordx4 v[200:203], v[154:155], off offset:512
	global_load_dwordx4 v[204:207], v[156:157], off offset:528
	global_load_dwordx4 v[242:245], v[156:157], off offset:512
	v_sub_f32_e32 v179, v215, v225
	v_sub_f32_e32 v178, v214, v225
	v_sub_f32_e32 v213, v213, v225
	v_sub_f32_e32 v212, v212, v225
	v_pk_mul_f32 v[212:213], v[0:1], v[212:213] op_sel_hi:[0,1]
	v_pk_mul_f32 v[178:179], v[0:1], v[178:179] op_sel_hi:[0,1]
	v_pk_fma_f32 v[178:179], v[222:223], v[178:179], v[240:241]
	v_pk_fma_f32 v[212:213], v[220:221], v[212:213], v[238:239]
; __device__ __forceinline__ size_t blk_off(int r, int c, int K) { return (size_t)(r >> 8) * 256 * K + (size_t)(c >> 6) * (256 * 64) + (size_t)((r & 255) * 64 + (c & 63)); }
; __device__ __forceinline__ u32x4 pack8(const f32x4 a, const f32x4 b) { u32x4 w; w.x = cvt_pk_bf16(a[0], a[1]); w.y = cvt_pk_bf16(a[2], a[3]); w.z = cvt_pk_bf16(b[0], b[1]); w.w = cvt_pk_bf16(b[2], b[3]); return w; }
;     __device__ __forceinline__ void operator()(const f32x4 (&acc)[2][2][4][2], const pg8::Unit& u, int wr, int wc, int fr, int fq) const {
;     ...
;                 for (int bj = 0; bj < 2; ++bj) { float* yp = Y + (size_t)row * D_ + col0 + bj * 128; f32x4 v[2];
; #pragma unroll
;                     for (int n = 0; n < 2; ++n) { v[n] = (((yv[bj][n] - mu) * rs) * gq[bj][n] + bq_[bj][n]) * ALPHA_ + acc[ai][bj][m][n] * sc;
;                         *(f32x4*)(yp + 4 * n) = v[n]; s1 += (v[n][0] + v[n][1]) + (v[n][2] + v[n][3]); s2 += (v[n][0] * v[n][0] + v[n][1] * v[n][1]) + (v[n][2] * v[n][2] + v[n][3] * v[n][3]); }
;                     *(u32x4*)(Yb + blk_off(row, col0 + bj * 128, D_)) = pack8(v[0], v[1]); }
	v_pk_mul_f32 v[178:179], v[178:179], s[18:19] op_sel_hi:[1,0]
	v_pk_mul_f32 v[212:213], v[212:213], s[18:19] op_sel_hi:[1,0]
	v_pk_fma_f32 v[128:129], v[128:129], 0.5, v[178:179] op_sel_hi:[1,0,1]
	v_pk_fma_f32 v[126:127], v[126:127], 0.5, v[212:213] op_sel_hi:[1,0,1]
	v_add_f32_e32 v179, v128, v129
	v_add_f32_e32 v178, v126, v127
	v_add_f32_e32 v178, v178, v179
	v_add_f32_e32 v195, 0, v178
	v_mul_f32_e32 v178, v127, v127
	v_mul_f32_e32 v179, v129, v129
	v_fmac_f32_e32 v178, v126, v126
	v_fmac_f32_e32 v179, v128, v128
	v_add_f32_e32 v212, v178, v179
	v_sub_f32_e32 v179, v211, v225
	v_sub_f32_e32 v178, v210, v225
	v_sub_f32_e32 v209, v209, v225
	v_sub_f32_e32 v208, v208, v225
	v_pk_mul_f32 v[208:209], v[0:1], v[208:209] op_sel_hi:[0,1]
	v_pk_mul_f32 v[178:179], v[0:1], v[178:179] op_sel_hi:[0,1]
	v_pk_fma_f32 v[178:179], v[218:219], v[178:179], v[236:237]
	v_pk_fma_f32 v[208:209], v[216:217], v[208:209], v[234:235]
	v_pk_mul_f32 v[178:179], v[178:179], s[18:19] op_sel_hi:[1,0]
	v_pk_mul_f32 v[208:209], v[208:209], s[18:19] op_sel_hi:[1,0]
	v_pk_add_f32 v[166:167], v[166:167], v[166:167] op_sel:[0,1] op_sel_hi:[1,0]
	v_pk_fma_f32 v[124:125], v[124:125], 0.5, v[178:179] op_sel_hi:[1,0,1]
	v_pk_fma_f32 v[122:123], v[122:123], 0.5, v[208:209] op_sel_hi:[1,0,1]
	v_mov_b32_e32 v159, v166
	v_add_f32_e32 v178, v122, v123
	v_add_f32_e32 v179, v124, v125
	v_pk_add_f32 v[168:169], v[168:169], v[168:169] op_sel:[0,1] op_sel_hi:[1,0]
	v_permlane16_swap_b32_e32 v166, v159
	v_add_f32_e32 v178, v178, v179
	v_add_f32_e32 v167, v166, v159
	v_mov_b32_e32 v159, v168
	v_add_f32_e32 v178, v195, v178
	v_mul_f32_e32 v179, v123, v123
	v_mul_f32_e32 v195, v125, v125
	v_permlane16_swap_b32_e32 v168, v159
	s_ashr_i32 s16, s3, 8
	s_nop 0
	s_nop 1
	v_bfe_u32 v135, v227, 4, 2
	v_sub_u32_e32 v134, 0, v135
	v_lshlrev_b32_e32 v134, 4, v134
	v_ashrrev_i32_e32 v135, 31, v134
	v_lshl_add_u64 v[134:135], v[136:137], 0, v[134:135]
	v_permlane16_swap_b32_e32 v126, v122
	v_permlane16_swap_b32_e32 v127, v123
	v_permlane16_swap_b32_e32 v128, v124
	v_permlane16_swap_b32_e32 v129, v125
	v_permlane32_swap_b32_e32 v126, v122
	v_permlane32_swap_b32_e32 v127, v123
	v_permlane32_swap_b32_e32 v128, v124
	v_permlane32_swap_b32_e32 v129, v125
	v_mov_b32_e32 v166, v126
	v_mov_b32_e32 v169, v127
	v_mov_b32_e32 v208, v128
	v_mov_b32_e32 v209, v129
	v_bfe_u32 v176, v227, 3, 1
	v_mul_i32_i24_e32 v176, 0xffff8040, v176
	v_ashrrev_i32_e32 v177, 31, v176
	v_lshl_add_u64 v[134:135], v[134:135], 0, v[176:177]
	v_mov_b32_e32 v176, 0x8000
	v_mov_b32_e32 v177, 0
	v_lshl_add_u64 v[176:177], v[134:135], 0, v[176:177]
	v_mov_b32_dpp v126, v122 row_ror:8 row_mask:0xf bank_mask:0xc
	v_mov_b32_dpp v127, v123 row_ror:8 row_mask:0xf bank_mask:0xc
	v_mov_b32_dpp v128, v124 row_ror:8 row_mask:0xf bank_mask:0xc
	v_mov_b32_dpp v129, v125 row_ror:8 row_mask:0xf bank_mask:0xc
	v_mov_b32_dpp v122, v166 row_ror:8 row_mask:0xf bank_mask:0x3
	v_mov_b32_dpp v123, v169 row_ror:8 row_mask:0xf bank_mask:0x3
	v_mov_b32_dpp v124, v208 row_ror:8 row_mask:0xf bank_mask:0x3
	v_mov_b32_dpp v125, v209 row_ror:8 row_mask:0xf bank_mask:0x3
	global_store_dwordx4 v[134:135], v[126:129], off
	global_store_dwordx4 v[176:177], v[122:125], off
	s_nop 1
	v_mov_b32_dpp v122, v126 row_ror:8 row_mask:0xf bank_mask:0x3
	v_mov_b32_dpp v123, v127 row_ror:8 row_mask:0xf bank_mask:0x3
	v_mov_b32_dpp v124, v128 row_ror:8 row_mask:0xf bank_mask:0x3
	v_mov_b32_dpp v125, v129 row_ror:8 row_mask:0xf bank_mask:0x3
	v_mov_b32_e32 v126, v166
	v_mov_b32_e32 v127, v169
	v_mov_b32_e32 v128, v208
	v_mov_b32_e32 v129, v209
	s_nop 1
	v_permlane32_swap_b32_e32 v126, v122
	v_permlane32_swap_b32_e32 v127, v123
	v_permlane32_swap_b32_e32 v128, v124
	v_permlane32_swap_b32_e32 v129, v125
	v_permlane16_swap_b32_e32 v126, v122
	v_permlane16_swap_b32_e32 v127, v123
	v_permlane16_swap_b32_e32 v128, v124
	v_permlane16_swap_b32_e32 v129, v125
	v_fmac_f32_e32 v179, v122, v122
	v_fmac_f32_e32 v195, v124, v124
	v_cvt_pk_bf16_f32 v126, v126, v127
	v_cvt_pk_bf16_f32 v127, v128, v129
	v_cvt_pk_bf16_f32 v128, v122, v123
	v_cvt_pk_bf16_f32 v129, v124, v125
	v_add_f32_e32 v166, v168, v159
	s_ashr_i32 s17, s16, 31
	v_lshlrev_b32_e32 v159, 6, v158
	s_movk_i32 s3, 0x33c0
	s_lshl_b64 s[16:17], s[16:17], 19
	v_and_or_b32 v159, v159, s3, v194
	v_readlane_b32 s2, v253, 59
	v_readlane_b32 s3, v253, 60
	s_add_u32 s16, s2, s16
	s_addc_u32 s17, s3, s17
	s_lshl_b64 s[28:29], s[40:41], 15
	s_waitcnt vmcnt(6)
	v_sub_f32_e32 v123, v193, v225
	v_sub_f32_e32 v122, v192, v225
	v_sub_f32_e32 v125, v191, v225
	v_sub_f32_e32 v124, v190, v225
	v_pk_mul_f32 v[124:125], v[0:1], v[124:125] op_sel_hi:[0,1]
	v_pk_mul_f32 v[122:123], v[0:1], v[122:123] op_sel_hi:[0,1]
	s_add_u32 s50, s16, s28
	s_addc_u32 s51, s17, s29
	v_lshlrev_b32_e32 v159, 1, v159
	global_store_dwordx4 v159, v[126:129], s[50:51]
	s_waitcnt vmcnt(3)
; __device__ __forceinline__ float xsum16(float v) { const auto r = __builtin_amdgcn_permlane16_swap(__float_as_uint(v), __float_as_uint(v), false, false); return __uint_as_float(r[0]) + __uint_as_float(r[1]); }
; __device__ __forceinline__ float xsum32(float v) { const auto r = __builtin_amdgcn_permlane32_swap(__float_as_uint(v), __float_as_uint(v), false, false); return __uint_as_float(r[0]) + __uint_as_float(r[1]); }
; __device__ __forceinline__ size_t blk_off(int r, int c, int K) { return (size_t)(r >> 8) * 256 * K + (size_t)(c >> 6) * (256 * 64) + (size_t)((r & 255) * 64 + (c & 63)); }
; __device__ __forceinline__ u32x4 pack8(const f32x4 a, const f32x4 b) { u32x4 w; w.x = cvt_pk_bf16(a[0], a[1]); w.y = cvt_pk_bf16(a[2], a[3]); w.z = cvt_pk_bf16(b[0], b[1]); w.w = cvt_pk_bf16(b[2], b[3]); return w; }
;     __device__ __forceinline__ void operator()(const f32x4 (&acc)[2][2][4][2], const pg8::Unit& u, int wr, int wc, int fr, int fq) const {
;     ...
;                 for (int bj = 0; bj < 2; ++bj) { float* yp = Y + (size_t)row * D_ + col0 + bj * 128; f32x4 v[2];
; #pragma unroll
;                     for (int n = 0; n < 2; ++n) { v[n] = (((yv[bj][n] - mu) * rs) * gq[bj][n] + bq_[bj][n]) * ALPHA_ + acc[ai][bj][m][n] * sc;
;                         *(f32x4*)(yp + 4 * n) = v[n]; s1 += (v[n][0] + v[n][1]) + (v[n][2] + v[n][3]); s2 += (v[n][0] * v[n][0] + v[n][1] * v[n][1]) + (v[n][2] * v[n][2] + v[n][3] * v[n][3]); }
;                     *(u32x4*)(Yb + blk_off(row, col0 + bj * 128, D_)) = pack8(v[0], v[1]); }
;                 s1 = xsum32(xsum16(s1)); s2 = xsum32(xsum16(s2));
;                 if (fq == 0) *(f32x2*)(stn + (size_t)row * 32 + (u.pn * 4 + wc) * 2) = (f32x2){s1, s2}; asm volatile("" ::: "memory"); } }
	v_pk_fma_f32 v[122:123], v[202:203], v[122:123], v[244:245]
	v_pk_fma_f32 v[124:125], v[200:201], v[124:125], v[242:243]
	v_pk_mul_f32 v[122:123], v[122:123], s[18:19] op_sel_hi:[1,0]
	v_pk_mul_f32 v[124:125], v[124:125], s[18:19] op_sel_hi:[1,0]
	v_pk_fma_f32 v[120:121], v[120:121], 0.5, v[122:123] op_sel_hi:[1,0,1]
	v_pk_fma_f32 v[118:119], v[118:119], 0.5, v[124:125] op_sel_hi:[1,0,1]
	v_add_f32_e32 v123, v120, v121
	v_add_f32_e32 v122, v118, v119
	v_add_f32_e32 v122, v122, v123
	v_add_f32_e32 v126, v178, v122
	v_mul_f32_e32 v122, v119, v119
	v_mul_f32_e32 v123, v121, v121
	v_add_f32_e32 v179, v179, v195
	v_fmac_f32_e32 v122, v118, v118
	v_fmac_f32_e32 v123, v120, v120
	v_add_f32_e32 v179, v212, v179
	v_add_f32_e32 v122, v122, v123
	v_add_f32_e32 v127, v179, v122
	v_sub_f32_e32 v123, v189, v225
	v_sub_f32_e32 v122, v188, v225
	v_sub_f32_e32 v125, v187, v225
	v_sub_f32_e32 v124, v186, v225
	v_pk_mul_f32 v[124:125], v[0:1], v[124:125] op_sel_hi:[0,1]
	v_pk_mul_f32 v[122:123], v[0:1], v[122:123] op_sel_hi:[0,1]
	v_pk_fma_f32 v[122:123], v[198:199], v[122:123], v[206:207]
	v_pk_fma_f32 v[124:125], v[196:197], v[124:125], v[204:205]
	v_pk_mul_f32 v[122:123], v[122:123], s[18:19] op_sel_hi:[1,0]
	v_pk_mul_f32 v[124:125], v[124:125], s[18:19] op_sel_hi:[1,0]
	v_pk_fma_f32 v[116:117], v[116:117], 0.5, v[122:123] op_sel_hi:[1,0,1]
	v_pk_fma_f32 v[114:115], v[114:115], 0.5, v[124:125] op_sel_hi:[1,0,1]
	v_add_f32_e32 v122, v116, v117
	v_add_f32_e32 v0, v114, v115
	v_add_f32_e32 v0, v0, v122
	v_mul_f32_e32 v122, v115, v115
	v_mul_f32_e32 v123, v117, v117
	v_add_f32_e32 v0, v126, v0
	v_fmac_f32_e32 v122, v114, v114
	v_fmac_f32_e32 v123, v116, v116
	s_nop 0
	s_nop 1
	v_bfe_u32 v125, v227, 4, 2
	v_sub_u32_e32 v124, 0, v125
	v_lshlrev_b32_e32 v124, 4, v124
	v_ashrrev_i32_e32 v125, 31, v124
	v_lshl_add_u64 v[124:125], v[136:137], 0, v[124:125]
	v_permlane16_swap_b32_e32 v118, v114
	v_permlane16_swap_b32_e32 v119, v115
	v_permlane16_swap_b32_e32 v120, v116
	v_permlane16_swap_b32_e32 v121, v117
	v_permlane32_swap_b32_e32 v118, v114
	v_permlane32_swap_b32_e32 v119, v115
	v_permlane32_swap_b32_e32 v120, v116
	v_permlane32_swap_b32_e32 v121, v117
	v_mov_b32_e32 v134, v118
	v_mov_b32_e32 v135, v119
	v_mov_b32_e32 v168, v120
	v_mov_b32_e32 v169, v121
	v_bfe_u32 v128, v227, 3, 1
	v_mul_i32_i24_e32 v128, 0xffff8040, v128
	v_ashrrev_i32_e32 v129, 31, v128
	v_lshl_add_u64 v[124:125], v[124:125], 0, v[128:129]
	v_mov_b32_e32 v128, 0x8000
	v_mov_b32_e32 v129, 0
	v_lshl_add_u64 v[128:129], v[124:125], 0, v[128:129]
	v_mov_b32_dpp v118, v114 row_ror:8 row_mask:0xf bank_mask:0xc
	v_mov_b32_dpp v119, v115 row_ror:8 row_mask:0xf bank_mask:0xc
	v_mov_b32_dpp v120, v116 row_ror:8 row_mask:0xf bank_mask:0xc
	v_mov_b32_dpp v121, v117 row_ror:8 row_mask:0xf bank_mask:0xc
	v_mov_b32_dpp v114, v134 row_ror:8 row_mask:0xf bank_mask:0x3
	v_mov_b32_dpp v115, v135 row_ror:8 row_mask:0xf bank_mask:0x3
	v_mov_b32_dpp v116, v168 row_ror:8 row_mask:0xf bank_mask:0x3
	v_mov_b32_dpp v117, v169 row_ror:8 row_mask:0xf bank_mask:0x3
	global_store_dwordx4 v[124:125], v[118:121], off offset:512
	global_store_dwordx4 v[128:129], v[114:117], off offset:512
	s_nop 1
	v_mov_b32_dpp v114, v118 row_ror:8 row_mask:0xf bank_mask:0x3
	v_mov_b32_dpp v115, v119 row_ror:8 row_mask:0xf bank_mask:0x3
	v_mov_b32_dpp v116, v120 row_ror:8 row_mask:0xf bank_mask:0x3
	v_mov_b32_dpp v117, v121 row_ror:8 row_mask:0xf bank_mask:0x3
	v_mov_b32_e32 v118, v134
	v_mov_b32_e32 v119, v135
	v_mov_b32_e32 v120, v168
	v_mov_b32_e32 v121, v169
	s_nop 1
	v_permlane32_swap_b32_e32 v118, v114
	v_permlane32_swap_b32_e32 v119, v115
	v_permlane32_swap_b32_e32 v120, v116
	v_permlane32_swap_b32_e32 v121, v117
	v_permlane16_swap_b32_e32 v118, v114
	v_permlane16_swap_b32_e32 v119, v115
	v_permlane16_swap_b32_e32 v120, v116
	v_permlane16_swap_b32_e32 v121, v117
	v_add_f32_e32 v122, v122, v123
	v_cvt_pk_bf16_f32 v118, v118, v119
	v_cvt_pk_bf16_f32 v119, v120, v121
	v_cvt_pk_bf16_f32 v120, v114, v115
	v_mov_b32_e32 v114, v0
	v_add_f32_e32 v122, v127, v122
	s_nop 0
	v_permlane16_swap_b32_e32 v0, v114
	s_or_b32 s2, s40, 2
	v_add_f32_e32 v114, v0, v114
	v_mov_b32_e32 v0, v122
	s_ashr_i32 s3, s2, 31
	s_nop 0
	v_permlane16_swap_b32_e32 v122, v0
	s_lshl_b64 s[40:41], s[2:3], 15
	v_add_f32_e32 v115, v122, v0
	v_mov_b32_e32 v135, v133
	v_mov_b32_e32 v134, v132
	v_mov_b32_e32 v177, v175
	v_mov_b32_e32 v176, v174
	v_mov_b32_e32 v169, v167
	v_mov_b32_e32 v168, v166
	v_cvt_pk_bf16_f32 v121, v116, v117
	s_add_u32 s42, s16, s40
	v_mov_b32_e32 v116, v114
	v_mov_b32_e32 v117, v115
	v_permlane32_swap_b32_e32 v133, v135
	v_permlane32_swap_b32_e32 v132, v134
	v_permlane32_swap_b32_e32 v175, v177
	v_permlane32_swap_b32_e32 v174, v176
	v_permlane32_swap_b32_e32 v167, v169
	v_permlane32_swap_b32_e32 v166, v168
	s_addc_u32 s43, s17, s41
	v_permlane32_swap_b32_e32 v114, v116
	v_permlane32_swap_b32_e32 v115, v117
	global_store_dwordx4 v159, v[118:121], s[42:43]
	s_and_saveexec_b64 s[26:27], s[44:45]
	s_cbranch_execz .LBB0_374
	v_pk_add_f32 v[114:115], v[114:115], v[116:117]
	v_lshl_add_u64 v[116:117], s[30:31], 0, v[130:131]
	v_lshl_add_u64 v[116:117], s[24:25], 2, v[116:117]
	global_store_dwordx2 v[116:117], v[114:115], off
; __device__ __forceinline__ float xsum16(float v) { const auto r = __builtin_amdgcn_permlane16_swap(__float_as_uint(v), __float_as_uint(v), false, false); return __uint_as_float(r[0]) + __uint_as_float(r[1]); }
; __device__ __forceinline__ void row_stats4(const float* st, int rowb, int fq, float (&mu)[4], float (&rs)[4]) {
;     f32x4 a[4], b[4];
; #pragma unroll
;     for (int m = 0; m < 4; ++m) { const f32x4* p = (const f32x4*)(st + (size_t)(rowb + m * 16) * 32 + fq * 8); a[m] = p[0]; b[m] = p[1]; }
; #pragma unroll
;     for (int m = 0; m < 4; ++m) { float s1 = (a[m][0] + a[m][2]) + (b[m][0] + b[m][2]), s2 = (a[m][1] + a[m][3]) + (b[m][1] + b[m][3]);
;         s1 = xsum32(xsum16(s1)); s2 = xsum32(xsum16(s2));
;         const float mm = s1 * (1.0f / 1024.0f); mu[m] = mm; rs[m] = rsqrtf(fmaxf(s2 * (1.0f / 1024.0f) - mm * mm, 0.f) + LN_EPS_); }
;     asm volatile("" ::: "memory");
; }
;     __device__ __forceinline__ void operator()(const f32x4 (&acc)[2][2][4][2], const pg8::Unit& u, int wr, int wc, int fr, int fq) const {
;     ...
;             for (int m = 0; m < 4; ++m) { const int row = row0 + ai * 128 + m * 16; const float mu = mu4[m], rs = rs4[m];
;                 f32x4 yv[2][2], gq[2][2], bq_[2][2];
; #pragma unroll
;                 for (int bj = 0; bj < 2; ++bj)
; #pragma unroll
;                     for (int n = 0; n < 2; ++n) { yv[bj][n] = *(const f32x4*)(Yin + (size_t)row * D_ + col0 + bj * 128 + 4 * n); gq[bj][n] = *(const f32x4*)(g + col0 + bj * 128 + 4 * n); bq_[bj][n] = *(const f32x4*)(b + col0 + bj * 128 + 4 * n); }
;                 asm volatile("" ::: "memory");
;                 float s1 = 0.f, s2 = 0.f;
; #pragma unroll
;                 for (int bj = 0; bj < 2; ++bj) { float* yp = Y + (size_t)row * D_ + col0 + bj * 128; f32x4 v[2];
; #pragma unroll
;                     for (int n = 0; n < 2; ++n) { v[n] = (((yv[bj][n] - mu) * rs) * gq[bj][n] + bq_[bj][n]) * ALPHA_ + acc[ai][bj][m][n] * sc;
;                         *(f32x4*)(yp + 4 * n) = v[n]; s1 += (v[n][0] + v[n][1]) + (v[n][2] + v[n][3]); s2 += (v[n][0] * v[n][0] + v[n][1] * v[n][1]) + (v[n][2] * v[n][2] + v[n][3] * v[n][3]); }
;                     *(u32x4*)(Yb + blk_off(row, col0 + bj * 128, D_)) = pack8(v[0], v[1]); }
.LBB0_374:
	s_or_b64 exec, exec, s[26:27]
	v_pk_add_f32 v[114:115], v[132:133], v[134:135]
	s_mov_b32 s2, 0x3a800000
	v_pk_mul_f32 v[178:179], v[114:115], s[2:3] op_sel_hi:[1,0]
	s_mov_b32 s2, 0x800000
	v_fma_f32 v0, -v179, v179, v178
	v_max_f32_e32 v0, 0, v0
	v_add_f32_e32 v0, 0x3727c5ac, v0
	v_cmp_gt_f32_e32 vcc, s2, v0
	v_mul_f32_e32 v114, 0x4b800000, v0
	v_lshlrev_b64 v[212:213], 12, v[180:181]
	v_cndmask_b32_e32 v0, v0, v114, vcc
	v_rsq_f32_e32 v0, v0
	v_lshlrev_b32_e32 v159, 6, v180
	s_movk_i32 s2, 0x37c0
	v_mul_f32_e32 v114, 0x45800000, v0
	v_cndmask_b32_e32 v0, v0, v114, vcc
	v_lshl_add_u64 v[114:115], s[12:13], 0, v[212:213]
	v_lshl_add_u64 v[118:119], v[114:115], 0, v[152:153]
	global_load_dwordx4 v[186:189], v[118:119], off offset:16
	global_load_dwordx4 v[190:193], v[118:119], off
	global_load_dwordx4 v[196:199], v[154:155], off offset:16
	global_load_dwordx4 v[200:203], v[154:155], off
	global_load_dwordx4 v[204:207], v[156:157], off offset:16
	global_load_dwordx4 v[208:211], v[156:157], off
	global_load_dwordx4 v[114:117], v[118:119], off offset:528
	global_load_dwordx4 v[134:137], v[118:119], off offset:512
	s_nop 0
	global_load_dwordx4 v[118:121], v[154:155], off offset:528
	global_load_dwordx4 v[126:129], v[154:155], off offset:512
	global_load_dwordx4 v[122:125], v[156:157], off offset:528
	global_load_dwordx4 v[130:133], v[156:157], off offset:512
	v_and_or_b32 v159, v159, s2, v194
	s_load_dwordx16 s[60:75], s[34:35], 0x38
	s_mov_b32 s2, 0x3fd744fd
	v_lshlrev_b32_e32 v159, 1, v159
	s_waitcnt lgkmcnt(0)
	v_lshl_add_u64 v[180:181], s[74:75], 0, v[212:213]
	v_lshl_add_u64 v[180:181], v[180:181], 0, v[152:153]
	s_waitcnt vmcnt(11)
	v_sub_f32_e32 v189, v189, v179
	s_waitcnt vmcnt(10)
	v_sub_f32_e32 v193, v193, v179
	v_sub_f32_e32 v192, v192, v179
	v_sub_f32_e32 v191, v191, v179
	v_sub_f32_e32 v190, v190, v179
	v_pk_mul_f32 v[190:191], v[0:1], v[190:191] op_sel_hi:[0,1]
	v_pk_mul_f32 v[192:193], v[0:1], v[192:193] op_sel_hi:[0,1]
	v_sub_f32_e32 v188, v188, v179
	v_sub_f32_e32 v187, v187, v179
	v_sub_f32_e32 v186, v186, v179
	s_waitcnt vmcnt(6)
	v_pk_fma_f32 v[192:193], v[202:203], v[192:193], v[210:211]
	v_pk_fma_f32 v[190:191], v[200:201], v[190:191], v[208:209]
	v_pk_mul_f32 v[186:187], v[0:1], v[186:187] op_sel_hi:[0,1]
	v_pk_mul_f32 v[188:189], v[0:1], v[188:189] op_sel_hi:[0,1]
	v_pk_mul_f32 v[190:191], v[190:191], s[2:3] op_sel_hi:[1,0]
	v_pk_mul_f32 v[192:193], v[192:193], s[2:3] op_sel_hi:[1,0]
	v_pk_fma_f32 v[188:189], v[198:199], v[188:189], v[206:207]
	v_pk_fma_f32 v[186:187], v[196:197], v[186:187], v[204:205]
	v_pk_fma_f32 v[112:113], v[112:113], 0.5, v[192:193] op_sel_hi:[1,0,1]
	v_pk_fma_f32 v[110:111], v[110:111], 0.5, v[190:191] op_sel_hi:[1,0,1]
	v_pk_mul_f32 v[186:187], v[186:187], s[2:3] op_sel_hi:[1,0]
	v_pk_mul_f32 v[188:189], v[188:189], s[2:3] op_sel_hi:[1,0]
	v_add_f32_e32 v178, v110, v111
	v_add_f32_e32 v190, v112, v113
	v_pk_fma_f32 v[108:109], v[108:109], 0.5, v[188:189] op_sel_hi:[1,0,1]
	v_pk_fma_f32 v[106:107], v[106:107], 0.5, v[186:187] op_sel_hi:[1,0,1]
	v_add_f32_e32 v178, v178, v190
	v_add_f32_e32 v186, v106, v107
	v_add_f32_e32 v187, v108, v109
	v_add_f32_e32 v178, 0, v178
	v_add_f32_e32 v186, v186, v187
	v_mul_f32_e32 v190, v111, v111
	v_mul_f32_e32 v191, v113, v113
	v_add_f32_e32 v178, v178, v186
	v_mul_f32_e32 v186, v107, v107
	v_mul_f32_e32 v187, v109, v109
	s_nop 0
	v_fmac_f32_e32 v190, v110, v110
	v_fmac_f32_e32 v191, v112, v112
	s_nop 1
	v_bfe_u32 v189, v227, 4, 2
	v_sub_u32_e32 v188, 0, v189
	v_lshlrev_b32_e32 v188, 4, v188
	v_ashrrev_i32_e32 v189, 31, v188
	v_lshl_add_u64 v[188:189], v[180:181], 0, v[188:189]
	v_permlane16_swap_b32_e32 v110, v106
	v_permlane16_swap_b32_e32 v111, v107
	v_permlane16_swap_b32_e32 v112, v108
	v_permlane16_swap_b32_e32 v113, v109
	v_permlane32_swap_b32_e32 v110, v106
	v_permlane32_swap_b32_e32 v111, v107
	v_permlane32_swap_b32_e32 v112, v108
	v_permlane32_swap_b32_e32 v113, v109
	v_mov_b32_e32 v195, v110
	v_mov_b32_e32 v196, v111
	v_mov_b32_e32 v197, v112
	v_mov_b32_e32 v198, v113
	v_bfe_u32 v192, v227, 3, 1
	v_mul_i32_i24_e32 v192, 0xffff8040, v192
	v_ashrrev_i32_e32 v193, 31, v192
	v_lshl_add_u64 v[188:189], v[188:189], 0, v[192:193]
	v_mov_b32_e32 v192, 0x8000
	v_mov_b32_e32 v193, 0
	v_lshl_add_u64 v[192:193], v[188:189], 0, v[192:193]
	v_mov_b32_dpp v110, v106 row_ror:8 row_mask:0xf bank_mask:0xc
	v_mov_b32_dpp v111, v107 row_ror:8 row_mask:0xf bank_mask:0xc
	v_mov_b32_dpp v112, v108 row_ror:8 row_mask:0xf bank_mask:0xc
	v_mov_b32_dpp v113, v109 row_ror:8 row_mask:0xf bank_mask:0xc
	v_mov_b32_dpp v106, v195 row_ror:8 row_mask:0xf bank_mask:0x3
	v_mov_b32_dpp v107, v196 row_ror:8 row_mask:0xf bank_mask:0x3
	v_mov_b32_dpp v108, v197 row_ror:8 row_mask:0xf bank_mask:0x3
	v_mov_b32_dpp v109, v198 row_ror:8 row_mask:0xf bank_mask:0x3
	global_store_dwordx4 v[188:189], v[110:113], off
	global_store_dwordx4 v[192:193], v[106:109], off
	s_nop 1
	v_mov_b32_dpp v106, v110 row_ror:8 row_mask:0xf bank_mask:0x3
	v_mov_b32_dpp v107, v111 row_ror:8 row_mask:0xf bank_mask:0x3
	v_mov_b32_dpp v108, v112 row_ror:8 row_mask:0xf bank_mask:0x3
	v_mov_b32_dpp v109, v113 row_ror:8 row_mask:0xf bank_mask:0x3
	v_mov_b32_e32 v110, v195
	v_mov_b32_e32 v111, v196
	v_mov_b32_e32 v112, v197
	v_mov_b32_e32 v113, v198
	s_nop 1
	v_permlane32_swap_b32_e32 v110, v106
	v_permlane32_swap_b32_e32 v111, v107
	v_permlane32_swap_b32_e32 v112, v108
	v_permlane32_swap_b32_e32 v113, v109
	v_permlane16_swap_b32_e32 v110, v106
	v_permlane16_swap_b32_e32 v111, v107
	v_permlane16_swap_b32_e32 v112, v108
	v_permlane16_swap_b32_e32 v113, v109
	v_fmac_f32_e32 v186, v106, v106
	v_fmac_f32_e32 v187, v108, v108
	v_cvt_pk_bf16_f32 v110, v110, v111
	v_cvt_pk_bf16_f32 v111, v112, v113
	v_cvt_pk_bf16_f32 v112, v106, v107
	v_cvt_pk_bf16_f32 v113, v108, v109
	s_waitcnt vmcnt(6)
; __device__ __forceinline__ float xsum16(float v) { const auto r = __builtin_amdgcn_permlane16_swap(__float_as_uint(v), __float_as_uint(v), false, false); return __uint_as_float(r[0]) + __uint_as_float(r[1]); }
; __device__ __forceinline__ float xsum32(float v) { const auto r = __builtin_amdgcn_permlane32_swap(__float_as_uint(v), __float_as_uint(v), false, false); return __uint_as_float(r[0]) + __uint_as_float(r[1]); }
; __device__ __forceinline__ size_t blk_off(int r, int c, int K) { return (size_t)(r >> 8) * 256 * K + (size_t)(c >> 6) * (256 * 64) + (size_t)((r & 255) * 64 + (c & 63)); }
; __device__ __forceinline__ u32x4 pack8(const f32x4 a, const f32x4 b) { u32x4 w; w.x = cvt_pk_bf16(a[0], a[1]); w.y = cvt_pk_bf16(a[2], a[3]); w.z = cvt_pk_bf16(b[0], b[1]); w.w = cvt_pk_bf16(b[2], b[3]); return w; }
;     __device__ __forceinline__ void operator()(const f32x4 (&acc)[2][2][4][2], const pg8::Unit& u, int wr, int wc, int fr, int fq) const {
;     ...
;                 for (int bj = 0; bj < 2; ++bj) { float* yp = Y + (size_t)row * D_ + col0 + bj * 128; f32x4 v[2];
; #pragma unroll
;                     for (int n = 0; n < 2; ++n) { v[n] = (((yv[bj][n] - mu) * rs) * gq[bj][n] + bq_[bj][n]) * ALPHA_ + acc[ai][bj][m][n] * sc;
;                         *(f32x4*)(yp + 4 * n) = v[n]; s1 += (v[n][0] + v[n][1]) + (v[n][2] + v[n][3]); s2 += (v[n][0] * v[n][0] + v[n][1] * v[n][1]) + (v[n][2] * v[n][2] + v[n][3] * v[n][3]); }
;                     *(u32x4*)(Yb + blk_off(row, col0 + bj * 128, D_)) = pack8(v[0], v[1]); }
;                 s1 = xsum32(xsum16(s1)); s2 = xsum32(xsum16(s2));
;                 if (fq == 0) *(f32x2*)(stn + (size_t)row * 32 + (u.pn * 4 + wc) * 2) = (f32x2){s1, s2}; asm volatile("" ::: "memory"); } }
	v_sub_f32_e32 v107, v137, v179
	v_sub_f32_e32 v106, v136, v179
	v_sub_f32_e32 v109, v135, v179
	v_sub_f32_e32 v108, v134, v179
	v_pk_mul_f32 v[108:109], v[0:1], v[108:109] op_sel_hi:[0,1]
	v_pk_mul_f32 v[106:107], v[0:1], v[106:107] op_sel_hi:[0,1]
	s_waitcnt vmcnt(2)
	v_pk_fma_f32 v[106:107], v[128:129], v[106:107], v[132:133]
	v_pk_fma_f32 v[108:109], v[126:127], v[108:109], v[130:131]
	v_pk_mul_f32 v[106:107], v[106:107], s[2:3] op_sel_hi:[1,0]
	v_pk_mul_f32 v[108:109], v[108:109], s[2:3] op_sel_hi:[1,0]
	v_pk_fma_f32 v[104:105], v[104:105], 0.5, v[106:107] op_sel_hi:[1,0,1]
	v_pk_fma_f32 v[102:103], v[102:103], 0.5, v[108:109] op_sel_hi:[1,0,1]
	v_add_f32_e32 v107, v104, v105
	v_add_f32_e32 v106, v102, v103
	v_add_f32_e32 v106, v106, v107
	global_store_dwordx4 v159, v[110:113], s[50:51]
	v_mul_f32_e32 v107, v105, v105
	v_add_f32_e32 v190, v190, v191
	v_add_f32_e32 v110, v178, v106
	v_mul_f32_e32 v106, v103, v103
	v_add_f32_e32 v186, v186, v187
	v_fmac_f32_e32 v106, v102, v102
	v_fmac_f32_e32 v107, v104, v104
	v_add_f32_e32 v186, v190, v186
	v_add_f32_e32 v106, v106, v107
	v_add_f32_e32 v111, v186, v106
	v_sub_f32_e32 v107, v117, v179
	v_sub_f32_e32 v106, v116, v179
	v_sub_f32_e32 v109, v115, v179
	v_sub_f32_e32 v108, v114, v179
	v_pk_mul_f32 v[108:109], v[0:1], v[108:109] op_sel_hi:[0,1]
	v_pk_mul_f32 v[106:107], v[0:1], v[106:107] op_sel_hi:[0,1]
	v_pk_fma_f32 v[106:107], v[120:121], v[106:107], v[124:125]
	v_pk_fma_f32 v[108:109], v[118:119], v[108:109], v[122:123]
	v_pk_mul_f32 v[106:107], v[106:107], s[2:3] op_sel_hi:[1,0]
	v_pk_mul_f32 v[108:109], v[108:109], s[2:3] op_sel_hi:[1,0]
	v_pk_fma_f32 v[100:101], v[100:101], 0.5, v[106:107] op_sel_hi:[1,0,1]
	v_pk_fma_f32 v[98:99], v[98:99], 0.5, v[108:109] op_sel_hi:[1,0,1]
	v_add_f32_e32 v106, v100, v101
	v_add_f32_e32 v0, v98, v99
	v_add_f32_e32 v0, v0, v106
	v_mul_f32_e32 v106, v99, v99
	v_mul_f32_e32 v107, v101, v101
	v_add_f32_e32 v0, v110, v0
	v_fmac_f32_e32 v106, v98, v98
	v_fmac_f32_e32 v107, v100, v100
	s_nop 0
	s_nop 1
	v_bfe_u32 v109, v227, 4, 2
	v_sub_u32_e32 v108, 0, v109
	v_lshlrev_b32_e32 v108, 4, v108
	v_ashrrev_i32_e32 v109, 31, v108
	v_lshl_add_u64 v[108:109], v[180:181], 0, v[108:109]
	v_permlane16_swap_b32_e32 v102, v98
	v_permlane16_swap_b32_e32 v103, v99
	v_permlane16_swap_b32_e32 v104, v100
	v_permlane16_swap_b32_e32 v105, v101
	v_permlane32_swap_b32_e32 v102, v98
	v_permlane32_swap_b32_e32 v103, v99
	v_permlane32_swap_b32_e32 v104, v100
	v_permlane32_swap_b32_e32 v105, v101
	v_mov_b32_e32 v114, v102
	v_mov_b32_e32 v115, v103
	v_mov_b32_e32 v116, v104
	v_mov_b32_e32 v117, v105
	v_bfe_u32 v112, v227, 3, 1
	v_mul_i32_i24_e32 v112, 0xffff8040, v112
	v_ashrrev_i32_e32 v113, 31, v112
	v_lshl_add_u64 v[108:109], v[108:109], 0, v[112:113]
	v_mov_b32_e32 v112, 0x8000
	v_mov_b32_e32 v113, 0
	v_lshl_add_u64 v[112:113], v[108:109], 0, v[112:113]
	v_mov_b32_dpp v102, v98 row_ror:8 row_mask:0xf bank_mask:0xc
	v_mov_b32_dpp v103, v99 row_ror:8 row_mask:0xf bank_mask:0xc
	v_mov_b32_dpp v104, v100 row_ror:8 row_mask:0xf bank_mask:0xc
	v_mov_b32_dpp v105, v101 row_ror:8 row_mask:0xf bank_mask:0xc
	v_mov_b32_dpp v98, v114 row_ror:8 row_mask:0xf bank_mask:0x3
	v_mov_b32_dpp v99, v115 row_ror:8 row_mask:0xf bank_mask:0x3
	v_mov_b32_dpp v100, v116 row_ror:8 row_mask:0xf bank_mask:0x3
	v_mov_b32_dpp v101, v117 row_ror:8 row_mask:0xf bank_mask:0x3
	global_store_dwordx4 v[108:109], v[102:105], off offset:512
	global_store_dwordx4 v[112:113], v[98:101], off offset:512
	s_nop 1
	v_mov_b32_dpp v98, v102 row_ror:8 row_mask:0xf bank_mask:0x3
	v_mov_b32_dpp v99, v103 row_ror:8 row_mask:0xf bank_mask:0x3
	v_mov_b32_dpp v100, v104 row_ror:8 row_mask:0xf bank_mask:0x3
	v_mov_b32_dpp v101, v105 row_ror:8 row_mask:0xf bank_mask:0x3
	v_mov_b32_e32 v102, v114
	v_mov_b32_e32 v103, v115
	v_mov_b32_e32 v104, v116
	v_mov_b32_e32 v105, v117
	s_nop 1
	v_permlane32_swap_b32_e32 v102, v98
	v_permlane32_swap_b32_e32 v103, v99
	v_permlane32_swap_b32_e32 v104, v100
	v_permlane32_swap_b32_e32 v105, v101
	v_permlane16_swap_b32_e32 v102, v98
	v_permlane16_swap_b32_e32 v103, v99
	v_permlane16_swap_b32_e32 v104, v100
	v_permlane16_swap_b32_e32 v105, v101
	v_add_f32_e32 v106, v106, v107
	v_cvt_pk_bf16_f32 v102, v102, v103
	v_cvt_pk_bf16_f32 v103, v104, v105
	v_cvt_pk_bf16_f32 v104, v98, v99
	v_mov_b32_e32 v98, v0
	v_add_f32_e32 v106, v111, v106
	s_nop 0
	v_permlane16_swap_b32_e32 v0, v98
	v_add_f32_e32 v98, v0, v98
	v_mov_b32_e32 v0, v106
	s_nop 1
	v_permlane16_swap_b32_e32 v106, v0
	v_add_f32_e32 v99, v106, v0
	v_cvt_pk_bf16_f32 v105, v100, v101
	v_mov_b32_e32 v100, v98
	v_mov_b32_e32 v101, v99
	s_nop 0
	v_permlane32_swap_b32_e32 v98, v100
	v_permlane32_swap_b32_e32 v99, v101
	global_store_dwordx4 v159, v[102:105], s[42:43]
	s_and_saveexec_b64 s[26:27], s[44:45]
	s_cbranch_execz .LBB0_376
	v_pk_add_f32 v[98:99], v[98:99], v[100:101]
	v_lshl_add_u64 v[100:101], s[30:31], 0, v[172:173]
	v_lshl_add_u64 v[100:101], s[24:25], 2, v[100:101]
	global_store_dwordx2 v[100:101], v[98:99], off
; __device__ __forceinline__ size_t blk_off(int r, int c, int K) { return (size_t)(r >> 8) * 256 * K + (size_t)(c >> 6) * (256 * 64) + (size_t)((r & 255) * 64 + (c & 63)); }
; __device__ __forceinline__ u32x4 pack8(const f32x4 a, const f32x4 b) { u32x4 w; w.x = cvt_pk_bf16(a[0], a[1]); w.y = cvt_pk_bf16(a[2], a[3]); w.z = cvt_pk_bf16(b[0], b[1]); w.w = cvt_pk_bf16(b[2], b[3]); return w; }
;     __device__ __forceinline__ void operator()(const f32x4 (&acc)[2][2][4][2], const pg8::Unit& u, int wr, int wc, int fr, int fq) const {
;     ...
;             for (int m = 0; m < 4; ++m) { const int row = row0 + ai * 128 + m * 16; const float mu = mu4[m], rs = rs4[m];
;                 f32x4 yv[2][2], gq[2][2], bq_[2][2];
; #pragma unroll
;                 for (int bj = 0; bj < 2; ++bj)
; #pragma unroll
;                     for (int n = 0; n < 2; ++n) { yv[bj][n] = *(const f32x4*)(Yin + (size_t)row * D_ + col0 + bj * 128 + 4 * n); gq[bj][n] = *(const f32x4*)(g + col0 + bj * 128 + 4 * n); bq_[bj][n] = *(const f32x4*)(b + col0 + bj * 128 + 4 * n); }
;                 asm volatile("" ::: "memory");
;                 float s1 = 0.f, s2 = 0.f;
; #pragma unroll
;                 for (int bj = 0; bj < 2; ++bj) { float* yp = Y + (size_t)row * D_ + col0 + bj * 128; f32x4 v[2];
; #pragma unroll
;                     for (int n = 0; n < 2; ++n) { v[n] = (((yv[bj][n] - mu) * rs) * gq[bj][n] + bq_[bj][n]) * ALPHA_ + acc[ai][bj][m][n] * sc;
;                         *(f32x4*)(yp + 4 * n) = v[n]; s1 += (v[n][0] + v[n][1]) + (v[n][2] + v[n][3]); s2 += (v[n][0] * v[n][0] + v[n][1] * v[n][1]) + (v[n][2] * v[n][2] + v[n][3] * v[n][3]); }
;                     *(u32x4*)(Yb + blk_off(row, col0 + bj * 128, D_)) = pack8(v[0], v[1]); }
.LBB0_376:
	s_or_b64 exec, exec, s[26:27]
	v_pk_add_f32 v[98:99], v[174:175], v[176:177]
	s_mov_b32 s2, 0x3a800000
	v_pk_mul_f32 v[122:123], v[98:99], s[2:3] op_sel_hi:[1,0]
	s_mov_b32 s2, 0x800000
	v_fma_f32 v0, -v123, v123, v122
	v_max_f32_e32 v0, 0, v0
	v_add_f32_e32 v0, 0x3727c5ac, v0
	v_cmp_gt_f32_e32 vcc, s2, v0
	v_mul_f32_e32 v98, 0x4b800000, v0
	v_lshlrev_b64 v[124:125], 12, v[170:171]
	v_cndmask_b32_e32 v0, v0, v98, vcc
	v_rsq_f32_e32 v0, v0
	s_load_dwordx16 s[60:75], s[34:35], 0x38
	v_lshlrev_b32_e32 v122, 6, v170
	v_mul_f32_e32 v98, 0x45800000, v0
	v_cndmask_b32_e32 v0, v0, v98, vcc
	v_lshl_add_u64 v[98:99], s[12:13], 0, v[124:125]
	v_lshl_add_u64 v[102:103], v[98:99], 0, v[152:153]
	global_load_dwordx4 v[126:129], v[102:103], off offset:16
	global_load_dwordx4 v[130:133], v[102:103], off
	global_load_dwordx4 v[134:137], v[154:155], off offset:16
	global_load_dwordx4 v[172:175], v[154:155], off
	global_load_dwordx4 v[176:179], v[156:157], off offset:16
	global_load_dwordx4 v[186:189], v[156:157], off
	global_load_dwordx4 v[98:101], v[102:103], off offset:528
	global_load_dwordx4 v[118:121], v[102:103], off offset:512
	s_nop 0
	global_load_dwordx4 v[102:105], v[154:155], off offset:528
	global_load_dwordx4 v[110:113], v[154:155], off offset:512
	global_load_dwordx4 v[106:109], v[156:157], off offset:528
	global_load_dwordx4 v[114:117], v[156:157], off offset:512
	s_movk_i32 s2, 0x3bc0
	v_and_or_b32 v122, v122, s2, v194
	s_mov_b32 s2, 0x3fd744fd
	s_waitcnt lgkmcnt(0)
	v_lshl_add_u64 v[124:125], s[74:75], 0, v[124:125]
	v_lshl_add_u64 v[124:125], v[124:125], 0, v[152:153]
	v_lshlrev_b32_e32 v122, 1, v122
	s_waitcnt vmcnt(11)
	v_sub_f32_e32 v129, v129, v123
	s_waitcnt vmcnt(10)
	v_sub_f32_e32 v133, v133, v123
	v_sub_f32_e32 v132, v132, v123
	v_sub_f32_e32 v131, v131, v123
	v_sub_f32_e32 v130, v130, v123
	v_sub_f32_e32 v128, v128, v123
	v_sub_f32_e32 v127, v127, v123
	v_sub_f32_e32 v126, v126, v123
	v_pk_mul_f32 v[130:131], v[0:1], v[130:131] op_sel_hi:[0,1]
	v_pk_mul_f32 v[132:133], v[0:1], v[132:133] op_sel_hi:[0,1]
	v_pk_mul_f32 v[126:127], v[0:1], v[126:127] op_sel_hi:[0,1]
	v_pk_mul_f32 v[128:129], v[0:1], v[128:129] op_sel_hi:[0,1]
	s_waitcnt vmcnt(6)
	v_pk_fma_f32 v[132:133], v[174:175], v[132:133], v[188:189]
	v_pk_fma_f32 v[130:131], v[172:173], v[130:131], v[186:187]
	v_pk_fma_f32 v[128:129], v[136:137], v[128:129], v[178:179]
	v_pk_fma_f32 v[126:127], v[134:135], v[126:127], v[176:177]
	v_pk_mul_f32 v[130:131], v[130:131], s[2:3] op_sel_hi:[1,0]
	v_pk_mul_f32 v[132:133], v[132:133], s[2:3] op_sel_hi:[1,0]
	v_pk_mul_f32 v[126:127], v[126:127], s[2:3] op_sel_hi:[1,0]
	v_pk_mul_f32 v[128:129], v[128:129], s[2:3] op_sel_hi:[1,0]
	v_pk_fma_f32 v[96:97], v[96:97], 0.5, v[132:133] op_sel_hi:[1,0,1]
	v_pk_fma_f32 v[94:95], v[94:95], 0.5, v[130:131] op_sel_hi:[1,0,1]
	v_pk_fma_f32 v[92:93], v[92:93], 0.5, v[128:129] op_sel_hi:[1,0,1]
	v_pk_fma_f32 v[90:91], v[90:91], 0.5, v[126:127] op_sel_hi:[1,0,1]
	v_add_f32_e32 v130, v94, v95
	v_add_f32_e32 v131, v96, v97
	v_add_f32_e32 v126, v90, v91
	v_add_f32_e32 v127, v92, v93
	v_add_f32_e32 v130, v130, v131
	v_mul_f32_e32 v131, v95, v95
	v_mul_f32_e32 v132, v97, v97
	v_add_f32_e32 v126, v126, v127
	v_mul_f32_e32 v127, v91, v91
	v_mul_f32_e32 v128, v93, v93
	s_nop 0
	v_fmac_f32_e32 v131, v94, v94
	v_fmac_f32_e32 v132, v96, v96
	s_nop 1
	v_bfe_u32 v135, v227, 4, 2
	v_sub_u32_e32 v134, 0, v135
	v_lshlrev_b32_e32 v134, 4, v134
	v_ashrrev_i32_e32 v135, 31, v134
	v_lshl_add_u64 v[134:135], v[124:125], 0, v[134:135]
	v_permlane16_swap_b32_e32 v94, v90
	v_permlane16_swap_b32_e32 v95, v91
	v_permlane16_swap_b32_e32 v96, v92
	v_permlane16_swap_b32_e32 v97, v93
	v_permlane32_swap_b32_e32 v94, v90
	v_permlane32_swap_b32_e32 v95, v91
	v_permlane32_swap_b32_e32 v96, v92
	v_permlane32_swap_b32_e32 v97, v93
	v_mov_b32_e32 v129, v94
	v_mov_b32_e32 v133, v95
	v_mov_b32_e32 v159, v96
	v_mov_b32_e32 v170, v97
	v_bfe_u32 v136, v227, 3, 1
	v_mul_i32_i24_e32 v136, 0xffff8040, v136
	v_ashrrev_i32_e32 v137, 31, v136
	v_lshl_add_u64 v[134:135], v[134:135], 0, v[136:137]
	v_mov_b32_e32 v136, 0x8000
	v_mov_b32_e32 v137, 0
	v_lshl_add_u64 v[136:137], v[134:135], 0, v[136:137]
	v_mov_b32_dpp v94, v90 row_ror:8 row_mask:0xf bank_mask:0xc
	v_mov_b32_dpp v95, v91 row_ror:8 row_mask:0xf bank_mask:0xc
	v_mov_b32_dpp v96, v92 row_ror:8 row_mask:0xf bank_mask:0xc
	v_mov_b32_dpp v97, v93 row_ror:8 row_mask:0xf bank_mask:0xc
	v_mov_b32_dpp v90, v129 row_ror:8 row_mask:0xf bank_mask:0x3
	v_mov_b32_dpp v91, v133 row_ror:8 row_mask:0xf bank_mask:0x3
	v_mov_b32_dpp v92, v159 row_ror:8 row_mask:0xf bank_mask:0x3
	v_mov_b32_dpp v93, v170 row_ror:8 row_mask:0xf bank_mask:0x3
	global_store_dwordx4 v[134:135], v[94:97], off
	global_store_dwordx4 v[136:137], v[90:93], off
	s_nop 1
	v_mov_b32_dpp v90, v94 row_ror:8 row_mask:0xf bank_mask:0x3
	v_mov_b32_dpp v91, v95 row_ror:8 row_mask:0xf bank_mask:0x3
	v_mov_b32_dpp v92, v96 row_ror:8 row_mask:0xf bank_mask:0x3
	v_mov_b32_dpp v93, v97 row_ror:8 row_mask:0xf bank_mask:0x3
	v_mov_b32_e32 v94, v129
	v_mov_b32_e32 v95, v133
	v_mov_b32_e32 v96, v159
	v_mov_b32_e32 v97, v170
	s_nop 1
	v_permlane32_swap_b32_e32 v94, v90
	v_permlane32_swap_b32_e32 v95, v91
	v_permlane32_swap_b32_e32 v96, v92
	v_permlane32_swap_b32_e32 v97, v93
	v_permlane16_swap_b32_e32 v94, v90
	v_permlane16_swap_b32_e32 v95, v91
	v_permlane16_swap_b32_e32 v96, v92
	v_permlane16_swap_b32_e32 v97, v93
	v_fmac_f32_e32 v127, v90, v90
	v_fmac_f32_e32 v128, v92, v92
	v_cvt_pk_bf16_f32 v94, v94, v95
	v_cvt_pk_bf16_f32 v95, v96, v97
	v_cvt_pk_bf16_f32 v96, v90, v91
	v_cvt_pk_bf16_f32 v97, v92, v93
	s_waitcnt vmcnt(6)
; __device__ __forceinline__ float xsum16(float v) { const auto r = __builtin_amdgcn_permlane16_swap(__float_as_uint(v), __float_as_uint(v), false, false); return __uint_as_float(r[0]) + __uint_as_float(r[1]); }
; __device__ __forceinline__ float xsum32(float v) { const auto r = __builtin_amdgcn_permlane32_swap(__float_as_uint(v), __float_as_uint(v), false, false); return __uint_as_float(r[0]) + __uint_as_float(r[1]); }
; __device__ __forceinline__ size_t blk_off(int r, int c, int K) { return (size_t)(r >> 8) * 256 * K + (size_t)(c >> 6) * (256 * 64) + (size_t)((r & 255) * 64 + (c & 63)); }
; __device__ __forceinline__ u32x4 pack8(const f32x4 a, const f32x4 b) { u32x4 w; w.x = cvt_pk_bf16(a[0], a[1]); w.y = cvt_pk_bf16(a[2], a[3]); w.z = cvt_pk_bf16(b[0], b[1]); w.w = cvt_pk_bf16(b[2], b[3]); return w; }
;     __device__ __forceinline__ void operator()(const f32x4 (&acc)[2][2][4][2], const pg8::Unit& u, int wr, int wc, int fr, int fq) const {
;     ...
;                 for (int bj = 0; bj < 2; ++bj) { float* yp = Y + (size_t)row * D_ + col0 + bj * 128; f32x4 v[2];
; #pragma unroll
;                     for (int n = 0; n < 2; ++n) { v[n] = (((yv[bj][n] - mu) * rs) * gq[bj][n] + bq_[bj][n]) * ALPHA_ + acc[ai][bj][m][n] * sc;
;                         *(f32x4*)(yp + 4 * n) = v[n]; s1 += (v[n][0] + v[n][1]) + (v[n][2] + v[n][3]); s2 += (v[n][0] * v[n][0] + v[n][1] * v[n][1]) + (v[n][2] * v[n][2] + v[n][3] * v[n][3]); }
;                     *(u32x4*)(Yb + blk_off(row, col0 + bj * 128, D_)) = pack8(v[0], v[1]); }
;                 s1 = xsum32(xsum16(s1)); s2 = xsum32(xsum16(s2));
;                 if (fq == 0) *(f32x2*)(stn + (size_t)row * 32 + (u.pn * 4 + wc) * 2) = (f32x2){s1, s2}; asm volatile("" ::: "memory"); } }
	v_sub_f32_e32 v91, v121, v123
	v_sub_f32_e32 v90, v120, v123
	v_sub_f32_e32 v93, v119, v123
	v_sub_f32_e32 v92, v118, v123
	v_pk_mul_f32 v[92:93], v[0:1], v[92:93] op_sel_hi:[0,1]
	v_pk_mul_f32 v[90:91], v[0:1], v[90:91] op_sel_hi:[0,1]
	s_waitcnt vmcnt(2)
	v_pk_fma_f32 v[90:91], v[112:113], v[90:91], v[116:117]
	v_pk_fma_f32 v[92:93], v[110:111], v[92:93], v[114:115]
	v_pk_mul_f32 v[90:91], v[90:91], s[2:3] op_sel_hi:[1,0]
	v_pk_mul_f32 v[92:93], v[92:93], s[2:3] op_sel_hi:[1,0]
	v_pk_fma_f32 v[88:89], v[88:89], 0.5, v[90:91] op_sel_hi:[1,0,1]
	v_pk_fma_f32 v[86:87], v[86:87], 0.5, v[92:93] op_sel_hi:[1,0,1]
	v_add_f32_e32 v130, 0, v130
	v_add_f32_e32 v90, v86, v87
	v_add_f32_e32 v91, v88, v89
	v_add_f32_e32 v126, v130, v126
	v_add_f32_e32 v90, v90, v91
	global_store_dwordx4 v122, v[94:97], s[50:51]
	v_mul_f32_e32 v91, v89, v89
	v_add_f32_e32 v131, v131, v132
	v_add_f32_e32 v94, v126, v90
	v_mul_f32_e32 v90, v87, v87
	v_add_f32_e32 v127, v127, v128
	v_fmac_f32_e32 v90, v86, v86
	v_fmac_f32_e32 v91, v88, v88
	v_add_f32_e32 v127, v131, v127
	v_add_f32_e32 v90, v90, v91
	v_add_f32_e32 v95, v127, v90
	v_sub_f32_e32 v91, v101, v123
	v_sub_f32_e32 v90, v100, v123
	v_sub_f32_e32 v93, v99, v123
	v_sub_f32_e32 v92, v98, v123
	v_pk_mul_f32 v[92:93], v[0:1], v[92:93] op_sel_hi:[0,1]
	v_pk_mul_f32 v[90:91], v[0:1], v[90:91] op_sel_hi:[0,1]
	v_pk_fma_f32 v[90:91], v[104:105], v[90:91], v[108:109]
	v_pk_fma_f32 v[92:93], v[102:103], v[92:93], v[106:107]
	v_pk_mul_f32 v[90:91], v[90:91], s[2:3] op_sel_hi:[1,0]
	v_pk_mul_f32 v[92:93], v[92:93], s[2:3] op_sel_hi:[1,0]
	v_pk_fma_f32 v[84:85], v[84:85], 0.5, v[90:91] op_sel_hi:[1,0,1]
	v_pk_fma_f32 v[82:83], v[82:83], 0.5, v[92:93] op_sel_hi:[1,0,1]
	v_add_f32_e32 v90, v84, v85
	v_add_f32_e32 v0, v82, v83
	v_add_f32_e32 v0, v0, v90
	v_mul_f32_e32 v90, v83, v83
	v_mul_f32_e32 v91, v85, v85
	v_add_f32_e32 v0, v94, v0
	v_fmac_f32_e32 v90, v82, v82
	v_fmac_f32_e32 v91, v84, v84
	s_nop 0
	s_nop 1
	v_bfe_u32 v93, v227, 4, 2
	v_sub_u32_e32 v92, 0, v93
	v_lshlrev_b32_e32 v92, 4, v92
	v_ashrrev_i32_e32 v93, 31, v92
	v_lshl_add_u64 v[92:93], v[124:125], 0, v[92:93]
	v_permlane16_swap_b32_e32 v86, v82
	v_permlane16_swap_b32_e32 v87, v83
	v_permlane16_swap_b32_e32 v88, v84
	v_permlane16_swap_b32_e32 v89, v85
	v_permlane32_swap_b32_e32 v86, v82
	v_permlane32_swap_b32_e32 v87, v83
	v_permlane32_swap_b32_e32 v88, v84
	v_permlane32_swap_b32_e32 v89, v85
	v_mov_b32_e32 v98, v86
	v_mov_b32_e32 v99, v87
	v_mov_b32_e32 v100, v88
	v_mov_b32_e32 v101, v89
	v_bfe_u32 v96, v227, 3, 1
	v_mul_i32_i24_e32 v96, 0xffff8040, v96
	v_ashrrev_i32_e32 v97, 31, v96
	v_lshl_add_u64 v[92:93], v[92:93], 0, v[96:97]
	v_mov_b32_e32 v96, 0x8000
	v_mov_b32_e32 v97, 0
	v_lshl_add_u64 v[96:97], v[92:93], 0, v[96:97]
	v_mov_b32_dpp v86, v82 row_ror:8 row_mask:0xf bank_mask:0xc
	v_mov_b32_dpp v87, v83 row_ror:8 row_mask:0xf bank_mask:0xc
	v_mov_b32_dpp v88, v84 row_ror:8 row_mask:0xf bank_mask:0xc
	v_mov_b32_dpp v89, v85 row_ror:8 row_mask:0xf bank_mask:0xc
	v_mov_b32_dpp v82, v98 row_ror:8 row_mask:0xf bank_mask:0x3
	v_mov_b32_dpp v83, v99 row_ror:8 row_mask:0xf bank_mask:0x3
	v_mov_b32_dpp v84, v100 row_ror:8 row_mask:0xf bank_mask:0x3
	v_mov_b32_dpp v85, v101 row_ror:8 row_mask:0xf bank_mask:0x3
	global_store_dwordx4 v[92:93], v[86:89], off offset:512
	global_store_dwordx4 v[96:97], v[82:85], off offset:512
	s_nop 1
	v_mov_b32_dpp v82, v86 row_ror:8 row_mask:0xf bank_mask:0x3
	v_mov_b32_dpp v83, v87 row_ror:8 row_mask:0xf bank_mask:0x3
	v_mov_b32_dpp v84, v88 row_ror:8 row_mask:0xf bank_mask:0x3
	v_mov_b32_dpp v85, v89 row_ror:8 row_mask:0xf bank_mask:0x3
	v_mov_b32_e32 v86, v98
	v_mov_b32_e32 v87, v99
	v_mov_b32_e32 v88, v100
	v_mov_b32_e32 v89, v101
	s_nop 1
	v_permlane32_swap_b32_e32 v86, v82
	v_permlane32_swap_b32_e32 v87, v83
	v_permlane32_swap_b32_e32 v88, v84
	v_permlane32_swap_b32_e32 v89, v85
	v_permlane16_swap_b32_e32 v86, v82
	v_permlane16_swap_b32_e32 v87, v83
	v_permlane16_swap_b32_e32 v88, v84
	v_permlane16_swap_b32_e32 v89, v85
	v_add_f32_e32 v90, v90, v91
	v_cvt_pk_bf16_f32 v86, v86, v87
	v_cvt_pk_bf16_f32 v87, v88, v89
	v_cvt_pk_bf16_f32 v88, v82, v83
	v_mov_b32_e32 v82, v0
	v_add_f32_e32 v90, v95, v90
	s_nop 0
	v_permlane16_swap_b32_e32 v0, v82
	v_add_f32_e32 v82, v0, v82
	v_mov_b32_e32 v0, v90
	s_nop 1
	v_permlane16_swap_b32_e32 v90, v0
	v_add_f32_e32 v83, v90, v0
	v_cvt_pk_bf16_f32 v89, v84, v85
	v_mov_b32_e32 v84, v82
	v_mov_b32_e32 v85, v83
	s_nop 0
	v_permlane32_swap_b32_e32 v82, v84
	v_permlane32_swap_b32_e32 v83, v85
	global_store_dwordx4 v122, v[86:89], s[42:43]
	s_and_saveexec_b64 s[26:27], s[44:45]
	s_cbranch_execz .LBB0_378
	v_pk_add_f32 v[82:83], v[82:83], v[84:85]
	v_lshl_add_u64 v[84:85], s[30:31], 0, v[164:165]
	v_lshl_add_u64 v[84:85], s[24:25], 2, v[84:85]
	global_store_dwordx2 v[84:85], v[82:83], off
; __device__ __forceinline__ size_t blk_off(int r, int c, int K) { return (size_t)(r >> 8) * 256 * K + (size_t)(c >> 6) * (256 * 64) + (size_t)((r & 255) * 64 + (c & 63)); }
; __device__ __forceinline__ u32x4 pack8(const f32x4 a, const f32x4 b) { u32x4 w; w.x = cvt_pk_bf16(a[0], a[1]); w.y = cvt_pk_bf16(a[2], a[3]); w.z = cvt_pk_bf16(b[0], b[1]); w.w = cvt_pk_bf16(b[2], b[3]); return w; }
;     __device__ __forceinline__ void operator()(const f32x4 (&acc)[2][2][4][2], const pg8::Unit& u, int wr, int wc, int fr, int fq) const {
;     ...
;             for (int m = 0; m < 4; ++m) { const int row = row0 + ai * 128 + m * 16; const float mu = mu4[m], rs = rs4[m];
;                 f32x4 yv[2][2], gq[2][2], bq_[2][2];
; #pragma unroll
;                 for (int bj = 0; bj < 2; ++bj)
; #pragma unroll
;                     for (int n = 0; n < 2; ++n) { yv[bj][n] = *(const f32x4*)(Yin + (size_t)row * D_ + col0 + bj * 128 + 4 * n); gq[bj][n] = *(const f32x4*)(g + col0 + bj * 128 + 4 * n); bq_[bj][n] = *(const f32x4*)(b + col0 + bj * 128 + 4 * n); }
;                 asm volatile("" ::: "memory");
;                 float s1 = 0.f, s2 = 0.f;
; #pragma unroll
;                 for (int bj = 0; bj < 2; ++bj) { float* yp = Y + (size_t)row * D_ + col0 + bj * 128; f32x4 v[2];
; #pragma unroll
;                     for (int n = 0; n < 2; ++n) { v[n] = (((yv[bj][n] - mu) * rs) * gq[bj][n] + bq_[bj][n]) * ALPHA_ + acc[ai][bj][m][n] * sc;
;                         *(f32x4*)(yp + 4 * n) = v[n]; s1 += (v[n][0] + v[n][1]) + (v[n][2] + v[n][3]); s2 += (v[n][0] * v[n][0] + v[n][1] * v[n][1]) + (v[n][2] * v[n][2] + v[n][3] * v[n][3]); }
;                     *(u32x4*)(Yb + blk_off(row, col0 + bj * 128, D_)) = pack8(v[0], v[1]); }
.LBB0_378:
	s_or_b64 exec, exec, s[26:27]
	v_pk_add_f32 v[82:83], v[166:167], v[168:169]
	s_mov_b32 s2, 0x3a800000
	v_pk_mul_f32 v[106:107], v[82:83], s[2:3] op_sel_hi:[1,0]
	s_mov_b32 s2, 0x800000
	v_fma_f32 v0, -v107, v107, v106
	v_max_f32_e32 v0, 0, v0
	v_add_f32_e32 v0, 0x3727c5ac, v0
	v_cmp_gt_f32_e32 vcc, s2, v0
	v_mul_f32_e32 v82, 0x4b800000, v0
	v_lshlrev_b64 v[108:109], 12, v[162:163]
	v_cndmask_b32_e32 v0, v0, v82, vcc
	v_rsq_f32_e32 v0, v0
	s_load_dwordx16 s[60:75], s[34:35], 0x38
	v_lshlrev_b32_e32 v106, 6, v162
	v_mul_f32_e32 v82, 0x45800000, v0
	v_cndmask_b32_e32 v0, v0, v82, vcc
	v_lshl_add_u64 v[82:83], s[12:13], 0, v[108:109]
	v_lshl_add_u64 v[86:87], v[82:83], 0, v[152:153]
	global_load_dwordx4 v[110:113], v[86:87], off offset:16
	global_load_dwordx4 v[114:117], v[86:87], off
	global_load_dwordx4 v[118:121], v[154:155], off offset:16
	global_load_dwordx4 v[122:125], v[154:155], off
	global_load_dwordx4 v[126:129], v[156:157], off offset:16
	global_load_dwordx4 v[130:133], v[156:157], off
	global_load_dwordx4 v[82:85], v[86:87], off offset:528
	global_load_dwordx4 v[102:105], v[86:87], off offset:512
	s_nop 0
	global_load_dwordx4 v[86:89], v[154:155], off offset:528
	global_load_dwordx4 v[94:97], v[154:155], off offset:512
	global_load_dwordx4 v[90:93], v[156:157], off offset:528
	global_load_dwordx4 v[98:101], v[156:157], off offset:512
	s_movk_i32 s2, 0x3fc0
	v_and_or_b32 v106, v106, s2, v194
	s_mov_b32 s2, 0x3fd744fd
	s_waitcnt lgkmcnt(0)
	v_lshl_add_u64 v[108:109], s[74:75], 0, v[108:109]
	v_lshl_add_u64 v[108:109], v[108:109], 0, v[152:153]
	v_lshlrev_b32_e32 v106, 1, v106
	s_waitcnt vmcnt(11)
	v_sub_f32_e32 v113, v113, v107
	s_waitcnt vmcnt(10)
	v_sub_f32_e32 v117, v117, v107
	v_sub_f32_e32 v116, v116, v107
	v_sub_f32_e32 v115, v115, v107
	v_sub_f32_e32 v114, v114, v107
	v_sub_f32_e32 v112, v112, v107
	v_sub_f32_e32 v111, v111, v107
	v_sub_f32_e32 v110, v110, v107
	v_pk_mul_f32 v[114:115], v[0:1], v[114:115] op_sel_hi:[0,1]
	v_pk_mul_f32 v[116:117], v[0:1], v[116:117] op_sel_hi:[0,1]
	v_pk_mul_f32 v[110:111], v[0:1], v[110:111] op_sel_hi:[0,1]
	v_pk_mul_f32 v[112:113], v[0:1], v[112:113] op_sel_hi:[0,1]
	s_waitcnt vmcnt(6)
	v_pk_fma_f32 v[116:117], v[124:125], v[116:117], v[132:133]
	v_pk_fma_f32 v[114:115], v[122:123], v[114:115], v[130:131]
	v_pk_fma_f32 v[112:113], v[120:121], v[112:113], v[128:129]
	v_pk_fma_f32 v[110:111], v[118:119], v[110:111], v[126:127]
	v_pk_mul_f32 v[114:115], v[114:115], s[2:3] op_sel_hi:[1,0]
	v_pk_mul_f32 v[116:117], v[116:117], s[2:3] op_sel_hi:[1,0]
	v_pk_mul_f32 v[110:111], v[110:111], s[2:3] op_sel_hi:[1,0]
	v_pk_mul_f32 v[112:113], v[112:113], s[2:3] op_sel_hi:[1,0]
	v_pk_fma_f32 v[80:81], v[80:81], 0.5, v[116:117] op_sel_hi:[1,0,1]
	v_pk_fma_f32 v[78:79], v[78:79], 0.5, v[114:115] op_sel_hi:[1,0,1]
	v_pk_fma_f32 v[76:77], v[76:77], 0.5, v[112:113] op_sel_hi:[1,0,1]
	v_pk_fma_f32 v[74:75], v[74:75], 0.5, v[110:111] op_sel_hi:[1,0,1]
	v_add_f32_e32 v114, v78, v79
	v_add_f32_e32 v115, v80, v81
	v_add_f32_e32 v110, v74, v75
	v_add_f32_e32 v111, v76, v77
	v_add_f32_e32 v114, v114, v115
	v_mul_f32_e32 v115, v79, v79
	v_mul_f32_e32 v116, v81, v81
	v_add_f32_e32 v110, v110, v111
	v_mul_f32_e32 v111, v75, v75
	v_mul_f32_e32 v112, v77, v77
	s_nop 0
	v_fmac_f32_e32 v115, v78, v78
	v_fmac_f32_e32 v116, v80, v80
	s_nop 1
	v_bfe_u32 v119, v227, 4, 2
	v_sub_u32_e32 v118, 0, v119
	v_lshlrev_b32_e32 v118, 4, v118
	v_ashrrev_i32_e32 v119, 31, v118
	v_lshl_add_u64 v[118:119], v[108:109], 0, v[118:119]
	v_permlane16_swap_b32_e32 v78, v74
	v_permlane16_swap_b32_e32 v79, v75
	v_permlane16_swap_b32_e32 v80, v76
	v_permlane16_swap_b32_e32 v81, v77
	v_permlane32_swap_b32_e32 v78, v74
	v_permlane32_swap_b32_e32 v79, v75
	v_permlane32_swap_b32_e32 v80, v76
	v_permlane32_swap_b32_e32 v81, v77
	v_mov_b32_e32 v113, v78
	v_mov_b32_e32 v117, v79
	v_mov_b32_e32 v122, v80
	v_mov_b32_e32 v123, v81
	v_bfe_u32 v120, v227, 3, 1
	v_mul_i32_i24_e32 v120, 0xffff8040, v120
	v_ashrrev_i32_e32 v121, 31, v120
	v_lshl_add_u64 v[118:119], v[118:119], 0, v[120:121]
	v_mov_b32_e32 v120, 0x8000
	v_mov_b32_e32 v121, 0
	v_lshl_add_u64 v[120:121], v[118:119], 0, v[120:121]
	v_mov_b32_dpp v78, v74 row_ror:8 row_mask:0xf bank_mask:0xc
	v_mov_b32_dpp v79, v75 row_ror:8 row_mask:0xf bank_mask:0xc
	v_mov_b32_dpp v80, v76 row_ror:8 row_mask:0xf bank_mask:0xc
	v_mov_b32_dpp v81, v77 row_ror:8 row_mask:0xf bank_mask:0xc
	v_mov_b32_dpp v74, v113 row_ror:8 row_mask:0xf bank_mask:0x3
	v_mov_b32_dpp v75, v117 row_ror:8 row_mask:0xf bank_mask:0x3
	v_mov_b32_dpp v76, v122 row_ror:8 row_mask:0xf bank_mask:0x3
	v_mov_b32_dpp v77, v123 row_ror:8 row_mask:0xf bank_mask:0x3
	global_store_dwordx4 v[118:119], v[78:81], off
	global_store_dwordx4 v[120:121], v[74:77], off
	s_nop 1
	v_mov_b32_dpp v74, v78 row_ror:8 row_mask:0xf bank_mask:0x3
	v_mov_b32_dpp v75, v79 row_ror:8 row_mask:0xf bank_mask:0x3
	v_mov_b32_dpp v76, v80 row_ror:8 row_mask:0xf bank_mask:0x3
	v_mov_b32_dpp v77, v81 row_ror:8 row_mask:0xf bank_mask:0x3
	v_mov_b32_e32 v78, v113
	v_mov_b32_e32 v79, v117
	v_mov_b32_e32 v80, v122
	v_mov_b32_e32 v81, v123
	s_nop 1
	v_permlane32_swap_b32_e32 v78, v74
	v_permlane32_swap_b32_e32 v79, v75
	v_permlane32_swap_b32_e32 v80, v76
	v_permlane32_swap_b32_e32 v81, v77
	v_permlane16_swap_b32_e32 v78, v74
	v_permlane16_swap_b32_e32 v79, v75
	v_permlane16_swap_b32_e32 v80, v76
	v_permlane16_swap_b32_e32 v81, v77
	v_fmac_f32_e32 v111, v74, v74
	v_fmac_f32_e32 v112, v76, v76
	v_cvt_pk_bf16_f32 v78, v78, v79
	v_cvt_pk_bf16_f32 v79, v80, v81
	v_cvt_pk_bf16_f32 v80, v74, v75
	v_cvt_pk_bf16_f32 v81, v76, v77
	s_waitcnt vmcnt(6)
; __device__ __forceinline__ float xsum16(float v) { const auto r = __builtin_amdgcn_permlane16_swap(__float_as_uint(v), __float_as_uint(v), false, false); return __uint_as_float(r[0]) + __uint_as_float(r[1]); }
; __device__ __forceinline__ float xsum32(float v) { const auto r = __builtin_amdgcn_permlane32_swap(__float_as_uint(v), __float_as_uint(v), false, false); return __uint_as_float(r[0]) + __uint_as_float(r[1]); }
; __device__ __forceinline__ size_t blk_off(int r, int c, int K) { return (size_t)(r >> 8) * 256 * K + (size_t)(c >> 6) * (256 * 64) + (size_t)((r & 255) * 64 + (c & 63)); }
; __device__ __forceinline__ u32x4 pack8(const f32x4 a, const f32x4 b) { u32x4 w; w.x = cvt_pk_bf16(a[0], a[1]); w.y = cvt_pk_bf16(a[2], a[3]); w.z = cvt_pk_bf16(b[0], b[1]); w.w = cvt_pk_bf16(b[2], b[3]); return w; }
;     __device__ __forceinline__ void operator()(const f32x4 (&acc)[2][2][4][2], const pg8::Unit& u, int wr, int wc, int fr, int fq) const {
;     ...
;                 for (int bj = 0; bj < 2; ++bj) { float* yp = Y + (size_t)row * D_ + col0 + bj * 128; f32x4 v[2];
; #pragma unroll
;                     for (int n = 0; n < 2; ++n) { v[n] = (((yv[bj][n] - mu) * rs) * gq[bj][n] + bq_[bj][n]) * ALPHA_ + acc[ai][bj][m][n] * sc;
;                         *(f32x4*)(yp + 4 * n) = v[n]; s1 += (v[n][0] + v[n][1]) + (v[n][2] + v[n][3]); s2 += (v[n][0] * v[n][0] + v[n][1] * v[n][1]) + (v[n][2] * v[n][2] + v[n][3] * v[n][3]); }
;                     *(u32x4*)(Yb + blk_off(row, col0 + bj * 128, D_)) = pack8(v[0], v[1]); }
;                 s1 = xsum32(xsum16(s1)); s2 = xsum32(xsum16(s2));
;                 if (fq == 0) *(f32x2*)(stn + (size_t)row * 32 + (u.pn * 4 + wc) * 2) = (f32x2){s1, s2}; asm volatile("" ::: "memory"); } }
	v_sub_f32_e32 v75, v105, v107
	v_sub_f32_e32 v74, v104, v107
	v_sub_f32_e32 v77, v103, v107
	v_sub_f32_e32 v76, v102, v107
	v_pk_mul_f32 v[76:77], v[0:1], v[76:77] op_sel_hi:[0,1]
	v_pk_mul_f32 v[74:75], v[0:1], v[74:75] op_sel_hi:[0,1]
	s_waitcnt vmcnt(2)
	v_pk_fma_f32 v[74:75], v[96:97], v[74:75], v[100:101]
	v_pk_fma_f32 v[76:77], v[94:95], v[76:77], v[98:99]
	v_pk_mul_f32 v[74:75], v[74:75], s[2:3] op_sel_hi:[1,0]
	v_pk_mul_f32 v[76:77], v[76:77], s[2:3] op_sel_hi:[1,0]
	v_pk_fma_f32 v[72:73], v[72:73], 0.5, v[74:75] op_sel_hi:[1,0,1]
	v_pk_fma_f32 v[70:71], v[70:71], 0.5, v[76:77] op_sel_hi:[1,0,1]
	v_add_f32_e32 v114, 0, v114
	v_add_f32_e32 v74, v70, v71
	v_add_f32_e32 v75, v72, v73
	v_add_f32_e32 v110, v114, v110
	v_add_f32_e32 v74, v74, v75
	global_store_dwordx4 v106, v[78:81], s[50:51]
	v_mul_f32_e32 v75, v73, v73
	v_add_f32_e32 v115, v115, v116
	v_add_f32_e32 v78, v110, v74
	v_mul_f32_e32 v74, v71, v71
	v_add_f32_e32 v111, v111, v112
	v_fmac_f32_e32 v74, v70, v70
	v_fmac_f32_e32 v75, v72, v72
	v_add_f32_e32 v111, v115, v111
	v_add_f32_e32 v74, v74, v75
	v_add_f32_e32 v79, v111, v74
	v_sub_f32_e32 v75, v85, v107
	v_sub_f32_e32 v74, v84, v107
	v_sub_f32_e32 v77, v83, v107
	v_sub_f32_e32 v76, v82, v107
	v_pk_mul_f32 v[76:77], v[0:1], v[76:77] op_sel_hi:[0,1]
	v_pk_mul_f32 v[74:75], v[0:1], v[74:75] op_sel_hi:[0,1]
	v_pk_fma_f32 v[74:75], v[88:89], v[74:75], v[92:93]
	v_pk_fma_f32 v[76:77], v[86:87], v[76:77], v[90:91]
	v_pk_mul_f32 v[74:75], v[74:75], s[2:3] op_sel_hi:[1,0]
	v_pk_mul_f32 v[76:77], v[76:77], s[2:3] op_sel_hi:[1,0]
	v_pk_fma_f32 v[68:69], v[68:69], 0.5, v[74:75] op_sel_hi:[1,0,1]
	v_pk_fma_f32 v[66:67], v[66:67], 0.5, v[76:77] op_sel_hi:[1,0,1]
	v_add_f32_e32 v74, v68, v69
	v_add_f32_e32 v0, v66, v67
	v_add_f32_e32 v0, v0, v74
	v_mul_f32_e32 v74, v67, v67
	v_mul_f32_e32 v75, v69, v69
	v_add_f32_e32 v0, v78, v0
	v_fmac_f32_e32 v74, v66, v66
	v_fmac_f32_e32 v75, v68, v68
	s_nop 0
	s_nop 1
	v_bfe_u32 v77, v227, 4, 2
	v_sub_u32_e32 v76, 0, v77
	v_lshlrev_b32_e32 v76, 4, v76
	v_ashrrev_i32_e32 v77, 31, v76
	v_lshl_add_u64 v[76:77], v[108:109], 0, v[76:77]
	v_permlane16_swap_b32_e32 v70, v66
	v_permlane16_swap_b32_e32 v71, v67
	v_permlane16_swap_b32_e32 v72, v68
	v_permlane16_swap_b32_e32 v73, v69
	v_permlane32_swap_b32_e32 v70, v66
	v_permlane32_swap_b32_e32 v71, v67
	v_permlane32_swap_b32_e32 v72, v68
	v_permlane32_swap_b32_e32 v73, v69
	v_mov_b32_e32 v82, v70
	v_mov_b32_e32 v83, v71
	v_mov_b32_e32 v84, v72
	v_mov_b32_e32 v85, v73
	v_bfe_u32 v80, v227, 3, 1
	v_mul_i32_i24_e32 v80, 0xffff8040, v80
	v_ashrrev_i32_e32 v81, 31, v80
	v_lshl_add_u64 v[76:77], v[76:77], 0, v[80:81]
	v_mov_b32_e32 v80, 0x8000
	v_mov_b32_e32 v81, 0
	v_lshl_add_u64 v[80:81], v[76:77], 0, v[80:81]
	v_mov_b32_dpp v70, v66 row_ror:8 row_mask:0xf bank_mask:0xc
	v_mov_b32_dpp v71, v67 row_ror:8 row_mask:0xf bank_mask:0xc
	v_mov_b32_dpp v72, v68 row_ror:8 row_mask:0xf bank_mask:0xc
	v_mov_b32_dpp v73, v69 row_ror:8 row_mask:0xf bank_mask:0xc
	v_mov_b32_dpp v66, v82 row_ror:8 row_mask:0xf bank_mask:0x3
	v_mov_b32_dpp v67, v83 row_ror:8 row_mask:0xf bank_mask:0x3
	v_mov_b32_dpp v68, v84 row_ror:8 row_mask:0xf bank_mask:0x3
	v_mov_b32_dpp v69, v85 row_ror:8 row_mask:0xf bank_mask:0x3
	global_store_dwordx4 v[76:77], v[70:73], off offset:512
	global_store_dwordx4 v[80:81], v[66:69], off offset:512
	s_nop 1
	v_mov_b32_dpp v66, v70 row_ror:8 row_mask:0xf bank_mask:0x3
	v_mov_b32_dpp v67, v71 row_ror:8 row_mask:0xf bank_mask:0x3
	v_mov_b32_dpp v68, v72 row_ror:8 row_mask:0xf bank_mask:0x3
	v_mov_b32_dpp v69, v73 row_ror:8 row_mask:0xf bank_mask:0x3
	v_mov_b32_e32 v70, v82
	v_mov_b32_e32 v71, v83
	v_mov_b32_e32 v72, v84
	v_mov_b32_e32 v73, v85
	s_nop 1
	v_permlane32_swap_b32_e32 v70, v66
	v_permlane32_swap_b32_e32 v71, v67
	v_permlane32_swap_b32_e32 v72, v68
	v_permlane32_swap_b32_e32 v73, v69
	v_permlane16_swap_b32_e32 v70, v66
	v_permlane16_swap_b32_e32 v71, v67
	v_permlane16_swap_b32_e32 v72, v68
	v_permlane16_swap_b32_e32 v73, v69
	v_add_f32_e32 v74, v74, v75
	v_cvt_pk_bf16_f32 v70, v70, v71
	v_cvt_pk_bf16_f32 v71, v72, v73
	v_cvt_pk_bf16_f32 v72, v66, v67
	v_mov_b32_e32 v66, v0
	v_add_f32_e32 v74, v79, v74
	s_nop 0
	v_permlane16_swap_b32_e32 v0, v66
	v_add_f32_e32 v66, v0, v66
	v_mov_b32_e32 v0, v74
	s_nop 1
	v_permlane16_swap_b32_e32 v74, v0
	v_add_f32_e32 v67, v74, v0
	v_cvt_pk_bf16_f32 v73, v68, v69
	v_mov_b32_e32 v68, v66
	v_mov_b32_e32 v69, v67
	s_nop 0
	v_permlane32_swap_b32_e32 v66, v68
	v_permlane32_swap_b32_e32 v67, v69
	global_store_dwordx4 v106, v[70:73], s[42:43]
	s_and_saveexec_b64 s[26:27], s[44:45]
	s_cbranch_execz .LBB0_380
	v_pk_add_f32 v[66:67], v[66:67], v[68:69]
	v_lshl_add_u64 v[68:69], s[30:31], 0, v[160:161]
	v_lshl_add_u64 v[68:69], s[24:25], 2, v[68:69]
	global_store_dwordx2 v[68:69], v[66:67], off
; __device__ __forceinline__ float xsum16(float v) { const auto r = __builtin_amdgcn_permlane16_swap(__float_as_uint(v), __float_as_uint(v), false, false); return __uint_as_float(r[0]) + __uint_as_float(r[1]); }
; __device__ __forceinline__ float xsum32(float v) { const auto r = __builtin_amdgcn_permlane32_swap(__float_as_uint(v), __float_as_uint(v), false, false); return __uint_as_float(r[0]) + __uint_as_float(r[1]); }
; __device__ __forceinline__ void row_stats4(const float* st, int rowb, int fq, float (&mu)[4], float (&rs)[4]) {
;     f32x4 a[4], b[4];
; #pragma unroll
;     for (int m = 0; m < 4; ++m) { const f32x4* p = (const f32x4*)(st + (size_t)(rowb + m * 16) * 32 + fq * 8); a[m] = p[0]; b[m] = p[1]; }
; #pragma unroll
;     for (int m = 0; m < 4; ++m) { float s1 = (a[m][0] + a[m][2]) + (b[m][0] + b[m][2]), s2 = (a[m][1] + a[m][3]) + (b[m][1] + b[m][3]);
;         s1 = xsum32(xsum16(s1)); s2 = xsum32(xsum16(s2));
;         const float mm = s1 * (1.0f / 1024.0f); mu[m] = mm; rs[m] = rsqrtf(fmaxf(s2 * (1.0f / 1024.0f) - mm * mm, 0.f) + LN_EPS_); }
;     asm volatile("" ::: "memory");
; }
;     __device__ __forceinline__ void operator()(const f32x4 (&acc)[2][2][4][2], const pg8::Unit& u, int wr, int wc, int fr, int fq) const {
;     ...
;         for (int ai = 0; ai < 2; ++ai) { float mu4[4], rs4[4]; row_stats4(stp, row0 + ai * 128, fq, mu4, rs4);
; #pragma unroll
;             for (int m = 0; m < 4; ++m) { const int row = row0 + ai * 128 + m * 16; const float mu = mu4[m], rs = rs4[m];
;                 f32x4 yv[2][2], gq[2][2], bq_[2][2];
; #pragma unroll
;                 for (int bj = 0; bj < 2; ++bj)
; #pragma unroll
;                     for (int n = 0; n < 2; ++n) { yv[bj][n] = *(const f32x4*)(Yin + (size_t)row * D_ + col0 + bj * 128 + 4 * n); gq[bj][n] = *(const f32x4*)(g + col0 + bj * 128 + 4 * n); bq_[bj][n] = *(const f32x4*)(b + col0 + bj * 128 + 4 * n); }
;                 asm volatile("" ::: "memory");
;                 float s1 = 0.f, s2 = 0.f;
; #pragma unroll
;                 for (int bj = 0; bj < 2; ++bj) { float* yp = Y + (size_t)row * D_ + col0 + bj * 128; f32x4 v[2];
; #pragma unroll
;                     for (int n = 0; n < 2; ++n) { v[n] = (((yv[bj][n] - mu) * rs) * gq[bj][n] + bq_[bj][n]) * ALPHA_ + acc[ai][bj][m][n] * sc;
.LBB0_380:
	s_or_b64 exec, exec, s[26:27]
	v_add_u32_e32 v68, 0x80, v158
	v_ashrrev_i32_e32 v69, 31, v68
	v_add_u32_e32 v94, 0x90, v158
	v_lshlrev_b64 v[66:67], 7, v[68:69]
	v_ashrrev_i32_e32 v95, 31, v94
	v_lshl_add_u64 v[74:75], v[146:147], 0, v[66:67]
	v_lshlrev_b64 v[86:87], 7, v[94:95]
	v_add_u32_e32 v76, 0xa0, v158
	global_load_dwordx4 v[70:73], v[74:75], off
	global_load_dwordx4 v[78:81], v[74:75], off offset:16
	v_lshl_add_u64 v[74:75], v[146:147], 0, v[86:87]
	v_ashrrev_i32_e32 v77, 31, v76
	global_load_dwordx4 v[82:85], v[74:75], off
	global_load_dwordx4 v[88:91], v[74:75], off offset:16
	v_lshlrev_b64 v[74:75], 7, v[76:77]
	v_lshl_add_u64 v[74:75], v[146:147], 0, v[74:75]
	global_load_dwordx4 v[96:99], v[74:75], off
	global_load_dwordx4 v[100:103], v[74:75], off offset:16
	v_add_u32_e32 v74, 0xb0, v158
	v_ashrrev_i32_e32 v75, 31, v74
	v_lshlrev_b64 v[92:93], 7, v[74:75]
	v_lshl_add_u64 v[92:93], v[146:147], 0, v[92:93]
	global_load_dwordx4 v[104:107], v[92:93], off
	global_load_dwordx4 v[108:111], v[92:93], off offset:16
	v_lshlrev_b64 v[136:137], 12, v[68:69]
	v_lshl_add_u64 v[112:113], s[12:13], 0, v[136:137]
	v_lshl_add_u64 v[92:93], v[112:113], 0, v[152:153]
	global_load_dwordx4 v[112:115], v[92:93], off offset:16
	global_load_dwordx4 v[116:119], v[92:93], off
	global_load_dwordx4 v[120:123], v[154:155], off offset:16
	global_load_dwordx4 v[124:127], v[154:155], off
	global_load_dwordx4 v[128:131], v[156:157], off offset:16
	global_load_dwordx4 v[132:135], v[156:157], off
	s_mov_b32 s2, 0x3a800000
	s_mov_b32 s16, 0x3fd744fd
	s_load_dwordx16 s[60:75], s[34:35], 0x38
	s_waitcnt vmcnt(13)
	v_mov_b32_e32 v158, v70
	s_waitcnt vmcnt(12)
	v_mov_b32_e32 v159, v78
	v_mov_b32_e32 v160, v72
	v_mov_b32_e32 v161, v80
	v_mov_b32_e32 v78, v71
	v_mov_b32_e32 v80, v73
	s_waitcnt vmcnt(11)
	v_mov_b32_e32 v70, v82
	s_waitcnt vmcnt(10)
	v_mov_b32_e32 v71, v88
	v_mov_b32_e32 v72, v84
	v_mov_b32_e32 v73, v90
	v_mov_b32_e32 v88, v83
	v_mov_b32_e32 v90, v85
	s_waitcnt vmcnt(9)
	v_mov_b32_e32 v82, v96
	s_waitcnt vmcnt(8)
	v_mov_b32_e32 v83, v100
	v_mov_b32_e32 v84, v98
	v_mov_b32_e32 v85, v102
	v_mov_b32_e32 v100, v97
	v_pk_add_f32 v[96:97], v[158:159], v[160:161]
	v_pk_add_f32 v[78:79], v[78:79], v[80:81]
	v_pk_add_f32 v[80:81], v[82:83], v[84:85]
	v_pk_add_f32 v[84:85], v[96:97], v[96:97] op_sel:[0,1] op_sel_hi:[1,0]
	v_pk_add_f32 v[78:79], v[78:79], v[78:79] op_sel:[0,1] op_sel_hi:[1,0]
	v_mov_b32_e32 v0, v84
	v_mov_b32_e32 v69, v78
	s_nop 0
	v_permlane16_swap_b32_e32 v84, v0
	v_permlane16_swap_b32_e32 v78, v69
	v_add_f32_e32 v79, v84, v0
	v_add_f32_e32 v78, v78, v69
	v_mov_b32_e32 v85, v79
	v_mov_b32_e32 v84, v78
	s_nop 0
	v_permlane32_swap_b32_e32 v79, v85
	v_permlane32_swap_b32_e32 v78, v84
	v_pk_add_f32 v[78:79], v[78:79], v[84:85]
	v_mov_b32_e32 v102, v99
	v_pk_mul_f32 v[78:79], v[78:79], s[2:3] op_sel_hi:[1,0]
	s_mov_b32 s2, 0x800000
	v_fma_f32 v0, -v79, v79, v78
	v_max_f32_e32 v0, 0, v0
	v_add_f32_e32 v0, 0x3727c5ac, v0
	v_mul_f32_e32 v69, 0x4b800000, v0
	v_cmp_gt_f32_e32 vcc, s2, v0
	v_pk_add_f32 v[82:83], v[100:101], v[102:103]
	v_pk_add_f32 v[80:81], v[80:81], v[80:81] op_sel:[0,1] op_sel_hi:[1,0]
	v_cndmask_b32_e32 v0, v0, v69, vcc
	v_rsq_f32_e32 v0, v0
	v_pk_add_f32 v[82:83], v[82:83], v[82:83] op_sel:[0,1] op_sel_hi:[1,0]
	v_mov_b32_e32 v81, v80
	s_nop 1
	v_permlane16_swap_b32_e32 v80, v81
	v_mul_f32_e32 v69, 0x45800000, v0
	v_cndmask_b32_e32 v78, v0, v69, vcc
	v_mov_b32_e32 v0, v82
	s_nop 1
	v_permlane16_swap_b32_e32 v82, v0
	global_load_dwordx4 v[96:99], v[92:93], off offset:528
	global_load_dwordx4 v[100:103], v[92:93], off offset:512
	v_pk_add_f32 v[70:71], v[70:71], v[72:73]
	v_pk_add_f32 v[72:73], v[88:89], v[90:91]
	v_add_f32_e32 v89, v80, v81
	v_add_f32_e32 v88, v82, v0
	s_waitcnt vmcnt(9)
	v_mov_b32_e32 v80, v104
	s_waitcnt vmcnt(8)
	v_mov_b32_e32 v81, v108
	v_mov_b32_e32 v82, v106
	v_mov_b32_e32 v83, v110
	v_mov_b32_e32 v108, v105
	v_mov_b32_e32 v110, v107
	v_pk_add_f32 v[80:81], v[80:81], v[82:83]
	v_pk_add_f32 v[82:83], v[108:109], v[110:111]
	global_load_dwordx4 v[104:107], v[154:155], off offset:528
	global_load_dwordx4 v[108:111], v[154:155], off offset:512
	global_load_dwordx4 v[158:161], v[156:157], off offset:528
	global_load_dwordx4 v[162:165], v[156:157], off offset:512
	s_waitcnt vmcnt(10)
	v_sub_f32_e32 v93, v119, v79
	v_sub_f32_e32 v92, v118, v79
	v_sub_f32_e32 v117, v117, v79
	v_sub_f32_e32 v116, v116, v79
	v_pk_mul_f32 v[116:117], v[78:79], v[116:117] op_sel_hi:[0,1]
	v_pk_mul_f32 v[92:93], v[78:79], v[92:93] op_sel_hi:[0,1]
	s_waitcnt vmcnt(6)
	v_pk_fma_f32 v[92:93], v[126:127], v[92:93], v[134:135]
	v_pk_fma_f32 v[116:117], v[124:125], v[116:117], v[132:133]
	v_pk_mul_f32 v[92:93], v[92:93], s[16:17] op_sel_hi:[1,0]
	v_pk_mul_f32 v[116:117], v[116:117], s[16:17] op_sel_hi:[1,0]
	v_pk_fma_f32 v[64:65], v[64:65], 0.5, v[92:93] op_sel_hi:[1,0,1]
	v_pk_fma_f32 v[62:63], v[62:63], 0.5, v[116:117] op_sel_hi:[1,0,1]
	v_add_f32_e32 v93, v64, v65
	v_add_f32_e32 v92, v62, v63
	v_add_f32_e32 v92, v92, v93
	v_add_f32_e32 v116, 0, v92
	v_mul_f32_e32 v92, v63, v63
	v_mul_f32_e32 v93, v65, v65
	v_pk_add_f32 v[80:81], v[80:81], v[80:81] op_sel:[0,1] op_sel_hi:[1,0]
	v_fmac_f32_e32 v92, v62, v62
	v_fmac_f32_e32 v93, v64, v64
	v_mov_b32_e32 v0, v80
	v_add_f32_e32 v117, v92, v93
	v_sub_f32_e32 v93, v115, v79
	v_sub_f32_e32 v92, v114, v79
	v_sub_f32_e32 v113, v113, v79
	v_sub_f32_e32 v112, v112, v79
	v_pk_add_f32 v[82:83], v[82:83], v[82:83] op_sel:[0,1] op_sel_hi:[1,0]
	v_permlane16_swap_b32_e32 v80, v0
	v_pk_mul_f32 v[112:113], v[78:79], v[112:113] op_sel_hi:[0,1]
	v_pk_mul_f32 v[92:93], v[78:79], v[92:93] op_sel_hi:[0,1]
	v_add_f32_e32 v83, v80, v0
	v_mov_b32_e32 v0, v82
	v_pk_fma_f32 v[92:93], v[122:123], v[92:93], v[130:131]
	v_pk_fma_f32 v[112:113], v[120:121], v[112:113], v[128:129]
	v_permlane16_swap_b32_e32 v82, v0
	v_pk_mul_f32 v[112:113], v[112:113], s[16:17] op_sel_hi:[1,0]
	v_pk_mul_f32 v[92:93], v[92:93], s[16:17] op_sel_hi:[1,0]
	v_add_f32_e32 v82, v82, v0
	v_ashrrev_i32_e32 v80, 8, v68
	v_lshlrev_b32_e32 v0, 6, v68
	s_movk_i32 s2, 0x33c0
	v_pk_fma_f32 v[60:61], v[60:61], 0.5, v[92:93] op_sel_hi:[1,0,1]
	v_pk_fma_f32 v[58:59], v[58:59], 0.5, v[112:113] op_sel_hi:[1,0,1]
	v_ashrrev_i32_e32 v81, 31, v80
	v_and_or_b32 v0, v0, s2, v194
	s_waitcnt lgkmcnt(0)
; __device__ __forceinline__ float xsum16(float v) { const auto r = __builtin_amdgcn_permlane16_swap(__float_as_uint(v), __float_as_uint(v), false, false); return __uint_as_float(r[0]) + __uint_as_float(r[1]); }
; __device__ __forceinline__ float xsum32(float v) { const auto r = __builtin_amdgcn_permlane32_swap(__float_as_uint(v), __float_as_uint(v), false, false); return __uint_as_float(r[0]) + __uint_as_float(r[1]); }
; __device__ __forceinline__ size_t blk_off(int r, int c, int K) { return (size_t)(r >> 8) * 256 * K + (size_t)(c >> 6) * (256 * 64) + (size_t)((r & 255) * 64 + (c & 63)); }
; __device__ __forceinline__ u32x4 pack8(const f32x4 a, const f32x4 b) { u32x4 w; w.x = cvt_pk_bf16(a[0], a[1]); w.y = cvt_pk_bf16(a[2], a[3]); w.z = cvt_pk_bf16(b[0], b[1]); w.w = cvt_pk_bf16(b[2], b[3]); return w; }
;     __device__ __forceinline__ void operator()(const f32x4 (&acc)[2][2][4][2], const pg8::Unit& u, int wr, int wc, int fr, int fq) const {
;     ...
;                 for (int bj = 0; bj < 2; ++bj) { float* yp = Y + (size_t)row * D_ + col0 + bj * 128; f32x4 v[2];
; #pragma unroll
;                     for (int n = 0; n < 2; ++n) { v[n] = (((yv[bj][n] - mu) * rs) * gq[bj][n] + bq_[bj][n]) * ALPHA_ + acc[ai][bj][m][n] * sc;
;                         *(f32x4*)(yp + 4 * n) = v[n]; s1 += (v[n][0] + v[n][1]) + (v[n][2] + v[n][3]); s2 += (v[n][0] * v[n][0] + v[n][1] * v[n][1]) + (v[n][2] * v[n][2] + v[n][3] * v[n][3]); }
;                     *(u32x4*)(Yb + blk_off(row, col0 + bj * 128, D_)) = pack8(v[0], v[1]); }
;                 s1 = xsum32(xsum16(s1)); s2 = xsum32(xsum16(s2));
;                 if (fq == 0) *(f32x2*)(stn + (size_t)row * 32 + (u.pn * 4 + wc) * 2) = (f32x2){s1, s2}; asm volatile("" ::: "memory"); } }
	v_lshl_add_u64 v[68:69], s[74:75], 0, v[136:137]
	v_add_f32_e32 v92, v58, v59
	v_add_f32_e32 v93, v60, v61
	v_readlane_b32 s2, v253, 59
	v_lshlrev_b64 v[80:81], 19, v[80:81]
	v_lshl_add_u64 v[68:69], v[68:69], 0, v[152:153]
	v_add_f32_e32 v92, v92, v93
	v_mul_f32_e32 v93, v59, v59
	v_readlane_b32 s3, v253, 60
	s_nop 0
	s_nop 1
	v_bfe_u32 v85, v227, 4, 2
	v_sub_u32_e32 v84, 0, v85
	v_lshlrev_b32_e32 v84, 4, v84
	v_ashrrev_i32_e32 v85, 31, v84
	v_lshl_add_u64 v[84:85], v[68:69], 0, v[84:85]
	v_permlane16_swap_b32_e32 v62, v58
	v_permlane16_swap_b32_e32 v63, v59
	v_permlane16_swap_b32_e32 v64, v60
	v_permlane16_swap_b32_e32 v65, v61
	v_permlane32_swap_b32_e32 v62, v58
	v_permlane32_swap_b32_e32 v63, v59
	v_permlane32_swap_b32_e32 v64, v60
	v_permlane32_swap_b32_e32 v65, v61
	v_mov_b32_e32 v112, v62
	v_mov_b32_e32 v113, v63
	v_mov_b32_e32 v114, v64
	v_mov_b32_e32 v115, v65
	v_bfe_u32 v90, v227, 3, 1
	v_mul_i32_i24_e32 v90, 0xffff8040, v90
	v_ashrrev_i32_e32 v91, 31, v90
	v_lshl_add_u64 v[84:85], v[84:85], 0, v[90:91]
	v_mov_b32_e32 v90, 0x8000
	v_mov_b32_e32 v91, 0
	v_lshl_add_u64 v[90:91], v[84:85], 0, v[90:91]
	v_mov_b32_dpp v62, v58 row_ror:8 row_mask:0xf bank_mask:0xc
	v_mov_b32_dpp v63, v59 row_ror:8 row_mask:0xf bank_mask:0xc
	v_mov_b32_dpp v64, v60 row_ror:8 row_mask:0xf bank_mask:0xc
	v_mov_b32_dpp v65, v61 row_ror:8 row_mask:0xf bank_mask:0xc
	v_mov_b32_dpp v58, v112 row_ror:8 row_mask:0xf bank_mask:0x3
	v_mov_b32_dpp v59, v113 row_ror:8 row_mask:0xf bank_mask:0x3
	v_mov_b32_dpp v60, v114 row_ror:8 row_mask:0xf bank_mask:0x3
	v_mov_b32_dpp v61, v115 row_ror:8 row_mask:0xf bank_mask:0x3
	global_store_dwordx4 v[84:85], v[62:65], off
	global_store_dwordx4 v[90:91], v[58:61], off
	s_nop 1
	v_mov_b32_dpp v58, v62 row_ror:8 row_mask:0xf bank_mask:0x3
	v_mov_b32_dpp v59, v63 row_ror:8 row_mask:0xf bank_mask:0x3
	v_mov_b32_dpp v60, v64 row_ror:8 row_mask:0xf bank_mask:0x3
	v_mov_b32_dpp v61, v65 row_ror:8 row_mask:0xf bank_mask:0x3
	v_mov_b32_e32 v62, v112
	v_mov_b32_e32 v63, v113
	v_mov_b32_e32 v64, v114
	v_mov_b32_e32 v65, v115
	s_nop 1
	v_permlane32_swap_b32_e32 v62, v58
	v_permlane32_swap_b32_e32 v63, v59
	v_permlane32_swap_b32_e32 v64, v60
	v_permlane32_swap_b32_e32 v65, v61
	v_permlane16_swap_b32_e32 v62, v58
	v_permlane16_swap_b32_e32 v63, v59
	v_permlane16_swap_b32_e32 v64, v60
	v_permlane16_swap_b32_e32 v65, v61
	v_fmac_f32_e32 v93, v58, v58
	v_cvt_pk_bf16_f32 v62, v62, v63
	v_cvt_pk_bf16_f32 v63, v64, v65
	v_cvt_pk_bf16_f32 v64, v58, v59
	v_lshl_add_u64 v[58:59], s[2:3], 0, v[80:81]
	v_mul_f32_e32 v112, v61, v61
	v_lshl_add_u64 v[80:81], v[58:59], 0, s[28:29]
	v_lshlrev_b32_e32 v0, 1, v0
	v_fmac_f32_e32 v112, v60, v60
	v_cvt_pk_bf16_f32 v65, v60, v61
	v_lshl_add_u64 v[60:61], v[80:81], 0, v[0:1]
	global_store_dwordx4 v[60:61], v[62:65], off
	s_waitcnt vmcnt(7)
	v_sub_f32_e32 v61, v103, v79
	v_sub_f32_e32 v60, v102, v79
	v_sub_f32_e32 v63, v101, v79
	v_sub_f32_e32 v62, v100, v79
	v_pk_mul_f32 v[62:63], v[78:79], v[62:63] op_sel_hi:[0,1]
	v_pk_mul_f32 v[60:61], v[78:79], v[60:61] op_sel_hi:[0,1]
	v_add_f32_e32 v92, v116, v92
	s_waitcnt vmcnt(3)
	v_pk_fma_f32 v[60:61], v[110:111], v[60:61], v[164:165]
	v_pk_fma_f32 v[62:63], v[108:109], v[62:63], v[162:163]
	v_pk_mul_f32 v[60:61], v[60:61], s[16:17] op_sel_hi:[1,0]
	v_pk_mul_f32 v[62:63], v[62:63], s[16:17] op_sel_hi:[1,0]
	v_pk_fma_f32 v[56:57], v[56:57], 0.5, v[60:61] op_sel_hi:[1,0,1]
	v_pk_fma_f32 v[54:55], v[54:55], 0.5, v[62:63] op_sel_hi:[1,0,1]
	v_add_f32_e32 v61, v56, v57
	v_add_f32_e32 v60, v54, v55
	v_add_f32_e32 v60, v60, v61
	v_add_f32_e32 v64, v92, v60
	v_mul_f32_e32 v60, v55, v55
	v_mul_f32_e32 v61, v57, v57
	v_add_f32_e32 v93, v93, v112
	v_fmac_f32_e32 v60, v54, v54
	v_fmac_f32_e32 v61, v56, v56
	v_add_f32_e32 v93, v117, v93
	v_add_f32_e32 v60, v60, v61
	v_add_f32_e32 v65, v93, v60
	v_sub_f32_e32 v61, v99, v79
	v_sub_f32_e32 v60, v98, v79
	v_sub_f32_e32 v63, v97, v79
	v_sub_f32_e32 v62, v96, v79
	v_pk_mul_f32 v[62:63], v[78:79], v[62:63] op_sel_hi:[0,1]
	v_pk_mul_f32 v[60:61], v[78:79], v[60:61] op_sel_hi:[0,1]
	v_pk_fma_f32 v[60:61], v[106:107], v[60:61], v[160:161]
	v_pk_fma_f32 v[62:63], v[104:105], v[62:63], v[158:159]
	v_pk_mul_f32 v[60:61], v[60:61], s[16:17] op_sel_hi:[1,0]
	v_pk_mul_f32 v[62:63], v[62:63], s[16:17] op_sel_hi:[1,0]
	v_pk_fma_f32 v[52:53], v[52:53], 0.5, v[60:61] op_sel_hi:[1,0,1]
	v_pk_fma_f32 v[50:51], v[50:51], 0.5, v[62:63] op_sel_hi:[1,0,1]
	v_add_f32_e32 v61, v52, v53
	v_add_f32_e32 v60, v50, v51
	v_add_f32_e32 v60, v60, v61
	v_mul_f32_e32 v61, v51, v51
	v_mul_f32_e32 v62, v53, v53
	v_add_f32_e32 v60, v64, v60
	v_fmac_f32_e32 v61, v50, v50
	v_fmac_f32_e32 v62, v52, v52
	v_lshl_add_u64 v[78:79], v[58:59], 0, s[40:41]
	s_nop 0
	s_nop 1
	v_bfe_u32 v85, v227, 4, 2
	v_sub_u32_e32 v84, 0, v85
	v_lshlrev_b32_e32 v84, 4, v84
	v_ashrrev_i32_e32 v85, 31, v84
	v_lshl_add_u64 v[84:85], v[68:69], 0, v[84:85]
	v_permlane16_swap_b32_e32 v54, v50
	v_permlane16_swap_b32_e32 v55, v51
	v_permlane16_swap_b32_e32 v56, v52
	v_permlane16_swap_b32_e32 v57, v53
	v_permlane32_swap_b32_e32 v54, v50
	v_permlane32_swap_b32_e32 v55, v51
	v_permlane32_swap_b32_e32 v56, v52
	v_permlane32_swap_b32_e32 v57, v53
	v_mov_b32_e32 v63, v54
	v_mov_b32_e32 v64, v55
	v_mov_b32_e32 v92, v56
	v_mov_b32_e32 v93, v57
	v_bfe_u32 v90, v227, 3, 1
	v_mul_i32_i24_e32 v90, 0xffff8040, v90
	v_ashrrev_i32_e32 v91, 31, v90
	v_lshl_add_u64 v[84:85], v[84:85], 0, v[90:91]
	v_mov_b32_e32 v90, 0x8000
	v_mov_b32_e32 v91, 0
	v_lshl_add_u64 v[90:91], v[84:85], 0, v[90:91]
	v_mov_b32_dpp v54, v50 row_ror:8 row_mask:0xf bank_mask:0xc
	v_mov_b32_dpp v55, v51 row_ror:8 row_mask:0xf bank_mask:0xc
; __device__ __forceinline__ float xsum16(float v) { const auto r = __builtin_amdgcn_permlane16_swap(__float_as_uint(v), __float_as_uint(v), false, false); return __uint_as_float(r[0]) + __uint_as_float(r[1]); }
; __device__ __forceinline__ float xsum32(float v) { const auto r = __builtin_amdgcn_permlane32_swap(__float_as_uint(v), __float_as_uint(v), false, false); return __uint_as_float(r[0]) + __uint_as_float(r[1]); }
; __device__ __forceinline__ size_t blk_off(int r, int c, int K) { return (size_t)(r >> 8) * 256 * K + (size_t)(c >> 6) * (256 * 64) + (size_t)((r & 255) * 64 + (c & 63)); }
; __device__ __forceinline__ void row_stats4(const float* st, int rowb, int fq, float (&mu)[4], float (&rs)[4]) {
;     f32x4 a[4], b[4];
; #pragma unroll
;     for (int m = 0; m < 4; ++m) { const f32x4* p = (const f32x4*)(st + (size_t)(rowb + m * 16) * 32 + fq * 8); a[m] = p[0]; b[m] = p[1]; }
; #pragma unroll
;     for (int m = 0; m < 4; ++m) { float s1 = (a[m][0] + a[m][2]) + (b[m][0] + b[m][2]), s2 = (a[m][1] + a[m][3]) + (b[m][1] + b[m][3]);
;         s1 = xsum32(xsum16(s1)); s2 = xsum32(xsum16(s2));
;         const float mm = s1 * (1.0f / 1024.0f); mu[m] = mm; rs[m] = rsqrtf(fmaxf(s2 * (1.0f / 1024.0f) - mm * mm, 0.f) + LN_EPS_); }
;     asm volatile("" ::: "memory");
; }
;     __device__ __forceinline__ void operator()(const f32x4 (&acc)[2][2][4][2], const pg8::Unit& u, int wr, int wc, int fr, int fq) const {
;     ...
;                 for (int bj = 0; bj < 2; ++bj) { float* yp = Y + (size_t)row * D_ + col0 + bj * 128; f32x4 v[2];
; #pragma unroll
;                     for (int n = 0; n < 2; ++n) { v[n] = (((yv[bj][n] - mu) * rs) * gq[bj][n] + bq_[bj][n]) * ALPHA_ + acc[ai][bj][m][n] * sc;
;                         *(f32x4*)(yp + 4 * n) = v[n]; s1 += (v[n][0] + v[n][1]) + (v[n][2] + v[n][3]); s2 += (v[n][0] * v[n][0] + v[n][1] * v[n][1]) + (v[n][2] * v[n][2] + v[n][3] * v[n][3]); }
;                     *(u32x4*)(Yb + blk_off(row, col0 + bj * 128, D_)) = pack8(v[0], v[1]); }
;                 s1 = xsum32(xsum16(s1)); s2 = xsum32(xsum16(s2));
;                 if (fq == 0) *(f32x2*)(stn + (size_t)row * 32 + (u.pn * 4 + wc) * 2) = (f32x2){s1, s2}; asm volatile("" ::: "memory"); } }
	v_mov_b32_dpp v56, v52 row_ror:8 row_mask:0xf bank_mask:0xc
	v_mov_b32_dpp v57, v53 row_ror:8 row_mask:0xf bank_mask:0xc
	v_mov_b32_dpp v50, v63 row_ror:8 row_mask:0xf bank_mask:0x3
	v_mov_b32_dpp v51, v64 row_ror:8 row_mask:0xf bank_mask:0x3
	v_mov_b32_dpp v52, v92 row_ror:8 row_mask:0xf bank_mask:0x3
	v_mov_b32_dpp v53, v93 row_ror:8 row_mask:0xf bank_mask:0x3
	global_store_dwordx4 v[84:85], v[54:57], off offset:512
	global_store_dwordx4 v[90:91], v[50:53], off offset:512
	s_nop 1
	v_mov_b32_dpp v50, v54 row_ror:8 row_mask:0xf bank_mask:0x3
	v_mov_b32_dpp v51, v55 row_ror:8 row_mask:0xf bank_mask:0x3
	v_mov_b32_dpp v52, v56 row_ror:8 row_mask:0xf bank_mask:0x3
	v_mov_b32_dpp v53, v57 row_ror:8 row_mask:0xf bank_mask:0x3
	v_mov_b32_e32 v54, v63
	v_mov_b32_e32 v55, v64
	v_mov_b32_e32 v56, v92
	v_mov_b32_e32 v57, v93
	s_nop 1
	v_permlane32_swap_b32_e32 v54, v50
	v_permlane32_swap_b32_e32 v55, v51
	v_permlane32_swap_b32_e32 v56, v52
	v_permlane32_swap_b32_e32 v57, v53
	v_permlane16_swap_b32_e32 v54, v50
	v_permlane16_swap_b32_e32 v55, v51
	v_permlane16_swap_b32_e32 v56, v52
	v_permlane16_swap_b32_e32 v57, v53
	v_add_f32_e32 v61, v61, v62
	v_cvt_pk_bf16_f32 v54, v54, v55
	v_cvt_pk_bf16_f32 v55, v56, v57
	v_cvt_pk_bf16_f32 v56, v50, v51
	v_lshl_add_u64 v[50:51], v[78:79], 0, v[0:1]
	v_mov_b32_e32 v0, v60
	v_pk_add_f32 v[70:71], v[70:71], v[70:71] op_sel:[0,1] op_sel_hi:[1,0]
	v_pk_add_f32 v[72:73], v[72:73], v[72:73] op_sel:[0,1] op_sel_hi:[1,0]
	v_add_f32_e32 v61, v65, v61
	v_cvt_pk_bf16_f32 v57, v52, v53
	v_permlane16_swap_b32_e32 v60, v0
	v_mov_b32_e32 v71, v70
	v_mov_b32_e32 v73, v72
	global_store_dwordx4 v[50:51], v[54:57], off
	v_add_f32_e32 v50, v60, v0
	v_mov_b32_e32 v0, v61
	v_permlane16_swap_b32_e32 v70, v71
	v_permlane16_swap_b32_e32 v72, v73
	v_permlane16_swap_b32_e32 v61, v0
	v_add_f32_e32 v71, v70, v71
	v_add_f32_e32 v70, v72, v73
	v_add_f32_e32 v51, v61, v0
	v_mov_b32_e32 v73, v71
	v_mov_b32_e32 v72, v70
	v_mov_b32_e32 v91, v89
	v_mov_b32_e32 v90, v88
	v_mov_b32_e32 v85, v83
	v_mov_b32_e32 v84, v82
	v_mov_b32_e32 v52, v50
	v_mov_b32_e32 v53, v51
	v_permlane32_swap_b32_e32 v71, v73
	v_permlane32_swap_b32_e32 v70, v72
	v_permlane32_swap_b32_e32 v89, v91
	v_permlane32_swap_b32_e32 v88, v90
	v_permlane32_swap_b32_e32 v83, v85
	v_permlane32_swap_b32_e32 v82, v84
	v_permlane32_swap_b32_e32 v50, v52
	v_permlane32_swap_b32_e32 v51, v53
	s_and_saveexec_b64 s[26:27], s[44:45]
	s_cbranch_execz .LBB0_382
	v_pk_add_f32 v[50:51], v[50:51], v[52:53]
	v_lshl_add_u64 v[52:53], s[30:31], 0, v[66:67]
	v_lshl_add_u64 v[52:53], s[24:25], 2, v[52:53]
	global_store_dwordx2 v[52:53], v[50:51], off
.LBB0_382:
	s_or_b64 exec, exec, s[26:27]
	v_pk_add_f32 v[50:51], v[70:71], v[72:73]
	s_mov_b32 s2, 0x3a800000
	v_pk_mul_f32 v[92:93], v[50:51], s[2:3] op_sel_hi:[1,0]
	s_mov_b32 s2, 0x800000
	v_fma_f32 v0, -v93, v93, v92
	v_max_f32_e32 v0, 0, v0
	v_add_f32_e32 v0, 0x3727c5ac, v0
	v_cmp_gt_f32_e32 vcc, s2, v0
	v_mul_f32_e32 v50, 0x4b800000, v0
	v_lshlrev_b64 v[120:121], 12, v[94:95]
	v_cndmask_b32_e32 v0, v0, v50, vcc
	v_rsq_f32_e32 v0, v0
	s_movk_i32 s2, 0x37c0
	s_load_dwordx16 s[60:75], s[34:35], 0x38
	v_mul_f32_e32 v50, 0x45800000, v0
	v_cndmask_b32_e32 v92, v0, v50, vcc
	v_lshl_add_u64 v[50:51], s[12:13], 0, v[120:121]
	v_lshl_add_u64 v[54:55], v[50:51], 0, v[152:153]
	global_load_dwordx4 v[96:99], v[54:55], off offset:16
	global_load_dwordx4 v[100:103], v[54:55], off
	global_load_dwordx4 v[104:107], v[154:155], off offset:16
	global_load_dwordx4 v[108:111], v[154:155], off
	global_load_dwordx4 v[112:115], v[156:157], off offset:16
	global_load_dwordx4 v[116:119], v[156:157], off
	global_load_dwordx4 v[50:53], v[54:55], off offset:528
	global_load_dwordx4 v[70:73], v[54:55], off offset:512
	s_nop 0
	global_load_dwordx4 v[54:57], v[154:155], off offset:528
	global_load_dwordx4 v[62:65], v[154:155], off offset:512
	global_load_dwordx4 v[58:61], v[156:157], off offset:528
	global_load_dwordx4 v[66:69], v[156:157], off offset:512
	v_lshlrev_b32_e32 v0, 6, v94
	v_and_or_b32 v0, v0, s2, v194
	s_mov_b32 s2, 0x3fd744fd
	s_waitcnt lgkmcnt(0)
	v_lshl_add_u64 v[94:95], s[74:75], 0, v[120:121]
	v_lshlrev_b32_e32 v0, 1, v0
	v_lshl_add_u64 v[94:95], v[94:95], 0, v[152:153]
	s_waitcnt vmcnt(10)
	v_sub_f32_e32 v103, v103, v93
	v_sub_f32_e32 v102, v102, v93
	v_sub_f32_e32 v101, v101, v93
	v_sub_f32_e32 v100, v100, v93
	v_pk_mul_f32 v[100:101], v[92:93], v[100:101] op_sel_hi:[0,1]
	v_pk_mul_f32 v[102:103], v[92:93], v[102:103] op_sel_hi:[0,1]
	s_waitcnt vmcnt(6)
; __device__ __forceinline__ size_t blk_off(int r, int c, int K) { return (size_t)(r >> 8) * 256 * K + (size_t)(c >> 6) * (256 * 64) + (size_t)((r & 255) * 64 + (c & 63)); }
; __device__ __forceinline__ u32x4 pack8(const f32x4 a, const f32x4 b) { u32x4 w; w.x = cvt_pk_bf16(a[0], a[1]); w.y = cvt_pk_bf16(a[2], a[3]); w.z = cvt_pk_bf16(b[0], b[1]); w.w = cvt_pk_bf16(b[2], b[3]); return w; }
;     __device__ __forceinline__ void operator()(const f32x4 (&acc)[2][2][4][2], const pg8::Unit& u, int wr, int wc, int fr, int fq) const {
;     ...
;                 for (int bj = 0; bj < 2; ++bj) { float* yp = Y + (size_t)row * D_ + col0 + bj * 128; f32x4 v[2];
; #pragma unroll
;                     for (int n = 0; n < 2; ++n) { v[n] = (((yv[bj][n] - mu) * rs) * gq[bj][n] + bq_[bj][n]) * ALPHA_ + acc[ai][bj][m][n] * sc;
;                         *(f32x4*)(yp + 4 * n) = v[n]; s1 += (v[n][0] + v[n][1]) + (v[n][2] + v[n][3]); s2 += (v[n][0] * v[n][0] + v[n][1] * v[n][1]) + (v[n][2] * v[n][2] + v[n][3] * v[n][3]); }
;                     *(u32x4*)(Yb + blk_off(row, col0 + bj * 128, D_)) = pack8(v[0], v[1]); }
	v_pk_fma_f32 v[102:103], v[110:111], v[102:103], v[118:119]
	v_pk_fma_f32 v[100:101], v[108:109], v[100:101], v[116:117]
	v_pk_mul_f32 v[102:103], v[102:103], s[2:3] op_sel_hi:[1,0]
	v_pk_mul_f32 v[100:101], v[100:101], s[2:3] op_sel_hi:[1,0]
	v_pk_fma_f32 v[102:103], v[48:49], 0.5, v[102:103] op_sel_hi:[1,0,1]
	v_pk_fma_f32 v[100:101], v[46:47], 0.5, v[100:101] op_sel_hi:[1,0,1]
	v_add_f32_e32 v47, v102, v103
	v_add_f32_e32 v46, v100, v101
	v_add_f32_e32 v46, v46, v47
	v_add_f32_e32 v108, 0, v46
	v_mul_f32_e32 v46, v101, v101
	v_mul_f32_e32 v47, v103, v103
	v_fmac_f32_e32 v46, v100, v100
	v_fmac_f32_e32 v47, v102, v102
	v_add_f32_e32 v109, v46, v47
	v_sub_f32_e32 v47, v99, v93
	v_sub_f32_e32 v46, v98, v93
	v_sub_f32_e32 v49, v97, v93
	v_sub_f32_e32 v48, v96, v93
	v_pk_mul_f32 v[48:49], v[92:93], v[48:49] op_sel_hi:[0,1]
	v_pk_mul_f32 v[46:47], v[92:93], v[46:47] op_sel_hi:[0,1]
	v_pk_fma_f32 v[46:47], v[106:107], v[46:47], v[114:115]
	v_pk_fma_f32 v[48:49], v[104:105], v[48:49], v[112:113]
	v_pk_mul_f32 v[46:47], v[46:47], s[2:3] op_sel_hi:[1,0]
	v_pk_mul_f32 v[48:49], v[48:49], s[2:3] op_sel_hi:[1,0]
	v_pk_fma_f32 v[98:99], v[44:45], 0.5, v[46:47] op_sel_hi:[1,0,1]
	v_pk_fma_f32 v[96:97], v[42:43], 0.5, v[48:49] op_sel_hi:[1,0,1]
	v_add_f32_e32 v43, v98, v99
	v_add_f32_e32 v42, v96, v97
	v_add_f32_e32 v42, v42, v43
	v_add_f32_e32 v47, v108, v42
	v_mul_f32_e32 v42, v97, v97
	v_mul_f32_e32 v43, v99, v99
	v_fmac_f32_e32 v42, v96, v96
	v_fmac_f32_e32 v43, v98, v98
	v_add_f32_e32 v42, v42, v43
	v_add_f32_e32 v46, v109, v42
	v_cvt_pk_bf16_f32 v42, v100, v101
	v_cvt_pk_bf16_f32 v43, v102, v103
	v_cvt_pk_bf16_f32 v44, v96, v97
	v_cvt_pk_bf16_f32 v45, v98, v99
	v_lshl_add_u64 v[48:49], v[80:81], 0, v[0:1]
	s_nop 0
	s_nop 1
	v_bfe_u32 v105, v227, 4, 2
	v_sub_u32_e32 v104, 0, v105
	v_lshlrev_b32_e32 v104, 4, v104
	v_ashrrev_i32_e32 v105, 31, v104
	v_lshl_add_u64 v[104:105], v[94:95], 0, v[104:105]
	v_permlane16_swap_b32_e32 v100, v96
	v_permlane16_swap_b32_e32 v101, v97
	v_permlane16_swap_b32_e32 v102, v98
	v_permlane16_swap_b32_e32 v103, v99
	v_permlane32_swap_b32_e32 v100, v96
	v_permlane32_swap_b32_e32 v101, v97
	v_permlane32_swap_b32_e32 v102, v98
	v_permlane32_swap_b32_e32 v103, v99
	v_mov_b32_e32 v108, v100
	v_mov_b32_e32 v109, v101
	v_mov_b32_e32 v110, v102
	v_mov_b32_e32 v111, v103
	v_bfe_u32 v106, v227, 3, 1
	v_mul_i32_i24_e32 v106, 0xffff8040, v106
	v_ashrrev_i32_e32 v107, 31, v106
	v_lshl_add_u64 v[104:105], v[104:105], 0, v[106:107]
	v_mov_b32_e32 v106, 0x8000
	v_mov_b32_e32 v107, 0
	v_lshl_add_u64 v[106:107], v[104:105], 0, v[106:107]
	v_mov_b32_dpp v100, v96 row_ror:8 row_mask:0xf bank_mask:0xc
	v_mov_b32_dpp v101, v97 row_ror:8 row_mask:0xf bank_mask:0xc
	v_mov_b32_dpp v102, v98 row_ror:8 row_mask:0xf bank_mask:0xc
	v_mov_b32_dpp v103, v99 row_ror:8 row_mask:0xf bank_mask:0xc
	v_mov_b32_dpp v96, v108 row_ror:8 row_mask:0xf bank_mask:0x3
	v_mov_b32_dpp v97, v109 row_ror:8 row_mask:0xf bank_mask:0x3
	v_mov_b32_dpp v98, v110 row_ror:8 row_mask:0xf bank_mask:0x3
	v_mov_b32_dpp v99, v111 row_ror:8 row_mask:0xf bank_mask:0x3
	global_store_dwordx4 v[104:105], v[100:103], off
	global_store_dwordx4 v[106:107], v[96:99], off
	s_nop 1
	v_mov_b32_dpp v96, v100 row_ror:8 row_mask:0xf bank_mask:0x3
	v_mov_b32_dpp v97, v101 row_ror:8 row_mask:0xf bank_mask:0x3
	v_mov_b32_dpp v98, v102 row_ror:8 row_mask:0xf bank_mask:0x3
	v_mov_b32_dpp v99, v103 row_ror:8 row_mask:0xf bank_mask:0x3
	v_mov_b32_e32 v100, v108
	v_mov_b32_e32 v101, v109
	v_mov_b32_e32 v102, v110
	v_mov_b32_e32 v103, v111
	s_nop 1
	v_permlane32_swap_b32_e32 v100, v96
	v_permlane32_swap_b32_e32 v101, v97
	v_permlane32_swap_b32_e32 v102, v98
	v_permlane32_swap_b32_e32 v103, v99
	v_permlane16_swap_b32_e32 v100, v96
	v_permlane16_swap_b32_e32 v101, v97
	v_permlane16_swap_b32_e32 v102, v98
	v_permlane16_swap_b32_e32 v103, v99
	global_store_dwordx4 v[48:49], v[42:45], off
	s_waitcnt vmcnt(7)
	s_nop 0
	v_sub_f32_e32 v43, v73, v93
	v_sub_f32_e32 v42, v72, v93
	v_sub_f32_e32 v45, v71, v93
	v_sub_f32_e32 v44, v70, v93
	v_pk_mul_f32 v[44:45], v[92:93], v[44:45] op_sel_hi:[0,1]
	v_pk_mul_f32 v[42:43], v[92:93], v[42:43] op_sel_hi:[0,1]
	s_waitcnt vmcnt(3)
	v_pk_fma_f32 v[42:43], v[64:65], v[42:43], v[68:69]
	v_pk_fma_f32 v[44:45], v[62:63], v[44:45], v[66:67]
	v_pk_mul_f32 v[42:43], v[42:43], s[2:3] op_sel_hi:[1,0]
	v_pk_mul_f32 v[44:45], v[44:45], s[2:3] op_sel_hi:[1,0]
	v_pk_fma_f32 v[40:41], v[40:41], 0.5, v[42:43] op_sel_hi:[1,0,1]
	v_pk_fma_f32 v[38:39], v[38:39], 0.5, v[44:45] op_sel_hi:[1,0,1]
	v_add_f32_e32 v43, v40, v41
	v_add_f32_e32 v42, v38, v39
	v_add_f32_e32 v42, v42, v43
	v_add_f32_e32 v47, v47, v42
	v_mul_f32_e32 v42, v39, v39
	v_mul_f32_e32 v43, v41, v41
	v_fmac_f32_e32 v42, v38, v38
	v_fmac_f32_e32 v43, v40, v40
	v_add_f32_e32 v42, v42, v43
	v_add_f32_e32 v46, v46, v42
	v_sub_f32_e32 v43, v53, v93
	v_sub_f32_e32 v42, v52, v93
	v_sub_f32_e32 v45, v51, v93
	v_sub_f32_e32 v44, v50, v93
	v_pk_mul_f32 v[44:45], v[92:93], v[44:45] op_sel_hi:[0,1]
	v_pk_mul_f32 v[42:43], v[92:93], v[42:43] op_sel_hi:[0,1]
	v_pk_fma_f32 v[42:43], v[56:57], v[42:43], v[60:61]
	v_pk_fma_f32 v[44:45], v[54:55], v[44:45], v[58:59]
	v_pk_mul_f32 v[42:43], v[42:43], s[2:3] op_sel_hi:[1,0]
	v_pk_mul_f32 v[44:45], v[44:45], s[2:3] op_sel_hi:[1,0]
	v_pk_fma_f32 v[36:37], v[36:37], 0.5, v[42:43] op_sel_hi:[1,0,1]
	v_pk_fma_f32 v[34:35], v[34:35], 0.5, v[44:45] op_sel_hi:[1,0,1]
	v_add_f32_e32 v43, v36, v37
	v_add_f32_e32 v42, v34, v35
	v_add_f32_e32 v42, v42, v43
	v_mul_f32_e32 v43, v35, v35
	v_mul_f32_e32 v44, v37, v37
	v_add_f32_e32 v42, v47, v42
	v_fmac_f32_e32 v43, v34, v34
	v_fmac_f32_e32 v44, v36, v36
; __device__ __forceinline__ float xsum16(float v) { const auto r = __builtin_amdgcn_permlane16_swap(__float_as_uint(v), __float_as_uint(v), false, false); return __uint_as_float(r[0]) + __uint_as_float(r[1]); }
; __device__ __forceinline__ float xsum32(float v) { const auto r = __builtin_amdgcn_permlane32_swap(__float_as_uint(v), __float_as_uint(v), false, false); return __uint_as_float(r[0]) + __uint_as_float(r[1]); }
; __device__ __forceinline__ size_t blk_off(int r, int c, int K) { return (size_t)(r >> 8) * 256 * K + (size_t)(c >> 6) * (256 * 64) + (size_t)((r & 255) * 64 + (c & 63)); }
; __device__ __forceinline__ u32x4 pack8(const f32x4 a, const f32x4 b) { u32x4 w; w.x = cvt_pk_bf16(a[0], a[1]); w.y = cvt_pk_bf16(a[2], a[3]); w.z = cvt_pk_bf16(b[0], b[1]); w.w = cvt_pk_bf16(b[2], b[3]); return w; }
;     __device__ __forceinline__ void operator()(const f32x4 (&acc)[2][2][4][2], const pg8::Unit& u, int wr, int wc, int fr, int fq) const {
;     ...
;                 for (int bj = 0; bj < 2; ++bj) { float* yp = Y + (size_t)row * D_ + col0 + bj * 128; f32x4 v[2];
; #pragma unroll
;                     for (int n = 0; n < 2; ++n) { v[n] = (((yv[bj][n] - mu) * rs) * gq[bj][n] + bq_[bj][n]) * ALPHA_ + acc[ai][bj][m][n] * sc;
;                         *(f32x4*)(yp + 4 * n) = v[n]; s1 += (v[n][0] + v[n][1]) + (v[n][2] + v[n][3]); s2 += (v[n][0] * v[n][0] + v[n][1] * v[n][1]) + (v[n][2] * v[n][2] + v[n][3] * v[n][3]); }
;                     *(u32x4*)(Yb + blk_off(row, col0 + bj * 128, D_)) = pack8(v[0], v[1]); }
;                 s1 = xsum32(xsum16(s1)); s2 = xsum32(xsum16(s2));
;                 if (fq == 0) *(f32x2*)(stn + (size_t)row * 32 + (u.pn * 4 + wc) * 2) = (f32x2){s1, s2}; asm volatile("" ::: "memory"); } }
	s_nop 0
	s_nop 1
	v_bfe_u32 v49, v227, 4, 2
	v_sub_u32_e32 v48, 0, v49
	v_lshlrev_b32_e32 v48, 4, v48
	v_ashrrev_i32_e32 v49, 31, v48
	v_lshl_add_u64 v[48:49], v[94:95], 0, v[48:49]
	v_permlane16_swap_b32_e32 v38, v34
	v_permlane16_swap_b32_e32 v39, v35
	v_permlane16_swap_b32_e32 v40, v36
	v_permlane16_swap_b32_e32 v41, v37
	v_permlane32_swap_b32_e32 v38, v34
	v_permlane32_swap_b32_e32 v39, v35
	v_permlane32_swap_b32_e32 v40, v36
	v_permlane32_swap_b32_e32 v41, v37
	v_mov_b32_e32 v45, v38
	v_mov_b32_e32 v52, v39
	v_mov_b32_e32 v53, v40
	v_mov_b32_e32 v54, v41
	v_bfe_u32 v50, v227, 3, 1
	v_mul_i32_i24_e32 v50, 0xffff8040, v50
	v_ashrrev_i32_e32 v51, 31, v50
	v_lshl_add_u64 v[48:49], v[48:49], 0, v[50:51]
	v_mov_b32_e32 v50, 0x8000
	v_mov_b32_e32 v51, 0
	v_lshl_add_u64 v[50:51], v[48:49], 0, v[50:51]
	v_mov_b32_dpp v38, v34 row_ror:8 row_mask:0xf bank_mask:0xc
	v_mov_b32_dpp v39, v35 row_ror:8 row_mask:0xf bank_mask:0xc
	v_mov_b32_dpp v40, v36 row_ror:8 row_mask:0xf bank_mask:0xc
	v_mov_b32_dpp v41, v37 row_ror:8 row_mask:0xf bank_mask:0xc
	v_mov_b32_dpp v34, v45 row_ror:8 row_mask:0xf bank_mask:0x3
	v_mov_b32_dpp v35, v52 row_ror:8 row_mask:0xf bank_mask:0x3
	v_mov_b32_dpp v36, v53 row_ror:8 row_mask:0xf bank_mask:0x3
	v_mov_b32_dpp v37, v54 row_ror:8 row_mask:0xf bank_mask:0x3
	global_store_dwordx4 v[48:49], v[38:41], off offset:512
	global_store_dwordx4 v[50:51], v[34:37], off offset:512
	s_nop 1
	v_mov_b32_dpp v34, v38 row_ror:8 row_mask:0xf bank_mask:0x3
	v_mov_b32_dpp v35, v39 row_ror:8 row_mask:0xf bank_mask:0x3
	v_mov_b32_dpp v36, v40 row_ror:8 row_mask:0xf bank_mask:0x3
	v_mov_b32_dpp v37, v41 row_ror:8 row_mask:0xf bank_mask:0x3
	v_mov_b32_e32 v38, v45
	v_mov_b32_e32 v39, v52
	v_mov_b32_e32 v40, v53
	v_mov_b32_e32 v41, v54
	s_nop 1
	v_permlane32_swap_b32_e32 v38, v34
	v_permlane32_swap_b32_e32 v39, v35
	v_permlane32_swap_b32_e32 v40, v36
	v_permlane32_swap_b32_e32 v41, v37
	v_permlane16_swap_b32_e32 v38, v34
	v_permlane16_swap_b32_e32 v39, v35
	v_permlane16_swap_b32_e32 v40, v36
	v_permlane16_swap_b32_e32 v41, v37
	v_add_f32_e32 v43, v43, v44
	v_cvt_pk_bf16_f32 v38, v38, v39
	v_cvt_pk_bf16_f32 v39, v40, v41
	v_cvt_pk_bf16_f32 v40, v34, v35
	v_lshl_add_u64 v[34:35], v[78:79], 0, v[0:1]
	v_mov_b32_e32 v0, v42
	v_add_f32_e32 v43, v46, v43
	v_cvt_pk_bf16_f32 v41, v36, v37
	v_permlane16_swap_b32_e32 v42, v0
	global_store_dwordx4 v[34:35], v[38:41], off
	v_add_f32_e32 v34, v42, v0
	v_mov_b32_e32 v0, v43
	s_nop 1
	v_permlane16_swap_b32_e32 v43, v0
	v_add_f32_e32 v35, v43, v0
	v_mov_b32_e32 v36, v34
	v_mov_b32_e32 v37, v35
	s_nop 0
	v_permlane32_swap_b32_e32 v34, v36
	v_permlane32_swap_b32_e32 v35, v37
	s_and_saveexec_b64 s[26:27], s[44:45]
	s_cbranch_execz .LBB0_384
	v_pk_add_f32 v[34:35], v[34:35], v[36:37]
	v_lshl_add_u64 v[36:37], s[30:31], 0, v[86:87]
	v_lshl_add_u64 v[36:37], s[24:25], 2, v[36:37]
	global_store_dwordx2 v[36:37], v[34:35], off
.LBB0_384:
	s_or_b64 exec, exec, s[26:27]
	v_pk_add_f32 v[34:35], v[88:89], v[90:91]
	s_mov_b32 s2, 0x3a800000
	v_pk_mul_f32 v[58:59], v[34:35], s[2:3] op_sel_hi:[1,0]
	s_mov_b32 s2, 0x800000
	v_fma_f32 v0, -v59, v59, v58
	v_max_f32_e32 v0, 0, v0
	v_add_f32_e32 v0, 0x3727c5ac, v0
	v_cmp_gt_f32_e32 vcc, s2, v0
	v_mul_f32_e32 v34, 0x4b800000, v0
	v_lshlrev_b64 v[60:61], 12, v[76:77]
	v_cndmask_b32_e32 v0, v0, v34, vcc
	v_rsq_f32_e32 v0, v0
	s_movk_i32 s2, 0x3bc0
	s_load_dwordx16 s[60:75], s[34:35], 0x38
	v_mul_f32_e32 v34, 0x45800000, v0
	v_cndmask_b32_e32 v58, v0, v34, vcc
	v_lshl_add_u64 v[34:35], s[12:13], 0, v[60:61]
	v_lshl_add_u64 v[38:39], v[34:35], 0, v[152:153]
	global_load_dwordx4 v[62:65], v[38:39], off offset:16
	global_load_dwordx4 v[66:69], v[38:39], off
	global_load_dwordx4 v[70:73], v[154:155], off offset:16
	global_load_dwordx4 v[86:89], v[154:155], off
	global_load_dwordx4 v[90:93], v[156:157], off offset:16
	global_load_dwordx4 v[94:97], v[156:157], off
	global_load_dwordx4 v[34:37], v[38:39], off offset:528
	global_load_dwordx4 v[54:57], v[38:39], off offset:512
	s_nop 0
	global_load_dwordx4 v[38:41], v[154:155], off offset:528
	global_load_dwordx4 v[46:49], v[154:155], off offset:512
	global_load_dwordx4 v[42:45], v[156:157], off offset:528
	global_load_dwordx4 v[50:53], v[156:157], off offset:512
	v_lshlrev_b32_e32 v0, 6, v76
	v_and_or_b32 v0, v0, s2, v194
	s_mov_b32 s2, 0x3fd744fd
	s_waitcnt lgkmcnt(0)
	v_lshl_add_u64 v[60:61], s[74:75], 0, v[60:61]
	v_lshlrev_b32_e32 v0, 1, v0
	v_lshl_add_u64 v[60:61], v[60:61], 0, v[152:153]
	s_waitcnt vmcnt(10)
	v_sub_f32_e32 v69, v69, v59
	v_sub_f32_e32 v68, v68, v59
	v_sub_f32_e32 v67, v67, v59
	v_sub_f32_e32 v66, v66, v59
	v_pk_mul_f32 v[66:67], v[58:59], v[66:67] op_sel_hi:[0,1]
	v_pk_mul_f32 v[68:69], v[58:59], v[68:69] op_sel_hi:[0,1]
	s_waitcnt vmcnt(6)
; __device__ __forceinline__ size_t blk_off(int r, int c, int K) { return (size_t)(r >> 8) * 256 * K + (size_t)(c >> 6) * (256 * 64) + (size_t)((r & 255) * 64 + (c & 63)); }
; __device__ __forceinline__ u32x4 pack8(const f32x4 a, const f32x4 b) { u32x4 w; w.x = cvt_pk_bf16(a[0], a[1]); w.y = cvt_pk_bf16(a[2], a[3]); w.z = cvt_pk_bf16(b[0], b[1]); w.w = cvt_pk_bf16(b[2], b[3]); return w; }
;     __device__ __forceinline__ void operator()(const f32x4 (&acc)[2][2][4][2], const pg8::Unit& u, int wr, int wc, int fr, int fq) const {
;     ...
;                 for (int bj = 0; bj < 2; ++bj) { float* yp = Y + (size_t)row * D_ + col0 + bj * 128; f32x4 v[2];
; #pragma unroll
;                     for (int n = 0; n < 2; ++n) { v[n] = (((yv[bj][n] - mu) * rs) * gq[bj][n] + bq_[bj][n]) * ALPHA_ + acc[ai][bj][m][n] * sc;
;                         *(f32x4*)(yp + 4 * n) = v[n]; s1 += (v[n][0] + v[n][1]) + (v[n][2] + v[n][3]); s2 += (v[n][0] * v[n][0] + v[n][1] * v[n][1]) + (v[n][2] * v[n][2] + v[n][3] * v[n][3]); }
;                     *(u32x4*)(Yb + blk_off(row, col0 + bj * 128, D_)) = pack8(v[0], v[1]); }
	v_pk_fma_f32 v[68:69], v[88:89], v[68:69], v[96:97]
	v_pk_fma_f32 v[66:67], v[86:87], v[66:67], v[94:95]
	v_pk_mul_f32 v[68:69], v[68:69], s[2:3] op_sel_hi:[1,0]
	v_pk_mul_f32 v[66:67], v[66:67], s[2:3] op_sel_hi:[1,0]
	v_pk_fma_f32 v[68:69], v[32:33], 0.5, v[68:69] op_sel_hi:[1,0,1]
	v_pk_fma_f32 v[66:67], v[30:31], 0.5, v[66:67] op_sel_hi:[1,0,1]
	v_add_f32_e32 v31, v68, v69
	v_add_f32_e32 v30, v66, v67
	v_add_f32_e32 v30, v30, v31
	v_add_f32_e32 v86, 0, v30
	v_mul_f32_e32 v30, v67, v67
	v_mul_f32_e32 v31, v69, v69
	v_fmac_f32_e32 v30, v66, v66
	v_fmac_f32_e32 v31, v68, v68
	v_add_f32_e32 v87, v30, v31
	v_sub_f32_e32 v31, v65, v59
	v_sub_f32_e32 v30, v64, v59
	v_sub_f32_e32 v33, v63, v59
	v_sub_f32_e32 v32, v62, v59
	v_pk_mul_f32 v[32:33], v[58:59], v[32:33] op_sel_hi:[0,1]
	v_pk_mul_f32 v[30:31], v[58:59], v[30:31] op_sel_hi:[0,1]
	v_pk_fma_f32 v[30:31], v[72:73], v[30:31], v[92:93]
	v_pk_fma_f32 v[32:33], v[70:71], v[32:33], v[90:91]
	v_pk_mul_f32 v[30:31], v[30:31], s[2:3] op_sel_hi:[1,0]
	v_pk_mul_f32 v[32:33], v[32:33], s[2:3] op_sel_hi:[1,0]
	v_pk_fma_f32 v[64:65], v[28:29], 0.5, v[30:31] op_sel_hi:[1,0,1]
	v_pk_fma_f32 v[62:63], v[26:27], 0.5, v[32:33] op_sel_hi:[1,0,1]
	v_add_f32_e32 v27, v64, v65
	v_add_f32_e32 v26, v62, v63
	v_add_f32_e32 v26, v26, v27
	v_add_f32_e32 v31, v86, v26
	v_mul_f32_e32 v26, v63, v63
	v_mul_f32_e32 v27, v65, v65
	v_fmac_f32_e32 v26, v62, v62
	v_fmac_f32_e32 v27, v64, v64
	v_add_f32_e32 v26, v26, v27
	v_add_f32_e32 v30, v87, v26
	v_cvt_pk_bf16_f32 v26, v66, v67
	v_cvt_pk_bf16_f32 v27, v68, v69
	v_cvt_pk_bf16_f32 v28, v62, v63
	v_cvt_pk_bf16_f32 v29, v64, v65
	v_lshl_add_u64 v[32:33], v[80:81], 0, v[0:1]
	s_nop 0
	s_nop 1
	v_bfe_u32 v71, v227, 4, 2
	v_sub_u32_e32 v70, 0, v71
	v_lshlrev_b32_e32 v70, 4, v70
	v_ashrrev_i32_e32 v71, 31, v70
	v_lshl_add_u64 v[70:71], v[60:61], 0, v[70:71]
	v_permlane16_swap_b32_e32 v66, v62
	v_permlane16_swap_b32_e32 v67, v63
	v_permlane16_swap_b32_e32 v68, v64
	v_permlane16_swap_b32_e32 v69, v65
	v_permlane32_swap_b32_e32 v66, v62
	v_permlane32_swap_b32_e32 v67, v63
	v_permlane32_swap_b32_e32 v68, v64
	v_permlane32_swap_b32_e32 v69, v65
	v_mov_b32_e32 v86, v66
	v_mov_b32_e32 v87, v67
	v_mov_b32_e32 v88, v68
	v_mov_b32_e32 v89, v69
	v_bfe_u32 v72, v227, 3, 1
	v_mul_i32_i24_e32 v72, 0xffff8040, v72
	v_ashrrev_i32_e32 v73, 31, v72
	v_lshl_add_u64 v[70:71], v[70:71], 0, v[72:73]
	v_mov_b32_e32 v72, 0x8000
	v_mov_b32_e32 v73, 0
	v_lshl_add_u64 v[72:73], v[70:71], 0, v[72:73]
	v_mov_b32_dpp v66, v62 row_ror:8 row_mask:0xf bank_mask:0xc
	v_mov_b32_dpp v67, v63 row_ror:8 row_mask:0xf bank_mask:0xc
	v_mov_b32_dpp v68, v64 row_ror:8 row_mask:0xf bank_mask:0xc
	v_mov_b32_dpp v69, v65 row_ror:8 row_mask:0xf bank_mask:0xc
	v_mov_b32_dpp v62, v86 row_ror:8 row_mask:0xf bank_mask:0x3
	v_mov_b32_dpp v63, v87 row_ror:8 row_mask:0xf bank_mask:0x3
	v_mov_b32_dpp v64, v88 row_ror:8 row_mask:0xf bank_mask:0x3
	v_mov_b32_dpp v65, v89 row_ror:8 row_mask:0xf bank_mask:0x3
	global_store_dwordx4 v[70:71], v[66:69], off
	global_store_dwordx4 v[72:73], v[62:65], off
	s_nop 1
	v_mov_b32_dpp v62, v66 row_ror:8 row_mask:0xf bank_mask:0x3
	v_mov_b32_dpp v63, v67 row_ror:8 row_mask:0xf bank_mask:0x3
	v_mov_b32_dpp v64, v68 row_ror:8 row_mask:0xf bank_mask:0x3
	v_mov_b32_dpp v65, v69 row_ror:8 row_mask:0xf bank_mask:0x3
	v_mov_b32_e32 v66, v86
	v_mov_b32_e32 v67, v87
	v_mov_b32_e32 v68, v88
	v_mov_b32_e32 v69, v89
	s_nop 1
	v_permlane32_swap_b32_e32 v66, v62
	v_permlane32_swap_b32_e32 v67, v63
	v_permlane32_swap_b32_e32 v68, v64
	v_permlane32_swap_b32_e32 v69, v65
	v_permlane16_swap_b32_e32 v66, v62
	v_permlane16_swap_b32_e32 v67, v63
	v_permlane16_swap_b32_e32 v68, v64
	v_permlane16_swap_b32_e32 v69, v65
	global_store_dwordx4 v[32:33], v[26:29], off
	s_waitcnt vmcnt(7)
	s_nop 0
	v_sub_f32_e32 v27, v57, v59
	v_sub_f32_e32 v26, v56, v59
	v_sub_f32_e32 v29, v55, v59
	v_sub_f32_e32 v28, v54, v59
	v_pk_mul_f32 v[28:29], v[58:59], v[28:29] op_sel_hi:[0,1]
	v_pk_mul_f32 v[26:27], v[58:59], v[26:27] op_sel_hi:[0,1]
	s_waitcnt vmcnt(3)
	v_pk_fma_f32 v[26:27], v[48:49], v[26:27], v[52:53]
	v_pk_fma_f32 v[28:29], v[46:47], v[28:29], v[50:51]
	v_pk_mul_f32 v[26:27], v[26:27], s[2:3] op_sel_hi:[1,0]
	v_pk_mul_f32 v[28:29], v[28:29], s[2:3] op_sel_hi:[1,0]
	v_pk_fma_f32 v[24:25], v[24:25], 0.5, v[26:27] op_sel_hi:[1,0,1]
	v_pk_fma_f32 v[22:23], v[22:23], 0.5, v[28:29] op_sel_hi:[1,0,1]
	v_add_f32_e32 v27, v24, v25
	v_add_f32_e32 v26, v22, v23
	v_add_f32_e32 v26, v26, v27
	v_add_f32_e32 v31, v31, v26
	v_mul_f32_e32 v26, v23, v23
	v_mul_f32_e32 v27, v25, v25
	v_fmac_f32_e32 v26, v22, v22
	v_fmac_f32_e32 v27, v24, v24
	v_add_f32_e32 v26, v26, v27
	v_add_f32_e32 v30, v30, v26
	v_sub_f32_e32 v27, v37, v59
	v_sub_f32_e32 v26, v36, v59
	v_sub_f32_e32 v29, v35, v59
	v_sub_f32_e32 v28, v34, v59
	v_pk_mul_f32 v[28:29], v[58:59], v[28:29] op_sel_hi:[0,1]
	v_pk_mul_f32 v[26:27], v[58:59], v[26:27] op_sel_hi:[0,1]
	v_pk_fma_f32 v[26:27], v[40:41], v[26:27], v[44:45]
	v_pk_fma_f32 v[28:29], v[38:39], v[28:29], v[42:43]
	v_pk_mul_f32 v[26:27], v[26:27], s[2:3] op_sel_hi:[1,0]
	v_pk_mul_f32 v[28:29], v[28:29], s[2:3] op_sel_hi:[1,0]
	v_pk_fma_f32 v[20:21], v[20:21], 0.5, v[26:27] op_sel_hi:[1,0,1]
	v_pk_fma_f32 v[18:19], v[18:19], 0.5, v[28:29] op_sel_hi:[1,0,1]
	v_add_f32_e32 v27, v20, v21
	v_add_f32_e32 v26, v18, v19
	v_add_f32_e32 v26, v26, v27
	v_mul_f32_e32 v27, v19, v19
	v_mul_f32_e32 v28, v21, v21
	v_add_f32_e32 v26, v31, v26
	v_fmac_f32_e32 v27, v18, v18
	v_fmac_f32_e32 v28, v20, v20
	s_nop 0
	s_nop 1
	v_bfe_u32 v33, v227, 4, 2
	v_sub_u32_e32 v32, 0, v33
	v_lshlrev_b32_e32 v32, 4, v32
	v_ashrrev_i32_e32 v33, 31, v32
; __device__ __forceinline__ float xsum16(float v) { const auto r = __builtin_amdgcn_permlane16_swap(__float_as_uint(v), __float_as_uint(v), false, false); return __uint_as_float(r[0]) + __uint_as_float(r[1]); }
; __device__ __forceinline__ float xsum32(float v) { const auto r = __builtin_amdgcn_permlane32_swap(__float_as_uint(v), __float_as_uint(v), false, false); return __uint_as_float(r[0]) + __uint_as_float(r[1]); }
; __device__ __forceinline__ size_t blk_off(int r, int c, int K) { return (size_t)(r >> 8) * 256 * K + (size_t)(c >> 6) * (256 * 64) + (size_t)((r & 255) * 64 + (c & 63)); }
; __device__ __forceinline__ void row_stats4(const float* st, int rowb, int fq, float (&mu)[4], float (&rs)[4]) {
;     f32x4 a[4], b[4];
; #pragma unroll
;     for (int m = 0; m < 4; ++m) { const f32x4* p = (const f32x4*)(st + (size_t)(rowb + m * 16) * 32 + fq * 8); a[m] = p[0]; b[m] = p[1]; }
; #pragma unroll
;     for (int m = 0; m < 4; ++m) { float s1 = (a[m][0] + a[m][2]) + (b[m][0] + b[m][2]), s2 = (a[m][1] + a[m][3]) + (b[m][1] + b[m][3]);
;         s1 = xsum32(xsum16(s1)); s2 = xsum32(xsum16(s2));
;         const float mm = s1 * (1.0f / 1024.0f); mu[m] = mm; rs[m] = rsqrtf(fmaxf(s2 * (1.0f / 1024.0f) - mm * mm, 0.f) + LN_EPS_); }
;     asm volatile("" ::: "memory");
; }
;     __device__ __forceinline__ void operator()(const f32x4 (&acc)[2][2][4][2], const pg8::Unit& u, int wr, int wc, int fr, int fq) const {
;     ...
;                 for (int bj = 0; bj < 2; ++bj) { float* yp = Y + (size_t)row * D_ + col0 + bj * 128; f32x4 v[2];
; #pragma unroll
;                     for (int n = 0; n < 2; ++n) { v[n] = (((yv[bj][n] - mu) * rs) * gq[bj][n] + bq_[bj][n]) * ALPHA_ + acc[ai][bj][m][n] * sc;
;                         *(f32x4*)(yp + 4 * n) = v[n]; s1 += (v[n][0] + v[n][1]) + (v[n][2] + v[n][3]); s2 += (v[n][0] * v[n][0] + v[n][1] * v[n][1]) + (v[n][2] * v[n][2] + v[n][3] * v[n][3]); }
;                     *(u32x4*)(Yb + blk_off(row, col0 + bj * 128, D_)) = pack8(v[0], v[1]); }
;                 s1 = xsum32(xsum16(s1)); s2 = xsum32(xsum16(s2));
;                 if (fq == 0) *(f32x2*)(stn + (size_t)row * 32 + (u.pn * 4 + wc) * 2) = (f32x2){s1, s2}; asm volatile("" ::: "memory"); } }
	v_lshl_add_u64 v[32:33], v[60:61], 0, v[32:33]
	v_permlane16_swap_b32_e32 v22, v18
	v_permlane16_swap_b32_e32 v23, v19
	v_permlane16_swap_b32_e32 v24, v20
	v_permlane16_swap_b32_e32 v25, v21
	v_permlane32_swap_b32_e32 v22, v18
	v_permlane32_swap_b32_e32 v23, v19
	v_permlane32_swap_b32_e32 v24, v20
	v_permlane32_swap_b32_e32 v25, v21
	v_mov_b32_e32 v29, v22
	v_mov_b32_e32 v36, v23
	v_mov_b32_e32 v37, v24
	v_mov_b32_e32 v38, v25
	v_bfe_u32 v34, v227, 3, 1
	v_mul_i32_i24_e32 v34, 0xffff8040, v34
	v_ashrrev_i32_e32 v35, 31, v34
	v_lshl_add_u64 v[32:33], v[32:33], 0, v[34:35]
	v_mov_b32_e32 v34, 0x8000
	v_mov_b32_e32 v35, 0
	v_lshl_add_u64 v[34:35], v[32:33], 0, v[34:35]
	v_mov_b32_dpp v22, v18 row_ror:8 row_mask:0xf bank_mask:0xc
	v_mov_b32_dpp v23, v19 row_ror:8 row_mask:0xf bank_mask:0xc
	v_mov_b32_dpp v24, v20 row_ror:8 row_mask:0xf bank_mask:0xc
	v_mov_b32_dpp v25, v21 row_ror:8 row_mask:0xf bank_mask:0xc
	v_mov_b32_dpp v18, v29 row_ror:8 row_mask:0xf bank_mask:0x3
	v_mov_b32_dpp v19, v36 row_ror:8 row_mask:0xf bank_mask:0x3
	v_mov_b32_dpp v20, v37 row_ror:8 row_mask:0xf bank_mask:0x3
	v_mov_b32_dpp v21, v38 row_ror:8 row_mask:0xf bank_mask:0x3
	global_store_dwordx4 v[32:33], v[22:25], off offset:512
	global_store_dwordx4 v[34:35], v[18:21], off offset:512
	s_nop 1
	v_mov_b32_dpp v18, v22 row_ror:8 row_mask:0xf bank_mask:0x3
	v_mov_b32_dpp v19, v23 row_ror:8 row_mask:0xf bank_mask:0x3
	v_mov_b32_dpp v20, v24 row_ror:8 row_mask:0xf bank_mask:0x3
	v_mov_b32_dpp v21, v25 row_ror:8 row_mask:0xf bank_mask:0x3
	v_mov_b32_e32 v22, v29
	v_mov_b32_e32 v23, v36
	v_mov_b32_e32 v24, v37
	v_mov_b32_e32 v25, v38
	s_nop 1
	v_permlane32_swap_b32_e32 v22, v18
	v_permlane32_swap_b32_e32 v23, v19
	v_permlane32_swap_b32_e32 v24, v20
	v_permlane32_swap_b32_e32 v25, v21
	v_permlane16_swap_b32_e32 v22, v18
	v_permlane16_swap_b32_e32 v23, v19
	v_permlane16_swap_b32_e32 v24, v20
	v_permlane16_swap_b32_e32 v25, v21
	v_add_f32_e32 v27, v27, v28
	v_cvt_pk_bf16_f32 v22, v22, v23
	v_cvt_pk_bf16_f32 v23, v24, v25
	v_cvt_pk_bf16_f32 v24, v18, v19
	v_lshl_add_u64 v[18:19], v[78:79], 0, v[0:1]
	v_mov_b32_e32 v0, v26
	v_add_f32_e32 v27, v30, v27
	v_cvt_pk_bf16_f32 v25, v20, v21
	v_permlane16_swap_b32_e32 v26, v0
	global_store_dwordx4 v[18:19], v[22:25], off
	v_add_f32_e32 v18, v26, v0
	v_mov_b32_e32 v0, v27
	s_nop 1
	v_permlane16_swap_b32_e32 v27, v0
	v_add_f32_e32 v19, v27, v0
	v_mov_b32_e32 v20, v18
	v_mov_b32_e32 v21, v19
	s_nop 0
	v_permlane32_swap_b32_e32 v18, v20
	v_permlane32_swap_b32_e32 v19, v21
	s_and_saveexec_b64 s[26:27], s[44:45]
	s_cbranch_execz .LBB0_386
	v_pk_add_f32 v[18:19], v[18:19], v[20:21]
	v_lshlrev_b64 v[20:21], 7, v[76:77]
	v_lshl_add_u64 v[20:21], s[30:31], 0, v[20:21]
	v_lshl_add_u64 v[20:21], s[24:25], 2, v[20:21]
	global_store_dwordx2 v[20:21], v[18:19], off
.LBB0_386:
	s_or_b64 exec, exec, s[26:27]
	v_lshlrev_b64 v[26:27], 12, v[74:75]
	v_lshl_add_u64 v[18:19], s[12:13], 0, v[26:27]
	v_lshl_add_u64 v[28:29], v[18:19], 0, v[152:153]
	global_load_dwordx4 v[34:37], v[28:29], off
	global_load_dwordx4 v[38:41], v[28:29], off offset:16
	global_load_dwordx4 v[42:45], v[28:29], off offset:512
	global_load_dwordx4 v[46:49], v[156:157], off
	global_load_dwordx4 v[50:53], v[154:155], off
	global_load_dwordx4 v[54:57], v[154:155], off offset:16
	global_load_dwordx4 v[58:61], v[156:157], off offset:16
	global_load_dwordx4 v[62:65], v[154:155], off offset:512
	global_load_dwordx4 v[66:69], v[156:157], off offset:512
	s_load_dwordx16 s[60:75], s[34:35], 0x38
	v_pk_add_f32 v[18:19], v[82:83], v[84:85]
	s_mov_b32 s2, 0x3a800000
	v_pk_mul_f32 v[32:33], v[18:19], s[2:3] op_sel_hi:[1,0]
	global_load_dwordx4 v[18:21], v[154:155], off offset:528
	global_load_dwordx4 v[22:25], v[156:157], off offset:528
	s_waitcnt lgkmcnt(0)
	v_lshl_add_u64 v[26:27], s[74:75], 0, v[26:27]
	v_lshl_add_u64 v[30:31], v[26:27], 0, v[152:153]
	global_load_dwordx4 v[26:29], v[28:29], off offset:528
	v_fma_f32 v32, -v33, v33, v32
	v_lshlrev_b32_e32 v0, 6, v74
	s_movk_i32 s2, 0x3fc0
	v_max_f32_e32 v32, 0, v32
	v_and_or_b32 v0, v0, s2, v194
	v_add_f32_e32 v32, 0x3727c5ac, v32
	s_mov_b32 s2, 0x800000
	v_mul_f32_e32 v70, 0x4b800000, v32
	v_cmp_gt_f32_e32 vcc, s2, v32
	s_mov_b32 s2, 0x3fd744fd
	v_lshlrev_b32_e32 v0, 1, v0
	v_cndmask_b32_e32 v32, v32, v70, vcc
	v_rsq_f32_e32 v32, v32
	v_lshl_add_u64 v[70:71], v[80:81], 0, v[0:1]
	v_mul_f32_e32 v72, 0x45800000, v32
	v_cndmask_b32_e32 v32, v32, v72, vcc
	s_waitcnt vmcnt(11)
	v_sub_f32_e32 v37, v37, v33
	v_sub_f32_e32 v36, v36, v33
	v_sub_f32_e32 v35, v35, v33
	v_sub_f32_e32 v34, v34, v33
	s_waitcnt vmcnt(10)
	v_sub_f32_e32 v41, v41, v33
	v_sub_f32_e32 v40, v40, v33
	v_sub_f32_e32 v39, v39, v33
	v_sub_f32_e32 v38, v38, v33
	v_pk_mul_f32 v[34:35], v[32:33], v[34:35] op_sel_hi:[0,1]
	v_pk_mul_f32 v[36:37], v[32:33], v[36:37] op_sel_hi:[0,1]
	v_pk_mul_f32 v[38:39], v[32:33], v[38:39] op_sel_hi:[0,1]
	v_pk_mul_f32 v[40:41], v[32:33], v[40:41] op_sel_hi:[0,1]
	s_waitcnt vmcnt(7)
	v_pk_fma_f32 v[36:37], v[52:53], v[36:37], v[48:49]
	v_pk_fma_f32 v[34:35], v[50:51], v[34:35], v[46:47]
	s_waitcnt vmcnt(5)
; __device__ __forceinline__ float xsum16(float v) { const auto r = __builtin_amdgcn_permlane16_swap(__float_as_uint(v), __float_as_uint(v), false, false); return __uint_as_float(r[0]) + __uint_as_float(r[1]); }
; __device__ __forceinline__ float xsum32(float v) { const auto r = __builtin_amdgcn_permlane32_swap(__float_as_uint(v), __float_as_uint(v), false, false); return __uint_as_float(r[0]) + __uint_as_float(r[1]); }
; __device__ __forceinline__ size_t blk_off(int r, int c, int K) { return (size_t)(r >> 8) * 256 * K + (size_t)(c >> 6) * (256 * 64) + (size_t)((r & 255) * 64 + (c & 63)); }
; __device__ __forceinline__ u32x4 pack8(const f32x4 a, const f32x4 b) { u32x4 w; w.x = cvt_pk_bf16(a[0], a[1]); w.y = cvt_pk_bf16(a[2], a[3]); w.z = cvt_pk_bf16(b[0], b[1]); w.w = cvt_pk_bf16(b[2], b[3]); return w; }
;     __device__ __forceinline__ void operator()(const f32x4 (&acc)[2][2][4][2], const pg8::Unit& u, int wr, int wc, int fr, int fq) const {
;     ...
;                 for (int bj = 0; bj < 2; ++bj) { float* yp = Y + (size_t)row * D_ + col0 + bj * 128; f32x4 v[2];
; #pragma unroll
;                     for (int n = 0; n < 2; ++n) { v[n] = (((yv[bj][n] - mu) * rs) * gq[bj][n] + bq_[bj][n]) * ALPHA_ + acc[ai][bj][m][n] * sc;
;                         *(f32x4*)(yp + 4 * n) = v[n]; s1 += (v[n][0] + v[n][1]) + (v[n][2] + v[n][3]); s2 += (v[n][0] * v[n][0] + v[n][1] * v[n][1]) + (v[n][2] * v[n][2] + v[n][3] * v[n][3]); }
;                     *(u32x4*)(Yb + blk_off(row, col0 + bj * 128, D_)) = pack8(v[0], v[1]); }
;                 s1 = xsum32(xsum16(s1)); s2 = xsum32(xsum16(s2));
;                 if (fq == 0) *(f32x2*)(stn + (size_t)row * 32 + (u.pn * 4 + wc) * 2) = (f32x2){s1, s2}; asm volatile("" ::: "memory"); } }
	v_pk_fma_f32 v[40:41], v[56:57], v[40:41], v[60:61]
	v_pk_fma_f32 v[38:39], v[54:55], v[38:39], v[58:59]
	v_pk_mul_f32 v[34:35], v[34:35], s[2:3] op_sel_hi:[1,0]
	v_pk_mul_f32 v[36:37], v[36:37], s[2:3] op_sel_hi:[1,0]
	v_pk_mul_f32 v[38:39], v[38:39], s[2:3] op_sel_hi:[1,0]
	v_pk_mul_f32 v[40:41], v[40:41], s[2:3] op_sel_hi:[1,0]
	v_pk_fma_f32 v[16:17], v[16:17], 0.5, v[36:37] op_sel_hi:[1,0,1]
	v_pk_fma_f32 v[14:15], v[14:15], 0.5, v[34:35] op_sel_hi:[1,0,1]
	v_pk_fma_f32 v[12:13], v[12:13], 0.5, v[40:41] op_sel_hi:[1,0,1]
	v_pk_fma_f32 v[10:11], v[10:11], 0.5, v[38:39] op_sel_hi:[1,0,1]
	v_sub_f32_e32 v45, v45, v33
	v_sub_f32_e32 v44, v44, v33
	v_sub_f32_e32 v43, v43, v33
	v_sub_f32_e32 v42, v42, v33
	v_add_f32_e32 v38, v14, v15
	v_add_f32_e32 v39, v16, v17
	v_mul_f32_e32 v40, v15, v15
	v_mul_f32_e32 v41, v17, v17
	v_mul_f32_e32 v48, v11, v11
	v_mul_f32_e32 v49, v13, v13
	v_pk_mul_f32 v[42:43], v[32:33], v[42:43] op_sel_hi:[0,1]
	v_pk_mul_f32 v[44:45], v[32:33], v[44:45] op_sel_hi:[0,1]
	global_store_dwordx4 v[30:31], v[10:13], off offset:16
	v_add_f32_e32 v46, v10, v11
	v_add_f32_e32 v47, v12, v13
	v_cvt_pk_bf16_f32 v36, v10, v11
	v_add_f32_e32 v11, v38, v39
	v_fmac_f32_e32 v40, v14, v14
	v_fmac_f32_e32 v41, v16, v16
	v_fmac_f32_e32 v48, v10, v10
	v_fmac_f32_e32 v49, v12, v12
	s_waitcnt vmcnt(4)
	v_pk_fma_f32 v[44:45], v[64:65], v[44:45], v[68:69]
	v_pk_fma_f32 v[42:43], v[62:63], v[42:43], v[66:67]
	v_cvt_pk_bf16_f32 v37, v12, v13
	v_add_f32_e32 v13, v46, v47
	v_add_f32_e32 v10, 0, v11
	v_add_f32_e32 v11, v40, v41
	v_add_f32_e32 v12, v48, v49
	global_store_dwordx4 v[30:31], v[14:17], off
	v_cvt_pk_bf16_f32 v34, v14, v15
	v_cvt_pk_bf16_f32 v35, v16, v17
	v_add_f32_e32 v14, v10, v13
	v_add_f32_e32 v15, v11, v12
	v_pk_mul_f32 v[10:11], v[42:43], s[2:3] op_sel_hi:[1,0]
	v_pk_mul_f32 v[12:13], v[44:45], s[2:3] op_sel_hi:[1,0]
	v_pk_fma_f32 v[6:7], v[6:7], 0.5, v[10:11] op_sel_hi:[1,0,1]
	v_pk_fma_f32 v[8:9], v[8:9], 0.5, v[12:13] op_sel_hi:[1,0,1]
	v_add_f32_e32 v10, v6, v7
	v_add_f32_e32 v11, v8, v9
	v_add_f32_e32 v10, v10, v11
	v_add_f32_e32 v14, v14, v10
	v_mul_f32_e32 v10, v7, v7
	v_mul_f32_e32 v11, v9, v9
	v_fmac_f32_e32 v10, v6, v6
	v_fmac_f32_e32 v11, v8, v8
	v_add_f32_e32 v10, v10, v11
	v_add_f32_e32 v15, v15, v10
	s_waitcnt vmcnt(2)
	v_sub_f32_e32 v11, v29, v33
	v_sub_f32_e32 v10, v28, v33
	v_sub_f32_e32 v13, v27, v33
	v_sub_f32_e32 v12, v26, v33
	v_pk_mul_f32 v[12:13], v[32:33], v[12:13] op_sel_hi:[0,1]
	v_pk_mul_f32 v[10:11], v[32:33], v[10:11] op_sel_hi:[0,1]
	v_pk_fma_f32 v[10:11], v[20:21], v[10:11], v[24:25]
	v_pk_fma_f32 v[12:13], v[18:19], v[12:13], v[22:23]
	v_pk_mul_f32 v[10:11], v[10:11], s[2:3] op_sel_hi:[1,0]
	v_pk_mul_f32 v[12:13], v[12:13], s[2:3] op_sel_hi:[1,0]
	v_pk_fma_f32 v[4:5], v[4:5], 0.5, v[10:11] op_sel_hi:[1,0,1]
	v_pk_fma_f32 v[2:3], v[2:3], 0.5, v[12:13] op_sel_hi:[1,0,1]
	v_add_f32_e32 v11, v4, v5
	v_add_f32_e32 v10, v2, v3
	v_add_f32_e32 v10, v10, v11
	v_mul_f32_e32 v11, v3, v3
	v_mul_f32_e32 v12, v5, v5
	v_add_f32_e32 v10, v14, v10
	v_fmac_f32_e32 v11, v2, v2
	v_fmac_f32_e32 v12, v4, v4
	global_store_dwordx4 v[70:71], v[34:37], off
	s_nop 0
	s_nop 1
	v_bfe_u32 v17, v227, 4, 2
	v_sub_u32_e32 v16, 0, v17
	v_lshlrev_b32_e32 v16, 4, v16
	v_ashrrev_i32_e32 v17, 31, v16
	v_lshl_add_u64 v[16:17], v[30:31], 0, v[16:17]
	v_permlane16_swap_b32_e32 v6, v2
	v_permlane16_swap_b32_e32 v7, v3
	v_permlane16_swap_b32_e32 v8, v4
	v_permlane16_swap_b32_e32 v9, v5
	v_permlane32_swap_b32_e32 v6, v2
	v_permlane32_swap_b32_e32 v7, v3
	v_permlane32_swap_b32_e32 v8, v4
	v_permlane32_swap_b32_e32 v9, v5
	v_mov_b32_e32 v13, v6
	v_mov_b32_e32 v14, v7
	v_mov_b32_e32 v20, v8
	v_mov_b32_e32 v21, v9
	v_bfe_u32 v18, v227, 3, 1
	v_mul_i32_i24_e32 v18, 0xffff8040, v18
	v_ashrrev_i32_e32 v19, 31, v18
	v_lshl_add_u64 v[16:17], v[16:17], 0, v[18:19]
	v_mov_b32_e32 v18, 0x8000
	v_mov_b32_e32 v19, 0
	v_lshl_add_u64 v[18:19], v[16:17], 0, v[18:19]
	v_mov_b32_dpp v6, v2 row_ror:8 row_mask:0xf bank_mask:0xc
	v_mov_b32_dpp v7, v3 row_ror:8 row_mask:0xf bank_mask:0xc
	v_mov_b32_dpp v8, v4 row_ror:8 row_mask:0xf bank_mask:0xc
	v_mov_b32_dpp v9, v5 row_ror:8 row_mask:0xf bank_mask:0xc
	v_mov_b32_dpp v2, v13 row_ror:8 row_mask:0xf bank_mask:0x3
	v_mov_b32_dpp v3, v14 row_ror:8 row_mask:0xf bank_mask:0x3
	v_mov_b32_dpp v4, v20 row_ror:8 row_mask:0xf bank_mask:0x3
	v_mov_b32_dpp v5, v21 row_ror:8 row_mask:0xf bank_mask:0x3
	global_store_dwordx4 v[16:17], v[6:9], off offset:512
	global_store_dwordx4 v[18:19], v[2:5], off offset:512
	s_nop 1
	v_mov_b32_dpp v2, v6 row_ror:8 row_mask:0xf bank_mask:0x3
	v_mov_b32_dpp v3, v7 row_ror:8 row_mask:0xf bank_mask:0x3
	v_mov_b32_dpp v4, v8 row_ror:8 row_mask:0xf bank_mask:0x3
	v_mov_b32_dpp v5, v9 row_ror:8 row_mask:0xf bank_mask:0x3
	v_mov_b32_e32 v6, v13
	v_mov_b32_e32 v7, v14
	v_mov_b32_e32 v8, v20
	v_mov_b32_e32 v9, v21
	s_nop 1
	v_permlane32_swap_b32_e32 v6, v2
	v_permlane32_swap_b32_e32 v7, v3
	v_permlane32_swap_b32_e32 v8, v4
	v_permlane32_swap_b32_e32 v9, v5
	v_permlane16_swap_b32_e32 v6, v2
	v_permlane16_swap_b32_e32 v7, v3
	v_permlane16_swap_b32_e32 v8, v4
	v_permlane16_swap_b32_e32 v9, v5
	v_add_f32_e32 v11, v11, v12
	v_cvt_pk_bf16_f32 v6, v6, v7
	v_cvt_pk_bf16_f32 v7, v8, v9
	v_cvt_pk_bf16_f32 v8, v2, v3
	v_lshl_add_u64 v[2:3], v[78:79], 0, v[0:1]
	v_mov_b32_e32 v0, v10
	v_add_f32_e32 v11, v15, v11
	v_cvt_pk_bf16_f32 v9, v4, v5
	v_permlane16_swap_b32_e32 v10, v0
	global_store_dwordx4 v[2:3], v[6:9], off
	v_add_f32_e32 v2, v10, v0
	v_mov_b32_e32 v0, v11
	s_nop 1
	v_permlane16_swap_b32_e32 v11, v0
	v_add_f32_e32 v3, v11, v0
	v_mov_b32_e32 v4, v2
	v_mov_b32_e32 v5, v3
	s_nop 0
	v_permlane32_swap_b32_e32 v2, v4
	v_permlane32_swap_b32_e32 v3, v5
	s_and_saveexec_b64 s[26:27], s[44:45]
	s_cbranch_execz .LBB0_388
	v_pk_add_f32 v[2:3], v[2:3], v[4:5]
	v_lshlrev_b64 v[4:5], 7, v[74:75]
	v_lshl_add_u64 v[4:5], s[30:31], 0, v[4:5]
	v_lshl_add_u64 v[4:5], s[24:25], 2, v[4:5]
	global_store_dwordx2 v[4:5], v[2:3], off

; __device__ __forceinline__ float xsum16(float v) { const auto r = __builtin_amdgcn_permlane16_swap(__float_as_uint(v), __float_as_uint(v), false, false); return __uint_as_float(r[0]) + __uint_as_float(r[1]); }
; __device__ __forceinline__ float xsum32(float v) { const auto r = __builtin_amdgcn_permlane32_swap(__float_as_uint(v), __float_as_uint(v), false, false); return __uint_as_float(r[0]) + __uint_as_float(r[1]); }
; __device__ __forceinline__ void row_stats4(const float* st, int rowb, int fq, float (&mu)[4], float (&rs)[4]) {
;     f32x4 a[4], b[4];
; #pragma unroll
;     for (int m = 0; m < 4; ++m) { const f32x4* p = (const f32x4*)(st + (size_t)(rowb + m * 16) * 32 + fq * 8); a[m] = p[0]; b[m] = p[1]; }
; #pragma unroll
;     for (int m = 0; m < 4; ++m) { float s1 = (a[m][0] + a[m][2]) + (b[m][0] + b[m][2]), s2 = (a[m][1] + a[m][3]) + (b[m][1] + b[m][3]);
;         s1 = xsum32(xsum16(s1)); s2 = xsum32(xsum16(s2));
;         const float mm = s1 * (1.0f / 1024.0f); mu[m] = mm; rs[m] = rsqrtf(fmaxf(s2 * (1.0f / 1024.0f) - mm * mm, 0.f) + LN_EPS_); }
;     __device__ __forceinline__ void operator()(const f32x4 (&acc)[2][2][4][2], const pg8::Unit& u, int wr, int wc, int fr, int fq) const {
;         const int row0 = u.pm * 256 + wr * 64 + fr, col0 = u.pn * 256 + wc * 32 + fq * 8;
; #pragma unroll
;         for (int ai = 0; ai < 2; ++ai) { float mu4[4], rs4[4]; row_stats4(stp, row0 + ai * 128, fq, mu4, rs4);
; #pragma unroll
;             for (int m = 0; m < 4; ++m) { const int row = row0 + ai * 128 + m * 16; const float mu = mu4[m], rs = rs4[m];
;                 f32x4 yv[2][2], gq[2][2], bq_[2][2];
; #pragma unroll
;                 for (int bj = 0; bj < 2; ++bj)
; #pragma unroll
;                     for (int n = 0; n < 2; ++n) { yv[bj][n] = *(const f32x4*)(Yin + (size_t)row * D_ + col0 + bj * 128 + 4 * n); gq[bj][n] = *(const f32x4*)(g + col0 + bj * 128 + 4 * n); bq_[bj][n] = *(const f32x4*)(b + col0 + bj * 128 + 4 * n); }
.LBB0_1535:
	s_lshl_b32 s3, s3, 8
	s_add_i32 s3, s3, s0
	v_or_b32_e32 v158, s3, v184
	v_ashrrev_i32_e32 v159, 31, v158
	v_lshlrev_b64 v[130:131], 7, v[158:159]
	v_lshl_add_u64 v[136:137], v[146:147], 0, v[130:131]
	v_or_b32_e32 v180, 16, v158
	global_load_dwordx4 v[132:135], v[136:137], off
	global_load_dwordx4 v[166:169], v[136:137], off offset:16
	v_ashrrev_i32_e32 v181, 31, v180
	v_lshlrev_b64 v[172:173], 7, v[180:181]
	v_lshl_add_u64 v[136:137], v[146:147], 0, v[172:173]
	global_load_dwordx4 v[174:177], v[136:137], off
	global_load_dwordx4 v[186:189], v[136:137], off offset:16
	v_or_b32_e32 v170, 32, v158
	v_ashrrev_i32_e32 v171, 31, v170
	v_lshlrev_b64 v[164:165], 7, v[170:171]
	v_lshl_add_u64 v[136:137], v[146:147], 0, v[164:165]
	global_load_dwordx4 v[190:193], v[136:137], off
	global_load_dwordx4 v[198:201], v[136:137], off offset:16
	v_or_b32_e32 v162, 48, v158
	v_ashrrev_i32_e32 v163, 31, v162
	v_lshlrev_b64 v[160:161], 7, v[162:163]
	v_lshl_add_u64 v[182:183], v[146:147], 0, v[160:161]
	global_load_dwordx4 v[202:205], v[182:183], off
	global_load_dwordx4 v[206:209], v[182:183], off offset:16
	s_load_dwordx16 s[64:79], s[34:35], 0x38
	s_lshl_b32 s1, s2, 8
	s_lshl_b32 s14, s2, 3
	s_or_b32 s2, s1, s57
	v_or_b32_e32 v152, s2, v185
	v_ashrrev_i32_e32 v153, 31, v152
	v_lshlrev_b64 v[136:137], 12, v[158:159]
	v_lshlrev_b64 v[178:179], 2, v[152:153]
	s_waitcnt lgkmcnt(0)
	v_lshl_add_u64 v[136:137], s[78:79], 0, v[136:137]
	v_lshl_add_u64 v[156:157], s[8:9], 0, v[178:179]
	v_lshl_add_u64 v[154:155], s[10:11], 0, v[178:179]
	v_lshl_add_u64 v[136:137], v[136:137], 0, v[178:179]
	s_or_b32 s52, s14, s61
	s_mov_b32 s14, 0x3a800000
	global_load_dwordx4 v[210:213], v[136:137], off offset:16
	global_load_dwordx4 v[214:217], v[136:137], off
	global_load_dwordx4 v[218:221], v[156:157], off offset:16
	global_load_dwordx4 v[222:225], v[156:157], off
	global_load_dwordx4 v[234:237], v[154:155], off offset:16
	global_load_dwordx4 v[238:241], v[154:155], off
	s_mov_b32 s1, 0x800000
	s_mov_b32 s18, 0x3fd744fd
	v_bitop3_b32 v196, s2, 56, v185 bitop3:0xc8
	s_ashr_i32 s2, s2, 6
	s_ashr_i32 s53, s52, 31
	v_readlane_b32 s16, v253, 59
	v_readlane_b32 s17, v253, 60
	s_waitcnt vmcnt(0)
	v_mov_b32_e32 v178, v132
	v_mov_b32_e32 v179, v166
	v_mov_b32_e32 v182, v134
	v_mov_b32_e32 v183, v168
	v_mov_b32_e32 v166, v133
	v_mov_b32_e32 v168, v135
	v_pk_add_f32 v[132:133], v[178:179], v[182:183]
	v_pk_add_f32 v[134:135], v[166:167], v[168:169]
	v_pk_add_f32 v[132:133], v[132:133], v[132:133] op_sel:[0,1] op_sel_hi:[1,0]
	v_pk_add_f32 v[134:135], v[134:135], v[134:135] op_sel:[0,1] op_sel_hi:[1,0]
	v_mov_b32_e32 v166, v174
	v_mov_b32_e32 v167, v186
	v_mov_b32_e32 v168, v176
	v_mov_b32_e32 v169, v188
	v_mov_b32_e32 v0, v132
	v_mov_b32_e32 v133, v134
	v_pk_add_f32 v[166:167], v[166:167], v[168:169]
	v_permlane16_swap_b32_e32 v132, v0
	v_permlane16_swap_b32_e32 v134, v133
	v_mov_b32_e32 v188, v177
	v_pk_add_f32 v[166:167], v[166:167], v[166:167] op_sel:[0,1] op_sel_hi:[1,0]
	v_add_f32_e32 v177, v132, v0
	v_add_f32_e32 v176, v134, v133
	v_mov_b32_e32 v135, v166
	v_mov_b32_e32 v179, v177
	v_mov_b32_e32 v178, v176
	v_permlane16_swap_b32_e32 v166, v135
	v_permlane32_swap_b32_e32 v177, v179
	v_permlane32_swap_b32_e32 v176, v178
	v_mov_b32_e32 v186, v175
	v_add_f32_e32 v133, v166, v135
	v_pk_add_f32 v[166:167], v[176:177], v[178:179]
	v_pk_add_f32 v[168:169], v[186:187], v[188:189]
	v_pk_mul_f32 v[178:179], v[166:167], s[14:15] op_sel_hi:[1,0]
	v_pk_add_f32 v[168:169], v[168:169], v[168:169] op_sel:[0,1] op_sel_hi:[1,0]
	v_fma_f32 v0, -v179, v179, v178
	v_mov_b32_e32 v159, v168
	v_max_f32_e32 v0, 0, v0
	s_nop 0
	v_permlane16_swap_b32_e32 v168, v159
	v_add_f32_e32 v0, 0x3727c5ac, v0
	v_add_f32_e32 v132, v168, v159
	v_mul_f32_e32 v159, 0x4b800000, v0
	v_cmp_gt_f32_e32 vcc, s1, v0
	v_mov_b32_e32 v174, v190
	v_mov_b32_e32 v175, v198
	v_cndmask_b32_e32 v0, v0, v159, vcc
	v_rsq_f32_e32 v0, v0
	v_mov_b32_e32 v166, v192
	v_mov_b32_e32 v167, v200
	v_pk_add_f32 v[166:167], v[174:175], v[166:167]
	v_mul_f32_e32 v159, 0x45800000, v0
	v_pk_add_f32 v[166:167], v[166:167], v[166:167] op_sel:[0,1] op_sel_hi:[1,0]
	v_mov_b32_e32 v198, v191
	v_mov_b32_e32 v200, v193
	v_cndmask_b32_e32 v0, v0, v159, vcc
	v_pk_add_f32 v[168:169], v[198:199], v[200:201]
	v_mov_b32_e32 v159, v166
	v_pk_add_f32 v[168:169], v[168:169], v[168:169] op_sel:[0,1] op_sel_hi:[1,0]
	s_nop 0
	v_permlane16_swap_b32_e32 v166, v159
	v_add_f32_e32 v175, v166, v159
	v_mov_b32_e32 v159, v168
	s_nop 1
	v_permlane16_swap_b32_e32 v168, v159
	global_load_dwordx4 v[186:189], v[136:137], off offset:528
	global_load_dwordx4 v[190:193], v[136:137], off offset:512
	v_add_f32_e32 v174, v168, v159
	v_mov_b32_e32 v166, v202
	v_mov_b32_e32 v167, v206
	v_mov_b32_e32 v168, v204
	v_mov_b32_e32 v169, v208
	v_mov_b32_e32 v206, v203
	v_mov_b32_e32 v208, v205
	v_pk_add_f32 v[166:167], v[166:167], v[168:169]
	v_pk_add_f32 v[168:169], v[206:207], v[208:209]
	global_load_dwordx4 v[198:201], v[156:157], off offset:528
	global_load_dwordx4 v[202:205], v[156:157], off offset:512
	global_load_dwordx4 v[206:209], v[154:155], off offset:528
	global_load_dwordx4 v[242:245], v[154:155], off offset:512
	v_sub_f32_e32 v183, v215, v179
	v_sub_f32_e32 v182, v214, v179
	v_sub_f32_e32 v215, v217, v179
	v_sub_f32_e32 v214, v216, v179
	v_pk_mul_f32 v[214:215], v[0:1], v[214:215] op_sel_hi:[0,1]
	v_pk_mul_f32 v[182:183], v[0:1], v[182:183] op_sel_hi:[0,1]
	v_pk_fma_f32 v[182:183], v[222:223], v[182:183], v[238:239]
	v_pk_fma_f32 v[214:215], v[224:225], v[214:215], v[240:241]
	v_pk_fma_f32 v[126:127], v[182:183], s[18:19], v[126:127] op_sel_hi:[1,0,1]
; __device__ __forceinline__ size_t blk_off(int r, int c, int K) { return (size_t)(r >> 8) * 256 * K + (size_t)(c >> 6) * (256 * 64) + (size_t)((r & 255) * 64 + (c & 63)); }
; __device__ __forceinline__ u32x4 pack8(const f32x4 a, const f32x4 b) { u32x4 w; w.x = cvt_pk_bf16(a[0], a[1]); w.y = cvt_pk_bf16(a[2], a[3]); w.z = cvt_pk_bf16(b[0], b[1]); w.w = cvt_pk_bf16(b[2], b[3]); return w; }
;     __device__ __forceinline__ void operator()(const f32x4 (&acc)[2][2][4][2], const pg8::Unit& u, int wr, int wc, int fr, int fq) const {
;     ...
;                 for (int bj = 0; bj < 2; ++bj) { float* yp = Y + (size_t)row * D_ + col0 + bj * 128; f32x4 v[2];
; #pragma unroll
;                     for (int n = 0; n < 2; ++n) { v[n] = (((yv[bj][n] - mu) * rs) * gq[bj][n] + bq_[bj][n]) * ALPHA_ + acc[ai][bj][m][n] * sc;
;                         *(f32x4*)(yp + 4 * n) = v[n]; s1 += (v[n][0] + v[n][1]) + (v[n][2] + v[n][3]); s2 += (v[n][0] * v[n][0] + v[n][1] * v[n][1]) + (v[n][2] * v[n][2] + v[n][3] * v[n][3]); }
;                     *(u32x4*)(Yb + blk_off(row, col0 + bj * 128, D_)) = pack8(v[0], v[1]); }
	v_pk_fma_f32 v[128:129], v[214:215], s[18:19], v[128:129] op_sel_hi:[1,0,1]
	v_add_f32_e32 v178, v126, v127
	v_add_f32_e32 v182, v128, v129
	v_add_f32_e32 v178, v178, v182
	v_mul_f32_e32 v182, v127, v127
	v_mul_f32_e32 v183, v129, v129
	v_fmac_f32_e32 v182, v126, v126
	v_fmac_f32_e32 v183, v128, v128
	v_add_f32_e32 v197, v182, v183
	v_sub_f32_e32 v183, v211, v179
	v_sub_f32_e32 v182, v210, v179
	v_sub_f32_e32 v211, v213, v179
	v_sub_f32_e32 v210, v212, v179
	v_pk_mul_f32 v[210:211], v[0:1], v[210:211] op_sel_hi:[0,1]
	v_pk_mul_f32 v[182:183], v[0:1], v[182:183] op_sel_hi:[0,1]
	v_pk_fma_f32 v[182:183], v[218:219], v[182:183], v[234:235]
	v_pk_fma_f32 v[210:211], v[220:221], v[210:211], v[236:237]
	v_pk_add_f32 v[166:167], v[166:167], v[166:167] op_sel:[0,1] op_sel_hi:[1,0]
	v_pk_fma_f32 v[124:125], v[210:211], s[18:19], v[124:125] op_sel_hi:[1,0,1]
	v_pk_fma_f32 v[122:123], v[182:183], s[18:19], v[122:123] op_sel_hi:[1,0,1]
	v_mov_b32_e32 v159, v166
	v_add_f32_e32 v182, v122, v123
	v_add_f32_e32 v183, v124, v125
	v_pk_add_f32 v[168:169], v[168:169], v[168:169] op_sel:[0,1] op_sel_hi:[1,0]
	v_permlane16_swap_b32_e32 v166, v159
	v_add_f32_e32 v178, 0, v178
	v_add_f32_e32 v182, v182, v183
	v_add_f32_e32 v167, v166, v159
	v_mov_b32_e32 v159, v168
	s_ashr_i32 s14, s3, 8
	v_add_f32_e32 v178, v178, v182
	v_mul_f32_e32 v182, v123, v123
	v_mul_f32_e32 v183, v125, v125
	v_permlane16_swap_b32_e32 v168, v159
	s_ashr_i32 s15, s14, 31
	s_nop 0
	s_nop 1
	v_bfe_u32 v135, v227, 4, 2
	v_sub_u32_e32 v134, 0, v135
	v_lshlrev_b32_e32 v134, 4, v134
	v_ashrrev_i32_e32 v135, 31, v134
	v_lshl_add_u64 v[134:135], v[136:137], 0, v[134:135]
	v_permlane16_swap_b32_e32 v126, v122
	v_permlane16_swap_b32_e32 v127, v123
	v_permlane16_swap_b32_e32 v128, v124
	v_permlane16_swap_b32_e32 v129, v125
	v_permlane32_swap_b32_e32 v126, v122
	v_permlane32_swap_b32_e32 v127, v123
	v_permlane32_swap_b32_e32 v128, v124
	v_permlane32_swap_b32_e32 v129, v125
	v_mov_b32_e32 v166, v126
	v_mov_b32_e32 v169, v127
	v_mov_b32_e32 v210, v128
	v_mov_b32_e32 v211, v129
	v_bfe_u32 v176, v227, 3, 1
	v_mul_i32_i24_e32 v176, 0xffff8040, v176
	v_ashrrev_i32_e32 v177, 31, v176
	v_lshl_add_u64 v[134:135], v[134:135], 0, v[176:177]
	v_mov_b32_e32 v176, 0x8000
	v_mov_b32_e32 v177, 0
	v_lshl_add_u64 v[176:177], v[134:135], 0, v[176:177]
	v_mov_b32_dpp v126, v122 row_ror:8 row_mask:0xf bank_mask:0xc
	v_mov_b32_dpp v127, v123 row_ror:8 row_mask:0xf bank_mask:0xc
	v_mov_b32_dpp v128, v124 row_ror:8 row_mask:0xf bank_mask:0xc
	v_mov_b32_dpp v129, v125 row_ror:8 row_mask:0xf bank_mask:0xc
	v_mov_b32_dpp v122, v166 row_ror:8 row_mask:0xf bank_mask:0x3
	v_mov_b32_dpp v123, v169 row_ror:8 row_mask:0xf bank_mask:0x3
	v_mov_b32_dpp v124, v210 row_ror:8 row_mask:0xf bank_mask:0x3
	v_mov_b32_dpp v125, v211 row_ror:8 row_mask:0xf bank_mask:0x3
	global_store_dwordx4 v[134:135], v[126:129], off
	global_store_dwordx4 v[176:177], v[122:125], off
	s_nop 1
	v_mov_b32_dpp v122, v126 row_ror:8 row_mask:0xf bank_mask:0x3
	v_mov_b32_dpp v123, v127 row_ror:8 row_mask:0xf bank_mask:0x3
	v_mov_b32_dpp v124, v128 row_ror:8 row_mask:0xf bank_mask:0x3
	v_mov_b32_dpp v125, v129 row_ror:8 row_mask:0xf bank_mask:0x3
	v_mov_b32_e32 v126, v166
	v_mov_b32_e32 v127, v169
	v_mov_b32_e32 v128, v210
	v_mov_b32_e32 v129, v211
	s_nop 1
	v_permlane32_swap_b32_e32 v126, v122
	v_permlane32_swap_b32_e32 v127, v123
	v_permlane32_swap_b32_e32 v128, v124
	v_permlane32_swap_b32_e32 v129, v125
	v_permlane16_swap_b32_e32 v126, v122
	v_permlane16_swap_b32_e32 v127, v123
	v_permlane16_swap_b32_e32 v128, v124
	v_permlane16_swap_b32_e32 v129, v125
	v_fmac_f32_e32 v182, v122, v122
	v_fmac_f32_e32 v183, v124, v124
	v_cvt_pk_bf16_f32 v126, v126, v127
	v_cvt_pk_bf16_f32 v127, v128, v129
	v_cvt_pk_bf16_f32 v128, v122, v123
	v_cvt_pk_bf16_f32 v129, v124, v125
	v_add_f32_e32 v166, v168, v159
	s_lshl_b64 s[14:15], s[14:15], 19
	v_lshlrev_b32_e32 v159, 6, v158
	s_movk_i32 s1, 0x33c0
	s_ashr_i32 s3, s2, 31
	v_and_or_b32 v159, v159, s1, v196
	s_add_u32 s1, s16, s14
	s_addc_u32 s14, s17, s15
	s_lshl_b64 s[24:25], s[2:3], 15
	s_add_u32 s42, s1, s24
	s_addc_u32 s43, s14, s25
	v_lshlrev_b32_e32 v159, 1, v159
	global_store_dwordx4 v159, v[126:129], s[42:43]
	v_add_f32_e32 v182, v182, v183
	s_waitcnt vmcnt(7)
	v_sub_f32_e32 v123, v191, v179
	v_sub_f32_e32 v122, v190, v179
	v_sub_f32_e32 v125, v193, v179
	v_sub_f32_e32 v124, v192, v179
	v_pk_mul_f32 v[124:125], v[0:1], v[124:125] op_sel_hi:[0,1]
	v_pk_mul_f32 v[122:123], v[0:1], v[122:123] op_sel_hi:[0,1]
	v_add_f32_e32 v182, v197, v182
	s_or_b32 s2, s2, 2
	s_ashr_i32 s3, s2, 31
	s_lshl_b64 s[28:29], s[2:3], 15
	s_waitcnt vmcnt(3)
; __device__ __forceinline__ float xsum16(float v) { const auto r = __builtin_amdgcn_permlane16_swap(__float_as_uint(v), __float_as_uint(v), false, false); return __uint_as_float(r[0]) + __uint_as_float(r[1]); }
; __device__ __forceinline__ float xsum32(float v) { const auto r = __builtin_amdgcn_permlane32_swap(__float_as_uint(v), __float_as_uint(v), false, false); return __uint_as_float(r[0]) + __uint_as_float(r[1]); }
; __device__ __forceinline__ size_t blk_off(int r, int c, int K) { return (size_t)(r >> 8) * 256 * K + (size_t)(c >> 6) * (256 * 64) + (size_t)((r & 255) * 64 + (c & 63)); }
; __device__ __forceinline__ u32x4 pack8(const f32x4 a, const f32x4 b) { u32x4 w; w.x = cvt_pk_bf16(a[0], a[1]); w.y = cvt_pk_bf16(a[2], a[3]); w.z = cvt_pk_bf16(b[0], b[1]); w.w = cvt_pk_bf16(b[2], b[3]); return w; }
;     __device__ __forceinline__ void operator()(const f32x4 (&acc)[2][2][4][2], const pg8::Unit& u, int wr, int wc, int fr, int fq) const {
;     ...
;                 for (int bj = 0; bj < 2; ++bj) { float* yp = Y + (size_t)row * D_ + col0 + bj * 128; f32x4 v[2];
; #pragma unroll
;                     for (int n = 0; n < 2; ++n) { v[n] = (((yv[bj][n] - mu) * rs) * gq[bj][n] + bq_[bj][n]) * ALPHA_ + acc[ai][bj][m][n] * sc;
;                         *(f32x4*)(yp + 4 * n) = v[n]; s1 += (v[n][0] + v[n][1]) + (v[n][2] + v[n][3]); s2 += (v[n][0] * v[n][0] + v[n][1] * v[n][1]) + (v[n][2] * v[n][2] + v[n][3] * v[n][3]); }
;                     *(u32x4*)(Yb + blk_off(row, col0 + bj * 128, D_)) = pack8(v[0], v[1]); }
;                 s1 = xsum32(xsum16(s1)); s2 = xsum32(xsum16(s2));
;                 if (fq == 0) *(f32x2*)(stn + (size_t)row * 32 + (u.pn * 4 + wc) * 2) = (f32x2){s1, s2}; asm volatile("" ::: "memory"); } }
	v_pk_fma_f32 v[122:123], v[202:203], v[122:123], v[242:243]
	v_pk_fma_f32 v[124:125], v[204:205], v[124:125], v[244:245]
	v_pk_fma_f32 v[118:119], v[122:123], s[18:19], v[118:119] op_sel_hi:[1,0,1]
	v_pk_fma_f32 v[120:121], v[124:125], s[18:19], v[120:121] op_sel_hi:[1,0,1]
	v_add_f32_e32 v122, v118, v119
	v_add_f32_e32 v123, v120, v121
	v_add_f32_e32 v122, v122, v123
	v_add_f32_e32 v126, v178, v122
	v_mul_f32_e32 v122, v119, v119
	v_mul_f32_e32 v123, v121, v121
	v_fmac_f32_e32 v122, v118, v118
	v_fmac_f32_e32 v123, v120, v120
	v_add_f32_e32 v122, v122, v123
	v_add_f32_e32 v127, v182, v122
	v_sub_f32_e32 v123, v187, v179
	v_sub_f32_e32 v122, v186, v179
	v_sub_f32_e32 v125, v189, v179
	v_sub_f32_e32 v124, v188, v179
	v_pk_mul_f32 v[124:125], v[0:1], v[124:125] op_sel_hi:[0,1]
	v_pk_mul_f32 v[122:123], v[0:1], v[122:123] op_sel_hi:[0,1]
	v_pk_fma_f32 v[122:123], v[198:199], v[122:123], v[206:207]
	v_pk_fma_f32 v[124:125], v[200:201], v[124:125], v[208:209]
	v_pk_fma_f32 v[114:115], v[122:123], s[18:19], v[114:115] op_sel_hi:[1,0,1]
	v_pk_fma_f32 v[116:117], v[124:125], s[18:19], v[116:117] op_sel_hi:[1,0,1]
	v_add_f32_e32 v0, v114, v115
	v_add_f32_e32 v122, v116, v117
	v_add_f32_e32 v0, v0, v122
	v_mul_f32_e32 v122, v115, v115
	v_mul_f32_e32 v123, v117, v117
	v_add_f32_e32 v0, v126, v0
	v_fmac_f32_e32 v122, v114, v114
	v_fmac_f32_e32 v123, v116, v116
	s_nop 0
	s_nop 1
	v_bfe_u32 v125, v227, 4, 2
	v_sub_u32_e32 v124, 0, v125
	v_lshlrev_b32_e32 v124, 4, v124
	v_ashrrev_i32_e32 v125, 31, v124
	v_lshl_add_u64 v[124:125], v[136:137], 0, v[124:125]
	v_permlane16_swap_b32_e32 v118, v114
	v_permlane16_swap_b32_e32 v119, v115
	v_permlane16_swap_b32_e32 v120, v116
	v_permlane16_swap_b32_e32 v121, v117
	v_permlane32_swap_b32_e32 v118, v114
	v_permlane32_swap_b32_e32 v119, v115
	v_permlane32_swap_b32_e32 v120, v116
	v_permlane32_swap_b32_e32 v121, v117
	v_mov_b32_e32 v134, v118
	v_mov_b32_e32 v135, v119
	v_mov_b32_e32 v168, v120
	v_mov_b32_e32 v169, v121
	v_bfe_u32 v128, v227, 3, 1
	v_mul_i32_i24_e32 v128, 0xffff8040, v128
	v_ashrrev_i32_e32 v129, 31, v128
	v_lshl_add_u64 v[124:125], v[124:125], 0, v[128:129]
	v_mov_b32_e32 v128, 0x8000
	v_mov_b32_e32 v129, 0
	v_lshl_add_u64 v[128:129], v[124:125], 0, v[128:129]
	v_mov_b32_dpp v118, v114 row_ror:8 row_mask:0xf bank_mask:0xc
	v_mov_b32_dpp v119, v115 row_ror:8 row_mask:0xf bank_mask:0xc
	v_mov_b32_dpp v120, v116 row_ror:8 row_mask:0xf bank_mask:0xc
	v_mov_b32_dpp v121, v117 row_ror:8 row_mask:0xf bank_mask:0xc
	v_mov_b32_dpp v114, v134 row_ror:8 row_mask:0xf bank_mask:0x3
	v_mov_b32_dpp v115, v135 row_ror:8 row_mask:0xf bank_mask:0x3
	v_mov_b32_dpp v116, v168 row_ror:8 row_mask:0xf bank_mask:0x3
	v_mov_b32_dpp v117, v169 row_ror:8 row_mask:0xf bank_mask:0x3
	global_store_dwordx4 v[124:125], v[118:121], off offset:512
	global_store_dwordx4 v[128:129], v[114:117], off offset:512
	s_nop 1
	v_mov_b32_dpp v114, v118 row_ror:8 row_mask:0xf bank_mask:0x3
	v_mov_b32_dpp v115, v119 row_ror:8 row_mask:0xf bank_mask:0x3
	v_mov_b32_dpp v116, v120 row_ror:8 row_mask:0xf bank_mask:0x3
	v_mov_b32_dpp v117, v121 row_ror:8 row_mask:0xf bank_mask:0x3
	v_mov_b32_e32 v118, v134
	v_mov_b32_e32 v119, v135
	v_mov_b32_e32 v120, v168
	v_mov_b32_e32 v121, v169
	s_nop 1
	v_permlane32_swap_b32_e32 v118, v114
	v_permlane32_swap_b32_e32 v119, v115
	v_permlane32_swap_b32_e32 v120, v116
	v_permlane32_swap_b32_e32 v121, v117
	v_permlane16_swap_b32_e32 v118, v114
	v_permlane16_swap_b32_e32 v119, v115
	v_permlane16_swap_b32_e32 v120, v116
	v_permlane16_swap_b32_e32 v121, v117
	v_add_f32_e32 v122, v122, v123
	v_cvt_pk_bf16_f32 v118, v118, v119
	v_cvt_pk_bf16_f32 v119, v120, v121
	v_cvt_pk_bf16_f32 v120, v114, v115
	v_mov_b32_e32 v114, v0
	v_add_f32_e32 v122, v127, v122
	s_nop 0
	v_permlane16_swap_b32_e32 v0, v114
	v_add_f32_e32 v114, v0, v114
	v_mov_b32_e32 v0, v122
	s_nop 1
	v_permlane16_swap_b32_e32 v122, v0
	v_add_f32_e32 v115, v122, v0
	v_mov_b32_e32 v135, v133
	v_mov_b32_e32 v134, v132
	v_mov_b32_e32 v177, v175
	v_mov_b32_e32 v176, v174
	v_mov_b32_e32 v169, v167
	v_mov_b32_e32 v168, v166
	v_cvt_pk_bf16_f32 v121, v116, v117
	s_add_u32 s40, s1, s28
	v_mov_b32_e32 v116, v114
	v_mov_b32_e32 v117, v115
	v_permlane32_swap_b32_e32 v133, v135
	v_permlane32_swap_b32_e32 v132, v134
	v_permlane32_swap_b32_e32 v175, v177
	v_permlane32_swap_b32_e32 v174, v176
	v_permlane32_swap_b32_e32 v167, v169
	v_permlane32_swap_b32_e32 v166, v168
	s_addc_u32 s41, s14, s29
	v_permlane32_swap_b32_e32 v114, v116
	v_permlane32_swap_b32_e32 v115, v117
	global_store_dwordx4 v159, v[118:121], s[40:41]
	s_and_saveexec_b64 s[26:27], s[44:45]
	s_cbranch_execz .LBB0_1537
	v_pk_add_f32 v[114:115], v[114:115], v[116:117]
	v_lshl_add_u64 v[116:117], s[6:7], 0, v[130:131]
	v_lshl_add_u64 v[116:117], s[52:53], 2, v[116:117]
	global_store_dwordx2 v[116:117], v[114:115], off
; __device__ __forceinline__ size_t blk_off(int r, int c, int K) { return (size_t)(r >> 8) * 256 * K + (size_t)(c >> 6) * (256 * 64) + (size_t)((r & 255) * 64 + (c & 63)); }
; __device__ __forceinline__ u32x4 pack8(const f32x4 a, const f32x4 b) { u32x4 w; w.x = cvt_pk_bf16(a[0], a[1]); w.y = cvt_pk_bf16(a[2], a[3]); w.z = cvt_pk_bf16(b[0], b[1]); w.w = cvt_pk_bf16(b[2], b[3]); return w; }
;     __device__ __forceinline__ void operator()(const f32x4 (&acc)[2][2][4][2], const pg8::Unit& u, int wr, int wc, int fr, int fq) const {
;     ...
;             for (int m = 0; m < 4; ++m) { const int row = row0 + ai * 128 + m * 16; const float mu = mu4[m], rs = rs4[m];
;                 f32x4 yv[2][2], gq[2][2], bq_[2][2];
; #pragma unroll
;                 for (int bj = 0; bj < 2; ++bj)
; #pragma unroll
;                     for (int n = 0; n < 2; ++n) { yv[bj][n] = *(const f32x4*)(Yin + (size_t)row * D_ + col0 + bj * 128 + 4 * n); gq[bj][n] = *(const f32x4*)(g + col0 + bj * 128 + 4 * n); bq_[bj][n] = *(const f32x4*)(b + col0 + bj * 128 + 4 * n); }
;                 asm volatile("" ::: "memory");
;                 float s1 = 0.f, s2 = 0.f;
; #pragma unroll
;                 for (int bj = 0; bj < 2; ++bj) { float* yp = Y + (size_t)row * D_ + col0 + bj * 128; f32x4 v[2];
; #pragma unroll
;                     for (int n = 0; n < 2; ++n) { v[n] = (((yv[bj][n] - mu) * rs) * gq[bj][n] + bq_[bj][n]) * ALPHA_ + acc[ai][bj][m][n] * sc;
;                         *(f32x4*)(yp + 4 * n) = v[n]; s1 += (v[n][0] + v[n][1]) + (v[n][2] + v[n][3]); s2 += (v[n][0] * v[n][0] + v[n][1] * v[n][1]) + (v[n][2] * v[n][2] + v[n][3] * v[n][3]); }
;                     *(u32x4*)(Yb + blk_off(row, col0 + bj * 128, D_)) = pack8(v[0], v[1]); }
.LBB0_1537:
	s_or_b64 exec, exec, s[26:27]
	v_pk_add_f32 v[114:115], v[132:133], v[134:135]
	s_mov_b32 s2, 0x3a800000
	v_pk_mul_f32 v[178:179], v[114:115], s[2:3] op_sel_hi:[1,0]
	s_mov_b32 s1, 0x800000
	v_fma_f32 v0, -v179, v179, v178
	v_max_f32_e32 v0, 0, v0
	v_add_f32_e32 v0, 0x3727c5ac, v0
	v_cmp_gt_f32_e32 vcc, s1, v0
	v_mul_f32_e32 v114, 0x4b800000, v0
	s_load_dwordx16 s[64:79], s[34:35], 0x38
	v_cndmask_b32_e32 v0, v0, v114, vcc
	v_rsq_f32_e32 v0, v0
	v_lshlrev_b32_e32 v159, 6, v180
	s_mov_b32 s2, 0x3fd744fd
	v_mul_f32_e32 v114, 0x45800000, v0
	v_cndmask_b32_e32 v0, v0, v114, vcc
	v_lshlrev_b64 v[114:115], 12, v[180:181]
	s_waitcnt lgkmcnt(0)
	v_lshl_add_u64 v[114:115], s[78:79], 0, v[114:115]
	v_lshl_add_u64 v[182:183], v[152:153], 2, v[114:115]
	global_load_dwordx4 v[186:189], v[182:183], off offset:16
	global_load_dwordx4 v[190:193], v[182:183], off
	global_load_dwordx4 v[198:201], v[156:157], off offset:16
	global_load_dwordx4 v[202:205], v[156:157], off
	global_load_dwordx4 v[206:209], v[154:155], off offset:16
	global_load_dwordx4 v[210:213], v[154:155], off
	global_load_dwordx4 v[114:117], v[182:183], off offset:528
	global_load_dwordx4 v[134:137], v[182:183], off offset:512
	global_load_dwordx4 v[118:121], v[156:157], off offset:528
	global_load_dwordx4 v[126:129], v[156:157], off offset:512
	global_load_dwordx4 v[122:125], v[154:155], off offset:528
	global_load_dwordx4 v[130:133], v[154:155], off offset:512
	s_movk_i32 s1, 0x37c0
	v_and_or_b32 v159, v159, s1, v196
	v_lshlrev_b32_e32 v159, 1, v159
	s_waitcnt vmcnt(10)
	v_sub_f32_e32 v181, v191, v179
	v_sub_f32_e32 v180, v190, v179
	v_sub_f32_e32 v191, v193, v179
	v_sub_f32_e32 v190, v192, v179
	v_pk_mul_f32 v[190:191], v[0:1], v[190:191] op_sel_hi:[0,1]
	v_pk_mul_f32 v[180:181], v[0:1], v[180:181] op_sel_hi:[0,1]
	s_waitcnt vmcnt(6)
	v_pk_fma_f32 v[180:181], v[202:203], v[180:181], v[210:211]
	v_pk_fma_f32 v[190:191], v[204:205], v[190:191], v[212:213]
	v_pk_fma_f32 v[110:111], v[180:181], s[2:3], v[110:111] op_sel_hi:[1,0,1]
	v_pk_fma_f32 v[112:113], v[190:191], s[2:3], v[112:113] op_sel_hi:[1,0,1]
	v_add_f32_e32 v178, v110, v111
	v_add_f32_e32 v180, v112, v113
	v_add_f32_e32 v178, v178, v180
	v_mul_f32_e32 v180, v111, v111
	v_mul_f32_e32 v181, v113, v113
	v_fmac_f32_e32 v180, v110, v110
	v_fmac_f32_e32 v181, v112, v112
	v_add_f32_e32 v190, v180, v181
	v_sub_f32_e32 v181, v187, v179
	v_sub_f32_e32 v180, v186, v179
	v_sub_f32_e32 v187, v189, v179
	v_sub_f32_e32 v186, v188, v179
	v_pk_mul_f32 v[186:187], v[0:1], v[186:187] op_sel_hi:[0,1]
	v_pk_mul_f32 v[180:181], v[0:1], v[180:181] op_sel_hi:[0,1]
	v_pk_fma_f32 v[180:181], v[198:199], v[180:181], v[206:207]
	v_pk_fma_f32 v[186:187], v[200:201], v[186:187], v[208:209]
	v_pk_fma_f32 v[106:107], v[180:181], s[2:3], v[106:107] op_sel_hi:[1,0,1]
	v_pk_fma_f32 v[108:109], v[186:187], s[2:3], v[108:109] op_sel_hi:[1,0,1]
	v_add_f32_e32 v180, v106, v107
	v_add_f32_e32 v181, v108, v109
	v_add_f32_e32 v178, 0, v178
	v_add_f32_e32 v180, v180, v181
	v_add_f32_e32 v178, v178, v180
	v_mul_f32_e32 v180, v107, v107
	v_mul_f32_e32 v181, v109, v109
	s_nop 0
	s_nop 1
	v_bfe_u32 v187, v227, 4, 2
	v_sub_u32_e32 v186, 0, v187
	v_lshlrev_b32_e32 v186, 4, v186
	v_ashrrev_i32_e32 v187, 31, v186
	v_lshl_add_u64 v[186:187], v[182:183], 0, v[186:187]
	v_permlane16_swap_b32_e32 v110, v106
	v_permlane16_swap_b32_e32 v111, v107
	v_permlane16_swap_b32_e32 v112, v108
	v_permlane16_swap_b32_e32 v113, v109
	v_permlane32_swap_b32_e32 v110, v106
	v_permlane32_swap_b32_e32 v111, v107
	v_permlane32_swap_b32_e32 v112, v108
	v_permlane32_swap_b32_e32 v113, v109
	v_mov_b32_e32 v191, v110
	v_mov_b32_e32 v192, v111
	v_mov_b32_e32 v193, v112
	v_mov_b32_e32 v197, v113
	v_bfe_u32 v188, v227, 3, 1
	v_mul_i32_i24_e32 v188, 0xffff8040, v188
	v_ashrrev_i32_e32 v189, 31, v188
	v_lshl_add_u64 v[186:187], v[186:187], 0, v[188:189]
	v_mov_b32_e32 v188, 0x8000
	v_mov_b32_e32 v189, 0
	v_lshl_add_u64 v[188:189], v[186:187], 0, v[188:189]
	v_mov_b32_dpp v110, v106 row_ror:8 row_mask:0xf bank_mask:0xc
	v_mov_b32_dpp v111, v107 row_ror:8 row_mask:0xf bank_mask:0xc
	v_mov_b32_dpp v112, v108 row_ror:8 row_mask:0xf bank_mask:0xc
	v_mov_b32_dpp v113, v109 row_ror:8 row_mask:0xf bank_mask:0xc
	v_mov_b32_dpp v106, v191 row_ror:8 row_mask:0xf bank_mask:0x3
	v_mov_b32_dpp v107, v192 row_ror:8 row_mask:0xf bank_mask:0x3
	v_mov_b32_dpp v108, v193 row_ror:8 row_mask:0xf bank_mask:0x3
	v_mov_b32_dpp v109, v197 row_ror:8 row_mask:0xf bank_mask:0x3
	global_store_dwordx4 v[186:187], v[110:113], off
	global_store_dwordx4 v[188:189], v[106:109], off
	s_nop 1
	v_mov_b32_dpp v106, v110 row_ror:8 row_mask:0xf bank_mask:0x3
	v_mov_b32_dpp v107, v111 row_ror:8 row_mask:0xf bank_mask:0x3
	v_mov_b32_dpp v108, v112 row_ror:8 row_mask:0xf bank_mask:0x3
	v_mov_b32_dpp v109, v113 row_ror:8 row_mask:0xf bank_mask:0x3
	v_mov_b32_e32 v110, v191
	v_mov_b32_e32 v111, v192
	v_mov_b32_e32 v112, v193
	v_mov_b32_e32 v113, v197
	s_nop 1
	v_permlane32_swap_b32_e32 v110, v106
	v_permlane32_swap_b32_e32 v111, v107
	v_permlane32_swap_b32_e32 v112, v108
	v_permlane32_swap_b32_e32 v113, v109
	v_permlane16_swap_b32_e32 v110, v106
	v_permlane16_swap_b32_e32 v111, v107
	v_permlane16_swap_b32_e32 v112, v108
	v_permlane16_swap_b32_e32 v113, v109
	v_fmac_f32_e32 v180, v106, v106
	v_fmac_f32_e32 v181, v108, v108
	v_cvt_pk_bf16_f32 v110, v110, v111
	v_cvt_pk_bf16_f32 v111, v112, v113
	v_cvt_pk_bf16_f32 v112, v106, v107
	v_cvt_pk_bf16_f32 v113, v108, v109
	s_waitcnt vmcnt(6)
	v_sub_f32_e32 v107, v135, v179
	v_sub_f32_e32 v106, v134, v179
	v_sub_f32_e32 v109, v137, v179
	v_sub_f32_e32 v108, v136, v179
	v_pk_mul_f32 v[108:109], v[0:1], v[108:109] op_sel_hi:[0,1]
	v_pk_mul_f32 v[106:107], v[0:1], v[106:107] op_sel_hi:[0,1]
	s_waitcnt vmcnt(2)
; __device__ __forceinline__ float xsum16(float v) { const auto r = __builtin_amdgcn_permlane16_swap(__float_as_uint(v), __float_as_uint(v), false, false); return __uint_as_float(r[0]) + __uint_as_float(r[1]); }
; __device__ __forceinline__ float xsum32(float v) { const auto r = __builtin_amdgcn_permlane32_swap(__float_as_uint(v), __float_as_uint(v), false, false); return __uint_as_float(r[0]) + __uint_as_float(r[1]); }
; __device__ __forceinline__ size_t blk_off(int r, int c, int K) { return (size_t)(r >> 8) * 256 * K + (size_t)(c >> 6) * (256 * 64) + (size_t)((r & 255) * 64 + (c & 63)); }
; __device__ __forceinline__ u32x4 pack8(const f32x4 a, const f32x4 b) { u32x4 w; w.x = cvt_pk_bf16(a[0], a[1]); w.y = cvt_pk_bf16(a[2], a[3]); w.z = cvt_pk_bf16(b[0], b[1]); w.w = cvt_pk_bf16(b[2], b[3]); return w; }
;     __device__ __forceinline__ void operator()(const f32x4 (&acc)[2][2][4][2], const pg8::Unit& u, int wr, int wc, int fr, int fq) const {
;     ...
;                 for (int bj = 0; bj < 2; ++bj) { float* yp = Y + (size_t)row * D_ + col0 + bj * 128; f32x4 v[2];
; #pragma unroll
;                     for (int n = 0; n < 2; ++n) { v[n] = (((yv[bj][n] - mu) * rs) * gq[bj][n] + bq_[bj][n]) * ALPHA_ + acc[ai][bj][m][n] * sc;
;                         *(f32x4*)(yp + 4 * n) = v[n]; s1 += (v[n][0] + v[n][1]) + (v[n][2] + v[n][3]); s2 += (v[n][0] * v[n][0] + v[n][1] * v[n][1]) + (v[n][2] * v[n][2] + v[n][3] * v[n][3]); }
;                     *(u32x4*)(Yb + blk_off(row, col0 + bj * 128, D_)) = pack8(v[0], v[1]); }
;                 s1 = xsum32(xsum16(s1)); s2 = xsum32(xsum16(s2));
;                 if (fq == 0) *(f32x2*)(stn + (size_t)row * 32 + (u.pn * 4 + wc) * 2) = (f32x2){s1, s2}; asm volatile("" ::: "memory"); } }
	v_pk_fma_f32 v[106:107], v[126:127], v[106:107], v[130:131]
	v_pk_fma_f32 v[108:109], v[128:129], v[108:109], v[132:133]
	v_pk_fma_f32 v[102:103], v[106:107], s[2:3], v[102:103] op_sel_hi:[1,0,1]
	v_pk_fma_f32 v[104:105], v[108:109], s[2:3], v[104:105] op_sel_hi:[1,0,1]
	v_add_f32_e32 v106, v102, v103
	v_add_f32_e32 v107, v104, v105
	v_add_f32_e32 v106, v106, v107
	global_store_dwordx4 v159, v[110:113], s[42:43]
	v_mul_f32_e32 v107, v105, v105
	v_add_f32_e32 v180, v180, v181
	v_add_f32_e32 v110, v178, v106
	v_mul_f32_e32 v106, v103, v103
	v_fmac_f32_e32 v106, v102, v102
	v_fmac_f32_e32 v107, v104, v104
	v_add_f32_e32 v180, v190, v180
	v_add_f32_e32 v106, v106, v107
	v_add_f32_e32 v111, v180, v106
	v_sub_f32_e32 v107, v115, v179
	v_sub_f32_e32 v106, v114, v179
	v_sub_f32_e32 v109, v117, v179
	v_sub_f32_e32 v108, v116, v179
	v_pk_mul_f32 v[108:109], v[0:1], v[108:109] op_sel_hi:[0,1]
	v_pk_mul_f32 v[106:107], v[0:1], v[106:107] op_sel_hi:[0,1]
	v_pk_fma_f32 v[106:107], v[118:119], v[106:107], v[122:123]
	v_pk_fma_f32 v[108:109], v[120:121], v[108:109], v[124:125]
	v_pk_fma_f32 v[98:99], v[106:107], s[2:3], v[98:99] op_sel_hi:[1,0,1]
	v_pk_fma_f32 v[100:101], v[108:109], s[2:3], v[100:101] op_sel_hi:[1,0,1]
	v_add_f32_e32 v0, v98, v99
	v_add_f32_e32 v106, v100, v101
	v_add_f32_e32 v0, v0, v106
	v_mul_f32_e32 v106, v99, v99
	v_mul_f32_e32 v107, v101, v101
	v_add_f32_e32 v0, v110, v0
	v_fmac_f32_e32 v106, v98, v98
	v_fmac_f32_e32 v107, v100, v100
	s_nop 0
	s_nop 1
	v_bfe_u32 v109, v227, 4, 2
	v_sub_u32_e32 v108, 0, v109
	v_lshlrev_b32_e32 v108, 4, v108
	v_ashrrev_i32_e32 v109, 31, v108
	v_lshl_add_u64 v[108:109], v[182:183], 0, v[108:109]
	v_permlane16_swap_b32_e32 v102, v98
	v_permlane16_swap_b32_e32 v103, v99
	v_permlane16_swap_b32_e32 v104, v100
	v_permlane16_swap_b32_e32 v105, v101
	v_permlane32_swap_b32_e32 v102, v98
	v_permlane32_swap_b32_e32 v103, v99
	v_permlane32_swap_b32_e32 v104, v100
	v_permlane32_swap_b32_e32 v105, v101
	v_mov_b32_e32 v114, v102
	v_mov_b32_e32 v115, v103
	v_mov_b32_e32 v116, v104
	v_mov_b32_e32 v117, v105
	v_bfe_u32 v112, v227, 3, 1
	v_mul_i32_i24_e32 v112, 0xffff8040, v112
	v_ashrrev_i32_e32 v113, 31, v112
	v_lshl_add_u64 v[108:109], v[108:109], 0, v[112:113]
	v_mov_b32_e32 v112, 0x8000
	v_mov_b32_e32 v113, 0
	v_lshl_add_u64 v[112:113], v[108:109], 0, v[112:113]
	v_mov_b32_dpp v102, v98 row_ror:8 row_mask:0xf bank_mask:0xc
	v_mov_b32_dpp v103, v99 row_ror:8 row_mask:0xf bank_mask:0xc
	v_mov_b32_dpp v104, v100 row_ror:8 row_mask:0xf bank_mask:0xc
	v_mov_b32_dpp v105, v101 row_ror:8 row_mask:0xf bank_mask:0xc
	v_mov_b32_dpp v98, v114 row_ror:8 row_mask:0xf bank_mask:0x3
	v_mov_b32_dpp v99, v115 row_ror:8 row_mask:0xf bank_mask:0x3
	v_mov_b32_dpp v100, v116 row_ror:8 row_mask:0xf bank_mask:0x3
	v_mov_b32_dpp v101, v117 row_ror:8 row_mask:0xf bank_mask:0x3
	global_store_dwordx4 v[108:109], v[102:105], off offset:512
	global_store_dwordx4 v[112:113], v[98:101], off offset:512
	s_nop 1
	v_mov_b32_dpp v98, v102 row_ror:8 row_mask:0xf bank_mask:0x3
	v_mov_b32_dpp v99, v103 row_ror:8 row_mask:0xf bank_mask:0x3
	v_mov_b32_dpp v100, v104 row_ror:8 row_mask:0xf bank_mask:0x3
	v_mov_b32_dpp v101, v105 row_ror:8 row_mask:0xf bank_mask:0x3
	v_mov_b32_e32 v102, v114
	v_mov_b32_e32 v103, v115
	v_mov_b32_e32 v104, v116
	v_mov_b32_e32 v105, v117
	s_nop 1
	v_permlane32_swap_b32_e32 v102, v98
	v_permlane32_swap_b32_e32 v103, v99
	v_permlane32_swap_b32_e32 v104, v100
	v_permlane32_swap_b32_e32 v105, v101
	v_permlane16_swap_b32_e32 v102, v98
	v_permlane16_swap_b32_e32 v103, v99
	v_permlane16_swap_b32_e32 v104, v100
	v_permlane16_swap_b32_e32 v105, v101
	v_add_f32_e32 v106, v106, v107
	v_cvt_pk_bf16_f32 v102, v102, v103
	v_cvt_pk_bf16_f32 v103, v104, v105
	v_cvt_pk_bf16_f32 v104, v98, v99
	v_mov_b32_e32 v98, v0
	v_add_f32_e32 v106, v111, v106
	s_nop 0
	v_permlane16_swap_b32_e32 v0, v98
	v_add_f32_e32 v98, v0, v98
	v_mov_b32_e32 v0, v106
	s_nop 1
	v_permlane16_swap_b32_e32 v106, v0
	v_add_f32_e32 v99, v106, v0
	v_cvt_pk_bf16_f32 v105, v100, v101
	v_mov_b32_e32 v100, v98
	v_mov_b32_e32 v101, v99
	s_nop 0
	v_permlane32_swap_b32_e32 v98, v100
	v_permlane32_swap_b32_e32 v99, v101
	global_store_dwordx4 v159, v[102:105], s[40:41]
	s_and_saveexec_b64 s[26:27], s[44:45]
	s_cbranch_execz .LBB0_1539
	v_pk_add_f32 v[98:99], v[98:99], v[100:101]
	v_lshl_add_u64 v[100:101], s[6:7], 0, v[172:173]
	v_lshl_add_u64 v[100:101], s[52:53], 2, v[100:101]
	global_store_dwordx2 v[100:101], v[98:99], off
; __device__ __forceinline__ size_t blk_off(int r, int c, int K) { return (size_t)(r >> 8) * 256 * K + (size_t)(c >> 6) * (256 * 64) + (size_t)((r & 255) * 64 + (c & 63)); }
; __device__ __forceinline__ u32x4 pack8(const f32x4 a, const f32x4 b) { u32x4 w; w.x = cvt_pk_bf16(a[0], a[1]); w.y = cvt_pk_bf16(a[2], a[3]); w.z = cvt_pk_bf16(b[0], b[1]); w.w = cvt_pk_bf16(b[2], b[3]); return w; }
;     __device__ __forceinline__ void operator()(const f32x4 (&acc)[2][2][4][2], const pg8::Unit& u, int wr, int wc, int fr, int fq) const {
;     ...
;             for (int m = 0; m < 4; ++m) { const int row = row0 + ai * 128 + m * 16; const float mu = mu4[m], rs = rs4[m];
;                 f32x4 yv[2][2], gq[2][2], bq_[2][2];
; #pragma unroll
;                 for (int bj = 0; bj < 2; ++bj)
; #pragma unroll
;                     for (int n = 0; n < 2; ++n) { yv[bj][n] = *(const f32x4*)(Yin + (size_t)row * D_ + col0 + bj * 128 + 4 * n); gq[bj][n] = *(const f32x4*)(g + col0 + bj * 128 + 4 * n); bq_[bj][n] = *(const f32x4*)(b + col0 + bj * 128 + 4 * n); }
;                 asm volatile("" ::: "memory");
;                 float s1 = 0.f, s2 = 0.f;
; #pragma unroll
;                 for (int bj = 0; bj < 2; ++bj) { float* yp = Y + (size_t)row * D_ + col0 + bj * 128; f32x4 v[2];
; #pragma unroll
;                     for (int n = 0; n < 2; ++n) { v[n] = (((yv[bj][n] - mu) * rs) * gq[bj][n] + bq_[bj][n]) * ALPHA_ + acc[ai][bj][m][n] * sc;
;                         *(f32x4*)(yp + 4 * n) = v[n]; s1 += (v[n][0] + v[n][1]) + (v[n][2] + v[n][3]); s2 += (v[n][0] * v[n][0] + v[n][1] * v[n][1]) + (v[n][2] * v[n][2] + v[n][3] * v[n][3]); }
;                     *(u32x4*)(Yb + blk_off(row, col0 + bj * 128, D_)) = pack8(v[0], v[1]); }
.LBB0_1539:
	s_or_b64 exec, exec, s[26:27]
	v_pk_add_f32 v[98:99], v[174:175], v[176:177]
	s_mov_b32 s2, 0x3a800000
	v_pk_mul_f32 v[122:123], v[98:99], s[2:3] op_sel_hi:[1,0]
	s_mov_b32 s1, 0x800000
	v_fma_f32 v0, -v123, v123, v122
	v_max_f32_e32 v0, 0, v0
	v_add_f32_e32 v0, 0x3727c5ac, v0
	v_cmp_gt_f32_e32 vcc, s1, v0
	v_mul_f32_e32 v98, 0x4b800000, v0
	s_load_dwordx16 s[64:79], s[34:35], 0x38
	v_cndmask_b32_e32 v0, v0, v98, vcc
	v_rsq_f32_e32 v0, v0
	s_mov_b32 s2, 0x3fd744fd
	v_lshlrev_b32_e32 v122, 6, v170
	v_mul_f32_e32 v98, 0x45800000, v0
	v_cndmask_b32_e32 v0, v0, v98, vcc
	v_lshlrev_b64 v[98:99], 12, v[170:171]
	s_waitcnt lgkmcnt(0)
	v_lshl_add_u64 v[98:99], s[78:79], 0, v[98:99]
	v_lshl_add_u64 v[124:125], v[152:153], 2, v[98:99]
	global_load_dwordx4 v[126:129], v[124:125], off offset:16
	global_load_dwordx4 v[130:133], v[124:125], off
	global_load_dwordx4 v[134:137], v[156:157], off offset:16
	global_load_dwordx4 v[172:175], v[156:157], off
	global_load_dwordx4 v[176:179], v[154:155], off offset:16
	global_load_dwordx4 v[180:183], v[154:155], off
	global_load_dwordx4 v[98:101], v[124:125], off offset:528
	global_load_dwordx4 v[118:121], v[124:125], off offset:512
	global_load_dwordx4 v[102:105], v[156:157], off offset:528
	global_load_dwordx4 v[110:113], v[156:157], off offset:512
	global_load_dwordx4 v[106:109], v[154:155], off offset:528
	global_load_dwordx4 v[114:117], v[154:155], off offset:512
	s_movk_i32 s1, 0x3bc0
	v_and_or_b32 v122, v122, s1, v196
	v_lshlrev_b32_e32 v122, 1, v122
	s_waitcnt vmcnt(11)
	v_sub_f32_e32 v127, v127, v123
	s_waitcnt vmcnt(10)
	v_sub_f32_e32 v131, v131, v123
	v_sub_f32_e32 v130, v130, v123
	v_sub_f32_e32 v133, v133, v123
	v_sub_f32_e32 v132, v132, v123
	v_sub_f32_e32 v126, v126, v123
	v_sub_f32_e32 v129, v129, v123
	v_sub_f32_e32 v128, v128, v123
	v_pk_mul_f32 v[132:133], v[0:1], v[132:133] op_sel_hi:[0,1]
	v_pk_mul_f32 v[130:131], v[0:1], v[130:131] op_sel_hi:[0,1]
	v_pk_mul_f32 v[128:129], v[0:1], v[128:129] op_sel_hi:[0,1]
	v_pk_mul_f32 v[126:127], v[0:1], v[126:127] op_sel_hi:[0,1]
	s_waitcnt vmcnt(6)
	v_pk_fma_f32 v[130:131], v[172:173], v[130:131], v[180:181]
	v_pk_fma_f32 v[132:133], v[174:175], v[132:133], v[182:183]
	v_pk_fma_f32 v[126:127], v[134:135], v[126:127], v[176:177]
	v_pk_fma_f32 v[128:129], v[136:137], v[128:129], v[178:179]
	v_pk_fma_f32 v[96:97], v[132:133], s[2:3], v[96:97] op_sel_hi:[1,0,1]
	v_pk_fma_f32 v[94:95], v[130:131], s[2:3], v[94:95] op_sel_hi:[1,0,1]
	v_pk_fma_f32 v[92:93], v[128:129], s[2:3], v[92:93] op_sel_hi:[1,0,1]
	v_pk_fma_f32 v[90:91], v[126:127], s[2:3], v[90:91] op_sel_hi:[1,0,1]
	v_add_f32_e32 v130, v94, v95
	v_add_f32_e32 v131, v96, v97
	v_add_f32_e32 v126, v90, v91
	v_add_f32_e32 v127, v92, v93
	v_add_f32_e32 v130, v130, v131
	v_mul_f32_e32 v131, v95, v95
	v_mul_f32_e32 v132, v97, v97
	v_add_f32_e32 v126, v126, v127
	v_mul_f32_e32 v127, v91, v91
	v_mul_f32_e32 v128, v93, v93
	s_nop 0
	v_fmac_f32_e32 v131, v94, v94
	v_fmac_f32_e32 v132, v96, v96
	s_nop 1
	v_bfe_u32 v135, v227, 4, 2
	v_sub_u32_e32 v134, 0, v135
	v_lshlrev_b32_e32 v134, 4, v134
	v_ashrrev_i32_e32 v135, 31, v134
	v_lshl_add_u64 v[134:135], v[124:125], 0, v[134:135]
	v_permlane16_swap_b32_e32 v94, v90
	v_permlane16_swap_b32_e32 v95, v91
	v_permlane16_swap_b32_e32 v96, v92
	v_permlane16_swap_b32_e32 v97, v93
	v_permlane32_swap_b32_e32 v94, v90
	v_permlane32_swap_b32_e32 v95, v91
	v_permlane32_swap_b32_e32 v96, v92
	v_permlane32_swap_b32_e32 v97, v93
	v_mov_b32_e32 v129, v94
	v_mov_b32_e32 v133, v95
	v_mov_b32_e32 v159, v96
	v_mov_b32_e32 v170, v97
	v_bfe_u32 v136, v227, 3, 1
	v_mul_i32_i24_e32 v136, 0xffff8040, v136
	v_ashrrev_i32_e32 v137, 31, v136
	v_lshl_add_u64 v[134:135], v[134:135], 0, v[136:137]
	v_mov_b32_e32 v136, 0x8000
	v_mov_b32_e32 v137, 0
	v_lshl_add_u64 v[136:137], v[134:135], 0, v[136:137]
	v_mov_b32_dpp v94, v90 row_ror:8 row_mask:0xf bank_mask:0xc
	v_mov_b32_dpp v95, v91 row_ror:8 row_mask:0xf bank_mask:0xc
	v_mov_b32_dpp v96, v92 row_ror:8 row_mask:0xf bank_mask:0xc
	v_mov_b32_dpp v97, v93 row_ror:8 row_mask:0xf bank_mask:0xc
	v_mov_b32_dpp v90, v129 row_ror:8 row_mask:0xf bank_mask:0x3
	v_mov_b32_dpp v91, v133 row_ror:8 row_mask:0xf bank_mask:0x3
	v_mov_b32_dpp v92, v159 row_ror:8 row_mask:0xf bank_mask:0x3
	v_mov_b32_dpp v93, v170 row_ror:8 row_mask:0xf bank_mask:0x3
	global_store_dwordx4 v[134:135], v[94:97], off
	global_store_dwordx4 v[136:137], v[90:93], off
	s_nop 1
	v_mov_b32_dpp v90, v94 row_ror:8 row_mask:0xf bank_mask:0x3
	v_mov_b32_dpp v91, v95 row_ror:8 row_mask:0xf bank_mask:0x3
	v_mov_b32_dpp v92, v96 row_ror:8 row_mask:0xf bank_mask:0x3
	v_mov_b32_dpp v93, v97 row_ror:8 row_mask:0xf bank_mask:0x3
	v_mov_b32_e32 v94, v129
	v_mov_b32_e32 v95, v133
	v_mov_b32_e32 v96, v159
	v_mov_b32_e32 v97, v170
	s_nop 1
	v_permlane32_swap_b32_e32 v94, v90
	v_permlane32_swap_b32_e32 v95, v91
	v_permlane32_swap_b32_e32 v96, v92
	v_permlane32_swap_b32_e32 v97, v93
	v_permlane16_swap_b32_e32 v94, v90
	v_permlane16_swap_b32_e32 v95, v91
	v_permlane16_swap_b32_e32 v96, v92
	v_permlane16_swap_b32_e32 v97, v93
	v_fmac_f32_e32 v127, v90, v90
	v_fmac_f32_e32 v128, v92, v92
	v_cvt_pk_bf16_f32 v94, v94, v95
	v_cvt_pk_bf16_f32 v95, v96, v97
	v_cvt_pk_bf16_f32 v96, v90, v91
	v_cvt_pk_bf16_f32 v97, v92, v93
	s_waitcnt vmcnt(6)
	v_sub_f32_e32 v91, v119, v123
	v_sub_f32_e32 v90, v118, v123
	v_sub_f32_e32 v93, v121, v123
	v_sub_f32_e32 v92, v120, v123
	v_pk_mul_f32 v[92:93], v[0:1], v[92:93] op_sel_hi:[0,1]
	v_pk_mul_f32 v[90:91], v[0:1], v[90:91] op_sel_hi:[0,1]
	s_waitcnt vmcnt(2)
; __device__ __forceinline__ float xsum16(float v) { const auto r = __builtin_amdgcn_permlane16_swap(__float_as_uint(v), __float_as_uint(v), false, false); return __uint_as_float(r[0]) + __uint_as_float(r[1]); }
; __device__ __forceinline__ float xsum32(float v) { const auto r = __builtin_amdgcn_permlane32_swap(__float_as_uint(v), __float_as_uint(v), false, false); return __uint_as_float(r[0]) + __uint_as_float(r[1]); }
; __device__ __forceinline__ size_t blk_off(int r, int c, int K) { return (size_t)(r >> 8) * 256 * K + (size_t)(c >> 6) * (256 * 64) + (size_t)((r & 255) * 64 + (c & 63)); }
; __device__ __forceinline__ u32x4 pack8(const f32x4 a, const f32x4 b) { u32x4 w; w.x = cvt_pk_bf16(a[0], a[1]); w.y = cvt_pk_bf16(a[2], a[3]); w.z = cvt_pk_bf16(b[0], b[1]); w.w = cvt_pk_bf16(b[2], b[3]); return w; }
;     __device__ __forceinline__ void operator()(const f32x4 (&acc)[2][2][4][2], const pg8::Unit& u, int wr, int wc, int fr, int fq) const {
;     ...
;                 for (int bj = 0; bj < 2; ++bj) { float* yp = Y + (size_t)row * D_ + col0 + bj * 128; f32x4 v[2];
; #pragma unroll
;                     for (int n = 0; n < 2; ++n) { v[n] = (((yv[bj][n] - mu) * rs) * gq[bj][n] + bq_[bj][n]) * ALPHA_ + acc[ai][bj][m][n] * sc;
;                         *(f32x4*)(yp + 4 * n) = v[n]; s1 += (v[n][0] + v[n][1]) + (v[n][2] + v[n][3]); s2 += (v[n][0] * v[n][0] + v[n][1] * v[n][1]) + (v[n][2] * v[n][2] + v[n][3] * v[n][3]); }
;                     *(u32x4*)(Yb + blk_off(row, col0 + bj * 128, D_)) = pack8(v[0], v[1]); }
;                 s1 = xsum32(xsum16(s1)); s2 = xsum32(xsum16(s2));
;                 if (fq == 0) *(f32x2*)(stn + (size_t)row * 32 + (u.pn * 4 + wc) * 2) = (f32x2){s1, s2}; asm volatile("" ::: "memory"); } }
	v_pk_fma_f32 v[90:91], v[110:111], v[90:91], v[114:115]
	v_pk_fma_f32 v[92:93], v[112:113], v[92:93], v[116:117]
	v_pk_fma_f32 v[86:87], v[90:91], s[2:3], v[86:87] op_sel_hi:[1,0,1]
	v_pk_fma_f32 v[88:89], v[92:93], s[2:3], v[88:89] op_sel_hi:[1,0,1]
	v_add_f32_e32 v130, 0, v130
	v_add_f32_e32 v90, v86, v87
	v_add_f32_e32 v91, v88, v89
	v_add_f32_e32 v126, v130, v126
	v_add_f32_e32 v90, v90, v91
	global_store_dwordx4 v122, v[94:97], s[42:43]
	v_mul_f32_e32 v91, v89, v89
	v_add_f32_e32 v131, v131, v132
	v_add_f32_e32 v94, v126, v90
	v_mul_f32_e32 v90, v87, v87
	v_add_f32_e32 v127, v127, v128
	v_fmac_f32_e32 v90, v86, v86
	v_fmac_f32_e32 v91, v88, v88
	v_add_f32_e32 v127, v131, v127
	v_add_f32_e32 v90, v90, v91
	v_add_f32_e32 v95, v127, v90
	v_sub_f32_e32 v91, v99, v123
	v_sub_f32_e32 v90, v98, v123
	v_sub_f32_e32 v93, v101, v123
	v_sub_f32_e32 v92, v100, v123
	v_pk_mul_f32 v[92:93], v[0:1], v[92:93] op_sel_hi:[0,1]
	v_pk_mul_f32 v[90:91], v[0:1], v[90:91] op_sel_hi:[0,1]
	v_pk_fma_f32 v[90:91], v[102:103], v[90:91], v[106:107]
	v_pk_fma_f32 v[92:93], v[104:105], v[92:93], v[108:109]
	v_pk_fma_f32 v[82:83], v[90:91], s[2:3], v[82:83] op_sel_hi:[1,0,1]
	v_pk_fma_f32 v[84:85], v[92:93], s[2:3], v[84:85] op_sel_hi:[1,0,1]
	v_add_f32_e32 v0, v82, v83
	v_add_f32_e32 v90, v84, v85
	v_add_f32_e32 v0, v0, v90
	v_mul_f32_e32 v90, v83, v83
	v_mul_f32_e32 v91, v85, v85
	v_add_f32_e32 v0, v94, v0
	v_fmac_f32_e32 v90, v82, v82
	v_fmac_f32_e32 v91, v84, v84
	s_nop 0
	s_nop 1
	v_bfe_u32 v93, v227, 4, 2
	v_sub_u32_e32 v92, 0, v93
	v_lshlrev_b32_e32 v92, 4, v92
	v_ashrrev_i32_e32 v93, 31, v92
	v_lshl_add_u64 v[92:93], v[124:125], 0, v[92:93]
	v_permlane16_swap_b32_e32 v86, v82
	v_permlane16_swap_b32_e32 v87, v83
	v_permlane16_swap_b32_e32 v88, v84
	v_permlane16_swap_b32_e32 v89, v85
	v_permlane32_swap_b32_e32 v86, v82
	v_permlane32_swap_b32_e32 v87, v83
	v_permlane32_swap_b32_e32 v88, v84
	v_permlane32_swap_b32_e32 v89, v85
	v_mov_b32_e32 v98, v86
	v_mov_b32_e32 v99, v87
	v_mov_b32_e32 v100, v88
	v_mov_b32_e32 v101, v89
	v_bfe_u32 v96, v227, 3, 1
	v_mul_i32_i24_e32 v96, 0xffff8040, v96
	v_ashrrev_i32_e32 v97, 31, v96
	v_lshl_add_u64 v[92:93], v[92:93], 0, v[96:97]
	v_mov_b32_e32 v96, 0x8000
	v_mov_b32_e32 v97, 0
	v_lshl_add_u64 v[96:97], v[92:93], 0, v[96:97]
	v_mov_b32_dpp v86, v82 row_ror:8 row_mask:0xf bank_mask:0xc
	v_mov_b32_dpp v87, v83 row_ror:8 row_mask:0xf bank_mask:0xc
	v_mov_b32_dpp v88, v84 row_ror:8 row_mask:0xf bank_mask:0xc
	v_mov_b32_dpp v89, v85 row_ror:8 row_mask:0xf bank_mask:0xc
	v_mov_b32_dpp v82, v98 row_ror:8 row_mask:0xf bank_mask:0x3
	v_mov_b32_dpp v83, v99 row_ror:8 row_mask:0xf bank_mask:0x3
	v_mov_b32_dpp v84, v100 row_ror:8 row_mask:0xf bank_mask:0x3
	v_mov_b32_dpp v85, v101 row_ror:8 row_mask:0xf bank_mask:0x3
	global_store_dwordx4 v[92:93], v[86:89], off offset:512
	global_store_dwordx4 v[96:97], v[82:85], off offset:512
	s_nop 1
	v_mov_b32_dpp v82, v86 row_ror:8 row_mask:0xf bank_mask:0x3
	v_mov_b32_dpp v83, v87 row_ror:8 row_mask:0xf bank_mask:0x3
	v_mov_b32_dpp v84, v88 row_ror:8 row_mask:0xf bank_mask:0x3
	v_mov_b32_dpp v85, v89 row_ror:8 row_mask:0xf bank_mask:0x3
	v_mov_b32_e32 v86, v98
	v_mov_b32_e32 v87, v99
	v_mov_b32_e32 v88, v100
	v_mov_b32_e32 v89, v101
	s_nop 1
	v_permlane32_swap_b32_e32 v86, v82
	v_permlane32_swap_b32_e32 v87, v83
	v_permlane32_swap_b32_e32 v88, v84
	v_permlane32_swap_b32_e32 v89, v85
	v_permlane16_swap_b32_e32 v86, v82
	v_permlane16_swap_b32_e32 v87, v83
	v_permlane16_swap_b32_e32 v88, v84
	v_permlane16_swap_b32_e32 v89, v85
	v_add_f32_e32 v90, v90, v91
	v_cvt_pk_bf16_f32 v86, v86, v87
	v_cvt_pk_bf16_f32 v87, v88, v89
	v_cvt_pk_bf16_f32 v88, v82, v83
	v_mov_b32_e32 v82, v0
	v_add_f32_e32 v90, v95, v90
	s_nop 0
	v_permlane16_swap_b32_e32 v0, v82
	v_add_f32_e32 v82, v0, v82
	v_mov_b32_e32 v0, v90
	s_nop 1
	v_permlane16_swap_b32_e32 v90, v0
	v_add_f32_e32 v83, v90, v0
	v_cvt_pk_bf16_f32 v89, v84, v85
	v_mov_b32_e32 v84, v82
	v_mov_b32_e32 v85, v83
	s_nop 0
	v_permlane32_swap_b32_e32 v82, v84
	v_permlane32_swap_b32_e32 v83, v85
	global_store_dwordx4 v122, v[86:89], s[40:41]
	s_and_saveexec_b64 s[26:27], s[44:45]
	s_cbranch_execz .LBB0_1541
	v_pk_add_f32 v[82:83], v[82:83], v[84:85]
	v_lshl_add_u64 v[84:85], s[6:7], 0, v[164:165]
	v_lshl_add_u64 v[84:85], s[52:53], 2, v[84:85]
	global_store_dwordx2 v[84:85], v[82:83], off
; __device__ __forceinline__ size_t blk_off(int r, int c, int K) { return (size_t)(r >> 8) * 256 * K + (size_t)(c >> 6) * (256 * 64) + (size_t)((r & 255) * 64 + (c & 63)); }
; __device__ __forceinline__ u32x4 pack8(const f32x4 a, const f32x4 b) { u32x4 w; w.x = cvt_pk_bf16(a[0], a[1]); w.y = cvt_pk_bf16(a[2], a[3]); w.z = cvt_pk_bf16(b[0], b[1]); w.w = cvt_pk_bf16(b[2], b[3]); return w; }
;     __device__ __forceinline__ void operator()(const f32x4 (&acc)[2][2][4][2], const pg8::Unit& u, int wr, int wc, int fr, int fq) const {
;     ...
;             for (int m = 0; m < 4; ++m) { const int row = row0 + ai * 128 + m * 16; const float mu = mu4[m], rs = rs4[m];
;                 f32x4 yv[2][2], gq[2][2], bq_[2][2];
; #pragma unroll
;                 for (int bj = 0; bj < 2; ++bj)
; #pragma unroll
;                     for (int n = 0; n < 2; ++n) { yv[bj][n] = *(const f32x4*)(Yin + (size_t)row * D_ + col0 + bj * 128 + 4 * n); gq[bj][n] = *(const f32x4*)(g + col0 + bj * 128 + 4 * n); bq_[bj][n] = *(const f32x4*)(b + col0 + bj * 128 + 4 * n); }
;                 asm volatile("" ::: "memory");
;                 float s1 = 0.f, s2 = 0.f;
; #pragma unroll
;                 for (int bj = 0; bj < 2; ++bj) { float* yp = Y + (size_t)row * D_ + col0 + bj * 128; f32x4 v[2];
; #pragma unroll
;                     for (int n = 0; n < 2; ++n) { v[n] = (((yv[bj][n] - mu) * rs) * gq[bj][n] + bq_[bj][n]) * ALPHA_ + acc[ai][bj][m][n] * sc;
;                         *(f32x4*)(yp + 4 * n) = v[n]; s1 += (v[n][0] + v[n][1]) + (v[n][2] + v[n][3]); s2 += (v[n][0] * v[n][0] + v[n][1] * v[n][1]) + (v[n][2] * v[n][2] + v[n][3] * v[n][3]); }
;                     *(u32x4*)(Yb + blk_off(row, col0 + bj * 128, D_)) = pack8(v[0], v[1]); }
.LBB0_1541:
	s_or_b64 exec, exec, s[26:27]
	v_pk_add_f32 v[82:83], v[166:167], v[168:169]
	s_mov_b32 s2, 0x3a800000
	v_pk_mul_f32 v[106:107], v[82:83], s[2:3] op_sel_hi:[1,0]
	s_mov_b32 s1, 0x800000
	v_fma_f32 v0, -v107, v107, v106
	v_max_f32_e32 v0, 0, v0
	v_add_f32_e32 v0, 0x3727c5ac, v0
	v_cmp_gt_f32_e32 vcc, s1, v0
	v_mul_f32_e32 v82, 0x4b800000, v0
	s_load_dwordx16 s[64:79], s[34:35], 0x38
	v_cndmask_b32_e32 v0, v0, v82, vcc
	v_rsq_f32_e32 v0, v0
	s_mov_b32 s2, 0x3fd744fd
	v_lshlrev_b32_e32 v106, 6, v162
	v_mul_f32_e32 v82, 0x45800000, v0
	v_cndmask_b32_e32 v0, v0, v82, vcc
	v_lshlrev_b64 v[82:83], 12, v[162:163]
	s_waitcnt lgkmcnt(0)
	v_lshl_add_u64 v[82:83], s[78:79], 0, v[82:83]
	v_lshl_add_u64 v[108:109], v[152:153], 2, v[82:83]
	global_load_dwordx4 v[110:113], v[108:109], off offset:16
	global_load_dwordx4 v[114:117], v[108:109], off
	global_load_dwordx4 v[118:121], v[156:157], off offset:16
	global_load_dwordx4 v[122:125], v[156:157], off
	global_load_dwordx4 v[126:129], v[154:155], off offset:16
	global_load_dwordx4 v[130:133], v[154:155], off
	global_load_dwordx4 v[82:85], v[108:109], off offset:528
	global_load_dwordx4 v[102:105], v[108:109], off offset:512
	global_load_dwordx4 v[86:89], v[156:157], off offset:528
	global_load_dwordx4 v[94:97], v[156:157], off offset:512
	global_load_dwordx4 v[90:93], v[154:155], off offset:528
	global_load_dwordx4 v[98:101], v[154:155], off offset:512
	s_movk_i32 s1, 0x3fc0
	v_and_or_b32 v106, v106, s1, v196
	v_lshlrev_b32_e32 v106, 1, v106
	s_waitcnt vmcnt(11)
	v_sub_f32_e32 v111, v111, v107
	s_waitcnt vmcnt(10)
	v_sub_f32_e32 v115, v115, v107
	v_sub_f32_e32 v114, v114, v107
	v_sub_f32_e32 v117, v117, v107
	v_sub_f32_e32 v116, v116, v107
	v_sub_f32_e32 v110, v110, v107
	v_sub_f32_e32 v113, v113, v107
	v_sub_f32_e32 v112, v112, v107
	v_pk_mul_f32 v[116:117], v[0:1], v[116:117] op_sel_hi:[0,1]
	v_pk_mul_f32 v[114:115], v[0:1], v[114:115] op_sel_hi:[0,1]
	v_pk_mul_f32 v[112:113], v[0:1], v[112:113] op_sel_hi:[0,1]
	v_pk_mul_f32 v[110:111], v[0:1], v[110:111] op_sel_hi:[0,1]
	s_waitcnt vmcnt(6)
	v_pk_fma_f32 v[114:115], v[122:123], v[114:115], v[130:131]
	v_pk_fma_f32 v[116:117], v[124:125], v[116:117], v[132:133]
	v_pk_fma_f32 v[110:111], v[118:119], v[110:111], v[126:127]
	v_pk_fma_f32 v[112:113], v[120:121], v[112:113], v[128:129]
	v_pk_fma_f32 v[80:81], v[116:117], s[2:3], v[80:81] op_sel_hi:[1,0,1]
	v_pk_fma_f32 v[78:79], v[114:115], s[2:3], v[78:79] op_sel_hi:[1,0,1]
	v_pk_fma_f32 v[76:77], v[112:113], s[2:3], v[76:77] op_sel_hi:[1,0,1]
	v_pk_fma_f32 v[74:75], v[110:111], s[2:3], v[74:75] op_sel_hi:[1,0,1]
	v_add_f32_e32 v114, v78, v79
	v_add_f32_e32 v115, v80, v81
	v_add_f32_e32 v110, v74, v75
	v_add_f32_e32 v111, v76, v77
	v_add_f32_e32 v114, v114, v115
	v_mul_f32_e32 v115, v79, v79
	v_mul_f32_e32 v116, v81, v81
	v_add_f32_e32 v110, v110, v111
	v_mul_f32_e32 v111, v75, v75
	v_mul_f32_e32 v112, v77, v77
	s_nop 0
	v_fmac_f32_e32 v115, v78, v78
	v_fmac_f32_e32 v116, v80, v80
	s_nop 1
	v_bfe_u32 v119, v227, 4, 2
	v_sub_u32_e32 v118, 0, v119
	v_lshlrev_b32_e32 v118, 4, v118
	v_ashrrev_i32_e32 v119, 31, v118
	v_lshl_add_u64 v[118:119], v[108:109], 0, v[118:119]
	v_permlane16_swap_b32_e32 v78, v74
	v_permlane16_swap_b32_e32 v79, v75
	v_permlane16_swap_b32_e32 v80, v76
	v_permlane16_swap_b32_e32 v81, v77
	v_permlane32_swap_b32_e32 v78, v74
	v_permlane32_swap_b32_e32 v79, v75
	v_permlane32_swap_b32_e32 v80, v76
	v_permlane32_swap_b32_e32 v81, v77
	v_mov_b32_e32 v113, v78
	v_mov_b32_e32 v117, v79
	v_mov_b32_e32 v122, v80
	v_mov_b32_e32 v123, v81
	v_bfe_u32 v120, v227, 3, 1
	v_mul_i32_i24_e32 v120, 0xffff8040, v120
	v_ashrrev_i32_e32 v121, 31, v120
	v_lshl_add_u64 v[118:119], v[118:119], 0, v[120:121]
	v_mov_b32_e32 v120, 0x8000
	v_mov_b32_e32 v121, 0
	v_lshl_add_u64 v[120:121], v[118:119], 0, v[120:121]
	v_mov_b32_dpp v78, v74 row_ror:8 row_mask:0xf bank_mask:0xc
	v_mov_b32_dpp v79, v75 row_ror:8 row_mask:0xf bank_mask:0xc
	v_mov_b32_dpp v80, v76 row_ror:8 row_mask:0xf bank_mask:0xc
	v_mov_b32_dpp v81, v77 row_ror:8 row_mask:0xf bank_mask:0xc
	v_mov_b32_dpp v74, v113 row_ror:8 row_mask:0xf bank_mask:0x3
	v_mov_b32_dpp v75, v117 row_ror:8 row_mask:0xf bank_mask:0x3
	v_mov_b32_dpp v76, v122 row_ror:8 row_mask:0xf bank_mask:0x3
	v_mov_b32_dpp v77, v123 row_ror:8 row_mask:0xf bank_mask:0x3
	global_store_dwordx4 v[118:119], v[78:81], off
	global_store_dwordx4 v[120:121], v[74:77], off
	s_nop 1
	v_mov_b32_dpp v74, v78 row_ror:8 row_mask:0xf bank_mask:0x3
	v_mov_b32_dpp v75, v79 row_ror:8 row_mask:0xf bank_mask:0x3
	v_mov_b32_dpp v76, v80 row_ror:8 row_mask:0xf bank_mask:0x3
	v_mov_b32_dpp v77, v81 row_ror:8 row_mask:0xf bank_mask:0x3
	v_mov_b32_e32 v78, v113
	v_mov_b32_e32 v79, v117
	v_mov_b32_e32 v80, v122
	v_mov_b32_e32 v81, v123
	s_nop 1
	v_permlane32_swap_b32_e32 v78, v74
	v_permlane32_swap_b32_e32 v79, v75
	v_permlane32_swap_b32_e32 v80, v76
	v_permlane32_swap_b32_e32 v81, v77
	v_permlane16_swap_b32_e32 v78, v74
	v_permlane16_swap_b32_e32 v79, v75
	v_permlane16_swap_b32_e32 v80, v76
	v_permlane16_swap_b32_e32 v81, v77
	v_fmac_f32_e32 v111, v74, v74
	v_fmac_f32_e32 v112, v76, v76
	v_cvt_pk_bf16_f32 v78, v78, v79
	v_cvt_pk_bf16_f32 v79, v80, v81
	v_cvt_pk_bf16_f32 v80, v74, v75
	v_cvt_pk_bf16_f32 v81, v76, v77
	s_waitcnt vmcnt(6)
	v_sub_f32_e32 v75, v103, v107
	v_sub_f32_e32 v74, v102, v107
	v_sub_f32_e32 v77, v105, v107
	v_sub_f32_e32 v76, v104, v107
	v_pk_mul_f32 v[76:77], v[0:1], v[76:77] op_sel_hi:[0,1]
	v_pk_mul_f32 v[74:75], v[0:1], v[74:75] op_sel_hi:[0,1]
	s_waitcnt vmcnt(2)
; __device__ __forceinline__ float xsum16(float v) { const auto r = __builtin_amdgcn_permlane16_swap(__float_as_uint(v), __float_as_uint(v), false, false); return __uint_as_float(r[0]) + __uint_as_float(r[1]); }
; __device__ __forceinline__ float xsum32(float v) { const auto r = __builtin_amdgcn_permlane32_swap(__float_as_uint(v), __float_as_uint(v), false, false); return __uint_as_float(r[0]) + __uint_as_float(r[1]); }
; __device__ __forceinline__ size_t blk_off(int r, int c, int K) { return (size_t)(r >> 8) * 256 * K + (size_t)(c >> 6) * (256 * 64) + (size_t)((r & 255) * 64 + (c & 63)); }
; __device__ __forceinline__ u32x4 pack8(const f32x4 a, const f32x4 b) { u32x4 w; w.x = cvt_pk_bf16(a[0], a[1]); w.y = cvt_pk_bf16(a[2], a[3]); w.z = cvt_pk_bf16(b[0], b[1]); w.w = cvt_pk_bf16(b[2], b[3]); return w; }
;     __device__ __forceinline__ void operator()(const f32x4 (&acc)[2][2][4][2], const pg8::Unit& u, int wr, int wc, int fr, int fq) const {
;     ...
;                 for (int bj = 0; bj < 2; ++bj) { float* yp = Y + (size_t)row * D_ + col0 + bj * 128; f32x4 v[2];
; #pragma unroll
;                     for (int n = 0; n < 2; ++n) { v[n] = (((yv[bj][n] - mu) * rs) * gq[bj][n] + bq_[bj][n]) * ALPHA_ + acc[ai][bj][m][n] * sc;
;                         *(f32x4*)(yp + 4 * n) = v[n]; s1 += (v[n][0] + v[n][1]) + (v[n][2] + v[n][3]); s2 += (v[n][0] * v[n][0] + v[n][1] * v[n][1]) + (v[n][2] * v[n][2] + v[n][3] * v[n][3]); }
;                     *(u32x4*)(Yb + blk_off(row, col0 + bj * 128, D_)) = pack8(v[0], v[1]); }
;                 s1 = xsum32(xsum16(s1)); s2 = xsum32(xsum16(s2));
;                 if (fq == 0) *(f32x2*)(stn + (size_t)row * 32 + (u.pn * 4 + wc) * 2) = (f32x2){s1, s2}; asm volatile("" ::: "memory"); } }
	v_pk_fma_f32 v[74:75], v[94:95], v[74:75], v[98:99]
	v_pk_fma_f32 v[76:77], v[96:97], v[76:77], v[100:101]
	v_pk_fma_f32 v[70:71], v[74:75], s[2:3], v[70:71] op_sel_hi:[1,0,1]
	v_pk_fma_f32 v[72:73], v[76:77], s[2:3], v[72:73] op_sel_hi:[1,0,1]
	v_add_f32_e32 v114, 0, v114
	v_add_f32_e32 v74, v70, v71
	v_add_f32_e32 v75, v72, v73
	v_add_f32_e32 v110, v114, v110
	v_add_f32_e32 v74, v74, v75
	global_store_dwordx4 v106, v[78:81], s[42:43]
	v_mul_f32_e32 v75, v73, v73
	v_add_f32_e32 v115, v115, v116
	v_add_f32_e32 v78, v110, v74
	v_mul_f32_e32 v74, v71, v71
	v_add_f32_e32 v111, v111, v112
	v_fmac_f32_e32 v74, v70, v70
	v_fmac_f32_e32 v75, v72, v72
	v_add_f32_e32 v111, v115, v111
	v_add_f32_e32 v74, v74, v75
	v_add_f32_e32 v79, v111, v74
	v_sub_f32_e32 v75, v83, v107
	v_sub_f32_e32 v74, v82, v107
	v_sub_f32_e32 v77, v85, v107
	v_sub_f32_e32 v76, v84, v107
	v_pk_mul_f32 v[76:77], v[0:1], v[76:77] op_sel_hi:[0,1]
	v_pk_mul_f32 v[74:75], v[0:1], v[74:75] op_sel_hi:[0,1]
	v_pk_fma_f32 v[74:75], v[86:87], v[74:75], v[90:91]
	v_pk_fma_f32 v[76:77], v[88:89], v[76:77], v[92:93]
	v_pk_fma_f32 v[66:67], v[74:75], s[2:3], v[66:67] op_sel_hi:[1,0,1]
	v_pk_fma_f32 v[68:69], v[76:77], s[2:3], v[68:69] op_sel_hi:[1,0,1]
	v_add_f32_e32 v0, v66, v67
	v_add_f32_e32 v74, v68, v69
	v_add_f32_e32 v0, v0, v74
	v_mul_f32_e32 v74, v67, v67
	v_mul_f32_e32 v75, v69, v69
	v_add_f32_e32 v0, v78, v0
	v_fmac_f32_e32 v74, v66, v66
	v_fmac_f32_e32 v75, v68, v68
	s_nop 0
	s_nop 1
	v_bfe_u32 v77, v227, 4, 2
	v_sub_u32_e32 v76, 0, v77
	v_lshlrev_b32_e32 v76, 4, v76
	v_ashrrev_i32_e32 v77, 31, v76
	v_lshl_add_u64 v[76:77], v[108:109], 0, v[76:77]
	v_permlane16_swap_b32_e32 v70, v66
	v_permlane16_swap_b32_e32 v71, v67
	v_permlane16_swap_b32_e32 v72, v68
	v_permlane16_swap_b32_e32 v73, v69
	v_permlane32_swap_b32_e32 v70, v66
	v_permlane32_swap_b32_e32 v71, v67
	v_permlane32_swap_b32_e32 v72, v68
	v_permlane32_swap_b32_e32 v73, v69
	v_mov_b32_e32 v82, v70
	v_mov_b32_e32 v83, v71
	v_mov_b32_e32 v84, v72
	v_mov_b32_e32 v85, v73
	v_bfe_u32 v80, v227, 3, 1
	v_mul_i32_i24_e32 v80, 0xffff8040, v80
	v_ashrrev_i32_e32 v81, 31, v80
	v_lshl_add_u64 v[76:77], v[76:77], 0, v[80:81]
	v_mov_b32_e32 v80, 0x8000
	v_mov_b32_e32 v81, 0
	v_lshl_add_u64 v[80:81], v[76:77], 0, v[80:81]
	v_mov_b32_dpp v70, v66 row_ror:8 row_mask:0xf bank_mask:0xc
	v_mov_b32_dpp v71, v67 row_ror:8 row_mask:0xf bank_mask:0xc
	v_mov_b32_dpp v72, v68 row_ror:8 row_mask:0xf bank_mask:0xc
	v_mov_b32_dpp v73, v69 row_ror:8 row_mask:0xf bank_mask:0xc
	v_mov_b32_dpp v66, v82 row_ror:8 row_mask:0xf bank_mask:0x3
	v_mov_b32_dpp v67, v83 row_ror:8 row_mask:0xf bank_mask:0x3
	v_mov_b32_dpp v68, v84 row_ror:8 row_mask:0xf bank_mask:0x3
	v_mov_b32_dpp v69, v85 row_ror:8 row_mask:0xf bank_mask:0x3
	global_store_dwordx4 v[76:77], v[70:73], off offset:512
	global_store_dwordx4 v[80:81], v[66:69], off offset:512
	s_nop 1
	v_mov_b32_dpp v66, v70 row_ror:8 row_mask:0xf bank_mask:0x3
	v_mov_b32_dpp v67, v71 row_ror:8 row_mask:0xf bank_mask:0x3
	v_mov_b32_dpp v68, v72 row_ror:8 row_mask:0xf bank_mask:0x3
	v_mov_b32_dpp v69, v73 row_ror:8 row_mask:0xf bank_mask:0x3
	v_mov_b32_e32 v70, v82
	v_mov_b32_e32 v71, v83
	v_mov_b32_e32 v72, v84
	v_mov_b32_e32 v73, v85
	s_nop 1
	v_permlane32_swap_b32_e32 v70, v66
	v_permlane32_swap_b32_e32 v71, v67
	v_permlane32_swap_b32_e32 v72, v68
	v_permlane32_swap_b32_e32 v73, v69
	v_permlane16_swap_b32_e32 v70, v66
	v_permlane16_swap_b32_e32 v71, v67
	v_permlane16_swap_b32_e32 v72, v68
	v_permlane16_swap_b32_e32 v73, v69
	v_add_f32_e32 v74, v74, v75
	v_cvt_pk_bf16_f32 v70, v70, v71
	v_cvt_pk_bf16_f32 v71, v72, v73
	v_cvt_pk_bf16_f32 v72, v66, v67
	v_mov_b32_e32 v66, v0
	v_add_f32_e32 v74, v79, v74
	s_nop 0
	v_permlane16_swap_b32_e32 v0, v66
	v_add_f32_e32 v66, v0, v66
	v_mov_b32_e32 v0, v74
	s_nop 1
	v_permlane16_swap_b32_e32 v74, v0
	v_add_f32_e32 v67, v74, v0
	v_cvt_pk_bf16_f32 v73, v68, v69
	v_mov_b32_e32 v68, v66
	v_mov_b32_e32 v69, v67
	s_nop 0
	v_permlane32_swap_b32_e32 v66, v68
	v_permlane32_swap_b32_e32 v67, v69
	global_store_dwordx4 v106, v[70:73], s[40:41]
	s_and_saveexec_b64 s[26:27], s[44:45]
	s_cbranch_execz .LBB0_1543
	v_pk_add_f32 v[66:67], v[66:67], v[68:69]
	v_lshl_add_u64 v[68:69], s[6:7], 0, v[160:161]
	v_lshl_add_u64 v[68:69], s[52:53], 2, v[68:69]
	global_store_dwordx2 v[68:69], v[66:67], off
; __device__ __forceinline__ float xsum16(float v) { const auto r = __builtin_amdgcn_permlane16_swap(__float_as_uint(v), __float_as_uint(v), false, false); return __uint_as_float(r[0]) + __uint_as_float(r[1]); }
; __device__ __forceinline__ float xsum32(float v) { const auto r = __builtin_amdgcn_permlane32_swap(__float_as_uint(v), __float_as_uint(v), false, false); return __uint_as_float(r[0]) + __uint_as_float(r[1]); }
; __device__ __forceinline__ void row_stats4(const float* st, int rowb, int fq, float (&mu)[4], float (&rs)[4]) {
;     f32x4 a[4], b[4];
; #pragma unroll
;     for (int m = 0; m < 4; ++m) { const f32x4* p = (const f32x4*)(st + (size_t)(rowb + m * 16) * 32 + fq * 8); a[m] = p[0]; b[m] = p[1]; }
; #pragma unroll
;     for (int m = 0; m < 4; ++m) { float s1 = (a[m][0] + a[m][2]) + (b[m][0] + b[m][2]), s2 = (a[m][1] + a[m][3]) + (b[m][1] + b[m][3]);
;         s1 = xsum32(xsum16(s1)); s2 = xsum32(xsum16(s2));
;         const float mm = s1 * (1.0f / 1024.0f); mu[m] = mm; rs[m] = rsqrtf(fmaxf(s2 * (1.0f / 1024.0f) - mm * mm, 0.f) + LN_EPS_); }
;     asm volatile("" ::: "memory");
; }
;     __device__ __forceinline__ void operator()(const f32x4 (&acc)[2][2][4][2], const pg8::Unit& u, int wr, int wc, int fr, int fq) const {
;     ...
;         for (int ai = 0; ai < 2; ++ai) { float mu4[4], rs4[4]; row_stats4(stp, row0 + ai * 128, fq, mu4, rs4);
; #pragma unroll
;             for (int m = 0; m < 4; ++m) { const int row = row0 + ai * 128 + m * 16; const float mu = mu4[m], rs = rs4[m];
;                 f32x4 yv[2][2], gq[2][2], bq_[2][2];
; #pragma unroll
;                 for (int bj = 0; bj < 2; ++bj)
; #pragma unroll
;                     for (int n = 0; n < 2; ++n) { yv[bj][n] = *(const f32x4*)(Yin + (size_t)row * D_ + col0 + bj * 128 + 4 * n); gq[bj][n] = *(const f32x4*)(g + col0 + bj * 128 + 4 * n); bq_[bj][n] = *(const f32x4*)(b + col0 + bj * 128 + 4 * n); }
.LBB0_1543:
	s_or_b64 exec, exec, s[26:27]
	v_add_u32_e32 v118, 0x80, v158
	v_ashrrev_i32_e32 v119, 31, v118
	v_lshlrev_b64 v[110:111], 7, v[118:119]
	v_lshl_add_u64 v[70:71], v[146:147], 0, v[110:111]
	global_load_dwordx4 v[66:69], v[70:71], off
	s_nop 0
	global_load_dwordx4 v[70:73], v[70:71], off offset:16
	v_add_u32_e32 v108, 0x90, v158
	v_ashrrev_i32_e32 v109, 31, v108
	v_lshlrev_b64 v[102:103], 7, v[108:109]
	v_lshl_add_u64 v[78:79], v[146:147], 0, v[102:103]
	global_load_dwordx4 v[74:77], v[78:79], off
	s_nop 0
	global_load_dwordx4 v[78:81], v[78:79], off offset:16
	v_add_u32_e32 v96, 0xa0, v158
	v_ashrrev_i32_e32 v97, 31, v96
	v_lshlrev_b64 v[82:83], 7, v[96:97]
	v_lshl_add_u64 v[86:87], v[146:147], 0, v[82:83]
	global_load_dwordx4 v[82:85], v[86:87], off
	s_nop 0
	global_load_dwordx4 v[86:89], v[86:87], off offset:16
	v_add_u32_e32 v94, 0xb0, v158
	v_ashrrev_i32_e32 v95, 31, v94
	v_lshlrev_b64 v[90:91], 7, v[94:95]
	v_lshl_add_u64 v[98:99], v[146:147], 0, v[90:91]
	global_load_dwordx4 v[90:93], v[98:99], off
	s_nop 0
	global_load_dwordx4 v[98:101], v[98:99], off offset:16
	s_mov_b32 s2, 0x3a800000
	s_mov_b32 s1, 0x800000
	s_load_dwordx16 s[64:79], s[34:35], 0x38
	s_mov_b32 s14, 0x3fd744fd
	s_waitcnt vmcnt(7)
	v_mov_b32_e32 v104, v66
	s_waitcnt vmcnt(6)
	v_mov_b32_e32 v105, v70
	v_mov_b32_e32 v106, v68
	v_mov_b32_e32 v107, v72
	v_pk_add_f32 v[104:105], v[104:105], v[106:107]
	v_mov_b32_e32 v70, v67
	v_pk_add_f32 v[104:105], v[104:105], v[104:105] op_sel:[0,1] op_sel_hi:[1,0]
	v_mov_b32_e32 v72, v69
	v_pk_add_f32 v[66:67], v[70:71], v[72:73]
	v_mov_b32_e32 v0, v104
	v_pk_add_f32 v[66:67], v[66:67], v[66:67] op_sel:[0,1] op_sel_hi:[1,0]
	s_nop 0
	v_permlane16_swap_b32_e32 v104, v0
	v_add_f32_e32 v67, v104, v0
	v_mov_b32_e32 v0, v66
	s_nop 1
	v_permlane16_swap_b32_e32 v66, v0
	v_add_f32_e32 v66, v66, v0
	v_mov_b32_e32 v69, v67
	v_mov_b32_e32 v68, v66
	s_nop 0
	v_permlane32_swap_b32_e32 v67, v69
	v_permlane32_swap_b32_e32 v66, v68
	v_pk_add_f32 v[66:67], v[66:67], v[68:69]
	s_waitcnt vmcnt(5)
	v_mov_b32_e32 v68, v76
	v_pk_mul_f32 v[116:117], v[66:67], s[2:3] op_sel_hi:[1,0]
	s_waitcnt vmcnt(4)
	v_mov_b32_e32 v67, v78
	v_fma_f32 v0, -v117, v117, v116
	v_max_f32_e32 v0, 0, v0
	v_add_f32_e32 v0, 0x3727c5ac, v0
	v_cmp_gt_f32_e32 vcc, s1, v0
	v_mul_f32_e32 v66, 0x4b800000, v0
	v_mov_b32_e32 v69, v80
	v_cndmask_b32_e32 v0, v0, v66, vcc
	v_rsq_f32_e32 v0, v0
	v_mov_b32_e32 v78, v75
	v_mov_b32_e32 v80, v77
	v_readlane_b32 s2, v253, 59
	v_mul_f32_e32 v66, 0x45800000, v0
	v_cndmask_b32_e32 v116, v0, v66, vcc
	v_mov_b32_e32 v66, v74
	v_pk_add_f32 v[66:67], v[66:67], v[68:69]
	v_pk_add_f32 v[68:69], v[78:79], v[80:81]
	v_pk_add_f32 v[66:67], v[66:67], v[66:67] op_sel:[0,1] op_sel_hi:[1,0]
	v_pk_add_f32 v[68:69], v[68:69], v[68:69] op_sel:[0,1] op_sel_hi:[1,0]
	v_mov_b32_e32 v0, v66
	s_nop 1
	v_permlane16_swap_b32_e32 v66, v0
	v_add_f32_e32 v113, v66, v0
	v_mov_b32_e32 v0, v68
	s_nop 1
	v_permlane16_swap_b32_e32 v68, v0
	v_add_f32_e32 v112, v68, v0
	s_waitcnt vmcnt(3)
	v_mov_b32_e32 v66, v82
	s_waitcnt vmcnt(2)
	v_mov_b32_e32 v67, v86
	v_mov_b32_e32 v68, v84
	v_mov_b32_e32 v69, v88
	v_pk_add_f32 v[66:67], v[66:67], v[68:69]
	v_mov_b32_e32 v86, v83
	v_pk_add_f32 v[66:67], v[66:67], v[66:67] op_sel:[0,1] op_sel_hi:[1,0]
	v_mov_b32_e32 v88, v85
	v_pk_add_f32 v[68:69], v[86:87], v[88:89]
	v_mov_b32_e32 v0, v66
	v_pk_add_f32 v[68:69], v[68:69], v[68:69] op_sel:[0,1] op_sel_hi:[1,0]
	s_nop 0
	v_permlane16_swap_b32_e32 v66, v0
	v_add_f32_e32 v105, v66, v0
	v_mov_b32_e32 v0, v68
	s_nop 1
	v_permlane16_swap_b32_e32 v68, v0
	v_add_f32_e32 v104, v68, v0
	s_waitcnt vmcnt(1)
	v_mov_b32_e32 v66, v90
	s_waitcnt vmcnt(0)
	v_mov_b32_e32 v67, v98
	v_mov_b32_e32 v68, v92
	v_mov_b32_e32 v69, v100
	v_pk_add_f32 v[66:67], v[66:67], v[68:69]
	v_mov_b32_e32 v98, v91
	v_pk_add_f32 v[66:67], v[66:67], v[66:67] op_sel:[0,1] op_sel_hi:[1,0]
	v_mov_b32_e32 v100, v93
	v_mov_b32_e32 v0, v66
	s_nop 1
	v_permlane16_swap_b32_e32 v66, v0
	v_pk_add_f32 v[68:69], v[98:99], v[100:101]
	v_add_f32_e32 v99, v66, v0
	v_ashrrev_i32_e32 v66, 8, v118
	v_ashrrev_i32_e32 v67, 31, v66
	v_pk_add_f32 v[68:69], v[68:69], v[68:69] op_sel:[0,1] op_sel_hi:[1,0]
	v_lshlrev_b64 v[120:121], 19, v[66:67]
	v_lshlrev_b64 v[66:67], 12, v[118:119]
	v_mov_b32_e32 v0, v68
	s_waitcnt lgkmcnt(0)
	v_lshl_add_u64 v[66:67], s[78:79], 0, v[66:67]
	v_permlane16_swap_b32_e32 v68, v0
	v_lshl_add_u64 v[122:123], v[152:153], 2, v[66:67]
	v_add_f32_e32 v98, v68, v0
	global_load_dwordx4 v[74:77], v[122:123], off offset:16
	global_load_dwordx4 v[86:89], v[122:123], off
	global_load_dwordx4 v[66:69], v[156:157], off offset:16
	global_load_dwordx4 v[78:81], v[156:157], off
	global_load_dwordx4 v[70:73], v[154:155], off offset:16
	global_load_dwordx4 v[82:85], v[154:155], off
	global_load_dwordx4 v[90:93], v[122:123], off offset:528
	global_load_dwordx4 v[124:127], v[122:123], off offset:512
	global_load_dwordx4 v[128:131], v[156:157], off offset:528
	global_load_dwordx4 v[132:135], v[156:157], off offset:512
	global_load_dwordx4 v[158:161], v[154:155], off offset:528
	global_load_dwordx4 v[162:165], v[154:155], off offset:512
	v_lshlrev_b32_e32 v0, 6, v118
	s_movk_i32 s1, 0x33c0
	v_readlane_b32 s3, v253, 60
	v_and_or_b32 v0, v0, s1, v196
	v_lshlrev_b32_e32 v0, 1, v0
	v_mov_b32_e32 v115, v113
	v_mov_b32_e32 v114, v112
	v_mov_b32_e32 v107, v105
	v_mov_b32_e32 v106, v104
	v_mov_b32_e32 v101, v99
	v_mov_b32_e32 v100, v98
	v_permlane32_swap_b32_e32 v113, v115
	v_permlane32_swap_b32_e32 v112, v114
	v_permlane32_swap_b32_e32 v105, v107
	v_permlane32_swap_b32_e32 v104, v106
	v_permlane32_swap_b32_e32 v99, v101
	v_permlane32_swap_b32_e32 v98, v100
	s_waitcnt vmcnt(11)
; __device__ __forceinline__ size_t blk_off(int r, int c, int K) { return (size_t)(r >> 8) * 256 * K + (size_t)(c >> 6) * (256 * 64) + (size_t)((r & 255) * 64 + (c & 63)); }
; __device__ __forceinline__ u32x4 pack8(const f32x4 a, const f32x4 b) { u32x4 w; w.x = cvt_pk_bf16(a[0], a[1]); w.y = cvt_pk_bf16(a[2], a[3]); w.z = cvt_pk_bf16(b[0], b[1]); w.w = cvt_pk_bf16(b[2], b[3]); return w; }
;     __device__ __forceinline__ void operator()(const f32x4 (&acc)[2][2][4][2], const pg8::Unit& u, int wr, int wc, int fr, int fq) const {
;     ...
;             for (int m = 0; m < 4; ++m) { const int row = row0 + ai * 128 + m * 16; const float mu = mu4[m], rs = rs4[m];
;                 f32x4 yv[2][2], gq[2][2], bq_[2][2];
; #pragma unroll
;                 for (int bj = 0; bj < 2; ++bj)
; #pragma unroll
;                     for (int n = 0; n < 2; ++n) { yv[bj][n] = *(const f32x4*)(Yin + (size_t)row * D_ + col0 + bj * 128 + 4 * n); gq[bj][n] = *(const f32x4*)(g + col0 + bj * 128 + 4 * n); bq_[bj][n] = *(const f32x4*)(b + col0 + bj * 128 + 4 * n); }
;                 asm volatile("" ::: "memory");
;                 float s1 = 0.f, s2 = 0.f;
; #pragma unroll
;                 for (int bj = 0; bj < 2; ++bj) { float* yp = Y + (size_t)row * D_ + col0 + bj * 128; f32x4 v[2];
; #pragma unroll
;                     for (int n = 0; n < 2; ++n) { v[n] = (((yv[bj][n] - mu) * rs) * gq[bj][n] + bq_[bj][n]) * ALPHA_ + acc[ai][bj][m][n] * sc;
;                         *(f32x4*)(yp + 4 * n) = v[n]; s1 += (v[n][0] + v[n][1]) + (v[n][2] + v[n][3]); s2 += (v[n][0] * v[n][0] + v[n][1] * v[n][1]) + (v[n][2] * v[n][2] + v[n][3] * v[n][3]); }
;                     *(u32x4*)(Yb + blk_off(row, col0 + bj * 128, D_)) = pack8(v[0], v[1]); }
	v_sub_f32_e32 v75, v75, v117
	s_waitcnt vmcnt(10)
	v_sub_f32_e32 v87, v87, v117
	v_sub_f32_e32 v86, v86, v117
	v_sub_f32_e32 v89, v89, v117
	v_sub_f32_e32 v88, v88, v117
	v_sub_f32_e32 v74, v74, v117
	v_sub_f32_e32 v77, v77, v117
	v_sub_f32_e32 v76, v76, v117
	v_pk_mul_f32 v[88:89], v[116:117], v[88:89] op_sel_hi:[0,1]
	v_pk_mul_f32 v[86:87], v[116:117], v[86:87] op_sel_hi:[0,1]
	v_pk_mul_f32 v[76:77], v[116:117], v[76:77] op_sel_hi:[0,1]
	v_pk_mul_f32 v[74:75], v[116:117], v[74:75] op_sel_hi:[0,1]
	s_waitcnt vmcnt(6)
	v_pk_fma_f32 v[78:79], v[78:79], v[86:87], v[82:83]
	v_pk_fma_f32 v[80:81], v[80:81], v[88:89], v[84:85]
	v_pk_fma_f32 v[66:67], v[66:67], v[74:75], v[70:71]
	v_pk_fma_f32 v[68:69], v[68:69], v[76:77], v[72:73]
	v_pk_fma_f32 v[64:65], v[80:81], s[14:15], v[64:65] op_sel_hi:[1,0,1]
	v_pk_fma_f32 v[62:63], v[78:79], s[14:15], v[62:63] op_sel_hi:[1,0,1]
	v_pk_fma_f32 v[60:61], v[68:69], s[14:15], v[60:61] op_sel_hi:[1,0,1]
	v_pk_fma_f32 v[58:59], v[66:67], s[14:15], v[58:59] op_sel_hi:[1,0,1]
	v_add_f32_e32 v78, v62, v63
	v_add_f32_e32 v79, v64, v65
	v_add_f32_e32 v66, v58, v59
	v_add_f32_e32 v67, v60, v61
	v_add_f32_e32 v78, v78, v79
	v_mul_f32_e32 v79, v63, v63
	v_mul_f32_e32 v80, v65, v65
	v_add_f32_e32 v66, v66, v67
	v_mul_f32_e32 v67, v59, v59
	s_nop 0
	v_fmac_f32_e32 v79, v62, v62
	v_fmac_f32_e32 v80, v64, v64
	s_nop 1
	v_bfe_u32 v69, v227, 4, 2
	v_sub_u32_e32 v68, 0, v69
	v_lshlrev_b32_e32 v68, 4, v68
	v_ashrrev_i32_e32 v69, 31, v68
	v_lshl_add_u64 v[68:69], v[122:123], 0, v[68:69]
	v_permlane16_swap_b32_e32 v62, v58
	v_permlane16_swap_b32_e32 v63, v59
	v_permlane16_swap_b32_e32 v64, v60
	v_permlane16_swap_b32_e32 v65, v61
	v_permlane32_swap_b32_e32 v62, v58
	v_permlane32_swap_b32_e32 v63, v59
	v_permlane32_swap_b32_e32 v64, v60
	v_permlane32_swap_b32_e32 v65, v61
	v_mov_b32_e32 v72, v62
	v_mov_b32_e32 v73, v63
	v_mov_b32_e32 v74, v64
	v_mov_b32_e32 v75, v65
	v_bfe_u32 v70, v227, 3, 1
	v_mul_i32_i24_e32 v70, 0xffff8040, v70
	v_ashrrev_i32_e32 v71, 31, v70
	v_lshl_add_u64 v[68:69], v[68:69], 0, v[70:71]
	v_mov_b32_e32 v70, 0x8000
	v_mov_b32_e32 v71, 0
	v_lshl_add_u64 v[70:71], v[68:69], 0, v[70:71]
	v_mov_b32_dpp v62, v58 row_ror:8 row_mask:0xf bank_mask:0xc
	v_mov_b32_dpp v63, v59 row_ror:8 row_mask:0xf bank_mask:0xc
	v_mov_b32_dpp v64, v60 row_ror:8 row_mask:0xf bank_mask:0xc
	v_mov_b32_dpp v65, v61 row_ror:8 row_mask:0xf bank_mask:0xc
	v_mov_b32_dpp v58, v72 row_ror:8 row_mask:0xf bank_mask:0x3
	v_mov_b32_dpp v59, v73 row_ror:8 row_mask:0xf bank_mask:0x3
	v_mov_b32_dpp v60, v74 row_ror:8 row_mask:0xf bank_mask:0x3
	v_mov_b32_dpp v61, v75 row_ror:8 row_mask:0xf bank_mask:0x3
	global_store_dwordx4 v[68:69], v[62:65], off
	global_store_dwordx4 v[70:71], v[58:61], off
	s_nop 1
	v_mov_b32_dpp v58, v62 row_ror:8 row_mask:0xf bank_mask:0x3
	v_mov_b32_dpp v59, v63 row_ror:8 row_mask:0xf bank_mask:0x3
	v_mov_b32_dpp v60, v64 row_ror:8 row_mask:0xf bank_mask:0x3
	v_mov_b32_dpp v61, v65 row_ror:8 row_mask:0xf bank_mask:0x3
	v_mov_b32_e32 v62, v72
	v_mov_b32_e32 v63, v73
	v_mov_b32_e32 v64, v74
	v_mov_b32_e32 v65, v75
	s_nop 1
	v_permlane32_swap_b32_e32 v62, v58
	v_permlane32_swap_b32_e32 v63, v59
	v_permlane32_swap_b32_e32 v64, v60
	v_permlane32_swap_b32_e32 v65, v61
	v_permlane16_swap_b32_e32 v62, v58
	v_permlane16_swap_b32_e32 v63, v59
	v_permlane16_swap_b32_e32 v64, v60
	v_permlane16_swap_b32_e32 v65, v61
	v_fmac_f32_e32 v67, v58, v58
	v_cvt_pk_bf16_f32 v62, v62, v63
	v_cvt_pk_bf16_f32 v63, v64, v65
	v_cvt_pk_bf16_f32 v64, v58, v59
	v_lshl_add_u64 v[58:59], s[2:3], 0, v[120:121]
	v_mul_f32_e32 v68, v61, v61
	v_lshl_add_u64 v[76:77], v[58:59], 0, s[24:25]
	v_fmac_f32_e32 v68, v60, v60
	v_cvt_pk_bf16_f32 v65, v60, v61
	v_lshl_add_u64 v[60:61], v[76:77], 0, v[0:1]
	global_store_dwordx4 v[60:61], v[62:65], off
	s_waitcnt vmcnt(7)
	v_sub_f32_e32 v61, v125, v117
	v_sub_f32_e32 v60, v124, v117
	v_sub_f32_e32 v63, v127, v117
	v_sub_f32_e32 v62, v126, v117
	v_pk_mul_f32 v[62:63], v[116:117], v[62:63] op_sel_hi:[0,1]
	v_pk_mul_f32 v[60:61], v[116:117], v[60:61] op_sel_hi:[0,1]
	s_waitcnt vmcnt(3)
	v_pk_fma_f32 v[60:61], v[132:133], v[60:61], v[162:163]
	v_pk_fma_f32 v[62:63], v[134:135], v[62:63], v[164:165]
	v_pk_fma_f32 v[54:55], v[60:61], s[14:15], v[54:55] op_sel_hi:[1,0,1]
	v_pk_fma_f32 v[56:57], v[62:63], s[14:15], v[56:57] op_sel_hi:[1,0,1]
	v_add_f32_e32 v78, 0, v78
	v_add_f32_e32 v60, v54, v55
	v_add_f32_e32 v61, v56, v57
	v_add_f32_e32 v66, v78, v66
	v_add_f32_e32 v60, v60, v61
	v_add_f32_e32 v64, v66, v60
	v_mul_f32_e32 v60, v55, v55
	v_mul_f32_e32 v61, v57, v57
	v_add_f32_e32 v79, v79, v80
	v_add_f32_e32 v67, v67, v68
	v_fmac_f32_e32 v60, v54, v54
	v_fmac_f32_e32 v61, v56, v56
	v_add_f32_e32 v67, v79, v67
	v_add_f32_e32 v60, v60, v61
	v_add_f32_e32 v65, v67, v60
	v_sub_f32_e32 v61, v91, v117
	v_sub_f32_e32 v60, v90, v117
	v_sub_f32_e32 v63, v93, v117
	v_sub_f32_e32 v62, v92, v117
	v_pk_mul_f32 v[62:63], v[116:117], v[62:63] op_sel_hi:[0,1]
	v_pk_mul_f32 v[60:61], v[116:117], v[60:61] op_sel_hi:[0,1]
	v_pk_fma_f32 v[60:61], v[128:129], v[60:61], v[158:159]
	v_pk_fma_f32 v[62:63], v[130:131], v[62:63], v[160:161]
	v_pk_fma_f32 v[50:51], v[60:61], s[14:15], v[50:51] op_sel_hi:[1,0,1]
	v_pk_fma_f32 v[52:53], v[62:63], s[14:15], v[52:53] op_sel_hi:[1,0,1]
	v_add_f32_e32 v60, v50, v51
	v_add_f32_e32 v61, v52, v53
	v_add_f32_e32 v60, v60, v61
	v_mul_f32_e32 v61, v51, v51
	v_mul_f32_e32 v62, v53, v53
	v_add_f32_e32 v60, v64, v60
	v_fmac_f32_e32 v61, v50, v50
	v_fmac_f32_e32 v62, v52, v52
	v_lshl_add_u64 v[74:75], v[58:59], 0, s[28:29]
	s_nop 0
	s_nop 1
	v_bfe_u32 v67, v227, 4, 2
	v_sub_u32_e32 v66, 0, v67
	v_lshlrev_b32_e32 v66, 4, v66
; __device__ __forceinline__ float xsum16(float v) { const auto r = __builtin_amdgcn_permlane16_swap(__float_as_uint(v), __float_as_uint(v), false, false); return __uint_as_float(r[0]) + __uint_as_float(r[1]); }
; __device__ __forceinline__ float xsum32(float v) { const auto r = __builtin_amdgcn_permlane32_swap(__float_as_uint(v), __float_as_uint(v), false, false); return __uint_as_float(r[0]) + __uint_as_float(r[1]); }
; __device__ __forceinline__ size_t blk_off(int r, int c, int K) { return (size_t)(r >> 8) * 256 * K + (size_t)(c >> 6) * (256 * 64) + (size_t)((r & 255) * 64 + (c & 63)); }
; __device__ __forceinline__ u32x4 pack8(const f32x4 a, const f32x4 b) { u32x4 w; w.x = cvt_pk_bf16(a[0], a[1]); w.y = cvt_pk_bf16(a[2], a[3]); w.z = cvt_pk_bf16(b[0], b[1]); w.w = cvt_pk_bf16(b[2], b[3]); return w; }
;     __device__ __forceinline__ void operator()(const f32x4 (&acc)[2][2][4][2], const pg8::Unit& u, int wr, int wc, int fr, int fq) const {
;     ...
;             for (int m = 0; m < 4; ++m) { const int row = row0 + ai * 128 + m * 16; const float mu = mu4[m], rs = rs4[m];
;                 f32x4 yv[2][2], gq[2][2], bq_[2][2];
; #pragma unroll
;                 for (int bj = 0; bj < 2; ++bj)
; #pragma unroll
;                     for (int n = 0; n < 2; ++n) { yv[bj][n] = *(const f32x4*)(Yin + (size_t)row * D_ + col0 + bj * 128 + 4 * n); gq[bj][n] = *(const f32x4*)(g + col0 + bj * 128 + 4 * n); bq_[bj][n] = *(const f32x4*)(b + col0 + bj * 128 + 4 * n); }
;                 asm volatile("" ::: "memory");
;                 float s1 = 0.f, s2 = 0.f;
; #pragma unroll
;                 for (int bj = 0; bj < 2; ++bj) { float* yp = Y + (size_t)row * D_ + col0 + bj * 128; f32x4 v[2];
; #pragma unroll
;                     for (int n = 0; n < 2; ++n) { v[n] = (((yv[bj][n] - mu) * rs) * gq[bj][n] + bq_[bj][n]) * ALPHA_ + acc[ai][bj][m][n] * sc;
;                         *(f32x4*)(yp + 4 * n) = v[n]; s1 += (v[n][0] + v[n][1]) + (v[n][2] + v[n][3]); s2 += (v[n][0] * v[n][0] + v[n][1] * v[n][1]) + (v[n][2] * v[n][2] + v[n][3] * v[n][3]); }
;                     *(u32x4*)(Yb + blk_off(row, col0 + bj * 128, D_)) = pack8(v[0], v[1]); }
;                 s1 = xsum32(xsum16(s1)); s2 = xsum32(xsum16(s2));
;                 if (fq == 0) *(f32x2*)(stn + (size_t)row * 32 + (u.pn * 4 + wc) * 2) = (f32x2){s1, s2}; asm volatile("" ::: "memory"); } }
	v_ashrrev_i32_e32 v67, 31, v66
	v_lshl_add_u64 v[66:67], v[122:123], 0, v[66:67]
	v_permlane16_swap_b32_e32 v54, v50
	v_permlane16_swap_b32_e32 v55, v51
	v_permlane16_swap_b32_e32 v56, v52
	v_permlane16_swap_b32_e32 v57, v53
	v_permlane32_swap_b32_e32 v54, v50
	v_permlane32_swap_b32_e32 v55, v51
	v_permlane32_swap_b32_e32 v56, v52
	v_permlane32_swap_b32_e32 v57, v53
	v_mov_b32_e32 v63, v54
	v_mov_b32_e32 v64, v55
	v_mov_b32_e32 v70, v56
	v_mov_b32_e32 v71, v57
	v_bfe_u32 v68, v227, 3, 1
	v_mul_i32_i24_e32 v68, 0xffff8040, v68
	v_ashrrev_i32_e32 v69, 31, v68
	v_lshl_add_u64 v[66:67], v[66:67], 0, v[68:69]
	v_mov_b32_e32 v68, 0x8000
	v_mov_b32_e32 v69, 0
	v_lshl_add_u64 v[68:69], v[66:67], 0, v[68:69]
	v_mov_b32_dpp v54, v50 row_ror:8 row_mask:0xf bank_mask:0xc
	v_mov_b32_dpp v55, v51 row_ror:8 row_mask:0xf bank_mask:0xc
	v_mov_b32_dpp v56, v52 row_ror:8 row_mask:0xf bank_mask:0xc
	v_mov_b32_dpp v57, v53 row_ror:8 row_mask:0xf bank_mask:0xc
	v_mov_b32_dpp v50, v63 row_ror:8 row_mask:0xf bank_mask:0x3
	v_mov_b32_dpp v51, v64 row_ror:8 row_mask:0xf bank_mask:0x3
	v_mov_b32_dpp v52, v70 row_ror:8 row_mask:0xf bank_mask:0x3
	v_mov_b32_dpp v53, v71 row_ror:8 row_mask:0xf bank_mask:0x3
	global_store_dwordx4 v[66:67], v[54:57], off offset:512
	global_store_dwordx4 v[68:69], v[50:53], off offset:512
	s_nop 1
	v_mov_b32_dpp v50, v54 row_ror:8 row_mask:0xf bank_mask:0x3
	v_mov_b32_dpp v51, v55 row_ror:8 row_mask:0xf bank_mask:0x3
	v_mov_b32_dpp v52, v56 row_ror:8 row_mask:0xf bank_mask:0x3
	v_mov_b32_dpp v53, v57 row_ror:8 row_mask:0xf bank_mask:0x3
	v_mov_b32_e32 v54, v63
	v_mov_b32_e32 v55, v64
	v_mov_b32_e32 v56, v70
	v_mov_b32_e32 v57, v71
	s_nop 1
	v_permlane32_swap_b32_e32 v54, v50
	v_permlane32_swap_b32_e32 v55, v51
	v_permlane32_swap_b32_e32 v56, v52
	v_permlane32_swap_b32_e32 v57, v53
	v_permlane16_swap_b32_e32 v54, v50
	v_permlane16_swap_b32_e32 v55, v51
	v_permlane16_swap_b32_e32 v56, v52
	v_permlane16_swap_b32_e32 v57, v53
	v_add_f32_e32 v61, v61, v62
	v_cvt_pk_bf16_f32 v54, v54, v55
	v_cvt_pk_bf16_f32 v55, v56, v57
	v_cvt_pk_bf16_f32 v56, v50, v51
	v_lshl_add_u64 v[50:51], v[74:75], 0, v[0:1]
	v_mov_b32_e32 v0, v60
	v_add_f32_e32 v61, v65, v61
	v_cvt_pk_bf16_f32 v57, v52, v53
	v_permlane16_swap_b32_e32 v60, v0
	global_store_dwordx4 v[50:51], v[54:57], off
	v_add_f32_e32 v50, v60, v0
	v_mov_b32_e32 v0, v61
	s_nop 1
	v_permlane16_swap_b32_e32 v61, v0
	v_add_f32_e32 v51, v61, v0
	v_mov_b32_e32 v52, v50
	v_mov_b32_e32 v53, v51
	s_nop 0
	v_permlane32_swap_b32_e32 v50, v52
	v_permlane32_swap_b32_e32 v51, v53
	s_and_saveexec_b64 s[24:25], s[44:45]
	s_cbranch_execz .LBB0_1545
	v_pk_add_f32 v[50:51], v[50:51], v[52:53]
	v_lshl_add_u64 v[52:53], s[6:7], 0, v[110:111]
	v_lshl_add_u64 v[52:53], s[52:53], 2, v[52:53]
	global_store_dwordx2 v[52:53], v[50:51], off
.LBB0_1545:
	s_or_b64 exec, exec, s[24:25]
	v_pk_add_f32 v[50:51], v[112:113], v[114:115]
	s_mov_b32 s2, 0x3a800000
	v_pk_mul_f32 v[78:79], v[50:51], s[2:3] op_sel_hi:[1,0]
	s_mov_b32 s1, 0x800000
	v_fma_f32 v0, -v79, v79, v78
	v_max_f32_e32 v0, 0, v0
	v_add_f32_e32 v0, 0x3727c5ac, v0
	v_cmp_gt_f32_e32 vcc, s1, v0
	v_mul_f32_e32 v50, 0x4b800000, v0
	s_load_dwordx16 s[64:79], s[34:35], 0x38
	v_cndmask_b32_e32 v0, v0, v50, vcc
	v_rsq_f32_e32 v0, v0
	s_mov_b32 s2, 0x3fd744fd
	s_movk_i32 s1, 0x37c0
	v_mul_f32_e32 v50, 0x45800000, v0
	v_cndmask_b32_e32 v78, v0, v50, vcc
	v_lshlrev_b64 v[50:51], 12, v[108:109]
	s_waitcnt lgkmcnt(0)
	v_lshl_add_u64 v[50:51], s[78:79], 0, v[50:51]
	v_lshl_add_u64 v[80:81], v[152:153], 2, v[50:51]
	global_load_dwordx4 v[82:85], v[80:81], off offset:16
	global_load_dwordx4 v[86:89], v[80:81], off
	global_load_dwordx4 v[90:93], v[156:157], off offset:16
	global_load_dwordx4 v[110:113], v[156:157], off
	global_load_dwordx4 v[114:117], v[154:155], off offset:16
	global_load_dwordx4 v[118:121], v[154:155], off
	global_load_dwordx4 v[50:53], v[80:81], off offset:528
	global_load_dwordx4 v[70:73], v[80:81], off offset:512
	global_load_dwordx4 v[54:57], v[156:157], off offset:528
	global_load_dwordx4 v[62:65], v[156:157], off offset:512
	global_load_dwordx4 v[58:61], v[154:155], off offset:528
	global_load_dwordx4 v[66:69], v[154:155], off offset:512
	v_lshlrev_b32_e32 v0, 6, v108
	v_and_or_b32 v0, v0, s1, v196
	v_lshlrev_b32_e32 v0, 1, v0
	s_waitcnt vmcnt(10)
	v_sub_f32_e32 v87, v87, v79
	v_sub_f32_e32 v86, v86, v79
	v_sub_f32_e32 v89, v89, v79
	v_sub_f32_e32 v88, v88, v79
	v_pk_mul_f32 v[88:89], v[78:79], v[88:89] op_sel_hi:[0,1]
	v_pk_mul_f32 v[86:87], v[78:79], v[86:87] op_sel_hi:[0,1]
	s_waitcnt vmcnt(6)
; __device__ __forceinline__ size_t blk_off(int r, int c, int K) { return (size_t)(r >> 8) * 256 * K + (size_t)(c >> 6) * (256 * 64) + (size_t)((r & 255) * 64 + (c & 63)); }
; __device__ __forceinline__ u32x4 pack8(const f32x4 a, const f32x4 b) { u32x4 w; w.x = cvt_pk_bf16(a[0], a[1]); w.y = cvt_pk_bf16(a[2], a[3]); w.z = cvt_pk_bf16(b[0], b[1]); w.w = cvt_pk_bf16(b[2], b[3]); return w; }
;     __device__ __forceinline__ void operator()(const f32x4 (&acc)[2][2][4][2], const pg8::Unit& u, int wr, int wc, int fr, int fq) const {
;     ...
;                 for (int bj = 0; bj < 2; ++bj) { float* yp = Y + (size_t)row * D_ + col0 + bj * 128; f32x4 v[2];
; #pragma unroll
;                     for (int n = 0; n < 2; ++n) { v[n] = (((yv[bj][n] - mu) * rs) * gq[bj][n] + bq_[bj][n]) * ALPHA_ + acc[ai][bj][m][n] * sc;
;                         *(f32x4*)(yp + 4 * n) = v[n]; s1 += (v[n][0] + v[n][1]) + (v[n][2] + v[n][3]); s2 += (v[n][0] * v[n][0] + v[n][1] * v[n][1]) + (v[n][2] * v[n][2] + v[n][3] * v[n][3]); }
;                     *(u32x4*)(Yb + blk_off(row, col0 + bj * 128, D_)) = pack8(v[0], v[1]); }
	v_pk_fma_f32 v[86:87], v[110:111], v[86:87], v[118:119]
	v_pk_fma_f32 v[88:89], v[112:113], v[88:89], v[120:121]
	v_pk_fma_f32 v[86:87], v[86:87], s[2:3], v[46:47] op_sel_hi:[1,0,1]
	v_pk_fma_f32 v[88:89], v[88:89], s[2:3], v[48:49] op_sel_hi:[1,0,1]
	v_add_f32_e32 v46, v86, v87
	v_add_f32_e32 v47, v88, v89
	v_add_f32_e32 v46, v46, v47
	v_add_f32_e32 v108, 0, v46
	v_mul_f32_e32 v46, v87, v87
	v_mul_f32_e32 v47, v89, v89
	v_fmac_f32_e32 v46, v86, v86
	v_fmac_f32_e32 v47, v88, v88
	v_add_f32_e32 v109, v46, v47
	v_sub_f32_e32 v47, v83, v79
	v_sub_f32_e32 v46, v82, v79
	v_sub_f32_e32 v49, v85, v79
	v_sub_f32_e32 v48, v84, v79
	v_pk_mul_f32 v[48:49], v[78:79], v[48:49] op_sel_hi:[0,1]
	v_pk_mul_f32 v[46:47], v[78:79], v[46:47] op_sel_hi:[0,1]
	v_pk_fma_f32 v[46:47], v[90:91], v[46:47], v[114:115]
	v_pk_fma_f32 v[48:49], v[92:93], v[48:49], v[116:117]
	v_pk_fma_f32 v[82:83], v[46:47], s[2:3], v[42:43] op_sel_hi:[1,0,1]
	v_pk_fma_f32 v[84:85], v[48:49], s[2:3], v[44:45] op_sel_hi:[1,0,1]
	v_add_f32_e32 v42, v82, v83
	v_add_f32_e32 v43, v84, v85
	v_add_f32_e32 v42, v42, v43
	v_add_f32_e32 v47, v108, v42
	v_mul_f32_e32 v42, v83, v83
	v_mul_f32_e32 v43, v85, v85
	v_fmac_f32_e32 v42, v82, v82
	v_fmac_f32_e32 v43, v84, v84
	v_add_f32_e32 v42, v42, v43
	v_add_f32_e32 v46, v109, v42
	v_cvt_pk_bf16_f32 v42, v86, v87
	v_cvt_pk_bf16_f32 v43, v88, v89
	v_cvt_pk_bf16_f32 v44, v82, v83
	v_cvt_pk_bf16_f32 v45, v84, v85
	v_lshl_add_u64 v[48:49], v[76:77], 0, v[0:1]
	s_nop 0
	s_nop 1
	v_bfe_u32 v91, v227, 4, 2
	v_sub_u32_e32 v90, 0, v91
	v_lshlrev_b32_e32 v90, 4, v90
	v_ashrrev_i32_e32 v91, 31, v90
	v_lshl_add_u64 v[90:91], v[80:81], 0, v[90:91]
	v_permlane16_swap_b32_e32 v86, v82
	v_permlane16_swap_b32_e32 v87, v83
	v_permlane16_swap_b32_e32 v88, v84
	v_permlane16_swap_b32_e32 v89, v85
	v_permlane32_swap_b32_e32 v86, v82
	v_permlane32_swap_b32_e32 v87, v83
	v_permlane32_swap_b32_e32 v88, v84
	v_permlane32_swap_b32_e32 v89, v85
	v_mov_b32_e32 v108, v86
	v_mov_b32_e32 v109, v87
	v_mov_b32_e32 v110, v88
	v_mov_b32_e32 v111, v89
	v_bfe_u32 v92, v227, 3, 1
	v_mul_i32_i24_e32 v92, 0xffff8040, v92
	v_ashrrev_i32_e32 v93, 31, v92
	v_lshl_add_u64 v[90:91], v[90:91], 0, v[92:93]
	v_mov_b32_e32 v92, 0x8000
	v_mov_b32_e32 v93, 0
	v_lshl_add_u64 v[92:93], v[90:91], 0, v[92:93]
	v_mov_b32_dpp v86, v82 row_ror:8 row_mask:0xf bank_mask:0xc
	v_mov_b32_dpp v87, v83 row_ror:8 row_mask:0xf bank_mask:0xc
	v_mov_b32_dpp v88, v84 row_ror:8 row_mask:0xf bank_mask:0xc
	v_mov_b32_dpp v89, v85 row_ror:8 row_mask:0xf bank_mask:0xc
	v_mov_b32_dpp v82, v108 row_ror:8 row_mask:0xf bank_mask:0x3
	v_mov_b32_dpp v83, v109 row_ror:8 row_mask:0xf bank_mask:0x3
	v_mov_b32_dpp v84, v110 row_ror:8 row_mask:0xf bank_mask:0x3
	v_mov_b32_dpp v85, v111 row_ror:8 row_mask:0xf bank_mask:0x3
	global_store_dwordx4 v[90:91], v[86:89], off
	global_store_dwordx4 v[92:93], v[82:85], off
	s_nop 1
	v_mov_b32_dpp v82, v86 row_ror:8 row_mask:0xf bank_mask:0x3
	v_mov_b32_dpp v83, v87 row_ror:8 row_mask:0xf bank_mask:0x3
	v_mov_b32_dpp v84, v88 row_ror:8 row_mask:0xf bank_mask:0x3
	v_mov_b32_dpp v85, v89 row_ror:8 row_mask:0xf bank_mask:0x3
	v_mov_b32_e32 v86, v108
	v_mov_b32_e32 v87, v109
	v_mov_b32_e32 v88, v110
	v_mov_b32_e32 v89, v111
	s_nop 1
	v_permlane32_swap_b32_e32 v86, v82
	v_permlane32_swap_b32_e32 v87, v83
	v_permlane32_swap_b32_e32 v88, v84
	v_permlane32_swap_b32_e32 v89, v85
	v_permlane16_swap_b32_e32 v86, v82
	v_permlane16_swap_b32_e32 v87, v83
	v_permlane16_swap_b32_e32 v88, v84
	v_permlane16_swap_b32_e32 v89, v85
	global_store_dwordx4 v[48:49], v[42:45], off
	s_waitcnt vmcnt(7)
	s_nop 0
	v_sub_f32_e32 v43, v71, v79
	v_sub_f32_e32 v42, v70, v79
	v_sub_f32_e32 v45, v73, v79
	v_sub_f32_e32 v44, v72, v79
	v_pk_mul_f32 v[44:45], v[78:79], v[44:45] op_sel_hi:[0,1]
	v_pk_mul_f32 v[42:43], v[78:79], v[42:43] op_sel_hi:[0,1]
	s_waitcnt vmcnt(3)
	v_pk_fma_f32 v[42:43], v[62:63], v[42:43], v[66:67]
	v_pk_fma_f32 v[44:45], v[64:65], v[44:45], v[68:69]
	v_pk_fma_f32 v[38:39], v[42:43], s[2:3], v[38:39] op_sel_hi:[1,0,1]
	v_pk_fma_f32 v[40:41], v[44:45], s[2:3], v[40:41] op_sel_hi:[1,0,1]
	v_add_f32_e32 v42, v38, v39
	v_add_f32_e32 v43, v40, v41
	v_add_f32_e32 v42, v42, v43
	v_add_f32_e32 v47, v47, v42
	v_mul_f32_e32 v42, v39, v39
	v_mul_f32_e32 v43, v41, v41
	v_fmac_f32_e32 v42, v38, v38
	v_fmac_f32_e32 v43, v40, v40
	v_add_f32_e32 v42, v42, v43
	v_add_f32_e32 v46, v46, v42
	v_sub_f32_e32 v43, v51, v79
	v_sub_f32_e32 v42, v50, v79
	v_sub_f32_e32 v45, v53, v79
	v_sub_f32_e32 v44, v52, v79
	v_pk_mul_f32 v[44:45], v[78:79], v[44:45] op_sel_hi:[0,1]
	v_pk_mul_f32 v[42:43], v[78:79], v[42:43] op_sel_hi:[0,1]
	v_pk_fma_f32 v[42:43], v[54:55], v[42:43], v[58:59]
	v_pk_fma_f32 v[44:45], v[56:57], v[44:45], v[60:61]
	v_pk_fma_f32 v[34:35], v[42:43], s[2:3], v[34:35] op_sel_hi:[1,0,1]
	v_pk_fma_f32 v[36:37], v[44:45], s[2:3], v[36:37] op_sel_hi:[1,0,1]
	v_add_f32_e32 v42, v34, v35
	v_add_f32_e32 v43, v36, v37
	v_add_f32_e32 v42, v42, v43
	v_mul_f32_e32 v43, v35, v35
	v_mul_f32_e32 v44, v37, v37
	v_add_f32_e32 v42, v47, v42
	v_fmac_f32_e32 v43, v34, v34
	v_fmac_f32_e32 v44, v36, v36
	s_nop 0
	s_nop 1
	v_bfe_u32 v49, v227, 4, 2
	v_sub_u32_e32 v48, 0, v49
	v_lshlrev_b32_e32 v48, 4, v48
	v_ashrrev_i32_e32 v49, 31, v48
	v_lshl_add_u64 v[48:49], v[80:81], 0, v[48:49]
	v_permlane16_swap_b32_e32 v38, v34
	v_permlane16_swap_b32_e32 v39, v35
	v_permlane16_swap_b32_e32 v40, v36
	v_permlane16_swap_b32_e32 v41, v37
	v_permlane32_swap_b32_e32 v38, v34
	v_permlane32_swap_b32_e32 v39, v35
	v_permlane32_swap_b32_e32 v40, v36
	v_permlane32_swap_b32_e32 v41, v37
	v_mov_b32_e32 v45, v38
	v_mov_b32_e32 v52, v39
	v_mov_b32_e32 v53, v40
; __device__ __forceinline__ float xsum16(float v) { const auto r = __builtin_amdgcn_permlane16_swap(__float_as_uint(v), __float_as_uint(v), false, false); return __uint_as_float(r[0]) + __uint_as_float(r[1]); }
; __device__ __forceinline__ float xsum32(float v) { const auto r = __builtin_amdgcn_permlane32_swap(__float_as_uint(v), __float_as_uint(v), false, false); return __uint_as_float(r[0]) + __uint_as_float(r[1]); }
; __device__ __forceinline__ size_t blk_off(int r, int c, int K) { return (size_t)(r >> 8) * 256 * K + (size_t)(c >> 6) * (256 * 64) + (size_t)((r & 255) * 64 + (c & 63)); }
; __device__ __forceinline__ u32x4 pack8(const f32x4 a, const f32x4 b) { u32x4 w; w.x = cvt_pk_bf16(a[0], a[1]); w.y = cvt_pk_bf16(a[2], a[3]); w.z = cvt_pk_bf16(b[0], b[1]); w.w = cvt_pk_bf16(b[2], b[3]); return w; }
;     __device__ __forceinline__ void operator()(const f32x4 (&acc)[2][2][4][2], const pg8::Unit& u, int wr, int wc, int fr, int fq) const {
;     ...
;             for (int m = 0; m < 4; ++m) { const int row = row0 + ai * 128 + m * 16; const float mu = mu4[m], rs = rs4[m];
;                 f32x4 yv[2][2], gq[2][2], bq_[2][2];
; #pragma unroll
;                 for (int bj = 0; bj < 2; ++bj)
; #pragma unroll
;                     for (int n = 0; n < 2; ++n) { yv[bj][n] = *(const f32x4*)(Yin + (size_t)row * D_ + col0 + bj * 128 + 4 * n); gq[bj][n] = *(const f32x4*)(g + col0 + bj * 128 + 4 * n); bq_[bj][n] = *(const f32x4*)(b + col0 + bj * 128 + 4 * n); }
;                 asm volatile("" ::: "memory");
;                 float s1 = 0.f, s2 = 0.f;
; #pragma unroll
;                 for (int bj = 0; bj < 2; ++bj) { float* yp = Y + (size_t)row * D_ + col0 + bj * 128; f32x4 v[2];
; #pragma unroll
;                     for (int n = 0; n < 2; ++n) { v[n] = (((yv[bj][n] - mu) * rs) * gq[bj][n] + bq_[bj][n]) * ALPHA_ + acc[ai][bj][m][n] * sc;
;                         *(f32x4*)(yp + 4 * n) = v[n]; s1 += (v[n][0] + v[n][1]) + (v[n][2] + v[n][3]); s2 += (v[n][0] * v[n][0] + v[n][1] * v[n][1]) + (v[n][2] * v[n][2] + v[n][3] * v[n][3]); }
;                     *(u32x4*)(Yb + blk_off(row, col0 + bj * 128, D_)) = pack8(v[0], v[1]); }
;                 s1 = xsum32(xsum16(s1)); s2 = xsum32(xsum16(s2));
;                 if (fq == 0) *(f32x2*)(stn + (size_t)row * 32 + (u.pn * 4 + wc) * 2) = (f32x2){s1, s2}; asm volatile("" ::: "memory"); } }
	v_mov_b32_e32 v54, v41
	v_bfe_u32 v50, v227, 3, 1
	v_mul_i32_i24_e32 v50, 0xffff8040, v50
	v_ashrrev_i32_e32 v51, 31, v50
	v_lshl_add_u64 v[48:49], v[48:49], 0, v[50:51]
	v_mov_b32_e32 v50, 0x8000
	v_mov_b32_e32 v51, 0
	v_lshl_add_u64 v[50:51], v[48:49], 0, v[50:51]
	v_mov_b32_dpp v38, v34 row_ror:8 row_mask:0xf bank_mask:0xc
	v_mov_b32_dpp v39, v35 row_ror:8 row_mask:0xf bank_mask:0xc
	v_mov_b32_dpp v40, v36 row_ror:8 row_mask:0xf bank_mask:0xc
	v_mov_b32_dpp v41, v37 row_ror:8 row_mask:0xf bank_mask:0xc
	v_mov_b32_dpp v34, v45 row_ror:8 row_mask:0xf bank_mask:0x3
	v_mov_b32_dpp v35, v52 row_ror:8 row_mask:0xf bank_mask:0x3
	v_mov_b32_dpp v36, v53 row_ror:8 row_mask:0xf bank_mask:0x3
	v_mov_b32_dpp v37, v54 row_ror:8 row_mask:0xf bank_mask:0x3
	global_store_dwordx4 v[48:49], v[38:41], off offset:512
	global_store_dwordx4 v[50:51], v[34:37], off offset:512
	s_nop 1
	v_mov_b32_dpp v34, v38 row_ror:8 row_mask:0xf bank_mask:0x3
	v_mov_b32_dpp v35, v39 row_ror:8 row_mask:0xf bank_mask:0x3
	v_mov_b32_dpp v36, v40 row_ror:8 row_mask:0xf bank_mask:0x3
	v_mov_b32_dpp v37, v41 row_ror:8 row_mask:0xf bank_mask:0x3
	v_mov_b32_e32 v38, v45
	v_mov_b32_e32 v39, v52
	v_mov_b32_e32 v40, v53
	v_mov_b32_e32 v41, v54
	s_nop 1
	v_permlane32_swap_b32_e32 v38, v34
	v_permlane32_swap_b32_e32 v39, v35
	v_permlane32_swap_b32_e32 v40, v36
	v_permlane32_swap_b32_e32 v41, v37
	v_permlane16_swap_b32_e32 v38, v34
	v_permlane16_swap_b32_e32 v39, v35
	v_permlane16_swap_b32_e32 v40, v36
	v_permlane16_swap_b32_e32 v41, v37
	v_add_f32_e32 v43, v43, v44
	v_cvt_pk_bf16_f32 v38, v38, v39
	v_cvt_pk_bf16_f32 v39, v40, v41
	v_cvt_pk_bf16_f32 v40, v34, v35
	v_lshl_add_u64 v[34:35], v[74:75], 0, v[0:1]
	v_mov_b32_e32 v0, v42
	v_add_f32_e32 v43, v46, v43
	v_cvt_pk_bf16_f32 v41, v36, v37
	v_permlane16_swap_b32_e32 v42, v0
	global_store_dwordx4 v[34:35], v[38:41], off
	v_add_f32_e32 v34, v42, v0
	v_mov_b32_e32 v0, v43
	s_nop 1
	v_permlane16_swap_b32_e32 v43, v0
	v_add_f32_e32 v35, v43, v0
	v_mov_b32_e32 v36, v34
	v_mov_b32_e32 v37, v35
	s_nop 0
	v_permlane32_swap_b32_e32 v34, v36
	v_permlane32_swap_b32_e32 v35, v37
	s_and_saveexec_b64 s[24:25], s[44:45]
	s_cbranch_execz .LBB0_1547
	v_pk_add_f32 v[34:35], v[34:35], v[36:37]
	v_lshl_add_u64 v[36:37], s[6:7], 0, v[102:103]
	v_lshl_add_u64 v[36:37], s[52:53], 2, v[36:37]
	global_store_dwordx2 v[36:37], v[34:35], off
.LBB0_1547:
	s_or_b64 exec, exec, s[24:25]
	v_pk_add_f32 v[34:35], v[104:105], v[106:107]
	s_mov_b32 s2, 0x3a800000
	v_pk_mul_f32 v[58:59], v[34:35], s[2:3] op_sel_hi:[1,0]
	s_mov_b32 s1, 0x800000
	v_fma_f32 v0, -v59, v59, v58
	v_max_f32_e32 v0, 0, v0
	v_add_f32_e32 v0, 0x3727c5ac, v0
	v_cmp_gt_f32_e32 vcc, s1, v0
	v_mul_f32_e32 v34, 0x4b800000, v0
	s_load_dwordx16 s[64:79], s[34:35], 0x38
	v_cndmask_b32_e32 v0, v0, v34, vcc
	v_rsq_f32_e32 v0, v0
	s_mov_b32 s2, 0x3fd744fd
	s_movk_i32 s1, 0x3bc0
	v_mul_f32_e32 v34, 0x45800000, v0
	v_cndmask_b32_e32 v58, v0, v34, vcc
	v_lshlrev_b64 v[34:35], 12, v[96:97]
	s_waitcnt lgkmcnt(0)
	v_lshl_add_u64 v[34:35], s[78:79], 0, v[34:35]
	v_lshl_add_u64 v[60:61], v[152:153], 2, v[34:35]
	global_load_dwordx4 v[62:65], v[60:61], off offset:16
	global_load_dwordx4 v[66:69], v[60:61], off
	global_load_dwordx4 v[70:73], v[156:157], off offset:16
	global_load_dwordx4 v[78:81], v[156:157], off
	global_load_dwordx4 v[82:85], v[154:155], off offset:16
	global_load_dwordx4 v[86:89], v[154:155], off
	global_load_dwordx4 v[34:37], v[60:61], off offset:528
	global_load_dwordx4 v[54:57], v[60:61], off offset:512
	global_load_dwordx4 v[38:41], v[156:157], off offset:528
	global_load_dwordx4 v[46:49], v[156:157], off offset:512
	global_load_dwordx4 v[42:45], v[154:155], off offset:528
	global_load_dwordx4 v[50:53], v[154:155], off offset:512
	v_lshlrev_b32_e32 v0, 6, v96
	v_and_or_b32 v0, v0, s1, v196
	v_lshlrev_b32_e32 v0, 1, v0
	s_waitcnt vmcnt(10)
	v_sub_f32_e32 v67, v67, v59
	v_sub_f32_e32 v66, v66, v59
	v_sub_f32_e32 v69, v69, v59
	v_sub_f32_e32 v68, v68, v59
	v_pk_mul_f32 v[68:69], v[58:59], v[68:69] op_sel_hi:[0,1]
	v_pk_mul_f32 v[66:67], v[58:59], v[66:67] op_sel_hi:[0,1]
	s_waitcnt vmcnt(6)
	v_pk_fma_f32 v[66:67], v[78:79], v[66:67], v[86:87]
	v_pk_fma_f32 v[68:69], v[80:81], v[68:69], v[88:89]
	v_pk_fma_f32 v[66:67], v[66:67], s[2:3], v[30:31] op_sel_hi:[1,0,1]
	v_pk_fma_f32 v[68:69], v[68:69], s[2:3], v[32:33] op_sel_hi:[1,0,1]
	v_add_f32_e32 v30, v66, v67
	v_add_f32_e32 v31, v68, v69
	v_add_f32_e32 v30, v30, v31
	v_add_f32_e32 v78, 0, v30
	v_mul_f32_e32 v30, v67, v67
	v_mul_f32_e32 v31, v69, v69
	v_fmac_f32_e32 v30, v66, v66
	v_fmac_f32_e32 v31, v68, v68
	v_add_f32_e32 v79, v30, v31
	v_sub_f32_e32 v31, v63, v59
	v_sub_f32_e32 v30, v62, v59
	v_sub_f32_e32 v33, v65, v59
	v_sub_f32_e32 v32, v64, v59
	v_pk_mul_f32 v[32:33], v[58:59], v[32:33] op_sel_hi:[0,1]
	v_pk_mul_f32 v[30:31], v[58:59], v[30:31] op_sel_hi:[0,1]
	v_pk_fma_f32 v[30:31], v[70:71], v[30:31], v[82:83]
	v_pk_fma_f32 v[32:33], v[72:73], v[32:33], v[84:85]
	v_pk_fma_f32 v[62:63], v[30:31], s[2:3], v[26:27] op_sel_hi:[1,0,1]
	v_pk_fma_f32 v[64:65], v[32:33], s[2:3], v[28:29] op_sel_hi:[1,0,1]
	v_add_f32_e32 v26, v62, v63
	v_add_f32_e32 v27, v64, v65
	v_add_f32_e32 v26, v26, v27
	v_add_f32_e32 v31, v78, v26
	v_mul_f32_e32 v26, v63, v63
	v_mul_f32_e32 v27, v65, v65
	v_fmac_f32_e32 v26, v62, v62
	v_fmac_f32_e32 v27, v64, v64
	v_add_f32_e32 v26, v26, v27
	v_add_f32_e32 v30, v79, v26
	v_cvt_pk_bf16_f32 v26, v66, v67
	v_cvt_pk_bf16_f32 v27, v68, v69
	v_cvt_pk_bf16_f32 v28, v62, v63
	v_cvt_pk_bf16_f32 v29, v64, v65
	v_lshl_add_u64 v[32:33], v[76:77], 0, v[0:1]
	s_nop 0
	s_nop 1
	v_bfe_u32 v71, v227, 4, 2
	v_sub_u32_e32 v70, 0, v71
; __device__ __forceinline__ float xsum16(float v) { const auto r = __builtin_amdgcn_permlane16_swap(__float_as_uint(v), __float_as_uint(v), false, false); return __uint_as_float(r[0]) + __uint_as_float(r[1]); }
; __device__ __forceinline__ float xsum32(float v) { const auto r = __builtin_amdgcn_permlane32_swap(__float_as_uint(v), __float_as_uint(v), false, false); return __uint_as_float(r[0]) + __uint_as_float(r[1]); }
; __device__ __forceinline__ size_t blk_off(int r, int c, int K) { return (size_t)(r >> 8) * 256 * K + (size_t)(c >> 6) * (256 * 64) + (size_t)((r & 255) * 64 + (c & 63)); }
; __device__ __forceinline__ u32x4 pack8(const f32x4 a, const f32x4 b) { u32x4 w; w.x = cvt_pk_bf16(a[0], a[1]); w.y = cvt_pk_bf16(a[2], a[3]); w.z = cvt_pk_bf16(b[0], b[1]); w.w = cvt_pk_bf16(b[2], b[3]); return w; }
;     __device__ __forceinline__ void operator()(const f32x4 (&acc)[2][2][4][2], const pg8::Unit& u, int wr, int wc, int fr, int fq) const {
;     ...
;                 for (int bj = 0; bj < 2; ++bj) { float* yp = Y + (size_t)row * D_ + col0 + bj * 128; f32x4 v[2];
; #pragma unroll
;                     for (int n = 0; n < 2; ++n) { v[n] = (((yv[bj][n] - mu) * rs) * gq[bj][n] + bq_[bj][n]) * ALPHA_ + acc[ai][bj][m][n] * sc;
;                         *(f32x4*)(yp + 4 * n) = v[n]; s1 += (v[n][0] + v[n][1]) + (v[n][2] + v[n][3]); s2 += (v[n][0] * v[n][0] + v[n][1] * v[n][1]) + (v[n][2] * v[n][2] + v[n][3] * v[n][3]); }
;                     *(u32x4*)(Yb + blk_off(row, col0 + bj * 128, D_)) = pack8(v[0], v[1]); }
;                 s1 = xsum32(xsum16(s1)); s2 = xsum32(xsum16(s2));
;                 if (fq == 0) *(f32x2*)(stn + (size_t)row * 32 + (u.pn * 4 + wc) * 2) = (f32x2){s1, s2}; asm volatile("" ::: "memory"); } }
	v_lshlrev_b32_e32 v70, 4, v70
	v_ashrrev_i32_e32 v71, 31, v70
	v_lshl_add_u64 v[70:71], v[60:61], 0, v[70:71]
	v_permlane16_swap_b32_e32 v66, v62
	v_permlane16_swap_b32_e32 v67, v63
	v_permlane16_swap_b32_e32 v68, v64
	v_permlane16_swap_b32_e32 v69, v65
	v_permlane32_swap_b32_e32 v66, v62
	v_permlane32_swap_b32_e32 v67, v63
	v_permlane32_swap_b32_e32 v68, v64
	v_permlane32_swap_b32_e32 v69, v65
	v_mov_b32_e32 v78, v66
	v_mov_b32_e32 v79, v67
	v_mov_b32_e32 v80, v68
	v_mov_b32_e32 v81, v69
	v_bfe_u32 v72, v227, 3, 1
	v_mul_i32_i24_e32 v72, 0xffff8040, v72
	v_ashrrev_i32_e32 v73, 31, v72
	v_lshl_add_u64 v[70:71], v[70:71], 0, v[72:73]
	v_mov_b32_e32 v72, 0x8000
	v_mov_b32_e32 v73, 0
	v_lshl_add_u64 v[72:73], v[70:71], 0, v[72:73]
	v_mov_b32_dpp v66, v62 row_ror:8 row_mask:0xf bank_mask:0xc
	v_mov_b32_dpp v67, v63 row_ror:8 row_mask:0xf bank_mask:0xc
	v_mov_b32_dpp v68, v64 row_ror:8 row_mask:0xf bank_mask:0xc
	v_mov_b32_dpp v69, v65 row_ror:8 row_mask:0xf bank_mask:0xc
	v_mov_b32_dpp v62, v78 row_ror:8 row_mask:0xf bank_mask:0x3
	v_mov_b32_dpp v63, v79 row_ror:8 row_mask:0xf bank_mask:0x3
	v_mov_b32_dpp v64, v80 row_ror:8 row_mask:0xf bank_mask:0x3
	v_mov_b32_dpp v65, v81 row_ror:8 row_mask:0xf bank_mask:0x3
	global_store_dwordx4 v[70:71], v[66:69], off
	global_store_dwordx4 v[72:73], v[62:65], off
	s_nop 1
	v_mov_b32_dpp v62, v66 row_ror:8 row_mask:0xf bank_mask:0x3
	v_mov_b32_dpp v63, v67 row_ror:8 row_mask:0xf bank_mask:0x3
	v_mov_b32_dpp v64, v68 row_ror:8 row_mask:0xf bank_mask:0x3
	v_mov_b32_dpp v65, v69 row_ror:8 row_mask:0xf bank_mask:0x3
	v_mov_b32_e32 v66, v78
	v_mov_b32_e32 v67, v79
	v_mov_b32_e32 v68, v80
	v_mov_b32_e32 v69, v81
	s_nop 1
	v_permlane32_swap_b32_e32 v66, v62
	v_permlane32_swap_b32_e32 v67, v63
	v_permlane32_swap_b32_e32 v68, v64
	v_permlane32_swap_b32_e32 v69, v65
	v_permlane16_swap_b32_e32 v66, v62
	v_permlane16_swap_b32_e32 v67, v63
	v_permlane16_swap_b32_e32 v68, v64
	v_permlane16_swap_b32_e32 v69, v65
	global_store_dwordx4 v[32:33], v[26:29], off
	s_waitcnt vmcnt(7)
	s_nop 0
	v_sub_f32_e32 v27, v55, v59
	v_sub_f32_e32 v26, v54, v59
	v_sub_f32_e32 v29, v57, v59
	v_sub_f32_e32 v28, v56, v59
	v_pk_mul_f32 v[28:29], v[58:59], v[28:29] op_sel_hi:[0,1]
	v_pk_mul_f32 v[26:27], v[58:59], v[26:27] op_sel_hi:[0,1]
	s_waitcnt vmcnt(3)
	v_pk_fma_f32 v[26:27], v[46:47], v[26:27], v[50:51]
	v_pk_fma_f32 v[28:29], v[48:49], v[28:29], v[52:53]
	v_pk_fma_f32 v[22:23], v[26:27], s[2:3], v[22:23] op_sel_hi:[1,0,1]
	v_pk_fma_f32 v[24:25], v[28:29], s[2:3], v[24:25] op_sel_hi:[1,0,1]
	v_add_f32_e32 v26, v22, v23
	v_add_f32_e32 v27, v24, v25
	v_add_f32_e32 v26, v26, v27
	v_add_f32_e32 v31, v31, v26
	v_mul_f32_e32 v26, v23, v23
	v_mul_f32_e32 v27, v25, v25
	v_fmac_f32_e32 v26, v22, v22
	v_fmac_f32_e32 v27, v24, v24
	v_add_f32_e32 v26, v26, v27
	v_add_f32_e32 v30, v30, v26
	v_sub_f32_e32 v27, v35, v59
	v_sub_f32_e32 v26, v34, v59
	v_sub_f32_e32 v29, v37, v59
	v_sub_f32_e32 v28, v36, v59
	v_pk_mul_f32 v[28:29], v[58:59], v[28:29] op_sel_hi:[0,1]
	v_pk_mul_f32 v[26:27], v[58:59], v[26:27] op_sel_hi:[0,1]
	v_pk_fma_f32 v[26:27], v[38:39], v[26:27], v[42:43]
	v_pk_fma_f32 v[28:29], v[40:41], v[28:29], v[44:45]
	v_pk_fma_f32 v[18:19], v[26:27], s[2:3], v[18:19] op_sel_hi:[1,0,1]
	v_pk_fma_f32 v[20:21], v[28:29], s[2:3], v[20:21] op_sel_hi:[1,0,1]
	v_add_f32_e32 v26, v18, v19
	v_add_f32_e32 v27, v20, v21
	v_add_f32_e32 v26, v26, v27
	v_mul_f32_e32 v27, v19, v19
	v_mul_f32_e32 v28, v21, v21
	v_add_f32_e32 v26, v31, v26
	v_fmac_f32_e32 v27, v18, v18
	v_fmac_f32_e32 v28, v20, v20
	s_nop 0
	s_nop 1
	v_bfe_u32 v33, v227, 4, 2
	v_sub_u32_e32 v32, 0, v33
	v_lshlrev_b32_e32 v32, 4, v32
	v_ashrrev_i32_e32 v33, 31, v32
	v_lshl_add_u64 v[32:33], v[60:61], 0, v[32:33]
	v_permlane16_swap_b32_e32 v22, v18
	v_permlane16_swap_b32_e32 v23, v19
	v_permlane16_swap_b32_e32 v24, v20
	v_permlane16_swap_b32_e32 v25, v21
	v_permlane32_swap_b32_e32 v22, v18
	v_permlane32_swap_b32_e32 v23, v19
	v_permlane32_swap_b32_e32 v24, v20
	v_permlane32_swap_b32_e32 v25, v21
	v_mov_b32_e32 v29, v22
	v_mov_b32_e32 v36, v23
	v_mov_b32_e32 v37, v24
	v_mov_b32_e32 v38, v25
	v_bfe_u32 v34, v227, 3, 1
	v_mul_i32_i24_e32 v34, 0xffff8040, v34
	v_ashrrev_i32_e32 v35, 31, v34
	v_lshl_add_u64 v[32:33], v[32:33], 0, v[34:35]
	v_mov_b32_e32 v34, 0x8000
	v_mov_b32_e32 v35, 0
	v_lshl_add_u64 v[34:35], v[32:33], 0, v[34:35]
	v_mov_b32_dpp v22, v18 row_ror:8 row_mask:0xf bank_mask:0xc
	v_mov_b32_dpp v23, v19 row_ror:8 row_mask:0xf bank_mask:0xc
	v_mov_b32_dpp v24, v20 row_ror:8 row_mask:0xf bank_mask:0xc
	v_mov_b32_dpp v25, v21 row_ror:8 row_mask:0xf bank_mask:0xc
	v_mov_b32_dpp v18, v29 row_ror:8 row_mask:0xf bank_mask:0x3
	v_mov_b32_dpp v19, v36 row_ror:8 row_mask:0xf bank_mask:0x3
	v_mov_b32_dpp v20, v37 row_ror:8 row_mask:0xf bank_mask:0x3
	v_mov_b32_dpp v21, v38 row_ror:8 row_mask:0xf bank_mask:0x3
	global_store_dwordx4 v[32:33], v[22:25], off offset:512
	global_store_dwordx4 v[34:35], v[18:21], off offset:512
	s_nop 1
	v_mov_b32_dpp v18, v22 row_ror:8 row_mask:0xf bank_mask:0x3
	v_mov_b32_dpp v19, v23 row_ror:8 row_mask:0xf bank_mask:0x3
	v_mov_b32_dpp v20, v24 row_ror:8 row_mask:0xf bank_mask:0x3
	v_mov_b32_dpp v21, v25 row_ror:8 row_mask:0xf bank_mask:0x3
	v_mov_b32_e32 v22, v29
	v_mov_b32_e32 v23, v36
	v_mov_b32_e32 v24, v37
	v_mov_b32_e32 v25, v38
	s_nop 1
	v_permlane32_swap_b32_e32 v22, v18
	v_permlane32_swap_b32_e32 v23, v19
	v_permlane32_swap_b32_e32 v24, v20
	v_permlane32_swap_b32_e32 v25, v21
	v_permlane16_swap_b32_e32 v22, v18
	v_permlane16_swap_b32_e32 v23, v19
	v_permlane16_swap_b32_e32 v24, v20
	v_permlane16_swap_b32_e32 v25, v21
	v_add_f32_e32 v27, v27, v28
	v_cvt_pk_bf16_f32 v22, v22, v23
	v_cvt_pk_bf16_f32 v23, v24, v25
	v_cvt_pk_bf16_f32 v24, v18, v19
	v_lshl_add_u64 v[18:19], v[74:75], 0, v[0:1]
	v_mov_b32_e32 v0, v26
	v_add_f32_e32 v27, v30, v27
	v_cvt_pk_bf16_f32 v25, v20, v21
	v_permlane16_swap_b32_e32 v26, v0
	global_store_dwordx4 v[18:19], v[22:25], off
	v_add_f32_e32 v18, v26, v0
	v_mov_b32_e32 v0, v27
	s_nop 1
	v_permlane16_swap_b32_e32 v27, v0
	v_add_f32_e32 v19, v27, v0
	v_mov_b32_e32 v20, v18
	v_mov_b32_e32 v21, v19
	s_nop 0
	v_permlane32_swap_b32_e32 v18, v20
	v_permlane32_swap_b32_e32 v19, v21
	s_and_saveexec_b64 s[24:25], s[44:45]
	s_cbranch_execz .LBB0_1549
	v_pk_add_f32 v[18:19], v[18:19], v[20:21]
	v_lshlrev_b64 v[20:21], 7, v[96:97]
	v_lshl_add_u64 v[20:21], s[6:7], 0, v[20:21]
	v_lshl_add_u64 v[20:21], s[52:53], 2, v[20:21]
	global_store_dwordx2 v[20:21], v[18:19], off
; __device__ __forceinline__ size_t blk_off(int r, int c, int K) { return (size_t)(r >> 8) * 256 * K + (size_t)(c >> 6) * (256 * 64) + (size_t)((r & 255) * 64 + (c & 63)); }
; __device__ __forceinline__ u32x4 pack8(const f32x4 a, const f32x4 b) { u32x4 w; w.x = cvt_pk_bf16(a[0], a[1]); w.y = cvt_pk_bf16(a[2], a[3]); w.z = cvt_pk_bf16(b[0], b[1]); w.w = cvt_pk_bf16(b[2], b[3]); return w; }
;     __device__ __forceinline__ void operator()(const f32x4 (&acc)[2][2][4][2], const pg8::Unit& u, int wr, int wc, int fr, int fq) const {
;     ...
;             for (int m = 0; m < 4; ++m) { const int row = row0 + ai * 128 + m * 16; const float mu = mu4[m], rs = rs4[m];
;                 f32x4 yv[2][2], gq[2][2], bq_[2][2];
; #pragma unroll
;                 for (int bj = 0; bj < 2; ++bj)
; #pragma unroll
;                     for (int n = 0; n < 2; ++n) { yv[bj][n] = *(const f32x4*)(Yin + (size_t)row * D_ + col0 + bj * 128 + 4 * n); gq[bj][n] = *(const f32x4*)(g + col0 + bj * 128 + 4 * n); bq_[bj][n] = *(const f32x4*)(b + col0 + bj * 128 + 4 * n); }
;                 asm volatile("" ::: "memory");
;                 float s1 = 0.f, s2 = 0.f;
; #pragma unroll
;                 for (int bj = 0; bj < 2; ++bj) { float* yp = Y + (size_t)row * D_ + col0 + bj * 128; f32x4 v[2];
; #pragma unroll
;                     for (int n = 0; n < 2; ++n) { v[n] = (((yv[bj][n] - mu) * rs) * gq[bj][n] + bq_[bj][n]) * ALPHA_ + acc[ai][bj][m][n] * sc;
;                         *(f32x4*)(yp + 4 * n) = v[n]; s1 += (v[n][0] + v[n][1]) + (v[n][2] + v[n][3]); s2 += (v[n][0] * v[n][0] + v[n][1] * v[n][1]) + (v[n][2] * v[n][2] + v[n][3] * v[n][3]); }
;                     *(u32x4*)(Yb + blk_off(row, col0 + bj * 128, D_)) = pack8(v[0], v[1]); }
.LBB0_1549:
	s_or_b64 exec, exec, s[24:25]
	v_pk_add_f32 v[18:19], v[98:99], v[100:101]
	s_mov_b32 s2, 0x3a800000
	v_pk_mul_f32 v[42:43], v[18:19], s[2:3] op_sel_hi:[1,0]
	s_mov_b32 s1, 0x800000
	v_fma_f32 v0, -v43, v43, v42
	v_max_f32_e32 v0, 0, v0
	v_add_f32_e32 v0, 0x3727c5ac, v0
	v_cmp_gt_f32_e32 vcc, s1, v0
	v_mul_f32_e32 v18, 0x4b800000, v0
	s_load_dwordx16 s[64:79], s[34:35], 0x38
	v_cndmask_b32_e32 v0, v0, v18, vcc
	v_rsq_f32_e32 v0, v0
	s_mov_b32 s2, 0x3fd744fd
	s_movk_i32 s1, 0x3fc0
	v_mul_f32_e32 v18, 0x45800000, v0
	v_cndmask_b32_e32 v42, v0, v18, vcc
	v_lshlrev_b64 v[18:19], 12, v[94:95]
	s_waitcnt lgkmcnt(0)
	v_lshl_add_u64 v[18:19], s[78:79], 0, v[18:19]
	v_lshl_add_u64 v[44:45], v[152:153], 2, v[18:19]
	global_load_dwordx4 v[46:49], v[44:45], off offset:16
	global_load_dwordx4 v[50:53], v[44:45], off
	global_load_dwordx4 v[54:57], v[156:157], off offset:16
	global_load_dwordx4 v[58:61], v[156:157], off
	global_load_dwordx4 v[62:65], v[154:155], off offset:16
	global_load_dwordx4 v[66:69], v[154:155], off
	global_load_dwordx4 v[18:21], v[44:45], off offset:528
	global_load_dwordx4 v[38:41], v[44:45], off offset:512
	global_load_dwordx4 v[22:25], v[156:157], off offset:528
	global_load_dwordx4 v[30:33], v[156:157], off offset:512
	global_load_dwordx4 v[26:29], v[154:155], off offset:528
	global_load_dwordx4 v[34:37], v[154:155], off offset:512
	v_lshlrev_b32_e32 v0, 6, v94
	v_and_or_b32 v0, v0, s1, v196
	v_lshlrev_b32_e32 v0, 1, v0
	s_waitcnt vmcnt(10)
	v_sub_f32_e32 v51, v51, v43
	v_sub_f32_e32 v50, v50, v43
	v_sub_f32_e32 v53, v53, v43
	v_sub_f32_e32 v52, v52, v43
	v_pk_mul_f32 v[52:53], v[42:43], v[52:53] op_sel_hi:[0,1]
	v_pk_mul_f32 v[50:51], v[42:43], v[50:51] op_sel_hi:[0,1]
	s_waitcnt vmcnt(6)
	v_pk_fma_f32 v[50:51], v[58:59], v[50:51], v[66:67]
	v_pk_fma_f32 v[52:53], v[60:61], v[52:53], v[68:69]
	v_pk_fma_f32 v[50:51], v[50:51], s[2:3], v[14:15] op_sel_hi:[1,0,1]
	v_pk_fma_f32 v[52:53], v[52:53], s[2:3], v[16:17] op_sel_hi:[1,0,1]
	v_add_f32_e32 v14, v50, v51
	v_add_f32_e32 v15, v52, v53
	v_add_f32_e32 v14, v14, v15
	v_add_f32_e32 v58, 0, v14
	v_mul_f32_e32 v14, v51, v51
	v_mul_f32_e32 v15, v53, v53
	v_fmac_f32_e32 v14, v50, v50
	v_fmac_f32_e32 v15, v52, v52
	v_add_f32_e32 v59, v14, v15
	v_sub_f32_e32 v15, v47, v43
	v_sub_f32_e32 v14, v46, v43
	v_sub_f32_e32 v17, v49, v43
	v_sub_f32_e32 v16, v48, v43
	v_pk_mul_f32 v[16:17], v[42:43], v[16:17] op_sel_hi:[0,1]
	v_pk_mul_f32 v[14:15], v[42:43], v[14:15] op_sel_hi:[0,1]
	v_pk_fma_f32 v[14:15], v[54:55], v[14:15], v[62:63]
	v_pk_fma_f32 v[16:17], v[56:57], v[16:17], v[64:65]
	v_pk_fma_f32 v[46:47], v[14:15], s[2:3], v[10:11] op_sel_hi:[1,0,1]
	v_pk_fma_f32 v[48:49], v[16:17], s[2:3], v[12:13] op_sel_hi:[1,0,1]
	v_add_f32_e32 v10, v46, v47
	v_add_f32_e32 v11, v48, v49
	v_add_f32_e32 v10, v10, v11
	v_add_f32_e32 v15, v58, v10
	v_mul_f32_e32 v10, v47, v47
	v_mul_f32_e32 v11, v49, v49
	v_fmac_f32_e32 v10, v46, v46
	v_fmac_f32_e32 v11, v48, v48
	v_add_f32_e32 v10, v10, v11
	v_add_f32_e32 v14, v59, v10
	v_cvt_pk_bf16_f32 v10, v50, v51
	v_cvt_pk_bf16_f32 v11, v52, v53
	v_cvt_pk_bf16_f32 v12, v46, v47
	v_cvt_pk_bf16_f32 v13, v48, v49
	v_lshl_add_u64 v[16:17], v[76:77], 0, v[0:1]
	s_nop 0
	s_nop 1
	v_bfe_u32 v55, v227, 4, 2
	v_sub_u32_e32 v54, 0, v55
	v_lshlrev_b32_e32 v54, 4, v54
	v_ashrrev_i32_e32 v55, 31, v54
	v_lshl_add_u64 v[54:55], v[44:45], 0, v[54:55]
	v_permlane16_swap_b32_e32 v50, v46
	v_permlane16_swap_b32_e32 v51, v47
	v_permlane16_swap_b32_e32 v52, v48
	v_permlane16_swap_b32_e32 v53, v49
	v_permlane32_swap_b32_e32 v50, v46
	v_permlane32_swap_b32_e32 v51, v47
	v_permlane32_swap_b32_e32 v52, v48
	v_permlane32_swap_b32_e32 v53, v49
	v_mov_b32_e32 v58, v50
	v_mov_b32_e32 v59, v51
	v_mov_b32_e32 v60, v52
	v_mov_b32_e32 v61, v53
	v_bfe_u32 v56, v227, 3, 1
	v_mul_i32_i24_e32 v56, 0xffff8040, v56
	v_ashrrev_i32_e32 v57, 31, v56
	v_lshl_add_u64 v[54:55], v[54:55], 0, v[56:57]
	v_mov_b32_e32 v56, 0x8000
	v_mov_b32_e32 v57, 0
	v_lshl_add_u64 v[56:57], v[54:55], 0, v[56:57]
	v_mov_b32_dpp v50, v46 row_ror:8 row_mask:0xf bank_mask:0xc
	v_mov_b32_dpp v51, v47 row_ror:8 row_mask:0xf bank_mask:0xc
	v_mov_b32_dpp v52, v48 row_ror:8 row_mask:0xf bank_mask:0xc
	v_mov_b32_dpp v53, v49 row_ror:8 row_mask:0xf bank_mask:0xc
	v_mov_b32_dpp v46, v58 row_ror:8 row_mask:0xf bank_mask:0x3
	v_mov_b32_dpp v47, v59 row_ror:8 row_mask:0xf bank_mask:0x3
	v_mov_b32_dpp v48, v60 row_ror:8 row_mask:0xf bank_mask:0x3
	v_mov_b32_dpp v49, v61 row_ror:8 row_mask:0xf bank_mask:0x3
	global_store_dwordx4 v[54:55], v[50:53], off
	global_store_dwordx4 v[56:57], v[46:49], off
	s_nop 1
	v_mov_b32_dpp v46, v50 row_ror:8 row_mask:0xf bank_mask:0x3
	v_mov_b32_dpp v47, v51 row_ror:8 row_mask:0xf bank_mask:0x3
	v_mov_b32_dpp v48, v52 row_ror:8 row_mask:0xf bank_mask:0x3
	v_mov_b32_dpp v49, v53 row_ror:8 row_mask:0xf bank_mask:0x3
	v_mov_b32_e32 v50, v58
	v_mov_b32_e32 v51, v59
	v_mov_b32_e32 v52, v60
	v_mov_b32_e32 v53, v61
	s_nop 1
	v_permlane32_swap_b32_e32 v50, v46
	v_permlane32_swap_b32_e32 v51, v47
	v_permlane32_swap_b32_e32 v52, v48
	v_permlane32_swap_b32_e32 v53, v49
	v_permlane16_swap_b32_e32 v50, v46
	v_permlane16_swap_b32_e32 v51, v47
	v_permlane16_swap_b32_e32 v52, v48
	v_permlane16_swap_b32_e32 v53, v49
	global_store_dwordx4 v[16:17], v[10:13], off
	s_waitcnt vmcnt(7)
; __device__ __forceinline__ float xsum16(float v) { const auto r = __builtin_amdgcn_permlane16_swap(__float_as_uint(v), __float_as_uint(v), false, false); return __uint_as_float(r[0]) + __uint_as_float(r[1]); }
; __device__ __forceinline__ float xsum32(float v) { const auto r = __builtin_amdgcn_permlane32_swap(__float_as_uint(v), __float_as_uint(v), false, false); return __uint_as_float(r[0]) + __uint_as_float(r[1]); }
; __device__ __forceinline__ size_t blk_off(int r, int c, int K) { return (size_t)(r >> 8) * 256 * K + (size_t)(c >> 6) * (256 * 64) + (size_t)((r & 255) * 64 + (c & 63)); }
; __device__ __forceinline__ u32x4 pack8(const f32x4 a, const f32x4 b) { u32x4 w; w.x = cvt_pk_bf16(a[0], a[1]); w.y = cvt_pk_bf16(a[2], a[3]); w.z = cvt_pk_bf16(b[0], b[1]); w.w = cvt_pk_bf16(b[2], b[3]); return w; }
;     __device__ __forceinline__ void operator()(const f32x4 (&acc)[2][2][4][2], const pg8::Unit& u, int wr, int wc, int fr, int fq) const {
;     ...
;                 for (int bj = 0; bj < 2; ++bj) { float* yp = Y + (size_t)row * D_ + col0 + bj * 128; f32x4 v[2];
; #pragma unroll
;                     for (int n = 0; n < 2; ++n) { v[n] = (((yv[bj][n] - mu) * rs) * gq[bj][n] + bq_[bj][n]) * ALPHA_ + acc[ai][bj][m][n] * sc;
;                         *(f32x4*)(yp + 4 * n) = v[n]; s1 += (v[n][0] + v[n][1]) + (v[n][2] + v[n][3]); s2 += (v[n][0] * v[n][0] + v[n][1] * v[n][1]) + (v[n][2] * v[n][2] + v[n][3] * v[n][3]); }
;                     *(u32x4*)(Yb + blk_off(row, col0 + bj * 128, D_)) = pack8(v[0], v[1]); }
;                 s1 = xsum32(xsum16(s1)); s2 = xsum32(xsum16(s2));
;                 if (fq == 0) *(f32x2*)(stn + (size_t)row * 32 + (u.pn * 4 + wc) * 2) = (f32x2){s1, s2}; asm volatile("" ::: "memory"); } }
	s_nop 0
	v_sub_f32_e32 v11, v39, v43
	v_sub_f32_e32 v10, v38, v43
	v_sub_f32_e32 v13, v41, v43
	v_sub_f32_e32 v12, v40, v43
	v_pk_mul_f32 v[12:13], v[42:43], v[12:13] op_sel_hi:[0,1]
	v_pk_mul_f32 v[10:11], v[42:43], v[10:11] op_sel_hi:[0,1]
	s_waitcnt vmcnt(3)
	v_pk_fma_f32 v[10:11], v[30:31], v[10:11], v[34:35]
	v_pk_fma_f32 v[12:13], v[32:33], v[12:13], v[36:37]
	v_pk_fma_f32 v[6:7], v[10:11], s[2:3], v[6:7] op_sel_hi:[1,0,1]
	v_pk_fma_f32 v[8:9], v[12:13], s[2:3], v[8:9] op_sel_hi:[1,0,1]
	v_add_f32_e32 v10, v6, v7
	v_add_f32_e32 v11, v8, v9
	v_add_f32_e32 v10, v10, v11
	v_add_f32_e32 v15, v15, v10
	v_mul_f32_e32 v10, v7, v7
	v_mul_f32_e32 v11, v9, v9
	v_fmac_f32_e32 v10, v6, v6
	v_fmac_f32_e32 v11, v8, v8
	v_add_f32_e32 v10, v10, v11
	v_add_f32_e32 v14, v14, v10
	v_sub_f32_e32 v11, v19, v43
	v_sub_f32_e32 v10, v18, v43
	v_sub_f32_e32 v13, v21, v43
	v_sub_f32_e32 v12, v20, v43
	v_pk_mul_f32 v[12:13], v[42:43], v[12:13] op_sel_hi:[0,1]
	v_pk_mul_f32 v[10:11], v[42:43], v[10:11] op_sel_hi:[0,1]
	v_pk_fma_f32 v[10:11], v[22:23], v[10:11], v[26:27]
	v_pk_fma_f32 v[12:13], v[24:25], v[12:13], v[28:29]
	v_pk_fma_f32 v[2:3], v[10:11], s[2:3], v[2:3] op_sel_hi:[1,0,1]
	v_pk_fma_f32 v[4:5], v[12:13], s[2:3], v[4:5] op_sel_hi:[1,0,1]
	v_add_f32_e32 v10, v2, v3
	v_add_f32_e32 v11, v4, v5
	v_add_f32_e32 v10, v10, v11
	v_mul_f32_e32 v11, v3, v3
	v_mul_f32_e32 v12, v5, v5
	v_add_f32_e32 v10, v15, v10
	v_fmac_f32_e32 v11, v2, v2
	v_fmac_f32_e32 v12, v4, v4
	s_nop 0
	s_nop 1
	v_bfe_u32 v17, v227, 4, 2
	v_sub_u32_e32 v16, 0, v17
	v_lshlrev_b32_e32 v16, 4, v16
	v_ashrrev_i32_e32 v17, 31, v16
	v_lshl_add_u64 v[16:17], v[44:45], 0, v[16:17]
	v_permlane16_swap_b32_e32 v6, v2
	v_permlane16_swap_b32_e32 v7, v3
	v_permlane16_swap_b32_e32 v8, v4
	v_permlane16_swap_b32_e32 v9, v5
	v_permlane32_swap_b32_e32 v6, v2
	v_permlane32_swap_b32_e32 v7, v3
	v_permlane32_swap_b32_e32 v8, v4
	v_permlane32_swap_b32_e32 v9, v5
	v_mov_b32_e32 v13, v6
	v_mov_b32_e32 v20, v7
	v_mov_b32_e32 v21, v8
	v_mov_b32_e32 v22, v9
	v_bfe_u32 v18, v227, 3, 1
	v_mul_i32_i24_e32 v18, 0xffff8040, v18
	v_ashrrev_i32_e32 v19, 31, v18
	v_lshl_add_u64 v[16:17], v[16:17], 0, v[18:19]
	v_mov_b32_e32 v18, 0x8000
	v_mov_b32_e32 v19, 0
	v_lshl_add_u64 v[18:19], v[16:17], 0, v[18:19]
	v_mov_b32_dpp v6, v2 row_ror:8 row_mask:0xf bank_mask:0xc
	v_mov_b32_dpp v7, v3 row_ror:8 row_mask:0xf bank_mask:0xc
	v_mov_b32_dpp v8, v4 row_ror:8 row_mask:0xf bank_mask:0xc
	v_mov_b32_dpp v9, v5 row_ror:8 row_mask:0xf bank_mask:0xc
	v_mov_b32_dpp v2, v13 row_ror:8 row_mask:0xf bank_mask:0x3
	v_mov_b32_dpp v3, v20 row_ror:8 row_mask:0xf bank_mask:0x3
	v_mov_b32_dpp v4, v21 row_ror:8 row_mask:0xf bank_mask:0x3
	v_mov_b32_dpp v5, v22 row_ror:8 row_mask:0xf bank_mask:0x3
	global_store_dwordx4 v[16:17], v[6:9], off offset:512
	global_store_dwordx4 v[18:19], v[2:5], off offset:512
	s_nop 1
	v_mov_b32_dpp v2, v6 row_ror:8 row_mask:0xf bank_mask:0x3
	v_mov_b32_dpp v3, v7 row_ror:8 row_mask:0xf bank_mask:0x3
	v_mov_b32_dpp v4, v8 row_ror:8 row_mask:0xf bank_mask:0x3
	v_mov_b32_dpp v5, v9 row_ror:8 row_mask:0xf bank_mask:0x3
	v_mov_b32_e32 v6, v13
	v_mov_b32_e32 v7, v20
	v_mov_b32_e32 v8, v21
	v_mov_b32_e32 v9, v22
	s_nop 1
	v_permlane32_swap_b32_e32 v6, v2
	v_permlane32_swap_b32_e32 v7, v3
	v_permlane32_swap_b32_e32 v8, v4
	v_permlane32_swap_b32_e32 v9, v5
	v_permlane16_swap_b32_e32 v6, v2
	v_permlane16_swap_b32_e32 v7, v3
	v_permlane16_swap_b32_e32 v8, v4
	v_permlane16_swap_b32_e32 v9, v5
	v_add_f32_e32 v11, v11, v12
	v_cvt_pk_bf16_f32 v6, v6, v7
	v_cvt_pk_bf16_f32 v7, v8, v9
	v_cvt_pk_bf16_f32 v8, v2, v3
	v_lshl_add_u64 v[2:3], v[74:75], 0, v[0:1]
	v_mov_b32_e32 v0, v10
	v_add_f32_e32 v11, v14, v11
	v_cvt_pk_bf16_f32 v9, v4, v5
	v_permlane16_swap_b32_e32 v10, v0
	global_store_dwordx4 v[2:3], v[6:9], off
	v_add_f32_e32 v2, v10, v0
	v_mov_b32_e32 v0, v11
	s_nop 1
	v_permlane16_swap_b32_e32 v11, v0
	v_add_f32_e32 v3, v11, v0
	v_mov_b32_e32 v4, v2
	v_mov_b32_e32 v5, v3
	s_nop 0
	v_permlane32_swap_b32_e32 v2, v4
	v_permlane32_swap_b32_e32 v3, v5
	s_and_saveexec_b64 s[24:25], s[44:45]
	s_cbranch_execz .LBB0_1551
	v_pk_add_f32 v[2:3], v[2:3], v[4:5]
	v_lshlrev_b64 v[4:5], 7, v[94:95]
	v_lshl_add_u64 v[4:5], s[6:7], 0, v[4:5]
	v_lshl_add_u64 v[4:5], s[52:53], 2, v[4:5]
	global_store_dwordx2 v[4:5], v[2:3], off

; __device__ __forceinline__ float xsum16(float v) { const auto r = __builtin_amdgcn_permlane16_swap(__float_as_uint(v), __float_as_uint(v), false, false); return __uint_as_float(r[0]) + __uint_as_float(r[1]); }
; __device__ __forceinline__ float xsum32(float v) { const auto r = __builtin_amdgcn_permlane32_swap(__float_as_uint(v), __float_as_uint(v), false, false); return __uint_as_float(r[0]) + __uint_as_float(r[1]); }
; __device__ __forceinline__ void row_stats4(const float* st, int rowb, int fq, float (&mu)[4], float (&rs)[4]) {
;     f32x4 a[4], b[4];
; #pragma unroll
;     for (int m = 0; m < 4; ++m) { const f32x4* p = (const f32x4*)(st + (size_t)(rowb + m * 16) * 32 + fq * 8); a[m] = p[0]; b[m] = p[1]; }
; #pragma unroll
;     for (int m = 0; m < 4; ++m) { float s1 = (a[m][0] + a[m][2]) + (b[m][0] + b[m][2]), s2 = (a[m][1] + a[m][3]) + (b[m][1] + b[m][3]);
;         s1 = xsum32(xsum16(s1)); s2 = xsum32(xsum16(s2));
;         const float mm = s1 * (1.0f / 1024.0f); mu[m] = mm; rs[m] = rsqrtf(fmaxf(s2 * (1.0f / 1024.0f) - mm * mm, 0.f) + LN_EPS_); }
;     __device__ __forceinline__ void operator()(const f32x4 (&acc)[2][2][4][2], const pg8::Unit& u, int wr, int wc, int fr, int fq) const {
;         const int row0 = u.pm * 256 + wr * 64 + fr, col0 = u.pn * 256 + wc * 32 + fq * 8;
; #pragma unroll
;         for (int ai = 0; ai < 2; ++ai) { float mu4[4], rs4[4]; row_stats4(stp, row0 + ai * 128, fq, mu4, rs4);
; #pragma unroll
;             for (int m = 0; m < 4; ++m) { const int row = row0 + ai * 128 + m * 16; const float mu = mu4[m], rs = rs4[m];
;                 f32x4 yv[2][2], gq[2][2], bq_[2][2];
; #pragma unroll
;                 for (int bj = 0; bj < 2; ++bj)
; #pragma unroll
;                     for (int n = 0; n < 2; ++n) { yv[bj][n] = *(const f32x4*)(Yin + (size_t)row * D_ + col0 + bj * 128 + 4 * n); gq[bj][n] = *(const f32x4*)(g + col0 + bj * 128 + 4 * n); bq_[bj][n] = *(const f32x4*)(b + col0 + bj * 128 + 4 * n); }
.LBB0_1703:
	s_lshl_b32 s3, s3, 8
	s_add_i32 s3, s3, s0
	v_or_b32_e32 v158, s3, v184
	v_ashrrev_i32_e32 v159, 31, v158
	v_lshlrev_b64 v[130:131], 7, v[158:159]
	v_lshl_add_u64 v[136:137], v[146:147], 0, v[130:131]
	v_or_b32_e32 v182, 16, v158
	global_load_dwordx4 v[132:135], v[136:137], off
	global_load_dwordx4 v[166:169], v[136:137], off offset:16
	v_ashrrev_i32_e32 v183, 31, v182
	v_lshlrev_b64 v[172:173], 7, v[182:183]
	v_lshl_add_u64 v[136:137], v[146:147], 0, v[172:173]
	global_load_dwordx4 v[174:177], v[136:137], off
	global_load_dwordx4 v[178:181], v[136:137], off offset:16
	v_or_b32_e32 v170, 32, v158
	v_ashrrev_i32_e32 v171, 31, v170
	v_lshlrev_b64 v[164:165], 7, v[170:171]
	v_lshl_add_u64 v[136:137], v[146:147], 0, v[164:165]
	global_load_dwordx4 v[186:189], v[136:137], off
	global_load_dwordx4 v[190:193], v[136:137], off offset:16
	s_load_dwordx16 s[60:75], s[34:35], 0x38
	s_lshl_b32 s1, s2, 8
	s_lshl_b32 s16, s2, 3
	s_or_b32 s2, s1, s53
	v_or_b32_e32 v162, 48, v158
	v_or_b32_e32 v152, s2, v185
	v_ashrrev_i32_e32 v163, 31, v162
	v_ashrrev_i32_e32 v153, 31, v152
	v_lshlrev_b64 v[136:137], 12, v[158:159]
	v_lshlrev_b64 v[160:161], 7, v[162:163]
	v_lshlrev_b64 v[198:199], 2, v[152:153]
	s_waitcnt lgkmcnt(0)
	v_lshl_add_u64 v[136:137], s[74:75], 0, v[136:137]
	v_lshl_add_u64 v[202:203], v[146:147], 0, v[160:161]
	v_lshl_add_u64 v[156:157], s[10:11], 0, v[198:199]
	v_lshl_add_u64 v[154:155], s[12:13], 0, v[198:199]
	v_lshl_add_u64 v[136:137], v[136:137], 0, v[198:199]
	global_load_dwordx4 v[198:201], v[202:203], off
	s_nop 0
	global_load_dwordx4 v[202:205], v[202:203], off offset:16
	s_or_b32 s38, s16, s15
	s_mov_b32 s16, 0x3a800000
	s_mov_b32 s1, 0x800000
	global_load_dwordx4 v[206:209], v[136:137], off offset:16
	global_load_dwordx4 v[210:213], v[136:137], off
	global_load_dwordx4 v[214:217], v[156:157], off offset:16
	global_load_dwordx4 v[218:221], v[156:157], off
	global_load_dwordx4 v[222:225], v[154:155], off offset:16
	global_load_dwordx4 v[234:237], v[154:155], off
	s_mov_b32 s18, 0x3fd744fd
	s_ashr_i32 s44, s2, 6
	v_bitop3_b32 v196, s2, 56, v185 bitop3:0xc8
	s_ashr_i32 s39, s38, 31
	s_ashr_i32 s45, s44, 31
	s_waitcnt vmcnt(0)
	v_mov_b32_e32 v228, v132
	v_mov_b32_e32 v229, v166
	v_mov_b32_e32 v238, v134
	v_mov_b32_e32 v239, v168
	v_mov_b32_e32 v166, v133
	v_mov_b32_e32 v168, v135
	v_pk_add_f32 v[132:133], v[228:229], v[238:239]
	v_pk_add_f32 v[134:135], v[166:167], v[168:169]
	v_pk_add_f32 v[132:133], v[132:133], v[132:133] op_sel:[0,1] op_sel_hi:[1,0]
	v_pk_add_f32 v[134:135], v[134:135], v[134:135] op_sel:[0,1] op_sel_hi:[1,0]
	v_mov_b32_e32 v166, v174
	v_mov_b32_e32 v167, v178
	v_mov_b32_e32 v168, v176
	v_mov_b32_e32 v169, v180
	v_mov_b32_e32 v0, v132
	v_mov_b32_e32 v133, v134
	v_pk_add_f32 v[166:167], v[166:167], v[168:169]
	v_permlane16_swap_b32_e32 v132, v0
	v_permlane16_swap_b32_e32 v134, v133
	v_mov_b32_e32 v178, v175
	v_mov_b32_e32 v180, v177
	v_pk_add_f32 v[166:167], v[166:167], v[166:167] op_sel:[0,1] op_sel_hi:[1,0]
	v_add_f32_e32 v177, v132, v0
	v_add_f32_e32 v176, v134, v133
	v_pk_add_f32 v[168:169], v[178:179], v[180:181]
	v_mov_b32_e32 v135, v166
	v_mov_b32_e32 v179, v177
	v_mov_b32_e32 v178, v176
	v_permlane16_swap_b32_e32 v166, v135
	v_permlane32_swap_b32_e32 v177, v179
	v_permlane32_swap_b32_e32 v176, v178
	v_add_f32_e32 v133, v166, v135
	v_pk_add_f32 v[166:167], v[176:177], v[178:179]
	v_pk_add_f32 v[168:169], v[168:169], v[168:169] op_sel:[0,1] op_sel_hi:[1,0]
	v_pk_mul_f32 v[228:229], v[166:167], s[16:17] op_sel_hi:[1,0]
	v_mov_b32_e32 v159, v168
	v_fma_f32 v0, -v229, v229, v228
	v_max_f32_e32 v0, 0, v0
	v_permlane16_swap_b32_e32 v168, v159
	v_add_f32_e32 v0, 0x3727c5ac, v0
	v_add_f32_e32 v132, v168, v159
	v_mul_f32_e32 v159, 0x4b800000, v0
	v_cmp_gt_f32_e32 vcc, s1, v0
	v_mov_b32_e32 v174, v186
	v_mov_b32_e32 v175, v190
	v_cndmask_b32_e32 v0, v0, v159, vcc
	v_rsq_f32_e32 v0, v0
	v_mov_b32_e32 v166, v188
	v_mov_b32_e32 v167, v192
	v_pk_add_f32 v[166:167], v[174:175], v[166:167]
	v_mul_f32_e32 v159, 0x45800000, v0
	v_pk_add_f32 v[166:167], v[166:167], v[166:167] op_sel:[0,1] op_sel_hi:[1,0]
	v_mov_b32_e32 v190, v187
	v_mov_b32_e32 v192, v189
	v_cndmask_b32_e32 v0, v0, v159, vcc
	v_pk_add_f32 v[168:169], v[190:191], v[192:193]
	v_mov_b32_e32 v159, v166
	v_pk_add_f32 v[168:169], v[168:169], v[168:169] op_sel:[0,1] op_sel_hi:[1,0]
	s_nop 0
	v_permlane16_swap_b32_e32 v166, v159
	v_add_f32_e32 v175, v166, v159
	v_mov_b32_e32 v159, v168
	s_nop 1
	v_permlane16_swap_b32_e32 v168, v159
	global_load_dwordx4 v[178:181], v[136:137], off offset:528
	global_load_dwordx4 v[186:189], v[136:137], off offset:512
	v_add_f32_e32 v174, v168, v159
	v_mov_b32_e32 v166, v198
	v_mov_b32_e32 v167, v202
	v_mov_b32_e32 v168, v200
	v_mov_b32_e32 v169, v204
	v_mov_b32_e32 v202, v199
	v_mov_b32_e32 v204, v201
	v_pk_add_f32 v[166:167], v[166:167], v[168:169]
	v_pk_add_f32 v[168:169], v[202:203], v[204:205]
	global_load_dwordx4 v[190:193], v[156:157], off offset:528
	global_load_dwordx4 v[198:201], v[156:157], off offset:512
	global_load_dwordx4 v[202:205], v[154:155], off offset:528
	global_load_dwordx4 v[238:241], v[154:155], off offset:512
	v_sub_f32_e32 v213, v213, v229
	v_sub_f32_e32 v212, v212, v229
	v_sub_f32_e32 v211, v211, v229
	v_sub_f32_e32 v210, v210, v229
	v_pk_mul_f32 v[210:211], v[0:1], v[210:211] op_sel_hi:[0,1]
	v_pk_mul_f32 v[212:213], v[0:1], v[212:213] op_sel_hi:[0,1]
	v_sub_f32_e32 v209, v209, v229
	v_sub_f32_e32 v208, v208, v229
	v_sub_f32_e32 v207, v207, v229
	v_sub_f32_e32 v206, v206, v229
	v_pk_fma_f32 v[212:213], v[220:221], v[212:213], v[236:237]
	v_pk_fma_f32 v[210:211], v[218:219], v[210:211], v[234:235]
; __device__ __forceinline__ size_t blk_off(int r, int c, int K) { return (size_t)(r >> 8) * 256 * K + (size_t)(c >> 6) * (256 * 64) + (size_t)((r & 255) * 64 + (c & 63)); }
; __device__ __forceinline__ u32x4 pack8(const f32x4 a, const f32x4 b) { u32x4 w; w.x = cvt_pk_bf16(a[0], a[1]); w.y = cvt_pk_bf16(a[2], a[3]); w.z = cvt_pk_bf16(b[0], b[1]); w.w = cvt_pk_bf16(b[2], b[3]); return w; }
;     __device__ __forceinline__ void operator()(const f32x4 (&acc)[2][2][4][2], const pg8::Unit& u, int wr, int wc, int fr, int fq) const {
;     ...
;                 for (int bj = 0; bj < 2; ++bj) { float* yp = Y + (size_t)row * D_ + col0 + bj * 128; f32x4 v[2];
; #pragma unroll
;                     for (int n = 0; n < 2; ++n) { v[n] = (((yv[bj][n] - mu) * rs) * gq[bj][n] + bq_[bj][n]) * ALPHA_ + acc[ai][bj][m][n] * sc;
;                         *(f32x4*)(yp + 4 * n) = v[n]; s1 += (v[n][0] + v[n][1]) + (v[n][2] + v[n][3]); s2 += (v[n][0] * v[n][0] + v[n][1] * v[n][1]) + (v[n][2] * v[n][2] + v[n][3] * v[n][3]); }
;                     *(u32x4*)(Yb + blk_off(row, col0 + bj * 128, D_)) = pack8(v[0], v[1]); }
	v_pk_mul_f32 v[206:207], v[0:1], v[206:207] op_sel_hi:[0,1]
	v_pk_mul_f32 v[208:209], v[0:1], v[208:209] op_sel_hi:[0,1]
	v_pk_mul_f32 v[210:211], v[210:211], s[18:19] op_sel_hi:[1,0]
	v_pk_mul_f32 v[212:213], v[212:213], s[18:19] op_sel_hi:[1,0]
	v_pk_fma_f32 v[208:209], v[216:217], v[208:209], v[224:225]
	v_pk_fma_f32 v[206:207], v[214:215], v[206:207], v[222:223]
	v_pk_fma_f32 v[128:129], v[128:129], 0.5, v[212:213] op_sel_hi:[1,0,1]
	v_pk_fma_f32 v[126:127], v[126:127], 0.5, v[210:211] op_sel_hi:[1,0,1]
	v_pk_mul_f32 v[206:207], v[206:207], s[18:19] op_sel_hi:[1,0]
	v_pk_mul_f32 v[208:209], v[208:209], s[18:19] op_sel_hi:[1,0]
	v_add_f32_e32 v197, v126, v127
	v_add_f32_e32 v210, v128, v129
	v_pk_fma_f32 v[124:125], v[124:125], 0.5, v[208:209] op_sel_hi:[1,0,1]
	v_pk_fma_f32 v[122:123], v[122:123], 0.5, v[206:207] op_sel_hi:[1,0,1]
	v_pk_add_f32 v[166:167], v[166:167], v[166:167] op_sel:[0,1] op_sel_hi:[1,0]
	v_add_f32_e32 v197, v197, v210
	v_add_f32_e32 v206, v122, v123
	v_add_f32_e32 v207, v124, v125
	v_mov_b32_e32 v159, v166
	v_add_f32_e32 v197, 0, v197
	v_add_f32_e32 v206, v206, v207
	v_pk_add_f32 v[168:169], v[168:169], v[168:169] op_sel:[0,1] op_sel_hi:[1,0]
	v_permlane16_swap_b32_e32 v166, v159
	v_mul_f32_e32 v210, v127, v127
	v_mul_f32_e32 v211, v129, v129
	v_add_f32_e32 v197, v197, v206
	v_mul_f32_e32 v206, v123, v123
	v_mul_f32_e32 v207, v125, v125
	v_add_f32_e32 v167, v166, v159
	v_mov_b32_e32 v159, v168
	s_ashr_i32 s16, s3, 8
	s_nop 0
	v_fmac_f32_e32 v210, v126, v126
	v_fmac_f32_e32 v211, v128, v128
	s_nop 1
	v_bfe_u32 v135, v227, 4, 2
	v_sub_u32_e32 v134, 0, v135
	v_lshlrev_b32_e32 v134, 4, v134
	v_ashrrev_i32_e32 v135, 31, v134
	v_lshl_add_u64 v[134:135], v[136:137], 0, v[134:135]
	v_permlane16_swap_b32_e32 v126, v122
	v_permlane16_swap_b32_e32 v127, v123
	v_permlane16_swap_b32_e32 v128, v124
	v_permlane16_swap_b32_e32 v129, v125
	v_permlane32_swap_b32_e32 v126, v122
	v_permlane32_swap_b32_e32 v127, v123
	v_permlane32_swap_b32_e32 v128, v124
	v_permlane32_swap_b32_e32 v129, v125
	v_mov_b32_e32 v166, v126
	v_mov_b32_e32 v169, v127
	v_mov_b32_e32 v208, v128
	v_mov_b32_e32 v209, v129
	v_bfe_u32 v176, v227, 3, 1
	v_mul_i32_i24_e32 v176, 0xffff8040, v176
	v_ashrrev_i32_e32 v177, 31, v176
	v_lshl_add_u64 v[134:135], v[134:135], 0, v[176:177]
	v_mov_b32_e32 v176, 0x8000
	v_mov_b32_e32 v177, 0
	v_lshl_add_u64 v[176:177], v[134:135], 0, v[176:177]
	v_mov_b32_dpp v126, v122 row_ror:8 row_mask:0xf bank_mask:0xc
	v_mov_b32_dpp v127, v123 row_ror:8 row_mask:0xf bank_mask:0xc
	v_mov_b32_dpp v128, v124 row_ror:8 row_mask:0xf bank_mask:0xc
	v_mov_b32_dpp v129, v125 row_ror:8 row_mask:0xf bank_mask:0xc
	v_mov_b32_dpp v122, v166 row_ror:8 row_mask:0xf bank_mask:0x3
	v_mov_b32_dpp v123, v169 row_ror:8 row_mask:0xf bank_mask:0x3
	v_mov_b32_dpp v124, v208 row_ror:8 row_mask:0xf bank_mask:0x3
	v_mov_b32_dpp v125, v209 row_ror:8 row_mask:0xf bank_mask:0x3
	global_store_dwordx4 v[134:135], v[126:129], off
	global_store_dwordx4 v[176:177], v[122:125], off
	s_nop 1
	v_mov_b32_dpp v122, v126 row_ror:8 row_mask:0xf bank_mask:0x3
	v_mov_b32_dpp v123, v127 row_ror:8 row_mask:0xf bank_mask:0x3
	v_mov_b32_dpp v124, v128 row_ror:8 row_mask:0xf bank_mask:0x3
	v_mov_b32_dpp v125, v129 row_ror:8 row_mask:0xf bank_mask:0x3
	v_mov_b32_e32 v126, v166
	v_mov_b32_e32 v127, v169
	v_mov_b32_e32 v128, v208
	v_mov_b32_e32 v129, v209
	s_nop 1
	v_permlane32_swap_b32_e32 v126, v122
	v_permlane32_swap_b32_e32 v127, v123
	v_permlane32_swap_b32_e32 v128, v124
	v_permlane32_swap_b32_e32 v129, v125
	v_permlane16_swap_b32_e32 v126, v122
	v_permlane16_swap_b32_e32 v127, v123
	v_permlane16_swap_b32_e32 v128, v124
	v_permlane16_swap_b32_e32 v129, v125
	v_fmac_f32_e32 v206, v122, v122
	v_fmac_f32_e32 v207, v124, v124
	v_cvt_pk_bf16_f32 v126, v126, v127
	v_cvt_pk_bf16_f32 v127, v128, v129
	v_cvt_pk_bf16_f32 v128, v122, v123
	v_cvt_pk_bf16_f32 v129, v124, v125
	v_permlane16_swap_b32_e32 v168, v159
	s_ashr_i32 s17, s16, 31
	v_add_f32_e32 v166, v168, v159
	s_lshl_b64 s[16:17], s[16:17], 19
	v_lshlrev_b32_e32 v159, 6, v158
	s_movk_i32 s1, 0x33c0
	v_readlane_b32 s2, v253, 59
	v_and_or_b32 v159, v159, s1, v196
	v_readlane_b32 s3, v253, 60
	s_add_u32 s1, s2, s16
	s_addc_u32 s16, s3, s17
	s_lshl_b64 s[24:25], s[44:45], 15
	s_add_u32 s48, s1, s24
	s_waitcnt vmcnt(6)
	v_sub_f32_e32 v123, v189, v229
	v_sub_f32_e32 v122, v188, v229
	v_sub_f32_e32 v125, v187, v229
	v_sub_f32_e32 v124, v186, v229
	v_pk_mul_f32 v[124:125], v[0:1], v[124:125] op_sel_hi:[0,1]
	v_pk_mul_f32 v[122:123], v[0:1], v[122:123] op_sel_hi:[0,1]
	s_addc_u32 s49, s16, s25
	v_lshlrev_b32_e32 v159, 1, v159
	global_store_dwordx4 v159, v[126:129], s[48:49]
	v_add_f32_e32 v210, v210, v211
	s_waitcnt vmcnt(3)
; __device__ __forceinline__ float xsum16(float v) { const auto r = __builtin_amdgcn_permlane16_swap(__float_as_uint(v), __float_as_uint(v), false, false); return __uint_as_float(r[0]) + __uint_as_float(r[1]); }
; __device__ __forceinline__ float xsum32(float v) { const auto r = __builtin_amdgcn_permlane32_swap(__float_as_uint(v), __float_as_uint(v), false, false); return __uint_as_float(r[0]) + __uint_as_float(r[1]); }
; __device__ __forceinline__ size_t blk_off(int r, int c, int K) { return (size_t)(r >> 8) * 256 * K + (size_t)(c >> 6) * (256 * 64) + (size_t)((r & 255) * 64 + (c & 63)); }
; __device__ __forceinline__ u32x4 pack8(const f32x4 a, const f32x4 b) { u32x4 w; w.x = cvt_pk_bf16(a[0], a[1]); w.y = cvt_pk_bf16(a[2], a[3]); w.z = cvt_pk_bf16(b[0], b[1]); w.w = cvt_pk_bf16(b[2], b[3]); return w; }
;     __device__ __forceinline__ void operator()(const f32x4 (&acc)[2][2][4][2], const pg8::Unit& u, int wr, int wc, int fr, int fq) const {
;     ...
;                 for (int bj = 0; bj < 2; ++bj) { float* yp = Y + (size_t)row * D_ + col0 + bj * 128; f32x4 v[2];
; #pragma unroll
;                     for (int n = 0; n < 2; ++n) { v[n] = (((yv[bj][n] - mu) * rs) * gq[bj][n] + bq_[bj][n]) * ALPHA_ + acc[ai][bj][m][n] * sc;
;                         *(f32x4*)(yp + 4 * n) = v[n]; s1 += (v[n][0] + v[n][1]) + (v[n][2] + v[n][3]); s2 += (v[n][0] * v[n][0] + v[n][1] * v[n][1]) + (v[n][2] * v[n][2] + v[n][3] * v[n][3]); }
;                     *(u32x4*)(Yb + blk_off(row, col0 + bj * 128, D_)) = pack8(v[0], v[1]); }
;                 s1 = xsum32(xsum16(s1)); s2 = xsum32(xsum16(s2));
;                 if (fq == 0) *(f32x2*)(stn + (size_t)row * 32 + (u.pn * 4 + wc) * 2) = (f32x2){s1, s2}; asm volatile("" ::: "memory"); } }
	v_pk_fma_f32 v[122:123], v[200:201], v[122:123], v[240:241]
	v_pk_fma_f32 v[124:125], v[198:199], v[124:125], v[238:239]
	v_pk_mul_f32 v[122:123], v[122:123], s[18:19] op_sel_hi:[1,0]
	v_pk_mul_f32 v[124:125], v[124:125], s[18:19] op_sel_hi:[1,0]
	v_pk_fma_f32 v[120:121], v[120:121], 0.5, v[122:123] op_sel_hi:[1,0,1]
	v_pk_fma_f32 v[118:119], v[118:119], 0.5, v[124:125] op_sel_hi:[1,0,1]
	v_add_f32_e32 v123, v120, v121
	v_add_f32_e32 v122, v118, v119
	v_add_f32_e32 v122, v122, v123
	v_add_f32_e32 v126, v197, v122
	v_mul_f32_e32 v122, v119, v119
	v_mul_f32_e32 v123, v121, v121
	v_add_f32_e32 v206, v206, v207
	v_fmac_f32_e32 v122, v118, v118
	v_fmac_f32_e32 v123, v120, v120
	v_add_f32_e32 v206, v210, v206
	v_add_f32_e32 v122, v122, v123
	v_add_f32_e32 v127, v206, v122
	v_sub_f32_e32 v123, v181, v229
	v_sub_f32_e32 v122, v180, v229
	v_sub_f32_e32 v125, v179, v229
	v_sub_f32_e32 v124, v178, v229
	v_pk_mul_f32 v[124:125], v[0:1], v[124:125] op_sel_hi:[0,1]
	v_pk_mul_f32 v[122:123], v[0:1], v[122:123] op_sel_hi:[0,1]
	v_pk_fma_f32 v[122:123], v[192:193], v[122:123], v[204:205]
	v_pk_fma_f32 v[124:125], v[190:191], v[124:125], v[202:203]
	v_pk_mul_f32 v[122:123], v[122:123], s[18:19] op_sel_hi:[1,0]
	v_pk_mul_f32 v[124:125], v[124:125], s[18:19] op_sel_hi:[1,0]
	v_pk_fma_f32 v[116:117], v[116:117], 0.5, v[122:123] op_sel_hi:[1,0,1]
	v_pk_fma_f32 v[114:115], v[114:115], 0.5, v[124:125] op_sel_hi:[1,0,1]
	v_add_f32_e32 v122, v116, v117
	v_add_f32_e32 v0, v114, v115
	v_add_f32_e32 v0, v0, v122
	v_mul_f32_e32 v122, v115, v115
	v_mul_f32_e32 v123, v117, v117
	v_add_f32_e32 v0, v126, v0
	v_fmac_f32_e32 v122, v114, v114
	v_fmac_f32_e32 v123, v116, v116
	s_nop 0
	s_nop 1
	v_bfe_u32 v125, v227, 4, 2
	v_sub_u32_e32 v124, 0, v125
	v_lshlrev_b32_e32 v124, 4, v124
	v_ashrrev_i32_e32 v125, 31, v124
	v_lshl_add_u64 v[124:125], v[136:137], 0, v[124:125]
	v_permlane16_swap_b32_e32 v118, v114
	v_permlane16_swap_b32_e32 v119, v115
	v_permlane16_swap_b32_e32 v120, v116
	v_permlane16_swap_b32_e32 v121, v117
	v_permlane32_swap_b32_e32 v118, v114
	v_permlane32_swap_b32_e32 v119, v115
	v_permlane32_swap_b32_e32 v120, v116
	v_permlane32_swap_b32_e32 v121, v117
	v_mov_b32_e32 v134, v118
	v_mov_b32_e32 v135, v119
	v_mov_b32_e32 v168, v120
	v_mov_b32_e32 v169, v121
	v_bfe_u32 v128, v227, 3, 1
	v_mul_i32_i24_e32 v128, 0xffff8040, v128
	v_ashrrev_i32_e32 v129, 31, v128
	v_lshl_add_u64 v[124:125], v[124:125], 0, v[128:129]
	v_mov_b32_e32 v128, 0x8000
	v_mov_b32_e32 v129, 0
	v_lshl_add_u64 v[128:129], v[124:125], 0, v[128:129]
	v_mov_b32_dpp v118, v114 row_ror:8 row_mask:0xf bank_mask:0xc
	v_mov_b32_dpp v119, v115 row_ror:8 row_mask:0xf bank_mask:0xc
	v_mov_b32_dpp v120, v116 row_ror:8 row_mask:0xf bank_mask:0xc
	v_mov_b32_dpp v121, v117 row_ror:8 row_mask:0xf bank_mask:0xc
	v_mov_b32_dpp v114, v134 row_ror:8 row_mask:0xf bank_mask:0x3
	v_mov_b32_dpp v115, v135 row_ror:8 row_mask:0xf bank_mask:0x3
	v_mov_b32_dpp v116, v168 row_ror:8 row_mask:0xf bank_mask:0x3
	v_mov_b32_dpp v117, v169 row_ror:8 row_mask:0xf bank_mask:0x3
	global_store_dwordx4 v[124:125], v[118:121], off offset:512
	global_store_dwordx4 v[128:129], v[114:117], off offset:512
	s_nop 1
	v_mov_b32_dpp v114, v118 row_ror:8 row_mask:0xf bank_mask:0x3
	v_mov_b32_dpp v115, v119 row_ror:8 row_mask:0xf bank_mask:0x3
	v_mov_b32_dpp v116, v120 row_ror:8 row_mask:0xf bank_mask:0x3
	v_mov_b32_dpp v117, v121 row_ror:8 row_mask:0xf bank_mask:0x3
	v_mov_b32_e32 v118, v134
	v_mov_b32_e32 v119, v135
	v_mov_b32_e32 v120, v168
	v_mov_b32_e32 v121, v169
	s_nop 1
	v_permlane32_swap_b32_e32 v118, v114
	v_permlane32_swap_b32_e32 v119, v115
	v_permlane32_swap_b32_e32 v120, v116
	v_permlane32_swap_b32_e32 v121, v117
	v_permlane16_swap_b32_e32 v118, v114
	v_permlane16_swap_b32_e32 v119, v115
	v_permlane16_swap_b32_e32 v120, v116
	v_permlane16_swap_b32_e32 v121, v117
	v_add_f32_e32 v122, v122, v123
	v_cvt_pk_bf16_f32 v118, v118, v119
	v_cvt_pk_bf16_f32 v119, v120, v121
	v_cvt_pk_bf16_f32 v120, v114, v115
	v_mov_b32_e32 v114, v0
	v_add_f32_e32 v122, v127, v122
	s_nop 0
	v_permlane16_swap_b32_e32 v0, v114
	s_or_b32 s2, s44, 2
	v_add_f32_e32 v114, v0, v114
	v_mov_b32_e32 v0, v122
	s_ashr_i32 s3, s2, 31
	s_nop 0
	v_permlane16_swap_b32_e32 v122, v0
	s_lshl_b64 s[44:45], s[2:3], 15
	v_add_f32_e32 v115, v122, v0
	v_mov_b32_e32 v135, v133
	v_mov_b32_e32 v134, v132
	v_mov_b32_e32 v177, v175
	v_mov_b32_e32 v176, v174
	v_mov_b32_e32 v169, v167
	v_mov_b32_e32 v168, v166
	v_cvt_pk_bf16_f32 v121, v116, v117
	s_add_u32 s46, s1, s44
	v_mov_b32_e32 v116, v114
	v_mov_b32_e32 v117, v115
	v_permlane32_swap_b32_e32 v133, v135
	v_permlane32_swap_b32_e32 v132, v134
	v_permlane32_swap_b32_e32 v175, v177
	v_permlane32_swap_b32_e32 v174, v176
	v_permlane32_swap_b32_e32 v167, v169
	v_permlane32_swap_b32_e32 v166, v168
	s_addc_u32 s47, s16, s45
	v_permlane32_swap_b32_e32 v114, v116
	v_permlane32_swap_b32_e32 v115, v117
	global_store_dwordx4 v159, v[118:121], s[46:47]
	s_and_saveexec_b64 s[26:27], s[40:41]
	s_cbranch_execz .LBB0_1705
	v_pk_add_f32 v[114:115], v[114:115], v[116:117]
	v_lshl_add_u64 v[116:117], s[8:9], 0, v[130:131]
	v_lshl_add_u64 v[116:117], s[38:39], 2, v[116:117]
	global_store_dwordx2 v[116:117], v[114:115], off
; __device__ __forceinline__ size_t blk_off(int r, int c, int K) { return (size_t)(r >> 8) * 256 * K + (size_t)(c >> 6) * (256 * 64) + (size_t)((r & 255) * 64 + (c & 63)); }
; __device__ __forceinline__ u32x4 pack8(const f32x4 a, const f32x4 b) { u32x4 w; w.x = cvt_pk_bf16(a[0], a[1]); w.y = cvt_pk_bf16(a[2], a[3]); w.z = cvt_pk_bf16(b[0], b[1]); w.w = cvt_pk_bf16(b[2], b[3]); return w; }
;     __device__ __forceinline__ void operator()(const f32x4 (&acc)[2][2][4][2], const pg8::Unit& u, int wr, int wc, int fr, int fq) const {
;     ...
;             for (int m = 0; m < 4; ++m) { const int row = row0 + ai * 128 + m * 16; const float mu = mu4[m], rs = rs4[m];
;                 f32x4 yv[2][2], gq[2][2], bq_[2][2];
; #pragma unroll
;                 for (int bj = 0; bj < 2; ++bj)
; #pragma unroll
;                     for (int n = 0; n < 2; ++n) { yv[bj][n] = *(const f32x4*)(Yin + (size_t)row * D_ + col0 + bj * 128 + 4 * n); gq[bj][n] = *(const f32x4*)(g + col0 + bj * 128 + 4 * n); bq_[bj][n] = *(const f32x4*)(b + col0 + bj * 128 + 4 * n); }
;                 asm volatile("" ::: "memory");
;                 float s1 = 0.f, s2 = 0.f;
; #pragma unroll
;                 for (int bj = 0; bj < 2; ++bj) { float* yp = Y + (size_t)row * D_ + col0 + bj * 128; f32x4 v[2];
; #pragma unroll
;                     for (int n = 0; n < 2; ++n) { v[n] = (((yv[bj][n] - mu) * rs) * gq[bj][n] + bq_[bj][n]) * ALPHA_ + acc[ai][bj][m][n] * sc;
;                         *(f32x4*)(yp + 4 * n) = v[n]; s1 += (v[n][0] + v[n][1]) + (v[n][2] + v[n][3]); s2 += (v[n][0] * v[n][0] + v[n][1] * v[n][1]) + (v[n][2] * v[n][2] + v[n][3] * v[n][3]); }
;                     *(u32x4*)(Yb + blk_off(row, col0 + bj * 128, D_)) = pack8(v[0], v[1]); }
.LBB0_1705:
	s_or_b64 exec, exec, s[26:27]
	v_pk_add_f32 v[114:115], v[132:133], v[134:135]
	s_mov_b32 s2, 0x3a800000
	v_pk_mul_f32 v[178:179], v[114:115], s[2:3] op_sel_hi:[1,0]
	s_mov_b32 s1, 0x800000
	v_fma_f32 v0, -v179, v179, v178
	v_max_f32_e32 v0, 0, v0
	v_add_f32_e32 v0, 0x3727c5ac, v0
	v_cmp_gt_f32_e32 vcc, s1, v0
	v_mul_f32_e32 v114, 0x4b800000, v0
	s_load_dwordx16 s[60:75], s[34:35], 0x38
	v_cndmask_b32_e32 v0, v0, v114, vcc
	v_rsq_f32_e32 v0, v0
	v_lshlrev_b32_e32 v159, 6, v182
	s_mov_b32 s2, 0x3fd744fd
	v_mul_f32_e32 v114, 0x45800000, v0
	v_cndmask_b32_e32 v0, v0, v114, vcc
	v_lshlrev_b64 v[114:115], 12, v[182:183]
	s_waitcnt lgkmcnt(0)
	v_lshl_add_u64 v[114:115], s[74:75], 0, v[114:115]
	v_lshl_add_u64 v[180:181], v[152:153], 2, v[114:115]
	global_load_dwordx4 v[186:189], v[180:181], off offset:16
	global_load_dwordx4 v[190:193], v[180:181], off
	global_load_dwordx4 v[198:201], v[156:157], off offset:16
	global_load_dwordx4 v[202:205], v[156:157], off
	global_load_dwordx4 v[206:209], v[154:155], off offset:16
	global_load_dwordx4 v[210:213], v[154:155], off
	global_load_dwordx4 v[114:117], v[180:181], off offset:528
	global_load_dwordx4 v[134:137], v[180:181], off offset:512
	global_load_dwordx4 v[118:121], v[156:157], off offset:528
	global_load_dwordx4 v[126:129], v[156:157], off offset:512
	global_load_dwordx4 v[122:125], v[154:155], off offset:528
	global_load_dwordx4 v[130:133], v[154:155], off offset:512
	s_movk_i32 s1, 0x37c0
	v_and_or_b32 v159, v159, s1, v196
	v_lshlrev_b32_e32 v159, 1, v159
	s_waitcnt vmcnt(11)
	v_sub_f32_e32 v187, v187, v179
	s_waitcnt vmcnt(10)
	v_sub_f32_e32 v183, v193, v179
	v_sub_f32_e32 v182, v192, v179
	v_sub_f32_e32 v191, v191, v179
	v_sub_f32_e32 v190, v190, v179
	v_pk_mul_f32 v[190:191], v[0:1], v[190:191] op_sel_hi:[0,1]
	v_pk_mul_f32 v[182:183], v[0:1], v[182:183] op_sel_hi:[0,1]
	s_waitcnt vmcnt(6)
	v_pk_fma_f32 v[182:183], v[204:205], v[182:183], v[212:213]
	v_pk_fma_f32 v[190:191], v[202:203], v[190:191], v[210:211]
	v_pk_mul_f32 v[182:183], v[182:183], s[2:3] op_sel_hi:[1,0]
	v_pk_mul_f32 v[190:191], v[190:191], s[2:3] op_sel_hi:[1,0]
	v_pk_fma_f32 v[112:113], v[112:113], 0.5, v[182:183] op_sel_hi:[1,0,1]
	v_pk_fma_f32 v[110:111], v[110:111], 0.5, v[190:191] op_sel_hi:[1,0,1]
	v_add_f32_e32 v182, v112, v113
	v_add_f32_e32 v178, v110, v111
	v_add_f32_e32 v178, v178, v182
	v_mul_f32_e32 v182, v111, v111
	v_mul_f32_e32 v183, v113, v113
	v_fmac_f32_e32 v182, v110, v110
	v_fmac_f32_e32 v183, v112, v112
	v_add_f32_e32 v190, v182, v183
	v_sub_f32_e32 v183, v189, v179
	v_sub_f32_e32 v182, v188, v179
	v_sub_f32_e32 v186, v186, v179
	v_pk_mul_f32 v[186:187], v[0:1], v[186:187] op_sel_hi:[0,1]
	v_pk_mul_f32 v[182:183], v[0:1], v[182:183] op_sel_hi:[0,1]
	v_pk_fma_f32 v[182:183], v[200:201], v[182:183], v[208:209]
	v_pk_fma_f32 v[186:187], v[198:199], v[186:187], v[206:207]
	v_pk_mul_f32 v[182:183], v[182:183], s[2:3] op_sel_hi:[1,0]
	v_pk_mul_f32 v[186:187], v[186:187], s[2:3] op_sel_hi:[1,0]
	v_pk_fma_f32 v[108:109], v[108:109], 0.5, v[182:183] op_sel_hi:[1,0,1]
	v_pk_fma_f32 v[106:107], v[106:107], 0.5, v[186:187] op_sel_hi:[1,0,1]
	v_add_f32_e32 v183, v108, v109
	v_add_f32_e32 v182, v106, v107
	v_add_f32_e32 v178, 0, v178
	v_add_f32_e32 v182, v182, v183
	v_add_f32_e32 v178, v178, v182
	v_mul_f32_e32 v182, v107, v107
	v_mul_f32_e32 v183, v109, v109
	s_nop 0
	s_nop 1
	v_bfe_u32 v187, v227, 4, 2
	v_sub_u32_e32 v186, 0, v187
	v_lshlrev_b32_e32 v186, 4, v186
	v_ashrrev_i32_e32 v187, 31, v186
	v_lshl_add_u64 v[186:187], v[180:181], 0, v[186:187]
	v_permlane16_swap_b32_e32 v110, v106
	v_permlane16_swap_b32_e32 v111, v107
	v_permlane16_swap_b32_e32 v112, v108
	v_permlane16_swap_b32_e32 v113, v109
	v_permlane32_swap_b32_e32 v110, v106
	v_permlane32_swap_b32_e32 v111, v107
	v_permlane32_swap_b32_e32 v112, v108
	v_permlane32_swap_b32_e32 v113, v109
	v_mov_b32_e32 v191, v110
	v_mov_b32_e32 v192, v111
	v_mov_b32_e32 v193, v112
	v_mov_b32_e32 v197, v113
	v_bfe_u32 v188, v227, 3, 1
	v_mul_i32_i24_e32 v188, 0xffff8040, v188
	v_ashrrev_i32_e32 v189, 31, v188
	v_lshl_add_u64 v[186:187], v[186:187], 0, v[188:189]
	v_mov_b32_e32 v188, 0x8000
	v_mov_b32_e32 v189, 0
	v_lshl_add_u64 v[188:189], v[186:187], 0, v[188:189]
	v_mov_b32_dpp v110, v106 row_ror:8 row_mask:0xf bank_mask:0xc
	v_mov_b32_dpp v111, v107 row_ror:8 row_mask:0xf bank_mask:0xc
	v_mov_b32_dpp v112, v108 row_ror:8 row_mask:0xf bank_mask:0xc
	v_mov_b32_dpp v113, v109 row_ror:8 row_mask:0xf bank_mask:0xc
	v_mov_b32_dpp v106, v191 row_ror:8 row_mask:0xf bank_mask:0x3
	v_mov_b32_dpp v107, v192 row_ror:8 row_mask:0xf bank_mask:0x3
	v_mov_b32_dpp v108, v193 row_ror:8 row_mask:0xf bank_mask:0x3
	v_mov_b32_dpp v109, v197 row_ror:8 row_mask:0xf bank_mask:0x3
	global_store_dwordx4 v[186:187], v[110:113], off
	global_store_dwordx4 v[188:189], v[106:109], off
	s_nop 1
	v_mov_b32_dpp v106, v110 row_ror:8 row_mask:0xf bank_mask:0x3
	v_mov_b32_dpp v107, v111 row_ror:8 row_mask:0xf bank_mask:0x3
	v_mov_b32_dpp v108, v112 row_ror:8 row_mask:0xf bank_mask:0x3
	v_mov_b32_dpp v109, v113 row_ror:8 row_mask:0xf bank_mask:0x3
	v_mov_b32_e32 v110, v191
	v_mov_b32_e32 v111, v192
	v_mov_b32_e32 v112, v193
	v_mov_b32_e32 v113, v197
	s_nop 1
	v_permlane32_swap_b32_e32 v110, v106
	v_permlane32_swap_b32_e32 v111, v107
	v_permlane32_swap_b32_e32 v112, v108
	v_permlane32_swap_b32_e32 v113, v109
	v_permlane16_swap_b32_e32 v110, v106
	v_permlane16_swap_b32_e32 v111, v107
	v_permlane16_swap_b32_e32 v112, v108
	v_permlane16_swap_b32_e32 v113, v109
	v_fmac_f32_e32 v182, v106, v106
	v_fmac_f32_e32 v183, v108, v108
	v_cvt_pk_bf16_f32 v110, v110, v111
	v_cvt_pk_bf16_f32 v111, v112, v113
	v_cvt_pk_bf16_f32 v112, v106, v107
	v_cvt_pk_bf16_f32 v113, v108, v109
	s_waitcnt vmcnt(6)
; __device__ __forceinline__ float xsum16(float v) { const auto r = __builtin_amdgcn_permlane16_swap(__float_as_uint(v), __float_as_uint(v), false, false); return __uint_as_float(r[0]) + __uint_as_float(r[1]); }
; __device__ __forceinline__ float xsum32(float v) { const auto r = __builtin_amdgcn_permlane32_swap(__float_as_uint(v), __float_as_uint(v), false, false); return __uint_as_float(r[0]) + __uint_as_float(r[1]); }
; __device__ __forceinline__ size_t blk_off(int r, int c, int K) { return (size_t)(r >> 8) * 256 * K + (size_t)(c >> 6) * (256 * 64) + (size_t)((r & 255) * 64 + (c & 63)); }
; __device__ __forceinline__ u32x4 pack8(const f32x4 a, const f32x4 b) { u32x4 w; w.x = cvt_pk_bf16(a[0], a[1]); w.y = cvt_pk_bf16(a[2], a[3]); w.z = cvt_pk_bf16(b[0], b[1]); w.w = cvt_pk_bf16(b[2], b[3]); return w; }
;     __device__ __forceinline__ void operator()(const f32x4 (&acc)[2][2][4][2], const pg8::Unit& u, int wr, int wc, int fr, int fq) const {
;     ...
;                 for (int bj = 0; bj < 2; ++bj) { float* yp = Y + (size_t)row * D_ + col0 + bj * 128; f32x4 v[2];
; #pragma unroll
;                     for (int n = 0; n < 2; ++n) { v[n] = (((yv[bj][n] - mu) * rs) * gq[bj][n] + bq_[bj][n]) * ALPHA_ + acc[ai][bj][m][n] * sc;
;                         *(f32x4*)(yp + 4 * n) = v[n]; s1 += (v[n][0] + v[n][1]) + (v[n][2] + v[n][3]); s2 += (v[n][0] * v[n][0] + v[n][1] * v[n][1]) + (v[n][2] * v[n][2] + v[n][3] * v[n][3]); }
;                     *(u32x4*)(Yb + blk_off(row, col0 + bj * 128, D_)) = pack8(v[0], v[1]); }
;                 s1 = xsum32(xsum16(s1)); s2 = xsum32(xsum16(s2));
;                 if (fq == 0) *(f32x2*)(stn + (size_t)row * 32 + (u.pn * 4 + wc) * 2) = (f32x2){s1, s2}; asm volatile("" ::: "memory"); } }
	v_sub_f32_e32 v107, v137, v179
	v_sub_f32_e32 v106, v136, v179
	v_sub_f32_e32 v109, v135, v179
	v_sub_f32_e32 v108, v134, v179
	v_pk_mul_f32 v[108:109], v[0:1], v[108:109] op_sel_hi:[0,1]
	v_pk_mul_f32 v[106:107], v[0:1], v[106:107] op_sel_hi:[0,1]
	s_waitcnt vmcnt(2)
	v_pk_fma_f32 v[106:107], v[128:129], v[106:107], v[132:133]
	v_pk_fma_f32 v[108:109], v[126:127], v[108:109], v[130:131]
	v_pk_mul_f32 v[106:107], v[106:107], s[2:3] op_sel_hi:[1,0]
	v_pk_mul_f32 v[108:109], v[108:109], s[2:3] op_sel_hi:[1,0]
	v_pk_fma_f32 v[104:105], v[104:105], 0.5, v[106:107] op_sel_hi:[1,0,1]
	v_pk_fma_f32 v[102:103], v[102:103], 0.5, v[108:109] op_sel_hi:[1,0,1]
	v_add_f32_e32 v107, v104, v105
	v_add_f32_e32 v106, v102, v103
	v_add_f32_e32 v106, v106, v107
	global_store_dwordx4 v159, v[110:113], s[48:49]
	v_mul_f32_e32 v107, v105, v105
	v_add_f32_e32 v182, v182, v183
	v_add_f32_e32 v110, v178, v106
	v_mul_f32_e32 v106, v103, v103
	v_fmac_f32_e32 v106, v102, v102
	v_fmac_f32_e32 v107, v104, v104
	v_add_f32_e32 v182, v190, v182
	v_add_f32_e32 v106, v106, v107
	v_add_f32_e32 v111, v182, v106
	v_sub_f32_e32 v107, v117, v179
	v_sub_f32_e32 v106, v116, v179
	v_sub_f32_e32 v109, v115, v179
	v_sub_f32_e32 v108, v114, v179
	v_pk_mul_f32 v[108:109], v[0:1], v[108:109] op_sel_hi:[0,1]
	v_pk_mul_f32 v[106:107], v[0:1], v[106:107] op_sel_hi:[0,1]
	v_pk_fma_f32 v[106:107], v[120:121], v[106:107], v[124:125]
	v_pk_fma_f32 v[108:109], v[118:119], v[108:109], v[122:123]
	v_pk_mul_f32 v[106:107], v[106:107], s[2:3] op_sel_hi:[1,0]
	v_pk_mul_f32 v[108:109], v[108:109], s[2:3] op_sel_hi:[1,0]
	v_pk_fma_f32 v[100:101], v[100:101], 0.5, v[106:107] op_sel_hi:[1,0,1]
	v_pk_fma_f32 v[98:99], v[98:99], 0.5, v[108:109] op_sel_hi:[1,0,1]
	v_add_f32_e32 v106, v100, v101
	v_add_f32_e32 v0, v98, v99
	v_add_f32_e32 v0, v0, v106
	v_mul_f32_e32 v106, v99, v99
	v_mul_f32_e32 v107, v101, v101
	v_add_f32_e32 v0, v110, v0
	v_fmac_f32_e32 v106, v98, v98
	v_fmac_f32_e32 v107, v100, v100
	s_nop 0
	s_nop 1
	v_bfe_u32 v109, v227, 4, 2
	v_sub_u32_e32 v108, 0, v109
	v_lshlrev_b32_e32 v108, 4, v108
	v_ashrrev_i32_e32 v109, 31, v108
	v_lshl_add_u64 v[108:109], v[180:181], 0, v[108:109]
	v_permlane16_swap_b32_e32 v102, v98
	v_permlane16_swap_b32_e32 v103, v99
	v_permlane16_swap_b32_e32 v104, v100
	v_permlane16_swap_b32_e32 v105, v101
	v_permlane32_swap_b32_e32 v102, v98
	v_permlane32_swap_b32_e32 v103, v99
	v_permlane32_swap_b32_e32 v104, v100
	v_permlane32_swap_b32_e32 v105, v101
	v_mov_b32_e32 v114, v102
	v_mov_b32_e32 v115, v103
	v_mov_b32_e32 v116, v104
	v_mov_b32_e32 v117, v105
	v_bfe_u32 v112, v227, 3, 1
	v_mul_i32_i24_e32 v112, 0xffff8040, v112
	v_ashrrev_i32_e32 v113, 31, v112
	v_lshl_add_u64 v[108:109], v[108:109], 0, v[112:113]
	v_mov_b32_e32 v112, 0x8000
	v_mov_b32_e32 v113, 0
	v_lshl_add_u64 v[112:113], v[108:109], 0, v[112:113]
	v_mov_b32_dpp v102, v98 row_ror:8 row_mask:0xf bank_mask:0xc
	v_mov_b32_dpp v103, v99 row_ror:8 row_mask:0xf bank_mask:0xc
	v_mov_b32_dpp v104, v100 row_ror:8 row_mask:0xf bank_mask:0xc
	v_mov_b32_dpp v105, v101 row_ror:8 row_mask:0xf bank_mask:0xc
	v_mov_b32_dpp v98, v114 row_ror:8 row_mask:0xf bank_mask:0x3
	v_mov_b32_dpp v99, v115 row_ror:8 row_mask:0xf bank_mask:0x3
	v_mov_b32_dpp v100, v116 row_ror:8 row_mask:0xf bank_mask:0x3
	v_mov_b32_dpp v101, v117 row_ror:8 row_mask:0xf bank_mask:0x3
	global_store_dwordx4 v[108:109], v[102:105], off offset:512
	global_store_dwordx4 v[112:113], v[98:101], off offset:512
	s_nop 1
	v_mov_b32_dpp v98, v102 row_ror:8 row_mask:0xf bank_mask:0x3
	v_mov_b32_dpp v99, v103 row_ror:8 row_mask:0xf bank_mask:0x3
	v_mov_b32_dpp v100, v104 row_ror:8 row_mask:0xf bank_mask:0x3
	v_mov_b32_dpp v101, v105 row_ror:8 row_mask:0xf bank_mask:0x3
	v_mov_b32_e32 v102, v114
	v_mov_b32_e32 v103, v115
	v_mov_b32_e32 v104, v116
	v_mov_b32_e32 v105, v117
	s_nop 1
	v_permlane32_swap_b32_e32 v102, v98
	v_permlane32_swap_b32_e32 v103, v99
	v_permlane32_swap_b32_e32 v104, v100
	v_permlane32_swap_b32_e32 v105, v101
	v_permlane16_swap_b32_e32 v102, v98
	v_permlane16_swap_b32_e32 v103, v99
	v_permlane16_swap_b32_e32 v104, v100
	v_permlane16_swap_b32_e32 v105, v101
	v_add_f32_e32 v106, v106, v107
	v_cvt_pk_bf16_f32 v102, v102, v103
	v_cvt_pk_bf16_f32 v103, v104, v105
	v_cvt_pk_bf16_f32 v104, v98, v99
	v_mov_b32_e32 v98, v0
	v_add_f32_e32 v106, v111, v106
	s_nop 0
	v_permlane16_swap_b32_e32 v0, v98
	v_add_f32_e32 v98, v0, v98
	v_mov_b32_e32 v0, v106
	s_nop 1
	v_permlane16_swap_b32_e32 v106, v0
	v_add_f32_e32 v99, v106, v0
	v_cvt_pk_bf16_f32 v105, v100, v101
	v_mov_b32_e32 v100, v98
	v_mov_b32_e32 v101, v99
	s_nop 0
	v_permlane32_swap_b32_e32 v98, v100
	v_permlane32_swap_b32_e32 v99, v101
	global_store_dwordx4 v159, v[102:105], s[46:47]
	s_and_saveexec_b64 s[26:27], s[40:41]
	s_cbranch_execz .LBB0_1707
	v_pk_add_f32 v[98:99], v[98:99], v[100:101]
	v_lshl_add_u64 v[100:101], s[8:9], 0, v[172:173]
	v_lshl_add_u64 v[100:101], s[38:39], 2, v[100:101]
	global_store_dwordx2 v[100:101], v[98:99], off
; __device__ __forceinline__ size_t blk_off(int r, int c, int K) { return (size_t)(r >> 8) * 256 * K + (size_t)(c >> 6) * (256 * 64) + (size_t)((r & 255) * 64 + (c & 63)); }
; __device__ __forceinline__ u32x4 pack8(const f32x4 a, const f32x4 b) { u32x4 w; w.x = cvt_pk_bf16(a[0], a[1]); w.y = cvt_pk_bf16(a[2], a[3]); w.z = cvt_pk_bf16(b[0], b[1]); w.w = cvt_pk_bf16(b[2], b[3]); return w; }
;     __device__ __forceinline__ void operator()(const f32x4 (&acc)[2][2][4][2], const pg8::Unit& u, int wr, int wc, int fr, int fq) const {
;     ...
;             for (int m = 0; m < 4; ++m) { const int row = row0 + ai * 128 + m * 16; const float mu = mu4[m], rs = rs4[m];
;                 f32x4 yv[2][2], gq[2][2], bq_[2][2];
; #pragma unroll
;                 for (int bj = 0; bj < 2; ++bj)
; #pragma unroll
;                     for (int n = 0; n < 2; ++n) { yv[bj][n] = *(const f32x4*)(Yin + (size_t)row * D_ + col0 + bj * 128 + 4 * n); gq[bj][n] = *(const f32x4*)(g + col0 + bj * 128 + 4 * n); bq_[bj][n] = *(const f32x4*)(b + col0 + bj * 128 + 4 * n); }
;                 asm volatile("" ::: "memory");
;                 float s1 = 0.f, s2 = 0.f;
; #pragma unroll
;                 for (int bj = 0; bj < 2; ++bj) { float* yp = Y + (size_t)row * D_ + col0 + bj * 128; f32x4 v[2];
; #pragma unroll
;                     for (int n = 0; n < 2; ++n) { v[n] = (((yv[bj][n] - mu) * rs) * gq[bj][n] + bq_[bj][n]) * ALPHA_ + acc[ai][bj][m][n] * sc;
;                         *(f32x4*)(yp + 4 * n) = v[n]; s1 += (v[n][0] + v[n][1]) + (v[n][2] + v[n][3]); s2 += (v[n][0] * v[n][0] + v[n][1] * v[n][1]) + (v[n][2] * v[n][2] + v[n][3] * v[n][3]); }
;                     *(u32x4*)(Yb + blk_off(row, col0 + bj * 128, D_)) = pack8(v[0], v[1]); }
.LBB0_1707:
	s_or_b64 exec, exec, s[26:27]
	v_pk_add_f32 v[98:99], v[174:175], v[176:177]
	s_mov_b32 s2, 0x3a800000
	v_pk_mul_f32 v[122:123], v[98:99], s[2:3] op_sel_hi:[1,0]
	s_mov_b32 s1, 0x800000
	v_fma_f32 v0, -v123, v123, v122
	v_max_f32_e32 v0, 0, v0
	v_add_f32_e32 v0, 0x3727c5ac, v0
	v_cmp_gt_f32_e32 vcc, s1, v0
	v_mul_f32_e32 v98, 0x4b800000, v0
	s_load_dwordx16 s[60:75], s[34:35], 0x38
	v_cndmask_b32_e32 v0, v0, v98, vcc
	v_rsq_f32_e32 v0, v0
	s_mov_b32 s2, 0x3fd744fd
	v_lshlrev_b32_e32 v122, 6, v170
	v_mul_f32_e32 v98, 0x45800000, v0
	v_cndmask_b32_e32 v0, v0, v98, vcc
	v_lshlrev_b64 v[98:99], 12, v[170:171]
	s_waitcnt lgkmcnt(0)
	v_lshl_add_u64 v[98:99], s[74:75], 0, v[98:99]
	v_lshl_add_u64 v[124:125], v[152:153], 2, v[98:99]
	global_load_dwordx4 v[126:129], v[124:125], off offset:16
	global_load_dwordx4 v[130:133], v[124:125], off
	global_load_dwordx4 v[134:137], v[156:157], off offset:16
	global_load_dwordx4 v[172:175], v[156:157], off
	global_load_dwordx4 v[176:179], v[154:155], off offset:16
	global_load_dwordx4 v[180:183], v[154:155], off
	global_load_dwordx4 v[98:101], v[124:125], off offset:528
	global_load_dwordx4 v[118:121], v[124:125], off offset:512
	global_load_dwordx4 v[102:105], v[156:157], off offset:528
	global_load_dwordx4 v[110:113], v[156:157], off offset:512
	global_load_dwordx4 v[106:109], v[154:155], off offset:528
	global_load_dwordx4 v[114:117], v[154:155], off offset:512
	s_movk_i32 s1, 0x3bc0
	v_and_or_b32 v122, v122, s1, v196
	v_lshlrev_b32_e32 v122, 1, v122
	s_waitcnt vmcnt(11)
	v_sub_f32_e32 v129, v129, v123
	s_waitcnt vmcnt(10)
	v_sub_f32_e32 v133, v133, v123
	v_sub_f32_e32 v132, v132, v123
	v_sub_f32_e32 v131, v131, v123
	v_sub_f32_e32 v130, v130, v123
	v_sub_f32_e32 v128, v128, v123
	v_sub_f32_e32 v127, v127, v123
	v_sub_f32_e32 v126, v126, v123
	v_pk_mul_f32 v[130:131], v[0:1], v[130:131] op_sel_hi:[0,1]
	v_pk_mul_f32 v[132:133], v[0:1], v[132:133] op_sel_hi:[0,1]
	v_pk_mul_f32 v[126:127], v[0:1], v[126:127] op_sel_hi:[0,1]
	v_pk_mul_f32 v[128:129], v[0:1], v[128:129] op_sel_hi:[0,1]
	s_waitcnt vmcnt(6)
	v_pk_fma_f32 v[132:133], v[174:175], v[132:133], v[182:183]
	v_pk_fma_f32 v[130:131], v[172:173], v[130:131], v[180:181]
	v_pk_fma_f32 v[128:129], v[136:137], v[128:129], v[178:179]
	v_pk_fma_f32 v[126:127], v[134:135], v[126:127], v[176:177]
	v_pk_mul_f32 v[130:131], v[130:131], s[2:3] op_sel_hi:[1,0]
	v_pk_mul_f32 v[132:133], v[132:133], s[2:3] op_sel_hi:[1,0]
	v_pk_mul_f32 v[126:127], v[126:127], s[2:3] op_sel_hi:[1,0]
	v_pk_mul_f32 v[128:129], v[128:129], s[2:3] op_sel_hi:[1,0]
	v_pk_fma_f32 v[96:97], v[96:97], 0.5, v[132:133] op_sel_hi:[1,0,1]
	v_pk_fma_f32 v[94:95], v[94:95], 0.5, v[130:131] op_sel_hi:[1,0,1]
	v_pk_fma_f32 v[92:93], v[92:93], 0.5, v[128:129] op_sel_hi:[1,0,1]
	v_pk_fma_f32 v[90:91], v[90:91], 0.5, v[126:127] op_sel_hi:[1,0,1]
	v_add_f32_e32 v130, v94, v95
	v_add_f32_e32 v131, v96, v97
	v_add_f32_e32 v126, v90, v91
	v_add_f32_e32 v127, v92, v93
	v_add_f32_e32 v130, v130, v131
	v_mul_f32_e32 v131, v95, v95
	v_mul_f32_e32 v132, v97, v97
	v_add_f32_e32 v126, v126, v127
	v_mul_f32_e32 v127, v91, v91
	v_mul_f32_e32 v128, v93, v93
	s_nop 0
	v_fmac_f32_e32 v131, v94, v94
	v_fmac_f32_e32 v132, v96, v96
	s_nop 1
	v_bfe_u32 v135, v227, 4, 2
	v_sub_u32_e32 v134, 0, v135
	v_lshlrev_b32_e32 v134, 4, v134
	v_ashrrev_i32_e32 v135, 31, v134
	v_lshl_add_u64 v[134:135], v[124:125], 0, v[134:135]
	v_permlane16_swap_b32_e32 v94, v90
	v_permlane16_swap_b32_e32 v95, v91
	v_permlane16_swap_b32_e32 v96, v92
	v_permlane16_swap_b32_e32 v97, v93
	v_permlane32_swap_b32_e32 v94, v90
	v_permlane32_swap_b32_e32 v95, v91
	v_permlane32_swap_b32_e32 v96, v92
	v_permlane32_swap_b32_e32 v97, v93
	v_mov_b32_e32 v129, v94
	v_mov_b32_e32 v133, v95
	v_mov_b32_e32 v159, v96
	v_mov_b32_e32 v170, v97
	v_bfe_u32 v136, v227, 3, 1
	v_mul_i32_i24_e32 v136, 0xffff8040, v136
	v_ashrrev_i32_e32 v137, 31, v136
	v_lshl_add_u64 v[134:135], v[134:135], 0, v[136:137]
	v_mov_b32_e32 v136, 0x8000
	v_mov_b32_e32 v137, 0
	v_lshl_add_u64 v[136:137], v[134:135], 0, v[136:137]
	v_mov_b32_dpp v94, v90 row_ror:8 row_mask:0xf bank_mask:0xc
	v_mov_b32_dpp v95, v91 row_ror:8 row_mask:0xf bank_mask:0xc
	v_mov_b32_dpp v96, v92 row_ror:8 row_mask:0xf bank_mask:0xc
	v_mov_b32_dpp v97, v93 row_ror:8 row_mask:0xf bank_mask:0xc
	v_mov_b32_dpp v90, v129 row_ror:8 row_mask:0xf bank_mask:0x3
	v_mov_b32_dpp v91, v133 row_ror:8 row_mask:0xf bank_mask:0x3
	v_mov_b32_dpp v92, v159 row_ror:8 row_mask:0xf bank_mask:0x3
	v_mov_b32_dpp v93, v170 row_ror:8 row_mask:0xf bank_mask:0x3
	global_store_dwordx4 v[134:135], v[94:97], off
	global_store_dwordx4 v[136:137], v[90:93], off
	s_nop 1
	v_mov_b32_dpp v90, v94 row_ror:8 row_mask:0xf bank_mask:0x3
	v_mov_b32_dpp v91, v95 row_ror:8 row_mask:0xf bank_mask:0x3
	v_mov_b32_dpp v92, v96 row_ror:8 row_mask:0xf bank_mask:0x3
	v_mov_b32_dpp v93, v97 row_ror:8 row_mask:0xf bank_mask:0x3
	v_mov_b32_e32 v94, v129
	v_mov_b32_e32 v95, v133
	v_mov_b32_e32 v96, v159
	v_mov_b32_e32 v97, v170
	s_nop 1
	v_permlane32_swap_b32_e32 v94, v90
	v_permlane32_swap_b32_e32 v95, v91
	v_permlane32_swap_b32_e32 v96, v92
	v_permlane32_swap_b32_e32 v97, v93
	v_permlane16_swap_b32_e32 v94, v90
	v_permlane16_swap_b32_e32 v95, v91
	v_permlane16_swap_b32_e32 v96, v92
	v_permlane16_swap_b32_e32 v97, v93
	v_fmac_f32_e32 v127, v90, v90
	v_fmac_f32_e32 v128, v92, v92
	v_cvt_pk_bf16_f32 v94, v94, v95
	v_cvt_pk_bf16_f32 v95, v96, v97
	v_cvt_pk_bf16_f32 v96, v90, v91
	v_cvt_pk_bf16_f32 v97, v92, v93
	s_waitcnt vmcnt(6)
	v_sub_f32_e32 v91, v121, v123
	v_sub_f32_e32 v90, v120, v123
	v_sub_f32_e32 v93, v119, v123
	v_sub_f32_e32 v92, v118, v123
	v_pk_mul_f32 v[92:93], v[0:1], v[92:93] op_sel_hi:[0,1]
	v_pk_mul_f32 v[90:91], v[0:1], v[90:91] op_sel_hi:[0,1]
	s_waitcnt vmcnt(2)
; __device__ __forceinline__ float xsum16(float v) { const auto r = __builtin_amdgcn_permlane16_swap(__float_as_uint(v), __float_as_uint(v), false, false); return __uint_as_float(r[0]) + __uint_as_float(r[1]); }
; __device__ __forceinline__ float xsum32(float v) { const auto r = __builtin_amdgcn_permlane32_swap(__float_as_uint(v), __float_as_uint(v), false, false); return __uint_as_float(r[0]) + __uint_as_float(r[1]); }
; __device__ __forceinline__ size_t blk_off(int r, int c, int K) { return (size_t)(r >> 8) * 256 * K + (size_t)(c >> 6) * (256 * 64) + (size_t)((r & 255) * 64 + (c & 63)); }
; __device__ __forceinline__ u32x4 pack8(const f32x4 a, const f32x4 b) { u32x4 w; w.x = cvt_pk_bf16(a[0], a[1]); w.y = cvt_pk_bf16(a[2], a[3]); w.z = cvt_pk_bf16(b[0], b[1]); w.w = cvt_pk_bf16(b[2], b[3]); return w; }
;     __device__ __forceinline__ void operator()(const f32x4 (&acc)[2][2][4][2], const pg8::Unit& u, int wr, int wc, int fr, int fq) const {
;     ...
;                 for (int bj = 0; bj < 2; ++bj) { float* yp = Y + (size_t)row * D_ + col0 + bj * 128; f32x4 v[2];
; #pragma unroll
;                     for (int n = 0; n < 2; ++n) { v[n] = (((yv[bj][n] - mu) * rs) * gq[bj][n] + bq_[bj][n]) * ALPHA_ + acc[ai][bj][m][n] * sc;
;                         *(f32x4*)(yp + 4 * n) = v[n]; s1 += (v[n][0] + v[n][1]) + (v[n][2] + v[n][3]); s2 += (v[n][0] * v[n][0] + v[n][1] * v[n][1]) + (v[n][2] * v[n][2] + v[n][3] * v[n][3]); }
;                     *(u32x4*)(Yb + blk_off(row, col0 + bj * 128, D_)) = pack8(v[0], v[1]); }
;                 s1 = xsum32(xsum16(s1)); s2 = xsum32(xsum16(s2));
;                 if (fq == 0) *(f32x2*)(stn + (size_t)row * 32 + (u.pn * 4 + wc) * 2) = (f32x2){s1, s2}; asm volatile("" ::: "memory"); } }
	v_pk_fma_f32 v[90:91], v[112:113], v[90:91], v[116:117]
	v_pk_fma_f32 v[92:93], v[110:111], v[92:93], v[114:115]
	v_pk_mul_f32 v[90:91], v[90:91], s[2:3] op_sel_hi:[1,0]
	v_pk_mul_f32 v[92:93], v[92:93], s[2:3] op_sel_hi:[1,0]
	v_pk_fma_f32 v[88:89], v[88:89], 0.5, v[90:91] op_sel_hi:[1,0,1]
	v_pk_fma_f32 v[86:87], v[86:87], 0.5, v[92:93] op_sel_hi:[1,0,1]
	v_add_f32_e32 v130, 0, v130
	v_add_f32_e32 v90, v86, v87
	v_add_f32_e32 v91, v88, v89
	v_add_f32_e32 v126, v130, v126
	v_add_f32_e32 v90, v90, v91
	global_store_dwordx4 v122, v[94:97], s[48:49]
	v_mul_f32_e32 v91, v89, v89
	v_add_f32_e32 v131, v131, v132
	v_add_f32_e32 v94, v126, v90
	v_mul_f32_e32 v90, v87, v87
	v_add_f32_e32 v127, v127, v128
	v_fmac_f32_e32 v90, v86, v86
	v_fmac_f32_e32 v91, v88, v88
	v_add_f32_e32 v127, v131, v127
	v_add_f32_e32 v90, v90, v91
	v_add_f32_e32 v95, v127, v90
	v_sub_f32_e32 v91, v101, v123
	v_sub_f32_e32 v90, v100, v123
	v_sub_f32_e32 v93, v99, v123
	v_sub_f32_e32 v92, v98, v123
	v_pk_mul_f32 v[92:93], v[0:1], v[92:93] op_sel_hi:[0,1]
	v_pk_mul_f32 v[90:91], v[0:1], v[90:91] op_sel_hi:[0,1]
	v_pk_fma_f32 v[90:91], v[104:105], v[90:91], v[108:109]
	v_pk_fma_f32 v[92:93], v[102:103], v[92:93], v[106:107]
	v_pk_mul_f32 v[90:91], v[90:91], s[2:3] op_sel_hi:[1,0]
	v_pk_mul_f32 v[92:93], v[92:93], s[2:3] op_sel_hi:[1,0]
	v_pk_fma_f32 v[84:85], v[84:85], 0.5, v[90:91] op_sel_hi:[1,0,1]
	v_pk_fma_f32 v[82:83], v[82:83], 0.5, v[92:93] op_sel_hi:[1,0,1]
	v_add_f32_e32 v90, v84, v85
	v_add_f32_e32 v0, v82, v83
	v_add_f32_e32 v0, v0, v90
	v_mul_f32_e32 v90, v83, v83
	v_mul_f32_e32 v91, v85, v85
	v_add_f32_e32 v0, v94, v0
	v_fmac_f32_e32 v90, v82, v82
	v_fmac_f32_e32 v91, v84, v84
	s_nop 0
	s_nop 1
	v_bfe_u32 v93, v227, 4, 2
	v_sub_u32_e32 v92, 0, v93
	v_lshlrev_b32_e32 v92, 4, v92
	v_ashrrev_i32_e32 v93, 31, v92
	v_lshl_add_u64 v[92:93], v[124:125], 0, v[92:93]
	v_permlane16_swap_b32_e32 v86, v82
	v_permlane16_swap_b32_e32 v87, v83
	v_permlane16_swap_b32_e32 v88, v84
	v_permlane16_swap_b32_e32 v89, v85
	v_permlane32_swap_b32_e32 v86, v82
	v_permlane32_swap_b32_e32 v87, v83
	v_permlane32_swap_b32_e32 v88, v84
	v_permlane32_swap_b32_e32 v89, v85
	v_mov_b32_e32 v98, v86
	v_mov_b32_e32 v99, v87
	v_mov_b32_e32 v100, v88
	v_mov_b32_e32 v101, v89
	v_bfe_u32 v96, v227, 3, 1
	v_mul_i32_i24_e32 v96, 0xffff8040, v96
	v_ashrrev_i32_e32 v97, 31, v96
	v_lshl_add_u64 v[92:93], v[92:93], 0, v[96:97]
	v_mov_b32_e32 v96, 0x8000
	v_mov_b32_e32 v97, 0
	v_lshl_add_u64 v[96:97], v[92:93], 0, v[96:97]
	v_mov_b32_dpp v86, v82 row_ror:8 row_mask:0xf bank_mask:0xc
	v_mov_b32_dpp v87, v83 row_ror:8 row_mask:0xf bank_mask:0xc
	v_mov_b32_dpp v88, v84 row_ror:8 row_mask:0xf bank_mask:0xc
	v_mov_b32_dpp v89, v85 row_ror:8 row_mask:0xf bank_mask:0xc
	v_mov_b32_dpp v82, v98 row_ror:8 row_mask:0xf bank_mask:0x3
	v_mov_b32_dpp v83, v99 row_ror:8 row_mask:0xf bank_mask:0x3
	v_mov_b32_dpp v84, v100 row_ror:8 row_mask:0xf bank_mask:0x3
	v_mov_b32_dpp v85, v101 row_ror:8 row_mask:0xf bank_mask:0x3
	global_store_dwordx4 v[92:93], v[86:89], off offset:512
	global_store_dwordx4 v[96:97], v[82:85], off offset:512
	s_nop 1
	v_mov_b32_dpp v82, v86 row_ror:8 row_mask:0xf bank_mask:0x3
	v_mov_b32_dpp v83, v87 row_ror:8 row_mask:0xf bank_mask:0x3
	v_mov_b32_dpp v84, v88 row_ror:8 row_mask:0xf bank_mask:0x3
	v_mov_b32_dpp v85, v89 row_ror:8 row_mask:0xf bank_mask:0x3
	v_mov_b32_e32 v86, v98
	v_mov_b32_e32 v87, v99
	v_mov_b32_e32 v88, v100
	v_mov_b32_e32 v89, v101
	s_nop 1
	v_permlane32_swap_b32_e32 v86, v82
	v_permlane32_swap_b32_e32 v87, v83
	v_permlane32_swap_b32_e32 v88, v84
	v_permlane32_swap_b32_e32 v89, v85
	v_permlane16_swap_b32_e32 v86, v82
	v_permlane16_swap_b32_e32 v87, v83
	v_permlane16_swap_b32_e32 v88, v84
	v_permlane16_swap_b32_e32 v89, v85
	v_add_f32_e32 v90, v90, v91
	v_cvt_pk_bf16_f32 v86, v86, v87
	v_cvt_pk_bf16_f32 v87, v88, v89
	v_cvt_pk_bf16_f32 v88, v82, v83
	v_mov_b32_e32 v82, v0
	v_add_f32_e32 v90, v95, v90
	s_nop 0
	v_permlane16_swap_b32_e32 v0, v82
	v_add_f32_e32 v82, v0, v82
	v_mov_b32_e32 v0, v90
	s_nop 1
	v_permlane16_swap_b32_e32 v90, v0
	v_add_f32_e32 v83, v90, v0
	v_cvt_pk_bf16_f32 v89, v84, v85
	v_mov_b32_e32 v84, v82
	v_mov_b32_e32 v85, v83
	s_nop 0
	v_permlane32_swap_b32_e32 v82, v84
	v_permlane32_swap_b32_e32 v83, v85
	global_store_dwordx4 v122, v[86:89], s[46:47]
	s_and_saveexec_b64 s[26:27], s[40:41]
	s_cbranch_execz .LBB0_1709
	v_pk_add_f32 v[82:83], v[82:83], v[84:85]
	v_lshl_add_u64 v[84:85], s[8:9], 0, v[164:165]
	v_lshl_add_u64 v[84:85], s[38:39], 2, v[84:85]
	global_store_dwordx2 v[84:85], v[82:83], off
; __device__ __forceinline__ size_t blk_off(int r, int c, int K) { return (size_t)(r >> 8) * 256 * K + (size_t)(c >> 6) * (256 * 64) + (size_t)((r & 255) * 64 + (c & 63)); }
; __device__ __forceinline__ u32x4 pack8(const f32x4 a, const f32x4 b) { u32x4 w; w.x = cvt_pk_bf16(a[0], a[1]); w.y = cvt_pk_bf16(a[2], a[3]); w.z = cvt_pk_bf16(b[0], b[1]); w.w = cvt_pk_bf16(b[2], b[3]); return w; }
;     __device__ __forceinline__ void operator()(const f32x4 (&acc)[2][2][4][2], const pg8::Unit& u, int wr, int wc, int fr, int fq) const {
;     ...
;             for (int m = 0; m < 4; ++m) { const int row = row0 + ai * 128 + m * 16; const float mu = mu4[m], rs = rs4[m];
;                 f32x4 yv[2][2], gq[2][2], bq_[2][2];
; #pragma unroll
;                 for (int bj = 0; bj < 2; ++bj)
; #pragma unroll
;                     for (int n = 0; n < 2; ++n) { yv[bj][n] = *(const f32x4*)(Yin + (size_t)row * D_ + col0 + bj * 128 + 4 * n); gq[bj][n] = *(const f32x4*)(g + col0 + bj * 128 + 4 * n); bq_[bj][n] = *(const f32x4*)(b + col0 + bj * 128 + 4 * n); }
;                 asm volatile("" ::: "memory");
;                 float s1 = 0.f, s2 = 0.f;
; #pragma unroll
;                 for (int bj = 0; bj < 2; ++bj) { float* yp = Y + (size_t)row * D_ + col0 + bj * 128; f32x4 v[2];
; #pragma unroll
;                     for (int n = 0; n < 2; ++n) { v[n] = (((yv[bj][n] - mu) * rs) * gq[bj][n] + bq_[bj][n]) * ALPHA_ + acc[ai][bj][m][n] * sc;
;                         *(f32x4*)(yp + 4 * n) = v[n]; s1 += (v[n][0] + v[n][1]) + (v[n][2] + v[n][3]); s2 += (v[n][0] * v[n][0] + v[n][1] * v[n][1]) + (v[n][2] * v[n][2] + v[n][3] * v[n][3]); }
;                     *(u32x4*)(Yb + blk_off(row, col0 + bj * 128, D_)) = pack8(v[0], v[1]); }
.LBB0_1709:
	s_or_b64 exec, exec, s[26:27]
	v_pk_add_f32 v[82:83], v[166:167], v[168:169]
	s_mov_b32 s2, 0x3a800000
	v_pk_mul_f32 v[106:107], v[82:83], s[2:3] op_sel_hi:[1,0]
	s_mov_b32 s1, 0x800000
	v_fma_f32 v0, -v107, v107, v106
	v_max_f32_e32 v0, 0, v0
	v_add_f32_e32 v0, 0x3727c5ac, v0
	v_cmp_gt_f32_e32 vcc, s1, v0
	v_mul_f32_e32 v82, 0x4b800000, v0
	s_load_dwordx16 s[60:75], s[34:35], 0x38
	v_cndmask_b32_e32 v0, v0, v82, vcc
	v_rsq_f32_e32 v0, v0
	s_mov_b32 s2, 0x3fd744fd
	v_lshlrev_b32_e32 v106, 6, v162
	v_mul_f32_e32 v82, 0x45800000, v0
	v_cndmask_b32_e32 v0, v0, v82, vcc
	v_lshlrev_b64 v[82:83], 12, v[162:163]
	s_waitcnt lgkmcnt(0)
	v_lshl_add_u64 v[82:83], s[74:75], 0, v[82:83]
	v_lshl_add_u64 v[108:109], v[152:153], 2, v[82:83]
	global_load_dwordx4 v[110:113], v[108:109], off offset:16
	global_load_dwordx4 v[114:117], v[108:109], off
	global_load_dwordx4 v[118:121], v[156:157], off offset:16
	global_load_dwordx4 v[122:125], v[156:157], off
	global_load_dwordx4 v[126:129], v[154:155], off offset:16
	global_load_dwordx4 v[130:133], v[154:155], off
	global_load_dwordx4 v[82:85], v[108:109], off offset:528
	global_load_dwordx4 v[102:105], v[108:109], off offset:512
	global_load_dwordx4 v[86:89], v[156:157], off offset:528
	global_load_dwordx4 v[94:97], v[156:157], off offset:512
	global_load_dwordx4 v[90:93], v[154:155], off offset:528
	global_load_dwordx4 v[98:101], v[154:155], off offset:512
	s_movk_i32 s1, 0x3fc0
	v_and_or_b32 v106, v106, s1, v196
	v_lshlrev_b32_e32 v106, 1, v106
	s_waitcnt vmcnt(11)
	v_sub_f32_e32 v113, v113, v107
	s_waitcnt vmcnt(10)
	v_sub_f32_e32 v117, v117, v107
	v_sub_f32_e32 v116, v116, v107
	v_sub_f32_e32 v115, v115, v107
	v_sub_f32_e32 v114, v114, v107
	v_sub_f32_e32 v112, v112, v107
	v_sub_f32_e32 v111, v111, v107
	v_sub_f32_e32 v110, v110, v107
	v_pk_mul_f32 v[114:115], v[0:1], v[114:115] op_sel_hi:[0,1]
	v_pk_mul_f32 v[116:117], v[0:1], v[116:117] op_sel_hi:[0,1]
	v_pk_mul_f32 v[110:111], v[0:1], v[110:111] op_sel_hi:[0,1]
	v_pk_mul_f32 v[112:113], v[0:1], v[112:113] op_sel_hi:[0,1]
	s_waitcnt vmcnt(6)
	v_pk_fma_f32 v[116:117], v[124:125], v[116:117], v[132:133]
	v_pk_fma_f32 v[114:115], v[122:123], v[114:115], v[130:131]
	v_pk_fma_f32 v[112:113], v[120:121], v[112:113], v[128:129]
	v_pk_fma_f32 v[110:111], v[118:119], v[110:111], v[126:127]
	v_pk_mul_f32 v[114:115], v[114:115], s[2:3] op_sel_hi:[1,0]
	v_pk_mul_f32 v[116:117], v[116:117], s[2:3] op_sel_hi:[1,0]
	v_pk_mul_f32 v[110:111], v[110:111], s[2:3] op_sel_hi:[1,0]
	v_pk_mul_f32 v[112:113], v[112:113], s[2:3] op_sel_hi:[1,0]
	v_pk_fma_f32 v[80:81], v[80:81], 0.5, v[116:117] op_sel_hi:[1,0,1]
	v_pk_fma_f32 v[78:79], v[78:79], 0.5, v[114:115] op_sel_hi:[1,0,1]
	v_pk_fma_f32 v[76:77], v[76:77], 0.5, v[112:113] op_sel_hi:[1,0,1]
	v_pk_fma_f32 v[74:75], v[74:75], 0.5, v[110:111] op_sel_hi:[1,0,1]
	v_add_f32_e32 v114, v78, v79
	v_add_f32_e32 v115, v80, v81
	v_add_f32_e32 v110, v74, v75
	v_add_f32_e32 v111, v76, v77
	v_add_f32_e32 v114, v114, v115
	v_mul_f32_e32 v115, v79, v79
	v_mul_f32_e32 v116, v81, v81
	v_add_f32_e32 v110, v110, v111
	v_mul_f32_e32 v111, v75, v75
	v_mul_f32_e32 v112, v77, v77
	s_nop 0
	v_fmac_f32_e32 v115, v78, v78
	v_fmac_f32_e32 v116, v80, v80
	s_nop 1
	v_bfe_u32 v119, v227, 4, 2
	v_sub_u32_e32 v118, 0, v119
	v_lshlrev_b32_e32 v118, 4, v118
	v_ashrrev_i32_e32 v119, 31, v118
	v_lshl_add_u64 v[118:119], v[108:109], 0, v[118:119]
	v_permlane16_swap_b32_e32 v78, v74
	v_permlane16_swap_b32_e32 v79, v75
	v_permlane16_swap_b32_e32 v80, v76
	v_permlane16_swap_b32_e32 v81, v77
	v_permlane32_swap_b32_e32 v78, v74
	v_permlane32_swap_b32_e32 v79, v75
	v_permlane32_swap_b32_e32 v80, v76
	v_permlane32_swap_b32_e32 v81, v77
	v_mov_b32_e32 v113, v78
	v_mov_b32_e32 v117, v79
	v_mov_b32_e32 v122, v80
	v_mov_b32_e32 v123, v81
	v_bfe_u32 v120, v227, 3, 1
	v_mul_i32_i24_e32 v120, 0xffff8040, v120
	v_ashrrev_i32_e32 v121, 31, v120
	v_lshl_add_u64 v[118:119], v[118:119], 0, v[120:121]
	v_mov_b32_e32 v120, 0x8000
	v_mov_b32_e32 v121, 0
	v_lshl_add_u64 v[120:121], v[118:119], 0, v[120:121]
	v_mov_b32_dpp v78, v74 row_ror:8 row_mask:0xf bank_mask:0xc
	v_mov_b32_dpp v79, v75 row_ror:8 row_mask:0xf bank_mask:0xc
	v_mov_b32_dpp v80, v76 row_ror:8 row_mask:0xf bank_mask:0xc
	v_mov_b32_dpp v81, v77 row_ror:8 row_mask:0xf bank_mask:0xc
	v_mov_b32_dpp v74, v113 row_ror:8 row_mask:0xf bank_mask:0x3
	v_mov_b32_dpp v75, v117 row_ror:8 row_mask:0xf bank_mask:0x3
	v_mov_b32_dpp v76, v122 row_ror:8 row_mask:0xf bank_mask:0x3
	v_mov_b32_dpp v77, v123 row_ror:8 row_mask:0xf bank_mask:0x3
	global_store_dwordx4 v[118:119], v[78:81], off
	global_store_dwordx4 v[120:121], v[74:77], off
	s_nop 1
	v_mov_b32_dpp v74, v78 row_ror:8 row_mask:0xf bank_mask:0x3
	v_mov_b32_dpp v75, v79 row_ror:8 row_mask:0xf bank_mask:0x3
	v_mov_b32_dpp v76, v80 row_ror:8 row_mask:0xf bank_mask:0x3
	v_mov_b32_dpp v77, v81 row_ror:8 row_mask:0xf bank_mask:0x3
	v_mov_b32_e32 v78, v113
	v_mov_b32_e32 v79, v117
	v_mov_b32_e32 v80, v122
	v_mov_b32_e32 v81, v123
	s_nop 1
	v_permlane32_swap_b32_e32 v78, v74
	v_permlane32_swap_b32_e32 v79, v75
	v_permlane32_swap_b32_e32 v80, v76
	v_permlane32_swap_b32_e32 v81, v77
	v_permlane16_swap_b32_e32 v78, v74
	v_permlane16_swap_b32_e32 v79, v75
	v_permlane16_swap_b32_e32 v80, v76
	v_permlane16_swap_b32_e32 v81, v77
	v_fmac_f32_e32 v111, v74, v74
	v_fmac_f32_e32 v112, v76, v76
	v_cvt_pk_bf16_f32 v78, v78, v79
	v_cvt_pk_bf16_f32 v79, v80, v81
	v_cvt_pk_bf16_f32 v80, v74, v75
	v_cvt_pk_bf16_f32 v81, v76, v77
	s_waitcnt vmcnt(6)
	v_sub_f32_e32 v75, v105, v107
	v_sub_f32_e32 v74, v104, v107
	v_sub_f32_e32 v77, v103, v107
	v_sub_f32_e32 v76, v102, v107
	v_pk_mul_f32 v[76:77], v[0:1], v[76:77] op_sel_hi:[0,1]
	v_pk_mul_f32 v[74:75], v[0:1], v[74:75] op_sel_hi:[0,1]
	s_waitcnt vmcnt(2)
; __device__ __forceinline__ float xsum16(float v) { const auto r = __builtin_amdgcn_permlane16_swap(__float_as_uint(v), __float_as_uint(v), false, false); return __uint_as_float(r[0]) + __uint_as_float(r[1]); }
; __device__ __forceinline__ float xsum32(float v) { const auto r = __builtin_amdgcn_permlane32_swap(__float_as_uint(v), __float_as_uint(v), false, false); return __uint_as_float(r[0]) + __uint_as_float(r[1]); }
; __device__ __forceinline__ size_t blk_off(int r, int c, int K) { return (size_t)(r >> 8) * 256 * K + (size_t)(c >> 6) * (256 * 64) + (size_t)((r & 255) * 64 + (c & 63)); }
; __device__ __forceinline__ u32x4 pack8(const f32x4 a, const f32x4 b) { u32x4 w; w.x = cvt_pk_bf16(a[0], a[1]); w.y = cvt_pk_bf16(a[2], a[3]); w.z = cvt_pk_bf16(b[0], b[1]); w.w = cvt_pk_bf16(b[2], b[3]); return w; }
;     __device__ __forceinline__ void operator()(const f32x4 (&acc)[2][2][4][2], const pg8::Unit& u, int wr, int wc, int fr, int fq) const {
;     ...
;                 for (int bj = 0; bj < 2; ++bj) { float* yp = Y + (size_t)row * D_ + col0 + bj * 128; f32x4 v[2];
; #pragma unroll
;                     for (int n = 0; n < 2; ++n) { v[n] = (((yv[bj][n] - mu) * rs) * gq[bj][n] + bq_[bj][n]) * ALPHA_ + acc[ai][bj][m][n] * sc;
;                         *(f32x4*)(yp + 4 * n) = v[n]; s1 += (v[n][0] + v[n][1]) + (v[n][2] + v[n][3]); s2 += (v[n][0] * v[n][0] + v[n][1] * v[n][1]) + (v[n][2] * v[n][2] + v[n][3] * v[n][3]); }
;                     *(u32x4*)(Yb + blk_off(row, col0 + bj * 128, D_)) = pack8(v[0], v[1]); }
;                 s1 = xsum32(xsum16(s1)); s2 = xsum32(xsum16(s2));
;                 if (fq == 0) *(f32x2*)(stn + (size_t)row * 32 + (u.pn * 4 + wc) * 2) = (f32x2){s1, s2}; asm volatile("" ::: "memory"); } }
	v_pk_fma_f32 v[74:75], v[96:97], v[74:75], v[100:101]
	v_pk_fma_f32 v[76:77], v[94:95], v[76:77], v[98:99]
	v_pk_mul_f32 v[74:75], v[74:75], s[2:3] op_sel_hi:[1,0]
	v_pk_mul_f32 v[76:77], v[76:77], s[2:3] op_sel_hi:[1,0]
	v_pk_fma_f32 v[72:73], v[72:73], 0.5, v[74:75] op_sel_hi:[1,0,1]
	v_pk_fma_f32 v[70:71], v[70:71], 0.5, v[76:77] op_sel_hi:[1,0,1]
	v_add_f32_e32 v114, 0, v114
	v_add_f32_e32 v74, v70, v71
	v_add_f32_e32 v75, v72, v73
	v_add_f32_e32 v110, v114, v110
	v_add_f32_e32 v74, v74, v75
	global_store_dwordx4 v106, v[78:81], s[48:49]
	v_mul_f32_e32 v75, v73, v73
	v_add_f32_e32 v115, v115, v116
	v_add_f32_e32 v78, v110, v74
	v_mul_f32_e32 v74, v71, v71
	v_add_f32_e32 v111, v111, v112
	v_fmac_f32_e32 v74, v70, v70
	v_fmac_f32_e32 v75, v72, v72
	v_add_f32_e32 v111, v115, v111
	v_add_f32_e32 v74, v74, v75
	v_add_f32_e32 v79, v111, v74
	v_sub_f32_e32 v75, v85, v107
	v_sub_f32_e32 v74, v84, v107
	v_sub_f32_e32 v77, v83, v107
	v_sub_f32_e32 v76, v82, v107
	v_pk_mul_f32 v[76:77], v[0:1], v[76:77] op_sel_hi:[0,1]
	v_pk_mul_f32 v[74:75], v[0:1], v[74:75] op_sel_hi:[0,1]
	v_pk_fma_f32 v[74:75], v[88:89], v[74:75], v[92:93]
	v_pk_fma_f32 v[76:77], v[86:87], v[76:77], v[90:91]
	v_pk_mul_f32 v[74:75], v[74:75], s[2:3] op_sel_hi:[1,0]
	v_pk_mul_f32 v[76:77], v[76:77], s[2:3] op_sel_hi:[1,0]
	v_pk_fma_f32 v[68:69], v[68:69], 0.5, v[74:75] op_sel_hi:[1,0,1]
	v_pk_fma_f32 v[66:67], v[66:67], 0.5, v[76:77] op_sel_hi:[1,0,1]
	v_add_f32_e32 v74, v68, v69
	v_add_f32_e32 v0, v66, v67
	v_add_f32_e32 v0, v0, v74
	v_mul_f32_e32 v74, v67, v67
	v_mul_f32_e32 v75, v69, v69
	v_add_f32_e32 v0, v78, v0
	v_fmac_f32_e32 v74, v66, v66
	v_fmac_f32_e32 v75, v68, v68
	s_nop 0
	s_nop 1
	v_bfe_u32 v77, v227, 4, 2
	v_sub_u32_e32 v76, 0, v77
	v_lshlrev_b32_e32 v76, 4, v76
	v_ashrrev_i32_e32 v77, 31, v76
	v_lshl_add_u64 v[76:77], v[108:109], 0, v[76:77]
	v_permlane16_swap_b32_e32 v70, v66
	v_permlane16_swap_b32_e32 v71, v67
	v_permlane16_swap_b32_e32 v72, v68
	v_permlane16_swap_b32_e32 v73, v69
	v_permlane32_swap_b32_e32 v70, v66
	v_permlane32_swap_b32_e32 v71, v67
	v_permlane32_swap_b32_e32 v72, v68
	v_permlane32_swap_b32_e32 v73, v69
	v_mov_b32_e32 v82, v70
	v_mov_b32_e32 v83, v71
	v_mov_b32_e32 v84, v72
	v_mov_b32_e32 v85, v73
	v_bfe_u32 v80, v227, 3, 1
	v_mul_i32_i24_e32 v80, 0xffff8040, v80
	v_ashrrev_i32_e32 v81, 31, v80
	v_lshl_add_u64 v[76:77], v[76:77], 0, v[80:81]
	v_mov_b32_e32 v80, 0x8000
	v_mov_b32_e32 v81, 0
	v_lshl_add_u64 v[80:81], v[76:77], 0, v[80:81]
	v_mov_b32_dpp v70, v66 row_ror:8 row_mask:0xf bank_mask:0xc
	v_mov_b32_dpp v71, v67 row_ror:8 row_mask:0xf bank_mask:0xc
	v_mov_b32_dpp v72, v68 row_ror:8 row_mask:0xf bank_mask:0xc
	v_mov_b32_dpp v73, v69 row_ror:8 row_mask:0xf bank_mask:0xc
	v_mov_b32_dpp v66, v82 row_ror:8 row_mask:0xf bank_mask:0x3
	v_mov_b32_dpp v67, v83 row_ror:8 row_mask:0xf bank_mask:0x3
	v_mov_b32_dpp v68, v84 row_ror:8 row_mask:0xf bank_mask:0x3
	v_mov_b32_dpp v69, v85 row_ror:8 row_mask:0xf bank_mask:0x3
	global_store_dwordx4 v[76:77], v[70:73], off offset:512
	global_store_dwordx4 v[80:81], v[66:69], off offset:512
	s_nop 1
	v_mov_b32_dpp v66, v70 row_ror:8 row_mask:0xf bank_mask:0x3
	v_mov_b32_dpp v67, v71 row_ror:8 row_mask:0xf bank_mask:0x3
	v_mov_b32_dpp v68, v72 row_ror:8 row_mask:0xf bank_mask:0x3
	v_mov_b32_dpp v69, v73 row_ror:8 row_mask:0xf bank_mask:0x3
	v_mov_b32_e32 v70, v82
	v_mov_b32_e32 v71, v83
	v_mov_b32_e32 v72, v84
	v_mov_b32_e32 v73, v85
	s_nop 1
	v_permlane32_swap_b32_e32 v70, v66
	v_permlane32_swap_b32_e32 v71, v67
	v_permlane32_swap_b32_e32 v72, v68
	v_permlane32_swap_b32_e32 v73, v69
	v_permlane16_swap_b32_e32 v70, v66
	v_permlane16_swap_b32_e32 v71, v67
	v_permlane16_swap_b32_e32 v72, v68
	v_permlane16_swap_b32_e32 v73, v69
	v_add_f32_e32 v74, v74, v75
	v_cvt_pk_bf16_f32 v70, v70, v71
	v_cvt_pk_bf16_f32 v71, v72, v73
	v_cvt_pk_bf16_f32 v72, v66, v67
	v_mov_b32_e32 v66, v0
	v_add_f32_e32 v74, v79, v74
	s_nop 0
	v_permlane16_swap_b32_e32 v0, v66
	v_add_f32_e32 v66, v0, v66
	v_mov_b32_e32 v0, v74
	s_nop 1
	v_permlane16_swap_b32_e32 v74, v0
	v_add_f32_e32 v67, v74, v0
	v_cvt_pk_bf16_f32 v73, v68, v69
	v_mov_b32_e32 v68, v66
	v_mov_b32_e32 v69, v67
	s_nop 0
	v_permlane32_swap_b32_e32 v66, v68
	v_permlane32_swap_b32_e32 v67, v69
	global_store_dwordx4 v106, v[70:73], s[46:47]
	s_and_saveexec_b64 s[26:27], s[40:41]
	s_cbranch_execz .LBB0_1711
	v_pk_add_f32 v[66:67], v[66:67], v[68:69]
	v_lshl_add_u64 v[68:69], s[8:9], 0, v[160:161]
	v_lshl_add_u64 v[68:69], s[38:39], 2, v[68:69]
	global_store_dwordx2 v[68:69], v[66:67], off
; __device__ __forceinline__ float xsum16(float v) { const auto r = __builtin_amdgcn_permlane16_swap(__float_as_uint(v), __float_as_uint(v), false, false); return __uint_as_float(r[0]) + __uint_as_float(r[1]); }
; __device__ __forceinline__ float xsum32(float v) { const auto r = __builtin_amdgcn_permlane32_swap(__float_as_uint(v), __float_as_uint(v), false, false); return __uint_as_float(r[0]) + __uint_as_float(r[1]); }
; __device__ __forceinline__ void row_stats4(const float* st, int rowb, int fq, float (&mu)[4], float (&rs)[4]) {
;     ...
;     for (int m = 0; m < 4; ++m) { const f32x4* p = (const f32x4*)(st + (size_t)(rowb + m * 16) * 32 + fq * 8); a[m] = p[0]; b[m] = p[1]; }
; #pragma unroll
;     for (int m = 0; m < 4; ++m) { float s1 = (a[m][0] + a[m][2]) + (b[m][0] + b[m][2]), s2 = (a[m][1] + a[m][3]) + (b[m][1] + b[m][3]);
;         s1 = xsum32(xsum16(s1)); s2 = xsum32(xsum16(s2));
;         const float mm = s1 * (1.0f / 1024.0f); mu[m] = mm; rs[m] = rsqrtf(fmaxf(s2 * (1.0f / 1024.0f) - mm * mm, 0.f) + LN_EPS_); }
;     __device__ __forceinline__ void operator()(const f32x4 (&acc)[2][2][4][2], const pg8::Unit& u, int wr, int wc, int fr, int fq) const {
;     ...
;         for (int ai = 0; ai < 2; ++ai) { float mu4[4], rs4[4]; row_stats4(stp, row0 + ai * 128, fq, mu4, rs4);
; #pragma unroll
;             for (int m = 0; m < 4; ++m) { const int row = row0 + ai * 128 + m * 16; const float mu = mu4[m], rs = rs4[m];
;                 f32x4 yv[2][2], gq[2][2], bq_[2][2];
; #pragma unroll
;                 for (int bj = 0; bj < 2; ++bj)
; #pragma unroll
;                     for (int n = 0; n < 2; ++n) { yv[bj][n] = *(const f32x4*)(Yin + (size_t)row * D_ + col0 + bj * 128 + 4 * n); gq[bj][n] = *(const f32x4*)(g + col0 + bj * 128 + 4 * n); bq_[bj][n] = *(const f32x4*)(b + col0 + bj * 128 + 4 * n); }
.LBB0_1711:
	s_or_b64 exec, exec, s[26:27]
	v_add_u32_e32 v68, 0x80, v158
	v_ashrrev_i32_e32 v69, 31, v68
	v_lshlrev_b64 v[66:67], 7, v[68:69]
	v_lshl_add_u64 v[74:75], v[146:147], 0, v[66:67]
	v_add_u32_e32 v96, 0x90, v158
	global_load_dwordx4 v[70:73], v[74:75], off
	global_load_dwordx4 v[82:85], v[74:75], off offset:16
	v_ashrrev_i32_e32 v97, 31, v96
	v_lshlrev_b64 v[86:87], 7, v[96:97]
	v_add_u32_e32 v80, 0xa0, v158
	v_lshl_add_u64 v[74:75], v[146:147], 0, v[86:87]
	v_ashrrev_i32_e32 v81, 31, v80
	global_load_dwordx4 v[88:91], v[74:75], off
	global_load_dwordx4 v[92:95], v[74:75], off offset:16
	v_lshlrev_b64 v[74:75], 7, v[80:81]
	v_lshl_add_u64 v[74:75], v[146:147], 0, v[74:75]
	global_load_dwordx4 v[98:101], v[74:75], off
	global_load_dwordx4 v[102:105], v[74:75], off offset:16
	v_add_u32_e32 v74, 0xb0, v158
	v_ashrrev_i32_e32 v75, 31, v74
	v_lshlrev_b64 v[76:77], 7, v[74:75]
	v_lshl_add_u64 v[76:77], v[146:147], 0, v[76:77]
	global_load_dwordx4 v[106:109], v[76:77], off
	global_load_dwordx4 v[110:113], v[76:77], off offset:16
	s_load_dwordx16 s[60:75], s[34:35], 0x38
	v_lshlrev_b64 v[78:79], 12, v[68:69]
	s_mov_b32 s2, 0x3a800000
	s_mov_b32 s1, 0x800000
	s_waitcnt lgkmcnt(0)
	v_lshl_add_u64 v[78:79], s[74:75], 0, v[78:79]
	v_lshl_add_u64 v[76:77], v[152:153], 2, v[78:79]
	global_load_dwordx4 v[114:117], v[76:77], off offset:16
	global_load_dwordx4 v[118:121], v[76:77], off
	global_load_dwordx4 v[122:125], v[156:157], off offset:16
	global_load_dwordx4 v[126:129], v[156:157], off
	global_load_dwordx4 v[130:133], v[154:155], off offset:16
	global_load_dwordx4 v[134:137], v[154:155], off
	s_mov_b32 s16, 0x3fd744fd
	s_waitcnt vmcnt(13)
	v_mov_b32_e32 v78, v70
	s_waitcnt vmcnt(12)
	v_mov_b32_e32 v79, v82
	v_mov_b32_e32 v158, v72
	v_mov_b32_e32 v159, v84
	v_mov_b32_e32 v82, v71
	v_mov_b32_e32 v84, v73
	v_pk_add_f32 v[78:79], v[78:79], v[158:159]
	v_pk_add_f32 v[82:83], v[82:83], v[84:85]
	v_pk_add_f32 v[78:79], v[78:79], v[78:79] op_sel:[0,1] op_sel_hi:[1,0]
	v_pk_add_f32 v[82:83], v[82:83], v[82:83] op_sel:[0,1] op_sel_hi:[1,0]
	v_mov_b32_e32 v0, v78
	v_mov_b32_e32 v69, v82
	s_nop 0
	v_permlane16_swap_b32_e32 v78, v0
	v_permlane16_swap_b32_e32 v82, v69
	v_add_f32_e32 v79, v78, v0
	v_add_f32_e32 v78, v82, v69
	v_mov_b32_e32 v83, v79
	v_mov_b32_e32 v82, v78
	s_waitcnt vmcnt(11)
	v_mov_b32_e32 v70, v88
	s_waitcnt vmcnt(10)
	v_mov_b32_e32 v71, v92
	v_mov_b32_e32 v72, v90
	v_mov_b32_e32 v73, v94
	v_mov_b32_e32 v92, v89
	v_mov_b32_e32 v94, v91
	v_permlane32_swap_b32_e32 v79, v83
	v_permlane32_swap_b32_e32 v78, v82
	s_waitcnt vmcnt(9)
	v_mov_b32_e32 v88, v98
	s_waitcnt vmcnt(8)
	v_mov_b32_e32 v89, v102
	v_mov_b32_e32 v90, v100
	v_mov_b32_e32 v91, v104
	v_mov_b32_e32 v102, v99
	v_mov_b32_e32 v104, v101
	v_pk_add_f32 v[70:71], v[70:71], v[72:73]
	v_pk_add_f32 v[72:73], v[92:93], v[94:95]
	v_pk_add_f32 v[78:79], v[78:79], v[82:83]
	global_load_dwordx4 v[92:95], v[76:77], off offset:528
	global_load_dwordx4 v[98:101], v[76:77], off offset:512
	v_pk_mul_f32 v[162:163], v[78:79], s[2:3] op_sel_hi:[1,0]
	s_waitcnt vmcnt(9)
	v_mov_b32_e32 v78, v106
	s_waitcnt vmcnt(8)
	v_mov_b32_e32 v79, v110
	v_mov_b32_e32 v82, v108
	v_mov_b32_e32 v83, v112
	v_mov_b32_e32 v110, v107
	v_mov_b32_e32 v112, v109
	v_pk_add_f32 v[84:85], v[88:89], v[90:91]
	v_pk_add_f32 v[88:89], v[102:103], v[104:105]
	v_pk_add_f32 v[78:79], v[78:79], v[82:83]
	v_pk_add_f32 v[82:83], v[110:111], v[112:113]
	global_load_dwordx4 v[102:105], v[156:157], off offset:528
	global_load_dwordx4 v[106:109], v[156:157], off offset:512
	global_load_dwordx4 v[110:113], v[154:155], off offset:528
	global_load_dwordx4 v[158:161], v[154:155], off offset:512
	v_fma_f32 v0, -v163, v163, v162
	v_max_f32_e32 v0, 0, v0
	v_add_f32_e32 v0, 0x3727c5ac, v0
	v_mul_f32_e32 v69, 0x4b800000, v0
	v_cmp_gt_f32_e32 vcc, s1, v0
	v_pk_add_f32 v[88:89], v[88:89], v[88:89] op_sel:[0,1] op_sel_hi:[1,0]
	v_pk_add_f32 v[78:79], v[78:79], v[78:79] op_sel:[0,1] op_sel_hi:[1,0]
	v_cndmask_b32_e32 v0, v0, v69, vcc
	v_rsq_f32_e32 v0, v0
	v_pk_add_f32 v[82:83], v[82:83], v[82:83] op_sel:[0,1] op_sel_hi:[1,0]
	s_waitcnt vmcnt(10)
	v_sub_f32_e32 v119, v119, v163
	v_sub_f32_e32 v118, v118, v163
	v_mul_f32_e32 v69, 0x45800000, v0
	v_cndmask_b32_e32 v162, v0, v69, vcc
	v_mov_b32_e32 v0, v88
	s_nop 1
	v_permlane16_swap_b32_e32 v88, v0
	v_add_f32_e32 v88, v88, v0
	v_mov_b32_e32 v0, v78
	s_nop 1
	v_permlane16_swap_b32_e32 v78, v0
	v_add_f32_e32 v83, v78, v0
	v_mov_b32_e32 v0, v82
	s_nop 1
	v_permlane16_swap_b32_e32 v82, v0
	v_add_f32_e32 v82, v82, v0
	v_ashrrev_i32_e32 v78, 8, v68
	v_lshlrev_b32_e32 v0, 6, v68
	v_sub_f32_e32 v69, v121, v163
	v_sub_f32_e32 v68, v120, v163
	v_pk_mul_f32 v[118:119], v[162:163], v[118:119] op_sel_hi:[0,1]
	v_pk_mul_f32 v[68:69], v[162:163], v[68:69] op_sel_hi:[0,1]
	s_waitcnt vmcnt(6)
; __device__ __forceinline__ size_t blk_off(int r, int c, int K) { return (size_t)(r >> 8) * 256 * K + (size_t)(c >> 6) * (256 * 64) + (size_t)((r & 255) * 64 + (c & 63)); }
; __device__ __forceinline__ u32x4 pack8(const f32x4 a, const f32x4 b) { u32x4 w; w.x = cvt_pk_bf16(a[0], a[1]); w.y = cvt_pk_bf16(a[2], a[3]); w.z = cvt_pk_bf16(b[0], b[1]); w.w = cvt_pk_bf16(b[2], b[3]); return w; }
;     __device__ __forceinline__ void operator()(const f32x4 (&acc)[2][2][4][2], const pg8::Unit& u, int wr, int wc, int fr, int fq) const {
;     ...
;                     for (int n = 0; n < 2; ++n) { yv[bj][n] = *(const f32x4*)(Yin + (size_t)row * D_ + col0 + bj * 128 + 4 * n); gq[bj][n] = *(const f32x4*)(g + col0 + bj * 128 + 4 * n); bq_[bj][n] = *(const f32x4*)(b + col0 + bj * 128 + 4 * n); }
;                 asm volatile("" ::: "memory");
;                 float s1 = 0.f, s2 = 0.f;
; #pragma unroll
;                 for (int bj = 0; bj < 2; ++bj) { float* yp = Y + (size_t)row * D_ + col0 + bj * 128; f32x4 v[2];
; #pragma unroll
;                     for (int n = 0; n < 2; ++n) { v[n] = (((yv[bj][n] - mu) * rs) * gq[bj][n] + bq_[bj][n]) * ALPHA_ + acc[ai][bj][m][n] * sc;
;                         *(f32x4*)(yp + 4 * n) = v[n]; s1 += (v[n][0] + v[n][1]) + (v[n][2] + v[n][3]); s2 += (v[n][0] * v[n][0] + v[n][1] * v[n][1]) + (v[n][2] * v[n][2] + v[n][3] * v[n][3]); }
;                     *(u32x4*)(Yb + blk_off(row, col0 + bj * 128, D_)) = pack8(v[0], v[1]); }
	v_pk_fma_f32 v[68:69], v[128:129], v[68:69], v[136:137]
	v_pk_fma_f32 v[118:119], v[126:127], v[118:119], v[134:135]
	v_pk_mul_f32 v[68:69], v[68:69], s[16:17] op_sel_hi:[1,0]
	v_pk_mul_f32 v[118:119], v[118:119], s[16:17] op_sel_hi:[1,0]
	v_pk_fma_f32 v[64:65], v[64:65], 0.5, v[68:69] op_sel_hi:[1,0,1]
	v_pk_fma_f32 v[62:63], v[62:63], 0.5, v[118:119] op_sel_hi:[1,0,1]
	v_add_f32_e32 v69, v64, v65
	v_add_f32_e32 v68, v62, v63
	v_add_f32_e32 v68, v68, v69
	v_add_f32_e32 v118, 0, v68
	v_mul_f32_e32 v68, v63, v63
	v_mul_f32_e32 v69, v65, v65
	v_fmac_f32_e32 v68, v62, v62
	v_fmac_f32_e32 v69, v64, v64
	v_add_f32_e32 v119, v68, v69
	v_sub_f32_e32 v69, v117, v163
	v_sub_f32_e32 v68, v116, v163
	v_sub_f32_e32 v115, v115, v163
	v_sub_f32_e32 v114, v114, v163
	v_pk_mul_f32 v[114:115], v[162:163], v[114:115] op_sel_hi:[0,1]
	v_pk_mul_f32 v[68:69], v[162:163], v[68:69] op_sel_hi:[0,1]
	v_pk_fma_f32 v[68:69], v[124:125], v[68:69], v[132:133]
	v_pk_fma_f32 v[114:115], v[122:123], v[114:115], v[130:131]
	v_pk_mul_f32 v[68:69], v[68:69], s[16:17] op_sel_hi:[1,0]
	v_pk_mul_f32 v[114:115], v[114:115], s[16:17] op_sel_hi:[1,0]
	v_pk_fma_f32 v[60:61], v[60:61], 0.5, v[68:69] op_sel_hi:[1,0,1]
	v_pk_fma_f32 v[58:59], v[58:59], 0.5, v[114:115] op_sel_hi:[1,0,1]
	v_ashrrev_i32_e32 v79, 31, v78
	v_add_f32_e32 v68, v58, v59
	v_add_f32_e32 v69, v60, v61
	v_readlane_b32 s2, v253, 59
	v_lshlrev_b64 v[78:79], 19, v[78:79]
	s_movk_i32 s1, 0x33c0
	v_add_f32_e32 v68, v68, v69
	v_mul_f32_e32 v69, v59, v59
	v_readlane_b32 s3, v253, 60
	v_and_or_b32 v0, v0, s1, v196
	s_nop 0
	s_nop 1
	v_bfe_u32 v91, v227, 4, 2
	v_sub_u32_e32 v90, 0, v91
	v_lshlrev_b32_e32 v90, 4, v90
	v_ashrrev_i32_e32 v91, 31, v90
	v_lshl_add_u64 v[90:91], v[76:77], 0, v[90:91]
	v_permlane16_swap_b32_e32 v62, v58
	v_permlane16_swap_b32_e32 v63, v59
	v_permlane16_swap_b32_e32 v64, v60
	v_permlane16_swap_b32_e32 v65, v61
	v_permlane32_swap_b32_e32 v62, v58
	v_permlane32_swap_b32_e32 v63, v59
	v_permlane32_swap_b32_e32 v64, v60
	v_permlane32_swap_b32_e32 v65, v61
	v_mov_b32_e32 v89, v62
	v_mov_b32_e32 v116, v63
	v_mov_b32_e32 v117, v64
	v_mov_b32_e32 v120, v65
	v_bfe_u32 v114, v227, 3, 1
	v_mul_i32_i24_e32 v114, 0xffff8040, v114
	v_ashrrev_i32_e32 v115, 31, v114
	v_lshl_add_u64 v[90:91], v[90:91], 0, v[114:115]
	v_mov_b32_e32 v114, 0x8000
	v_mov_b32_e32 v115, 0
	v_lshl_add_u64 v[114:115], v[90:91], 0, v[114:115]
	v_mov_b32_dpp v62, v58 row_ror:8 row_mask:0xf bank_mask:0xc
	v_mov_b32_dpp v63, v59 row_ror:8 row_mask:0xf bank_mask:0xc
	v_mov_b32_dpp v64, v60 row_ror:8 row_mask:0xf bank_mask:0xc
	v_mov_b32_dpp v65, v61 row_ror:8 row_mask:0xf bank_mask:0xc
	v_mov_b32_dpp v58, v89 row_ror:8 row_mask:0xf bank_mask:0x3
	v_mov_b32_dpp v59, v116 row_ror:8 row_mask:0xf bank_mask:0x3
	v_mov_b32_dpp v60, v117 row_ror:8 row_mask:0xf bank_mask:0x3
	v_mov_b32_dpp v61, v120 row_ror:8 row_mask:0xf bank_mask:0x3
	global_store_dwordx4 v[90:91], v[62:65], off
	global_store_dwordx4 v[114:115], v[58:61], off
	s_nop 1
	v_mov_b32_dpp v58, v62 row_ror:8 row_mask:0xf bank_mask:0x3
	v_mov_b32_dpp v59, v63 row_ror:8 row_mask:0xf bank_mask:0x3
	v_mov_b32_dpp v60, v64 row_ror:8 row_mask:0xf bank_mask:0x3
	v_mov_b32_dpp v61, v65 row_ror:8 row_mask:0xf bank_mask:0x3
	v_mov_b32_e32 v62, v89
	v_mov_b32_e32 v63, v116
	v_mov_b32_e32 v64, v117
	v_mov_b32_e32 v65, v120
	s_nop 1
	v_permlane32_swap_b32_e32 v62, v58
	v_permlane32_swap_b32_e32 v63, v59
	v_permlane32_swap_b32_e32 v64, v60
	v_permlane32_swap_b32_e32 v65, v61
	v_permlane16_swap_b32_e32 v62, v58
	v_permlane16_swap_b32_e32 v63, v59
	v_permlane16_swap_b32_e32 v64, v60
	v_permlane16_swap_b32_e32 v65, v61
	v_fmac_f32_e32 v69, v58, v58
	v_cvt_pk_bf16_f32 v62, v62, v63
	v_cvt_pk_bf16_f32 v63, v64, v65
	v_cvt_pk_bf16_f32 v64, v58, v59
	v_lshl_add_u64 v[58:59], s[2:3], 0, v[78:79]
	v_mul_f32_e32 v114, v61, v61
	v_lshl_add_u64 v[78:79], v[58:59], 0, s[24:25]
	v_lshlrev_b32_e32 v0, 1, v0
	v_fmac_f32_e32 v114, v60, v60
	v_cvt_pk_bf16_f32 v65, v60, v61
	v_lshl_add_u64 v[60:61], v[78:79], 0, v[0:1]
	global_store_dwordx4 v[60:61], v[62:65], off
	s_waitcnt vmcnt(7)
	v_sub_f32_e32 v61, v101, v163
	v_sub_f32_e32 v60, v100, v163
	v_sub_f32_e32 v63, v99, v163
	v_sub_f32_e32 v62, v98, v163
	v_pk_mul_f32 v[62:63], v[162:163], v[62:63] op_sel_hi:[0,1]
	v_pk_mul_f32 v[60:61], v[162:163], v[60:61] op_sel_hi:[0,1]
	s_waitcnt vmcnt(3)
; __device__ __forceinline__ float xsum16(float v) { const auto r = __builtin_amdgcn_permlane16_swap(__float_as_uint(v), __float_as_uint(v), false, false); return __uint_as_float(r[0]) + __uint_as_float(r[1]); }
; __device__ __forceinline__ float xsum32(float v) { const auto r = __builtin_amdgcn_permlane32_swap(__float_as_uint(v), __float_as_uint(v), false, false); return __uint_as_float(r[0]) + __uint_as_float(r[1]); }
; __device__ __forceinline__ size_t blk_off(int r, int c, int K) { return (size_t)(r >> 8) * 256 * K + (size_t)(c >> 6) * (256 * 64) + (size_t)((r & 255) * 64 + (c & 63)); }
; __device__ __forceinline__ u32x4 pack8(const f32x4 a, const f32x4 b) { u32x4 w; w.x = cvt_pk_bf16(a[0], a[1]); w.y = cvt_pk_bf16(a[2], a[3]); w.z = cvt_pk_bf16(b[0], b[1]); w.w = cvt_pk_bf16(b[2], b[3]); return w; }
;     __device__ __forceinline__ void operator()(const f32x4 (&acc)[2][2][4][2], const pg8::Unit& u, int wr, int wc, int fr, int fq) const {
;     ...
;                 for (int bj = 0; bj < 2; ++bj) { float* yp = Y + (size_t)row * D_ + col0 + bj * 128; f32x4 v[2];
; #pragma unroll
;                     for (int n = 0; n < 2; ++n) { v[n] = (((yv[bj][n] - mu) * rs) * gq[bj][n] + bq_[bj][n]) * ALPHA_ + acc[ai][bj][m][n] * sc;
;                         *(f32x4*)(yp + 4 * n) = v[n]; s1 += (v[n][0] + v[n][1]) + (v[n][2] + v[n][3]); s2 += (v[n][0] * v[n][0] + v[n][1] * v[n][1]) + (v[n][2] * v[n][2] + v[n][3] * v[n][3]); }
;                     *(u32x4*)(Yb + blk_off(row, col0 + bj * 128, D_)) = pack8(v[0], v[1]); }
;                 s1 = xsum32(xsum16(s1)); s2 = xsum32(xsum16(s2));
;                 if (fq == 0) *(f32x2*)(stn + (size_t)row * 32 + (u.pn * 4 + wc) * 2) = (f32x2){s1, s2}; asm volatile("" ::: "memory"); } }
	v_pk_fma_f32 v[60:61], v[108:109], v[60:61], v[160:161]
	v_pk_fma_f32 v[62:63], v[106:107], v[62:63], v[158:159]
	v_pk_mul_f32 v[60:61], v[60:61], s[16:17] op_sel_hi:[1,0]
	v_pk_mul_f32 v[62:63], v[62:63], s[16:17] op_sel_hi:[1,0]
	v_pk_fma_f32 v[56:57], v[56:57], 0.5, v[60:61] op_sel_hi:[1,0,1]
	v_pk_fma_f32 v[54:55], v[54:55], 0.5, v[62:63] op_sel_hi:[1,0,1]
	v_add_f32_e32 v61, v56, v57
	v_add_f32_e32 v60, v54, v55
	v_add_f32_e32 v68, v118, v68
	v_add_f32_e32 v60, v60, v61
	v_add_f32_e32 v64, v68, v60
	v_mul_f32_e32 v60, v55, v55
	v_mul_f32_e32 v61, v57, v57
	v_add_f32_e32 v69, v69, v114
	v_fmac_f32_e32 v60, v54, v54
	v_fmac_f32_e32 v61, v56, v56
	v_add_f32_e32 v69, v119, v69
	v_add_f32_e32 v60, v60, v61
	v_add_f32_e32 v65, v69, v60
	v_sub_f32_e32 v61, v95, v163
	v_sub_f32_e32 v60, v94, v163
	v_sub_f32_e32 v63, v93, v163
	v_sub_f32_e32 v62, v92, v163
	v_pk_mul_f32 v[62:63], v[162:163], v[62:63] op_sel_hi:[0,1]
	v_pk_mul_f32 v[60:61], v[162:163], v[60:61] op_sel_hi:[0,1]
	v_pk_fma_f32 v[60:61], v[104:105], v[60:61], v[112:113]
	v_pk_fma_f32 v[62:63], v[102:103], v[62:63], v[110:111]
	v_pk_mul_f32 v[60:61], v[60:61], s[16:17] op_sel_hi:[1,0]
	v_pk_mul_f32 v[62:63], v[62:63], s[16:17] op_sel_hi:[1,0]
	v_pk_fma_f32 v[52:53], v[52:53], 0.5, v[60:61] op_sel_hi:[1,0,1]
	v_pk_fma_f32 v[50:51], v[50:51], 0.5, v[62:63] op_sel_hi:[1,0,1]
	v_add_f32_e32 v61, v52, v53
	v_add_f32_e32 v60, v50, v51
	v_add_f32_e32 v60, v60, v61
	v_mul_f32_e32 v61, v51, v51
	v_mul_f32_e32 v62, v53, v53
	s_nop 0
	s_nop 1
	v_bfe_u32 v69, v227, 4, 2
	v_sub_u32_e32 v68, 0, v69
	v_lshlrev_b32_e32 v68, 4, v68
	v_ashrrev_i32_e32 v69, 31, v68
	v_lshl_add_u64 v[68:69], v[76:77], 0, v[68:69]
	v_permlane16_swap_b32_e32 v54, v50
	v_permlane16_swap_b32_e32 v55, v51
	v_permlane16_swap_b32_e32 v56, v52
	v_permlane16_swap_b32_e32 v57, v53
	v_permlane32_swap_b32_e32 v54, v50
	v_permlane32_swap_b32_e32 v55, v51
	v_permlane32_swap_b32_e32 v56, v52
	v_permlane32_swap_b32_e32 v57, v53
	v_mov_b32_e32 v63, v54
	v_mov_b32_e32 v89, v55
	v_mov_b32_e32 v92, v56
	v_mov_b32_e32 v93, v57
	v_bfe_u32 v90, v227, 3, 1
	v_mul_i32_i24_e32 v90, 0xffff8040, v90
	v_ashrrev_i32_e32 v91, 31, v90
	v_lshl_add_u64 v[68:69], v[68:69], 0, v[90:91]
	v_mov_b32_e32 v90, 0x8000
	v_mov_b32_e32 v91, 0
	v_lshl_add_u64 v[90:91], v[68:69], 0, v[90:91]
	v_mov_b32_dpp v54, v50 row_ror:8 row_mask:0xf bank_mask:0xc
	v_mov_b32_dpp v55, v51 row_ror:8 row_mask:0xf bank_mask:0xc
	v_mov_b32_dpp v56, v52 row_ror:8 row_mask:0xf bank_mask:0xc
	v_mov_b32_dpp v57, v53 row_ror:8 row_mask:0xf bank_mask:0xc
	v_mov_b32_dpp v50, v63 row_ror:8 row_mask:0xf bank_mask:0x3
	v_mov_b32_dpp v51, v89 row_ror:8 row_mask:0xf bank_mask:0x3
	v_mov_b32_dpp v52, v92 row_ror:8 row_mask:0xf bank_mask:0x3
	v_mov_b32_dpp v53, v93 row_ror:8 row_mask:0xf bank_mask:0x3
	global_store_dwordx4 v[68:69], v[54:57], off offset:512
	global_store_dwordx4 v[90:91], v[50:53], off offset:512
	s_nop 1
	v_mov_b32_dpp v50, v54 row_ror:8 row_mask:0xf bank_mask:0x3
	v_mov_b32_dpp v51, v55 row_ror:8 row_mask:0xf bank_mask:0x3
	v_mov_b32_dpp v52, v56 row_ror:8 row_mask:0xf bank_mask:0x3
	v_mov_b32_dpp v53, v57 row_ror:8 row_mask:0xf bank_mask:0x3
	v_mov_b32_e32 v54, v63
	v_mov_b32_e32 v55, v89
	v_mov_b32_e32 v56, v92
	v_mov_b32_e32 v57, v93
	s_nop 1
	v_permlane32_swap_b32_e32 v54, v50
	v_permlane32_swap_b32_e32 v55, v51
	v_permlane32_swap_b32_e32 v56, v52
	v_permlane32_swap_b32_e32 v57, v53
	v_permlane16_swap_b32_e32 v54, v50
	v_permlane16_swap_b32_e32 v55, v51
	v_permlane16_swap_b32_e32 v56, v52
	v_permlane16_swap_b32_e32 v57, v53
	v_add_f32_e32 v60, v64, v60
	v_fmac_f32_e32 v61, v50, v50
	v_fmac_f32_e32 v62, v52, v52
	v_lshl_add_u64 v[76:77], v[58:59], 0, s[44:45]
	v_add_f32_e32 v61, v61, v62
	v_cvt_pk_bf16_f32 v54, v54, v55
	v_cvt_pk_bf16_f32 v55, v56, v57
	v_cvt_pk_bf16_f32 v56, v50, v51
	v_lshl_add_u64 v[50:51], v[76:77], 0, v[0:1]
	v_mov_b32_e32 v0, v60
	v_pk_add_f32 v[70:71], v[70:71], v[70:71] op_sel:[0,1] op_sel_hi:[1,0]
	v_pk_add_f32 v[72:73], v[72:73], v[72:73] op_sel:[0,1] op_sel_hi:[1,0]
	v_pk_add_f32 v[84:85], v[84:85], v[84:85] op_sel:[0,1] op_sel_hi:[1,0]
	v_add_f32_e32 v61, v65, v61
	v_cvt_pk_bf16_f32 v57, v52, v53
	v_permlane16_swap_b32_e32 v60, v0
	v_mov_b32_e32 v71, v70
	v_mov_b32_e32 v73, v72
	v_mov_b32_e32 v85, v84
	global_store_dwordx4 v[50:51], v[54:57], off
	v_add_f32_e32 v50, v60, v0
	v_mov_b32_e32 v0, v61
	v_permlane16_swap_b32_e32 v70, v71
	v_permlane16_swap_b32_e32 v72, v73
	v_permlane16_swap_b32_e32 v84, v85
	v_permlane16_swap_b32_e32 v61, v0
	v_add_f32_e32 v71, v70, v71
	v_add_f32_e32 v70, v72, v73
	v_add_f32_e32 v89, v84, v85
	v_add_f32_e32 v51, v61, v0
	v_mov_b32_e32 v73, v71
	v_mov_b32_e32 v72, v70
	v_mov_b32_e32 v91, v89
	v_mov_b32_e32 v90, v88
	v_mov_b32_e32 v85, v83
	v_mov_b32_e32 v84, v82
	v_mov_b32_e32 v52, v50
	v_mov_b32_e32 v53, v51
	v_permlane32_swap_b32_e32 v71, v73
	v_permlane32_swap_b32_e32 v70, v72
	v_permlane32_swap_b32_e32 v89, v91
	v_permlane32_swap_b32_e32 v88, v90
	v_permlane32_swap_b32_e32 v83, v85
	v_permlane32_swap_b32_e32 v82, v84
	v_permlane32_swap_b32_e32 v50, v52
	v_permlane32_swap_b32_e32 v51, v53
	s_and_saveexec_b64 s[24:25], s[40:41]
	s_cbranch_execz .LBB0_1713
	v_pk_add_f32 v[50:51], v[50:51], v[52:53]
	v_lshl_add_u64 v[52:53], s[8:9], 0, v[66:67]
	v_lshl_add_u64 v[52:53], s[38:39], 2, v[52:53]
	global_store_dwordx2 v[52:53], v[50:51], off
; __device__ __forceinline__ size_t blk_off(int r, int c, int K) { return (size_t)(r >> 8) * 256 * K + (size_t)(c >> 6) * (256 * 64) + (size_t)((r & 255) * 64 + (c & 63)); }
; __device__ __forceinline__ u32x4 pack8(const f32x4 a, const f32x4 b) { u32x4 w; w.x = cvt_pk_bf16(a[0], a[1]); w.y = cvt_pk_bf16(a[2], a[3]); w.z = cvt_pk_bf16(b[0], b[1]); w.w = cvt_pk_bf16(b[2], b[3]); return w; }
;     __device__ __forceinline__ void operator()(const f32x4 (&acc)[2][2][4][2], const pg8::Unit& u, int wr, int wc, int fr, int fq) const {
;     ...
;             for (int m = 0; m < 4; ++m) { const int row = row0 + ai * 128 + m * 16; const float mu = mu4[m], rs = rs4[m];
;                 f32x4 yv[2][2], gq[2][2], bq_[2][2];
; #pragma unroll
;                 for (int bj = 0; bj < 2; ++bj)
; #pragma unroll
;                     for (int n = 0; n < 2; ++n) { yv[bj][n] = *(const f32x4*)(Yin + (size_t)row * D_ + col0 + bj * 128 + 4 * n); gq[bj][n] = *(const f32x4*)(g + col0 + bj * 128 + 4 * n); bq_[bj][n] = *(const f32x4*)(b + col0 + bj * 128 + 4 * n); }
;                 asm volatile("" ::: "memory");
;                 float s1 = 0.f, s2 = 0.f;
; #pragma unroll
;                 for (int bj = 0; bj < 2; ++bj) { float* yp = Y + (size_t)row * D_ + col0 + bj * 128; f32x4 v[2];
; #pragma unroll
;                     for (int n = 0; n < 2; ++n) { v[n] = (((yv[bj][n] - mu) * rs) * gq[bj][n] + bq_[bj][n]) * ALPHA_ + acc[ai][bj][m][n] * sc;
;                         *(f32x4*)(yp + 4 * n) = v[n]; s1 += (v[n][0] + v[n][1]) + (v[n][2] + v[n][3]); s2 += (v[n][0] * v[n][0] + v[n][1] * v[n][1]) + (v[n][2] * v[n][2] + v[n][3] * v[n][3]); }
;                     *(u32x4*)(Yb + blk_off(row, col0 + bj * 128, D_)) = pack8(v[0], v[1]); }
.LBB0_1713:
	s_or_b64 exec, exec, s[24:25]
	v_pk_add_f32 v[50:51], v[70:71], v[72:73]
	s_mov_b32 s2, 0x3a800000
	v_pk_mul_f32 v[92:93], v[50:51], s[2:3] op_sel_hi:[1,0]
	s_mov_b32 s1, 0x800000
	v_fma_f32 v0, -v93, v93, v92
	v_max_f32_e32 v0, 0, v0
	v_add_f32_e32 v0, 0x3727c5ac, v0
	v_cmp_gt_f32_e32 vcc, s1, v0
	v_mul_f32_e32 v50, 0x4b800000, v0
	s_load_dwordx16 s[60:75], s[34:35], 0x38
	v_cndmask_b32_e32 v0, v0, v50, vcc
	v_rsq_f32_e32 v0, v0
	s_mov_b32 s2, 0x3fd744fd
	s_movk_i32 s1, 0x37c0
	v_mul_f32_e32 v50, 0x45800000, v0
	v_cndmask_b32_e32 v92, v0, v50, vcc
	v_lshlrev_b64 v[50:51], 12, v[96:97]
	s_waitcnt lgkmcnt(0)
	v_lshl_add_u64 v[50:51], s[74:75], 0, v[50:51]
	v_lshl_add_u64 v[94:95], v[152:153], 2, v[50:51]
	global_load_dwordx4 v[98:101], v[94:95], off offset:16
	global_load_dwordx4 v[102:105], v[94:95], off
	global_load_dwordx4 v[106:109], v[156:157], off offset:16
	global_load_dwordx4 v[110:113], v[156:157], off
	global_load_dwordx4 v[114:117], v[154:155], off offset:16
	global_load_dwordx4 v[118:121], v[154:155], off
	global_load_dwordx4 v[50:53], v[94:95], off offset:528
	global_load_dwordx4 v[70:73], v[94:95], off offset:512
	global_load_dwordx4 v[54:57], v[156:157], off offset:528
	global_load_dwordx4 v[62:65], v[156:157], off offset:512
	global_load_dwordx4 v[58:61], v[154:155], off offset:528
	global_load_dwordx4 v[66:69], v[154:155], off offset:512
	v_lshlrev_b32_e32 v0, 6, v96
	v_and_or_b32 v0, v0, s1, v196
	v_lshlrev_b32_e32 v0, 1, v0
	s_waitcnt vmcnt(10)
	v_sub_f32_e32 v97, v105, v93
	v_sub_f32_e32 v96, v104, v93
	v_sub_f32_e32 v103, v103, v93
	v_sub_f32_e32 v102, v102, v93
	v_pk_mul_f32 v[102:103], v[92:93], v[102:103] op_sel_hi:[0,1]
	v_pk_mul_f32 v[96:97], v[92:93], v[96:97] op_sel_hi:[0,1]
	s_waitcnt vmcnt(6)
	v_pk_fma_f32 v[96:97], v[112:113], v[96:97], v[120:121]
	v_pk_fma_f32 v[102:103], v[110:111], v[102:103], v[118:119]
	v_pk_mul_f32 v[96:97], v[96:97], s[2:3] op_sel_hi:[1,0]
	v_pk_mul_f32 v[102:103], v[102:103], s[2:3] op_sel_hi:[1,0]
	v_pk_fma_f32 v[104:105], v[48:49], 0.5, v[96:97] op_sel_hi:[1,0,1]
	v_pk_fma_f32 v[102:103], v[46:47], 0.5, v[102:103] op_sel_hi:[1,0,1]
	v_add_f32_e32 v47, v104, v105
	v_add_f32_e32 v46, v102, v103
	v_add_f32_e32 v46, v46, v47
	v_add_f32_e32 v110, 0, v46
	v_mul_f32_e32 v46, v103, v103
	v_mul_f32_e32 v47, v105, v105
	v_fmac_f32_e32 v46, v102, v102
	v_fmac_f32_e32 v47, v104, v104
	v_add_f32_e32 v111, v46, v47
	v_sub_f32_e32 v47, v101, v93
	v_sub_f32_e32 v46, v100, v93
	v_sub_f32_e32 v49, v99, v93
	v_sub_f32_e32 v48, v98, v93
	v_pk_mul_f32 v[48:49], v[92:93], v[48:49] op_sel_hi:[0,1]
	v_pk_mul_f32 v[46:47], v[92:93], v[46:47] op_sel_hi:[0,1]
	v_pk_fma_f32 v[46:47], v[108:109], v[46:47], v[116:117]
	v_pk_fma_f32 v[48:49], v[106:107], v[48:49], v[114:115]
	v_pk_mul_f32 v[46:47], v[46:47], s[2:3] op_sel_hi:[1,0]
	v_pk_mul_f32 v[48:49], v[48:49], s[2:3] op_sel_hi:[1,0]
	v_pk_fma_f32 v[98:99], v[44:45], 0.5, v[46:47] op_sel_hi:[1,0,1]
	v_pk_fma_f32 v[96:97], v[42:43], 0.5, v[48:49] op_sel_hi:[1,0,1]
	v_add_f32_e32 v43, v98, v99
	v_add_f32_e32 v42, v96, v97
	v_add_f32_e32 v42, v42, v43
	v_add_f32_e32 v47, v110, v42
	v_mul_f32_e32 v42, v97, v97
	v_mul_f32_e32 v43, v99, v99
	v_fmac_f32_e32 v42, v96, v96
	v_fmac_f32_e32 v43, v98, v98
	v_add_f32_e32 v42, v42, v43
	v_add_f32_e32 v46, v111, v42
	v_cvt_pk_bf16_f32 v42, v102, v103
	v_cvt_pk_bf16_f32 v43, v104, v105
	v_cvt_pk_bf16_f32 v44, v96, v97
	v_cvt_pk_bf16_f32 v45, v98, v99
	v_lshl_add_u64 v[48:49], v[78:79], 0, v[0:1]
	s_nop 0
	s_nop 1
	v_bfe_u32 v101, v227, 4, 2
	v_sub_u32_e32 v100, 0, v101
	v_lshlrev_b32_e32 v100, 4, v100
	v_ashrrev_i32_e32 v101, 31, v100
	v_lshl_add_u64 v[100:101], v[94:95], 0, v[100:101]
	v_permlane16_swap_b32_e32 v102, v96
	v_permlane16_swap_b32_e32 v103, v97
	v_permlane16_swap_b32_e32 v104, v98
	v_permlane16_swap_b32_e32 v105, v99
	v_permlane32_swap_b32_e32 v102, v96
	v_permlane32_swap_b32_e32 v103, v97
	v_permlane32_swap_b32_e32 v104, v98
	v_permlane32_swap_b32_e32 v105, v99
	v_mov_b32_e32 v108, v102
	v_mov_b32_e32 v109, v103
	v_mov_b32_e32 v110, v104
	v_mov_b32_e32 v111, v105
	v_bfe_u32 v106, v227, 3, 1
	v_mul_i32_i24_e32 v106, 0xffff8040, v106
	v_ashrrev_i32_e32 v107, 31, v106
	v_lshl_add_u64 v[100:101], v[100:101], 0, v[106:107]
	v_mov_b32_e32 v106, 0x8000
	v_mov_b32_e32 v107, 0
	v_lshl_add_u64 v[106:107], v[100:101], 0, v[106:107]
	v_mov_b32_dpp v102, v96 row_ror:8 row_mask:0xf bank_mask:0xc
	v_mov_b32_dpp v103, v97 row_ror:8 row_mask:0xf bank_mask:0xc
	v_mov_b32_dpp v104, v98 row_ror:8 row_mask:0xf bank_mask:0xc
	v_mov_b32_dpp v105, v99 row_ror:8 row_mask:0xf bank_mask:0xc
	v_mov_b32_dpp v96, v108 row_ror:8 row_mask:0xf bank_mask:0x3
	v_mov_b32_dpp v97, v109 row_ror:8 row_mask:0xf bank_mask:0x3
	v_mov_b32_dpp v98, v110 row_ror:8 row_mask:0xf bank_mask:0x3
	v_mov_b32_dpp v99, v111 row_ror:8 row_mask:0xf bank_mask:0x3
	global_store_dwordx4 v[100:101], v[102:105], off
	global_store_dwordx4 v[106:107], v[96:99], off
	s_nop 1
	v_mov_b32_dpp v96, v102 row_ror:8 row_mask:0xf bank_mask:0x3
	v_mov_b32_dpp v97, v103 row_ror:8 row_mask:0xf bank_mask:0x3
	v_mov_b32_dpp v98, v104 row_ror:8 row_mask:0xf bank_mask:0x3
	v_mov_b32_dpp v99, v105 row_ror:8 row_mask:0xf bank_mask:0x3
	v_mov_b32_e32 v102, v108
	v_mov_b32_e32 v103, v109
	v_mov_b32_e32 v104, v110
	v_mov_b32_e32 v105, v111
	s_nop 1
	v_permlane32_swap_b32_e32 v102, v96
	v_permlane32_swap_b32_e32 v103, v97
	v_permlane32_swap_b32_e32 v104, v98
	v_permlane32_swap_b32_e32 v105, v99
	v_permlane16_swap_b32_e32 v102, v96
	v_permlane16_swap_b32_e32 v103, v97
	v_permlane16_swap_b32_e32 v104, v98
	v_permlane16_swap_b32_e32 v105, v99
	global_store_dwordx4 v[48:49], v[42:45], off
	s_waitcnt vmcnt(7)
; __device__ __forceinline__ float xsum16(float v) { const auto r = __builtin_amdgcn_permlane16_swap(__float_as_uint(v), __float_as_uint(v), false, false); return __uint_as_float(r[0]) + __uint_as_float(r[1]); }
; __device__ __forceinline__ float xsum32(float v) { const auto r = __builtin_amdgcn_permlane32_swap(__float_as_uint(v), __float_as_uint(v), false, false); return __uint_as_float(r[0]) + __uint_as_float(r[1]); }
; __device__ __forceinline__ size_t blk_off(int r, int c, int K) { return (size_t)(r >> 8) * 256 * K + (size_t)(c >> 6) * (256 * 64) + (size_t)((r & 255) * 64 + (c & 63)); }
; __device__ __forceinline__ u32x4 pack8(const f32x4 a, const f32x4 b) { u32x4 w; w.x = cvt_pk_bf16(a[0], a[1]); w.y = cvt_pk_bf16(a[2], a[3]); w.z = cvt_pk_bf16(b[0], b[1]); w.w = cvt_pk_bf16(b[2], b[3]); return w; }
;     __device__ __forceinline__ void operator()(const f32x4 (&acc)[2][2][4][2], const pg8::Unit& u, int wr, int wc, int fr, int fq) const {
;     ...
;                 for (int bj = 0; bj < 2; ++bj) { float* yp = Y + (size_t)row * D_ + col0 + bj * 128; f32x4 v[2];
; #pragma unroll
;                     for (int n = 0; n < 2; ++n) { v[n] = (((yv[bj][n] - mu) * rs) * gq[bj][n] + bq_[bj][n]) * ALPHA_ + acc[ai][bj][m][n] * sc;
;                         *(f32x4*)(yp + 4 * n) = v[n]; s1 += (v[n][0] + v[n][1]) + (v[n][2] + v[n][3]); s2 += (v[n][0] * v[n][0] + v[n][1] * v[n][1]) + (v[n][2] * v[n][2] + v[n][3] * v[n][3]); }
;                     *(u32x4*)(Yb + blk_off(row, col0 + bj * 128, D_)) = pack8(v[0], v[1]); }
;                 s1 = xsum32(xsum16(s1)); s2 = xsum32(xsum16(s2));
;                 if (fq == 0) *(f32x2*)(stn + (size_t)row * 32 + (u.pn * 4 + wc) * 2) = (f32x2){s1, s2}; asm volatile("" ::: "memory"); } }
	s_nop 0
	v_sub_f32_e32 v43, v73, v93
	v_sub_f32_e32 v42, v72, v93
	v_sub_f32_e32 v45, v71, v93
	v_sub_f32_e32 v44, v70, v93
	v_pk_mul_f32 v[44:45], v[92:93], v[44:45] op_sel_hi:[0,1]
	v_pk_mul_f32 v[42:43], v[92:93], v[42:43] op_sel_hi:[0,1]
	s_waitcnt vmcnt(3)
	v_pk_fma_f32 v[42:43], v[64:65], v[42:43], v[68:69]
	v_pk_fma_f32 v[44:45], v[62:63], v[44:45], v[66:67]
	v_pk_mul_f32 v[42:43], v[42:43], s[2:3] op_sel_hi:[1,0]
	v_pk_mul_f32 v[44:45], v[44:45], s[2:3] op_sel_hi:[1,0]
	v_pk_fma_f32 v[40:41], v[40:41], 0.5, v[42:43] op_sel_hi:[1,0,1]
	v_pk_fma_f32 v[38:39], v[38:39], 0.5, v[44:45] op_sel_hi:[1,0,1]
	v_add_f32_e32 v43, v40, v41
	v_add_f32_e32 v42, v38, v39
	v_add_f32_e32 v42, v42, v43
	v_add_f32_e32 v47, v47, v42
	v_mul_f32_e32 v42, v39, v39
	v_mul_f32_e32 v43, v41, v41
	v_fmac_f32_e32 v42, v38, v38
	v_fmac_f32_e32 v43, v40, v40
	v_add_f32_e32 v42, v42, v43
	v_add_f32_e32 v46, v46, v42
	v_sub_f32_e32 v43, v53, v93
	v_sub_f32_e32 v42, v52, v93
	v_sub_f32_e32 v45, v51, v93
	v_sub_f32_e32 v44, v50, v93
	v_pk_mul_f32 v[44:45], v[92:93], v[44:45] op_sel_hi:[0,1]
	v_pk_mul_f32 v[42:43], v[92:93], v[42:43] op_sel_hi:[0,1]
	v_pk_fma_f32 v[42:43], v[56:57], v[42:43], v[60:61]
	v_pk_fma_f32 v[44:45], v[54:55], v[44:45], v[58:59]
	v_pk_mul_f32 v[42:43], v[42:43], s[2:3] op_sel_hi:[1,0]
	v_pk_mul_f32 v[44:45], v[44:45], s[2:3] op_sel_hi:[1,0]
	v_pk_fma_f32 v[36:37], v[36:37], 0.5, v[42:43] op_sel_hi:[1,0,1]
	v_pk_fma_f32 v[34:35], v[34:35], 0.5, v[44:45] op_sel_hi:[1,0,1]
	v_add_f32_e32 v43, v36, v37
	v_add_f32_e32 v42, v34, v35
	v_add_f32_e32 v42, v42, v43
	v_mul_f32_e32 v43, v35, v35
	v_mul_f32_e32 v44, v37, v37
	v_add_f32_e32 v42, v47, v42
	v_fmac_f32_e32 v43, v34, v34
	v_fmac_f32_e32 v44, v36, v36
	s_nop 0
	s_nop 1
	v_bfe_u32 v49, v227, 4, 2
	v_sub_u32_e32 v48, 0, v49
	v_lshlrev_b32_e32 v48, 4, v48
	v_ashrrev_i32_e32 v49, 31, v48
	v_lshl_add_u64 v[48:49], v[94:95], 0, v[48:49]
	v_permlane16_swap_b32_e32 v38, v34
	v_permlane16_swap_b32_e32 v39, v35
	v_permlane16_swap_b32_e32 v40, v36
	v_permlane16_swap_b32_e32 v41, v37
	v_permlane32_swap_b32_e32 v38, v34
	v_permlane32_swap_b32_e32 v39, v35
	v_permlane32_swap_b32_e32 v40, v36
	v_permlane32_swap_b32_e32 v41, v37
	v_mov_b32_e32 v45, v38
	v_mov_b32_e32 v52, v39
	v_mov_b32_e32 v53, v40
	v_mov_b32_e32 v54, v41
	v_bfe_u32 v50, v227, 3, 1
	v_mul_i32_i24_e32 v50, 0xffff8040, v50
	v_ashrrev_i32_e32 v51, 31, v50
	v_lshl_add_u64 v[48:49], v[48:49], 0, v[50:51]
	v_mov_b32_e32 v50, 0x8000
	v_mov_b32_e32 v51, 0
	v_lshl_add_u64 v[50:51], v[48:49], 0, v[50:51]
	v_mov_b32_dpp v38, v34 row_ror:8 row_mask:0xf bank_mask:0xc
	v_mov_b32_dpp v39, v35 row_ror:8 row_mask:0xf bank_mask:0xc
	v_mov_b32_dpp v40, v36 row_ror:8 row_mask:0xf bank_mask:0xc
	v_mov_b32_dpp v41, v37 row_ror:8 row_mask:0xf bank_mask:0xc
	v_mov_b32_dpp v34, v45 row_ror:8 row_mask:0xf bank_mask:0x3
	v_mov_b32_dpp v35, v52 row_ror:8 row_mask:0xf bank_mask:0x3
	v_mov_b32_dpp v36, v53 row_ror:8 row_mask:0xf bank_mask:0x3
	v_mov_b32_dpp v37, v54 row_ror:8 row_mask:0xf bank_mask:0x3
	global_store_dwordx4 v[48:49], v[38:41], off offset:512
	global_store_dwordx4 v[50:51], v[34:37], off offset:512
	s_nop 1
	v_mov_b32_dpp v34, v38 row_ror:8 row_mask:0xf bank_mask:0x3
	v_mov_b32_dpp v35, v39 row_ror:8 row_mask:0xf bank_mask:0x3
	v_mov_b32_dpp v36, v40 row_ror:8 row_mask:0xf bank_mask:0x3
	v_mov_b32_dpp v37, v41 row_ror:8 row_mask:0xf bank_mask:0x3
	v_mov_b32_e32 v38, v45
	v_mov_b32_e32 v39, v52
	v_mov_b32_e32 v40, v53
	v_mov_b32_e32 v41, v54
	s_nop 1
	v_permlane32_swap_b32_e32 v38, v34
	v_permlane32_swap_b32_e32 v39, v35
	v_permlane32_swap_b32_e32 v40, v36
	v_permlane32_swap_b32_e32 v41, v37
	v_permlane16_swap_b32_e32 v38, v34
	v_permlane16_swap_b32_e32 v39, v35
	v_permlane16_swap_b32_e32 v40, v36
	v_permlane16_swap_b32_e32 v41, v37
	v_add_f32_e32 v43, v43, v44
	v_cvt_pk_bf16_f32 v38, v38, v39
	v_cvt_pk_bf16_f32 v39, v40, v41
	v_cvt_pk_bf16_f32 v40, v34, v35
	v_lshl_add_u64 v[34:35], v[76:77], 0, v[0:1]
	v_mov_b32_e32 v0, v42
	v_add_f32_e32 v43, v46, v43
	v_cvt_pk_bf16_f32 v41, v36, v37
	v_permlane16_swap_b32_e32 v42, v0
	global_store_dwordx4 v[34:35], v[38:41], off
	v_add_f32_e32 v34, v42, v0
	v_mov_b32_e32 v0, v43
	s_nop 1
	v_permlane16_swap_b32_e32 v43, v0
	v_add_f32_e32 v35, v43, v0
	v_mov_b32_e32 v36, v34
	v_mov_b32_e32 v37, v35
	s_nop 0
	v_permlane32_swap_b32_e32 v34, v36
	v_permlane32_swap_b32_e32 v35, v37
	s_and_saveexec_b64 s[24:25], s[40:41]
	s_cbranch_execz .LBB0_1715
	v_pk_add_f32 v[34:35], v[34:35], v[36:37]
	v_lshl_add_u64 v[36:37], s[8:9], 0, v[86:87]
	v_lshl_add_u64 v[36:37], s[38:39], 2, v[36:37]
	global_store_dwordx2 v[36:37], v[34:35], off
; __device__ __forceinline__ size_t blk_off(int r, int c, int K) { return (size_t)(r >> 8) * 256 * K + (size_t)(c >> 6) * (256 * 64) + (size_t)((r & 255) * 64 + (c & 63)); }
; __device__ __forceinline__ u32x4 pack8(const f32x4 a, const f32x4 b) { u32x4 w; w.x = cvt_pk_bf16(a[0], a[1]); w.y = cvt_pk_bf16(a[2], a[3]); w.z = cvt_pk_bf16(b[0], b[1]); w.w = cvt_pk_bf16(b[2], b[3]); return w; }
;     __device__ __forceinline__ void operator()(const f32x4 (&acc)[2][2][4][2], const pg8::Unit& u, int wr, int wc, int fr, int fq) const {
;     ...
;             for (int m = 0; m < 4; ++m) { const int row = row0 + ai * 128 + m * 16; const float mu = mu4[m], rs = rs4[m];
;                 f32x4 yv[2][2], gq[2][2], bq_[2][2];
; #pragma unroll
;                 for (int bj = 0; bj < 2; ++bj)
; #pragma unroll
;                     for (int n = 0; n < 2; ++n) { yv[bj][n] = *(const f32x4*)(Yin + (size_t)row * D_ + col0 + bj * 128 + 4 * n); gq[bj][n] = *(const f32x4*)(g + col0 + bj * 128 + 4 * n); bq_[bj][n] = *(const f32x4*)(b + col0 + bj * 128 + 4 * n); }
;                 asm volatile("" ::: "memory");
;                 float s1 = 0.f, s2 = 0.f;
; #pragma unroll
;                 for (int bj = 0; bj < 2; ++bj) { float* yp = Y + (size_t)row * D_ + col0 + bj * 128; f32x4 v[2];
; #pragma unroll
;                     for (int n = 0; n < 2; ++n) { v[n] = (((yv[bj][n] - mu) * rs) * gq[bj][n] + bq_[bj][n]) * ALPHA_ + acc[ai][bj][m][n] * sc;
;                         *(f32x4*)(yp + 4 * n) = v[n]; s1 += (v[n][0] + v[n][1]) + (v[n][2] + v[n][3]); s2 += (v[n][0] * v[n][0] + v[n][1] * v[n][1]) + (v[n][2] * v[n][2] + v[n][3] * v[n][3]); }
;                     *(u32x4*)(Yb + blk_off(row, col0 + bj * 128, D_)) = pack8(v[0], v[1]); }
.LBB0_1715:
	s_or_b64 exec, exec, s[24:25]
	v_pk_add_f32 v[34:35], v[88:89], v[90:91]
	s_mov_b32 s2, 0x3a800000
	v_pk_mul_f32 v[58:59], v[34:35], s[2:3] op_sel_hi:[1,0]
	s_mov_b32 s1, 0x800000
	v_fma_f32 v0, -v59, v59, v58
	v_max_f32_e32 v0, 0, v0
	v_add_f32_e32 v0, 0x3727c5ac, v0
	v_cmp_gt_f32_e32 vcc, s1, v0
	v_mul_f32_e32 v34, 0x4b800000, v0
	s_load_dwordx16 s[60:75], s[34:35], 0x38
	v_cndmask_b32_e32 v0, v0, v34, vcc
	v_rsq_f32_e32 v0, v0
	s_mov_b32 s2, 0x3fd744fd
	s_movk_i32 s1, 0x3bc0
	v_mul_f32_e32 v34, 0x45800000, v0
	v_cndmask_b32_e32 v58, v0, v34, vcc
	v_lshlrev_b64 v[34:35], 12, v[80:81]
	s_waitcnt lgkmcnt(0)
	v_lshl_add_u64 v[34:35], s[74:75], 0, v[34:35]
	v_lshl_add_u64 v[60:61], v[152:153], 2, v[34:35]
	global_load_dwordx4 v[62:65], v[60:61], off offset:16
	global_load_dwordx4 v[66:69], v[60:61], off
	global_load_dwordx4 v[70:73], v[156:157], off offset:16
	global_load_dwordx4 v[86:89], v[156:157], off
	global_load_dwordx4 v[90:93], v[154:155], off offset:16
	global_load_dwordx4 v[94:97], v[154:155], off
	global_load_dwordx4 v[34:37], v[60:61], off offset:528
	global_load_dwordx4 v[54:57], v[60:61], off offset:512
	global_load_dwordx4 v[38:41], v[156:157], off offset:528
	global_load_dwordx4 v[46:49], v[156:157], off offset:512
	global_load_dwordx4 v[42:45], v[154:155], off offset:528
	global_load_dwordx4 v[50:53], v[154:155], off offset:512
	v_lshlrev_b32_e32 v0, 6, v80
	v_and_or_b32 v0, v0, s1, v196
	v_lshlrev_b32_e32 v0, 1, v0
	s_waitcnt vmcnt(10)
	v_sub_f32_e32 v69, v69, v59
	v_sub_f32_e32 v68, v68, v59
	v_sub_f32_e32 v67, v67, v59
	v_sub_f32_e32 v66, v66, v59
	v_pk_mul_f32 v[66:67], v[58:59], v[66:67] op_sel_hi:[0,1]
	v_pk_mul_f32 v[68:69], v[58:59], v[68:69] op_sel_hi:[0,1]
	s_waitcnt vmcnt(6)
	v_pk_fma_f32 v[68:69], v[88:89], v[68:69], v[96:97]
	v_pk_fma_f32 v[66:67], v[86:87], v[66:67], v[94:95]
	v_pk_mul_f32 v[68:69], v[68:69], s[2:3] op_sel_hi:[1,0]
	v_pk_mul_f32 v[66:67], v[66:67], s[2:3] op_sel_hi:[1,0]
	v_pk_fma_f32 v[68:69], v[32:33], 0.5, v[68:69] op_sel_hi:[1,0,1]
	v_pk_fma_f32 v[66:67], v[30:31], 0.5, v[66:67] op_sel_hi:[1,0,1]
	v_add_f32_e32 v31, v68, v69
	v_add_f32_e32 v30, v66, v67
	v_add_f32_e32 v30, v30, v31
	v_add_f32_e32 v86, 0, v30
	v_mul_f32_e32 v30, v67, v67
	v_mul_f32_e32 v31, v69, v69
	v_fmac_f32_e32 v30, v66, v66
	v_fmac_f32_e32 v31, v68, v68
	v_add_f32_e32 v87, v30, v31
	v_sub_f32_e32 v31, v65, v59
	v_sub_f32_e32 v30, v64, v59
	v_sub_f32_e32 v33, v63, v59
	v_sub_f32_e32 v32, v62, v59
	v_pk_mul_f32 v[32:33], v[58:59], v[32:33] op_sel_hi:[0,1]
	v_pk_mul_f32 v[30:31], v[58:59], v[30:31] op_sel_hi:[0,1]
	v_pk_fma_f32 v[30:31], v[72:73], v[30:31], v[92:93]
	v_pk_fma_f32 v[32:33], v[70:71], v[32:33], v[90:91]
	v_pk_mul_f32 v[30:31], v[30:31], s[2:3] op_sel_hi:[1,0]
	v_pk_mul_f32 v[32:33], v[32:33], s[2:3] op_sel_hi:[1,0]
	v_pk_fma_f32 v[64:65], v[28:29], 0.5, v[30:31] op_sel_hi:[1,0,1]
	v_pk_fma_f32 v[62:63], v[26:27], 0.5, v[32:33] op_sel_hi:[1,0,1]
	v_add_f32_e32 v27, v64, v65
	v_add_f32_e32 v26, v62, v63
	v_add_f32_e32 v26, v26, v27
	v_add_f32_e32 v31, v86, v26
	v_mul_f32_e32 v26, v63, v63
	v_mul_f32_e32 v27, v65, v65
	v_fmac_f32_e32 v26, v62, v62
	v_fmac_f32_e32 v27, v64, v64
	v_add_f32_e32 v26, v26, v27
	v_add_f32_e32 v30, v87, v26
	v_cvt_pk_bf16_f32 v26, v66, v67
	v_cvt_pk_bf16_f32 v27, v68, v69
	v_cvt_pk_bf16_f32 v28, v62, v63
	v_cvt_pk_bf16_f32 v29, v64, v65
	v_lshl_add_u64 v[32:33], v[78:79], 0, v[0:1]
	s_nop 0
	s_nop 1
	v_bfe_u32 v71, v227, 4, 2
	v_sub_u32_e32 v70, 0, v71
	v_lshlrev_b32_e32 v70, 4, v70
	v_ashrrev_i32_e32 v71, 31, v70
	v_lshl_add_u64 v[70:71], v[60:61], 0, v[70:71]
	v_permlane16_swap_b32_e32 v66, v62
	v_permlane16_swap_b32_e32 v67, v63
	v_permlane16_swap_b32_e32 v68, v64
	v_permlane16_swap_b32_e32 v69, v65
	v_permlane32_swap_b32_e32 v66, v62
	v_permlane32_swap_b32_e32 v67, v63
	v_permlane32_swap_b32_e32 v68, v64
	v_permlane32_swap_b32_e32 v69, v65
	v_mov_b32_e32 v86, v66
	v_mov_b32_e32 v87, v67
	v_mov_b32_e32 v88, v68
	v_mov_b32_e32 v89, v69
	v_bfe_u32 v72, v227, 3, 1
	v_mul_i32_i24_e32 v72, 0xffff8040, v72
	v_ashrrev_i32_e32 v73, 31, v72
	v_lshl_add_u64 v[70:71], v[70:71], 0, v[72:73]
	v_mov_b32_e32 v72, 0x8000
	v_mov_b32_e32 v73, 0
	v_lshl_add_u64 v[72:73], v[70:71], 0, v[72:73]
	v_mov_b32_dpp v66, v62 row_ror:8 row_mask:0xf bank_mask:0xc
	v_mov_b32_dpp v67, v63 row_ror:8 row_mask:0xf bank_mask:0xc
	v_mov_b32_dpp v68, v64 row_ror:8 row_mask:0xf bank_mask:0xc
	v_mov_b32_dpp v69, v65 row_ror:8 row_mask:0xf bank_mask:0xc
	v_mov_b32_dpp v62, v86 row_ror:8 row_mask:0xf bank_mask:0x3
	v_mov_b32_dpp v63, v87 row_ror:8 row_mask:0xf bank_mask:0x3
	v_mov_b32_dpp v64, v88 row_ror:8 row_mask:0xf bank_mask:0x3
	v_mov_b32_dpp v65, v89 row_ror:8 row_mask:0xf bank_mask:0x3
	global_store_dwordx4 v[70:71], v[66:69], off
	global_store_dwordx4 v[72:73], v[62:65], off
	s_nop 1
	v_mov_b32_dpp v62, v66 row_ror:8 row_mask:0xf bank_mask:0x3
	v_mov_b32_dpp v63, v67 row_ror:8 row_mask:0xf bank_mask:0x3
	v_mov_b32_dpp v64, v68 row_ror:8 row_mask:0xf bank_mask:0x3
	v_mov_b32_dpp v65, v69 row_ror:8 row_mask:0xf bank_mask:0x3
	v_mov_b32_e32 v66, v86
	v_mov_b32_e32 v67, v87
	v_mov_b32_e32 v68, v88
	v_mov_b32_e32 v69, v89
	s_nop 1
	v_permlane32_swap_b32_e32 v66, v62
	v_permlane32_swap_b32_e32 v67, v63
	v_permlane32_swap_b32_e32 v68, v64
	v_permlane32_swap_b32_e32 v69, v65
	v_permlane16_swap_b32_e32 v66, v62
	v_permlane16_swap_b32_e32 v67, v63
	v_permlane16_swap_b32_e32 v68, v64
	v_permlane16_swap_b32_e32 v69, v65
	global_store_dwordx4 v[32:33], v[26:29], off
	s_waitcnt vmcnt(7)
; __device__ __forceinline__ float xsum16(float v) { const auto r = __builtin_amdgcn_permlane16_swap(__float_as_uint(v), __float_as_uint(v), false, false); return __uint_as_float(r[0]) + __uint_as_float(r[1]); }
; __device__ __forceinline__ float xsum32(float v) { const auto r = __builtin_amdgcn_permlane32_swap(__float_as_uint(v), __float_as_uint(v), false, false); return __uint_as_float(r[0]) + __uint_as_float(r[1]); }
; __device__ __forceinline__ size_t blk_off(int r, int c, int K) { return (size_t)(r >> 8) * 256 * K + (size_t)(c >> 6) * (256 * 64) + (size_t)((r & 255) * 64 + (c & 63)); }
; __device__ __forceinline__ u32x4 pack8(const f32x4 a, const f32x4 b) { u32x4 w; w.x = cvt_pk_bf16(a[0], a[1]); w.y = cvt_pk_bf16(a[2], a[3]); w.z = cvt_pk_bf16(b[0], b[1]); w.w = cvt_pk_bf16(b[2], b[3]); return w; }
;     __device__ __forceinline__ void operator()(const f32x4 (&acc)[2][2][4][2], const pg8::Unit& u, int wr, int wc, int fr, int fq) const {
;     ...
;                 for (int bj = 0; bj < 2; ++bj) { float* yp = Y + (size_t)row * D_ + col0 + bj * 128; f32x4 v[2];
; #pragma unroll
;                     for (int n = 0; n < 2; ++n) { v[n] = (((yv[bj][n] - mu) * rs) * gq[bj][n] + bq_[bj][n]) * ALPHA_ + acc[ai][bj][m][n] * sc;
;                         *(f32x4*)(yp + 4 * n) = v[n]; s1 += (v[n][0] + v[n][1]) + (v[n][2] + v[n][3]); s2 += (v[n][0] * v[n][0] + v[n][1] * v[n][1]) + (v[n][2] * v[n][2] + v[n][3] * v[n][3]); }
;                     *(u32x4*)(Yb + blk_off(row, col0 + bj * 128, D_)) = pack8(v[0], v[1]); }
;                 s1 = xsum32(xsum16(s1)); s2 = xsum32(xsum16(s2));
;                 if (fq == 0) *(f32x2*)(stn + (size_t)row * 32 + (u.pn * 4 + wc) * 2) = (f32x2){s1, s2}; asm volatile("" ::: "memory"); } }
	s_nop 0
	v_sub_f32_e32 v27, v57, v59
	v_sub_f32_e32 v26, v56, v59
	v_sub_f32_e32 v29, v55, v59
	v_sub_f32_e32 v28, v54, v59
	v_pk_mul_f32 v[28:29], v[58:59], v[28:29] op_sel_hi:[0,1]
	v_pk_mul_f32 v[26:27], v[58:59], v[26:27] op_sel_hi:[0,1]
	s_waitcnt vmcnt(3)
	v_pk_fma_f32 v[26:27], v[48:49], v[26:27], v[52:53]
	v_pk_fma_f32 v[28:29], v[46:47], v[28:29], v[50:51]
	v_pk_mul_f32 v[26:27], v[26:27], s[2:3] op_sel_hi:[1,0]
	v_pk_mul_f32 v[28:29], v[28:29], s[2:3] op_sel_hi:[1,0]
	v_pk_fma_f32 v[24:25], v[24:25], 0.5, v[26:27] op_sel_hi:[1,0,1]
	v_pk_fma_f32 v[22:23], v[22:23], 0.5, v[28:29] op_sel_hi:[1,0,1]
	v_add_f32_e32 v27, v24, v25
	v_add_f32_e32 v26, v22, v23
	v_add_f32_e32 v26, v26, v27
	v_add_f32_e32 v31, v31, v26
	v_mul_f32_e32 v26, v23, v23
	v_mul_f32_e32 v27, v25, v25
	v_fmac_f32_e32 v26, v22, v22
	v_fmac_f32_e32 v27, v24, v24
	v_add_f32_e32 v26, v26, v27
	v_add_f32_e32 v30, v30, v26
	v_sub_f32_e32 v27, v37, v59
	v_sub_f32_e32 v26, v36, v59
	v_sub_f32_e32 v29, v35, v59
	v_sub_f32_e32 v28, v34, v59
	v_pk_mul_f32 v[28:29], v[58:59], v[28:29] op_sel_hi:[0,1]
	v_pk_mul_f32 v[26:27], v[58:59], v[26:27] op_sel_hi:[0,1]
	v_pk_fma_f32 v[26:27], v[40:41], v[26:27], v[44:45]
	v_pk_fma_f32 v[28:29], v[38:39], v[28:29], v[42:43]
	v_pk_mul_f32 v[26:27], v[26:27], s[2:3] op_sel_hi:[1,0]
	v_pk_mul_f32 v[28:29], v[28:29], s[2:3] op_sel_hi:[1,0]
	v_pk_fma_f32 v[20:21], v[20:21], 0.5, v[26:27] op_sel_hi:[1,0,1]
	v_pk_fma_f32 v[18:19], v[18:19], 0.5, v[28:29] op_sel_hi:[1,0,1]
	v_add_f32_e32 v27, v20, v21
	v_add_f32_e32 v26, v18, v19
	v_add_f32_e32 v26, v26, v27
	v_mul_f32_e32 v27, v19, v19
	v_mul_f32_e32 v28, v21, v21
	v_add_f32_e32 v26, v31, v26
	v_fmac_f32_e32 v27, v18, v18
	v_fmac_f32_e32 v28, v20, v20
	s_nop 0
	s_nop 1
	v_bfe_u32 v33, v227, 4, 2
	v_sub_u32_e32 v32, 0, v33
	v_lshlrev_b32_e32 v32, 4, v32
	v_ashrrev_i32_e32 v33, 31, v32
	v_lshl_add_u64 v[32:33], v[60:61], 0, v[32:33]
	v_permlane16_swap_b32_e32 v22, v18
	v_permlane16_swap_b32_e32 v23, v19
	v_permlane16_swap_b32_e32 v24, v20
	v_permlane16_swap_b32_e32 v25, v21
	v_permlane32_swap_b32_e32 v22, v18
	v_permlane32_swap_b32_e32 v23, v19
	v_permlane32_swap_b32_e32 v24, v20
	v_permlane32_swap_b32_e32 v25, v21
	v_mov_b32_e32 v29, v22
	v_mov_b32_e32 v36, v23
	v_mov_b32_e32 v37, v24
	v_mov_b32_e32 v38, v25
	v_bfe_u32 v34, v227, 3, 1
	v_mul_i32_i24_e32 v34, 0xffff8040, v34
	v_ashrrev_i32_e32 v35, 31, v34
	v_lshl_add_u64 v[32:33], v[32:33], 0, v[34:35]
	v_mov_b32_e32 v34, 0x8000
	v_mov_b32_e32 v35, 0
	v_lshl_add_u64 v[34:35], v[32:33], 0, v[34:35]
	v_mov_b32_dpp v22, v18 row_ror:8 row_mask:0xf bank_mask:0xc
	v_mov_b32_dpp v23, v19 row_ror:8 row_mask:0xf bank_mask:0xc
	v_mov_b32_dpp v24, v20 row_ror:8 row_mask:0xf bank_mask:0xc
	v_mov_b32_dpp v25, v21 row_ror:8 row_mask:0xf bank_mask:0xc
	v_mov_b32_dpp v18, v29 row_ror:8 row_mask:0xf bank_mask:0x3
	v_mov_b32_dpp v19, v36 row_ror:8 row_mask:0xf bank_mask:0x3
	v_mov_b32_dpp v20, v37 row_ror:8 row_mask:0xf bank_mask:0x3
	v_mov_b32_dpp v21, v38 row_ror:8 row_mask:0xf bank_mask:0x3
	global_store_dwordx4 v[32:33], v[22:25], off offset:512
	global_store_dwordx4 v[34:35], v[18:21], off offset:512
	s_nop 1
	v_mov_b32_dpp v18, v22 row_ror:8 row_mask:0xf bank_mask:0x3
	v_mov_b32_dpp v19, v23 row_ror:8 row_mask:0xf bank_mask:0x3
	v_mov_b32_dpp v20, v24 row_ror:8 row_mask:0xf bank_mask:0x3
	v_mov_b32_dpp v21, v25 row_ror:8 row_mask:0xf bank_mask:0x3
	v_mov_b32_e32 v22, v29
	v_mov_b32_e32 v23, v36
	v_mov_b32_e32 v24, v37
	v_mov_b32_e32 v25, v38
	s_nop 1
	v_permlane32_swap_b32_e32 v22, v18
	v_permlane32_swap_b32_e32 v23, v19
	v_permlane32_swap_b32_e32 v24, v20
	v_permlane32_swap_b32_e32 v25, v21
	v_permlane16_swap_b32_e32 v22, v18
	v_permlane16_swap_b32_e32 v23, v19
	v_permlane16_swap_b32_e32 v24, v20
	v_permlane16_swap_b32_e32 v25, v21
	v_add_f32_e32 v27, v27, v28
	v_cvt_pk_bf16_f32 v22, v22, v23
	v_cvt_pk_bf16_f32 v23, v24, v25
	v_cvt_pk_bf16_f32 v24, v18, v19
	v_lshl_add_u64 v[18:19], v[76:77], 0, v[0:1]
	v_mov_b32_e32 v0, v26
	v_add_f32_e32 v27, v30, v27
	v_cvt_pk_bf16_f32 v25, v20, v21
	v_permlane16_swap_b32_e32 v26, v0
	global_store_dwordx4 v[18:19], v[22:25], off
	v_add_f32_e32 v18, v26, v0
	v_mov_b32_e32 v0, v27
	s_nop 1
	v_permlane16_swap_b32_e32 v27, v0
	v_add_f32_e32 v19, v27, v0
	v_mov_b32_e32 v20, v18
	v_mov_b32_e32 v21, v19
	s_nop 0
	v_permlane32_swap_b32_e32 v18, v20
	v_permlane32_swap_b32_e32 v19, v21
	s_and_saveexec_b64 s[24:25], s[40:41]
	s_cbranch_execz .LBB0_1717
	v_pk_add_f32 v[18:19], v[18:19], v[20:21]
	v_lshlrev_b64 v[20:21], 7, v[80:81]
	v_lshl_add_u64 v[20:21], s[8:9], 0, v[20:21]
	v_lshl_add_u64 v[20:21], s[38:39], 2, v[20:21]
	global_store_dwordx2 v[20:21], v[18:19], off
; __device__ __forceinline__ size_t blk_off(int r, int c, int K) { return (size_t)(r >> 8) * 256 * K + (size_t)(c >> 6) * (256 * 64) + (size_t)((r & 255) * 64 + (c & 63)); }
; __device__ __forceinline__ u32x4 pack8(const f32x4 a, const f32x4 b) { u32x4 w; w.x = cvt_pk_bf16(a[0], a[1]); w.y = cvt_pk_bf16(a[2], a[3]); w.z = cvt_pk_bf16(b[0], b[1]); w.w = cvt_pk_bf16(b[2], b[3]); return w; }
;     __device__ __forceinline__ void operator()(const f32x4 (&acc)[2][2][4][2], const pg8::Unit& u, int wr, int wc, int fr, int fq) const {
;     ...
;             for (int m = 0; m < 4; ++m) { const int row = row0 + ai * 128 + m * 16; const float mu = mu4[m], rs = rs4[m];
;                 f32x4 yv[2][2], gq[2][2], bq_[2][2];
; #pragma unroll
;                 for (int bj = 0; bj < 2; ++bj)
; #pragma unroll
;                     for (int n = 0; n < 2; ++n) { yv[bj][n] = *(const f32x4*)(Yin + (size_t)row * D_ + col0 + bj * 128 + 4 * n); gq[bj][n] = *(const f32x4*)(g + col0 + bj * 128 + 4 * n); bq_[bj][n] = *(const f32x4*)(b + col0 + bj * 128 + 4 * n); }
;                 asm volatile("" ::: "memory");
;                 float s1 = 0.f, s2 = 0.f;
; #pragma unroll
;                 for (int bj = 0; bj < 2; ++bj) { float* yp = Y + (size_t)row * D_ + col0 + bj * 128; f32x4 v[2];
; #pragma unroll
;                     for (int n = 0; n < 2; ++n) { v[n] = (((yv[bj][n] - mu) * rs) * gq[bj][n] + bq_[bj][n]) * ALPHA_ + acc[ai][bj][m][n] * sc;
;                         *(f32x4*)(yp + 4 * n) = v[n]; s1 += (v[n][0] + v[n][1]) + (v[n][2] + v[n][3]); s2 += (v[n][0] * v[n][0] + v[n][1] * v[n][1]) + (v[n][2] * v[n][2] + v[n][3] * v[n][3]); }
;                     *(u32x4*)(Yb + blk_off(row, col0 + bj * 128, D_)) = pack8(v[0], v[1]); }
.LBB0_1717:
	s_or_b64 exec, exec, s[24:25]
	v_pk_add_f32 v[18:19], v[82:83], v[84:85]
	s_mov_b32 s2, 0x3a800000
	v_pk_mul_f32 v[42:43], v[18:19], s[2:3] op_sel_hi:[1,0]
	s_mov_b32 s1, 0x800000
	v_fma_f32 v0, -v43, v43, v42
	v_max_f32_e32 v0, 0, v0
	v_add_f32_e32 v0, 0x3727c5ac, v0
	v_cmp_gt_f32_e32 vcc, s1, v0
	v_mul_f32_e32 v18, 0x4b800000, v0
	s_load_dwordx16 s[60:75], s[34:35], 0x38
	v_cndmask_b32_e32 v0, v0, v18, vcc
	v_rsq_f32_e32 v0, v0
	s_mov_b32 s2, 0x3fd744fd
	s_movk_i32 s1, 0x3fc0
	v_mul_f32_e32 v18, 0x45800000, v0
	v_cndmask_b32_e32 v42, v0, v18, vcc
	v_lshlrev_b64 v[18:19], 12, v[74:75]
	s_waitcnt lgkmcnt(0)
	v_lshl_add_u64 v[18:19], s[74:75], 0, v[18:19]
	v_lshl_add_u64 v[44:45], v[152:153], 2, v[18:19]
	global_load_dwordx4 v[46:49], v[44:45], off offset:16
	global_load_dwordx4 v[50:53], v[44:45], off
	global_load_dwordx4 v[54:57], v[156:157], off offset:16
	global_load_dwordx4 v[58:61], v[156:157], off
	global_load_dwordx4 v[62:65], v[154:155], off offset:16
	global_load_dwordx4 v[66:69], v[154:155], off
	global_load_dwordx4 v[18:21], v[44:45], off offset:528
	global_load_dwordx4 v[38:41], v[44:45], off offset:512
	global_load_dwordx4 v[22:25], v[156:157], off offset:528
	global_load_dwordx4 v[30:33], v[156:157], off offset:512
	global_load_dwordx4 v[26:29], v[154:155], off offset:528
	global_load_dwordx4 v[34:37], v[154:155], off offset:512
	v_lshlrev_b32_e32 v0, 6, v74
	v_and_or_b32 v0, v0, s1, v196
	v_lshlrev_b32_e32 v0, 1, v0
	s_waitcnt vmcnt(10)
	v_sub_f32_e32 v53, v53, v43
	v_sub_f32_e32 v52, v52, v43
	v_sub_f32_e32 v51, v51, v43
	v_sub_f32_e32 v50, v50, v43
	v_pk_mul_f32 v[50:51], v[42:43], v[50:51] op_sel_hi:[0,1]
	v_pk_mul_f32 v[52:53], v[42:43], v[52:53] op_sel_hi:[0,1]
	s_waitcnt vmcnt(6)
	v_pk_fma_f32 v[52:53], v[60:61], v[52:53], v[68:69]
	v_pk_fma_f32 v[50:51], v[58:59], v[50:51], v[66:67]
	v_pk_mul_f32 v[52:53], v[52:53], s[2:3] op_sel_hi:[1,0]
	v_pk_mul_f32 v[50:51], v[50:51], s[2:3] op_sel_hi:[1,0]
	v_pk_fma_f32 v[52:53], v[16:17], 0.5, v[52:53] op_sel_hi:[1,0,1]
	v_pk_fma_f32 v[50:51], v[14:15], 0.5, v[50:51] op_sel_hi:[1,0,1]
	v_add_f32_e32 v15, v52, v53
	v_add_f32_e32 v14, v50, v51
	v_add_f32_e32 v14, v14, v15
	v_add_f32_e32 v58, 0, v14
	v_mul_f32_e32 v14, v51, v51
	v_mul_f32_e32 v15, v53, v53
	v_fmac_f32_e32 v14, v50, v50
	v_fmac_f32_e32 v15, v52, v52
	v_add_f32_e32 v59, v14, v15
	v_sub_f32_e32 v15, v49, v43
	v_sub_f32_e32 v14, v48, v43
	v_sub_f32_e32 v17, v47, v43
	v_sub_f32_e32 v16, v46, v43
	v_pk_mul_f32 v[16:17], v[42:43], v[16:17] op_sel_hi:[0,1]
	v_pk_mul_f32 v[14:15], v[42:43], v[14:15] op_sel_hi:[0,1]
	v_pk_fma_f32 v[14:15], v[56:57], v[14:15], v[64:65]
	v_pk_fma_f32 v[16:17], v[54:55], v[16:17], v[62:63]
	v_pk_mul_f32 v[14:15], v[14:15], s[2:3] op_sel_hi:[1,0]
	v_pk_mul_f32 v[16:17], v[16:17], s[2:3] op_sel_hi:[1,0]
	v_pk_fma_f32 v[48:49], v[12:13], 0.5, v[14:15] op_sel_hi:[1,0,1]
	v_pk_fma_f32 v[46:47], v[10:11], 0.5, v[16:17] op_sel_hi:[1,0,1]
	v_add_f32_e32 v11, v48, v49
	v_add_f32_e32 v10, v46, v47
	v_add_f32_e32 v10, v10, v11
	v_add_f32_e32 v15, v58, v10
	v_mul_f32_e32 v10, v47, v47
	v_mul_f32_e32 v11, v49, v49
	v_fmac_f32_e32 v10, v46, v46
	v_fmac_f32_e32 v11, v48, v48
	v_add_f32_e32 v10, v10, v11
	v_add_f32_e32 v14, v59, v10
	v_cvt_pk_bf16_f32 v10, v50, v51
	v_cvt_pk_bf16_f32 v11, v52, v53
	v_cvt_pk_bf16_f32 v12, v46, v47
	v_cvt_pk_bf16_f32 v13, v48, v49
	v_lshl_add_u64 v[16:17], v[78:79], 0, v[0:1]
	s_nop 0
	s_nop 1
	v_bfe_u32 v55, v227, 4, 2
	v_sub_u32_e32 v54, 0, v55
	v_lshlrev_b32_e32 v54, 4, v54
	v_ashrrev_i32_e32 v55, 31, v54
	v_lshl_add_u64 v[54:55], v[44:45], 0, v[54:55]
	v_permlane16_swap_b32_e32 v50, v46
	v_permlane16_swap_b32_e32 v51, v47
	v_permlane16_swap_b32_e32 v52, v48
	v_permlane16_swap_b32_e32 v53, v49
	v_permlane32_swap_b32_e32 v50, v46
	v_permlane32_swap_b32_e32 v51, v47
	v_permlane32_swap_b32_e32 v52, v48
	v_permlane32_swap_b32_e32 v53, v49
	v_mov_b32_e32 v58, v50
	v_mov_b32_e32 v59, v51
	v_mov_b32_e32 v60, v52
	v_mov_b32_e32 v61, v53
	v_bfe_u32 v56, v227, 3, 1
	v_mul_i32_i24_e32 v56, 0xffff8040, v56
	v_ashrrev_i32_e32 v57, 31, v56
	v_lshl_add_u64 v[54:55], v[54:55], 0, v[56:57]
	v_mov_b32_e32 v56, 0x8000
	v_mov_b32_e32 v57, 0
	v_lshl_add_u64 v[56:57], v[54:55], 0, v[56:57]
	v_mov_b32_dpp v50, v46 row_ror:8 row_mask:0xf bank_mask:0xc
	v_mov_b32_dpp v51, v47 row_ror:8 row_mask:0xf bank_mask:0xc
	v_mov_b32_dpp v52, v48 row_ror:8 row_mask:0xf bank_mask:0xc
	v_mov_b32_dpp v53, v49 row_ror:8 row_mask:0xf bank_mask:0xc
	v_mov_b32_dpp v46, v58 row_ror:8 row_mask:0xf bank_mask:0x3
	v_mov_b32_dpp v47, v59 row_ror:8 row_mask:0xf bank_mask:0x3
	v_mov_b32_dpp v48, v60 row_ror:8 row_mask:0xf bank_mask:0x3
	v_mov_b32_dpp v49, v61 row_ror:8 row_mask:0xf bank_mask:0x3
	global_store_dwordx4 v[54:55], v[50:53], off
	global_store_dwordx4 v[56:57], v[46:49], off
	s_nop 1
	v_mov_b32_dpp v46, v50 row_ror:8 row_mask:0xf bank_mask:0x3
	v_mov_b32_dpp v47, v51 row_ror:8 row_mask:0xf bank_mask:0x3
	v_mov_b32_dpp v48, v52 row_ror:8 row_mask:0xf bank_mask:0x3
	v_mov_b32_dpp v49, v53 row_ror:8 row_mask:0xf bank_mask:0x3
	v_mov_b32_e32 v50, v58
	v_mov_b32_e32 v51, v59
	v_mov_b32_e32 v52, v60
	v_mov_b32_e32 v53, v61
	s_nop 1
	v_permlane32_swap_b32_e32 v50, v46
	v_permlane32_swap_b32_e32 v51, v47
	v_permlane32_swap_b32_e32 v52, v48
	v_permlane32_swap_b32_e32 v53, v49
	v_permlane16_swap_b32_e32 v50, v46
	v_permlane16_swap_b32_e32 v51, v47
	v_permlane16_swap_b32_e32 v52, v48
	v_permlane16_swap_b32_e32 v53, v49
	global_store_dwordx4 v[16:17], v[10:13], off
	s_waitcnt vmcnt(7)
; __device__ __forceinline__ float xsum16(float v) { const auto r = __builtin_amdgcn_permlane16_swap(__float_as_uint(v), __float_as_uint(v), false, false); return __uint_as_float(r[0]) + __uint_as_float(r[1]); }
; __device__ __forceinline__ float xsum32(float v) { const auto r = __builtin_amdgcn_permlane32_swap(__float_as_uint(v), __float_as_uint(v), false, false); return __uint_as_float(r[0]) + __uint_as_float(r[1]); }
; __device__ __forceinline__ size_t blk_off(int r, int c, int K) { return (size_t)(r >> 8) * 256 * K + (size_t)(c >> 6) * (256 * 64) + (size_t)((r & 255) * 64 + (c & 63)); }
; __device__ __forceinline__ u32x4 pack8(const f32x4 a, const f32x4 b) { u32x4 w; w.x = cvt_pk_bf16(a[0], a[1]); w.y = cvt_pk_bf16(a[2], a[3]); w.z = cvt_pk_bf16(b[0], b[1]); w.w = cvt_pk_bf16(b[2], b[3]); return w; }
;     __device__ __forceinline__ void operator()(const f32x4 (&acc)[2][2][4][2], const pg8::Unit& u, int wr, int wc, int fr, int fq) const {
;     ...
;                 for (int bj = 0; bj < 2; ++bj) { float* yp = Y + (size_t)row * D_ + col0 + bj * 128; f32x4 v[2];
; #pragma unroll
;                     for (int n = 0; n < 2; ++n) { v[n] = (((yv[bj][n] - mu) * rs) * gq[bj][n] + bq_[bj][n]) * ALPHA_ + acc[ai][bj][m][n] * sc;
;                         *(f32x4*)(yp + 4 * n) = v[n]; s1 += (v[n][0] + v[n][1]) + (v[n][2] + v[n][3]); s2 += (v[n][0] * v[n][0] + v[n][1] * v[n][1]) + (v[n][2] * v[n][2] + v[n][3] * v[n][3]); }
;                     *(u32x4*)(Yb + blk_off(row, col0 + bj * 128, D_)) = pack8(v[0], v[1]); }
;                 s1 = xsum32(xsum16(s1)); s2 = xsum32(xsum16(s2));
;                 if (fq == 0) *(f32x2*)(stn + (size_t)row * 32 + (u.pn * 4 + wc) * 2) = (f32x2){s1, s2}; asm volatile("" ::: "memory"); } }
	s_nop 0
	v_sub_f32_e32 v11, v41, v43
	v_sub_f32_e32 v10, v40, v43
	v_sub_f32_e32 v13, v39, v43
	v_sub_f32_e32 v12, v38, v43
	v_pk_mul_f32 v[12:13], v[42:43], v[12:13] op_sel_hi:[0,1]
	v_pk_mul_f32 v[10:11], v[42:43], v[10:11] op_sel_hi:[0,1]
	s_waitcnt vmcnt(3)
	v_pk_fma_f32 v[10:11], v[32:33], v[10:11], v[36:37]
	v_pk_fma_f32 v[12:13], v[30:31], v[12:13], v[34:35]
	v_pk_mul_f32 v[10:11], v[10:11], s[2:3] op_sel_hi:[1,0]
	v_pk_mul_f32 v[12:13], v[12:13], s[2:3] op_sel_hi:[1,0]
	v_pk_fma_f32 v[8:9], v[8:9], 0.5, v[10:11] op_sel_hi:[1,0,1]
	v_pk_fma_f32 v[6:7], v[6:7], 0.5, v[12:13] op_sel_hi:[1,0,1]
	v_add_f32_e32 v11, v8, v9
	v_add_f32_e32 v10, v6, v7
	v_add_f32_e32 v10, v10, v11
	v_add_f32_e32 v15, v15, v10
	v_mul_f32_e32 v10, v7, v7
	v_mul_f32_e32 v11, v9, v9
	v_fmac_f32_e32 v10, v6, v6
	v_fmac_f32_e32 v11, v8, v8
	v_add_f32_e32 v10, v10, v11
	v_add_f32_e32 v14, v14, v10
	v_sub_f32_e32 v11, v21, v43
	v_sub_f32_e32 v10, v20, v43
	v_sub_f32_e32 v13, v19, v43
	v_sub_f32_e32 v12, v18, v43
	v_pk_mul_f32 v[12:13], v[42:43], v[12:13] op_sel_hi:[0,1]
	v_pk_mul_f32 v[10:11], v[42:43], v[10:11] op_sel_hi:[0,1]
	v_pk_fma_f32 v[10:11], v[24:25], v[10:11], v[28:29]
	v_pk_fma_f32 v[12:13], v[22:23], v[12:13], v[26:27]
	v_pk_mul_f32 v[10:11], v[10:11], s[2:3] op_sel_hi:[1,0]
	v_pk_mul_f32 v[12:13], v[12:13], s[2:3] op_sel_hi:[1,0]
	v_pk_fma_f32 v[4:5], v[4:5], 0.5, v[10:11] op_sel_hi:[1,0,1]
	v_pk_fma_f32 v[2:3], v[2:3], 0.5, v[12:13] op_sel_hi:[1,0,1]
	v_add_f32_e32 v11, v4, v5
	v_add_f32_e32 v10, v2, v3
	v_add_f32_e32 v10, v10, v11
	v_mul_f32_e32 v11, v3, v3
	v_mul_f32_e32 v12, v5, v5
	v_add_f32_e32 v10, v15, v10
	v_fmac_f32_e32 v11, v2, v2
	v_fmac_f32_e32 v12, v4, v4
	s_nop 0
	s_nop 1
	v_bfe_u32 v17, v227, 4, 2
	v_sub_u32_e32 v16, 0, v17
	v_lshlrev_b32_e32 v16, 4, v16
	v_ashrrev_i32_e32 v17, 31, v16
	v_lshl_add_u64 v[16:17], v[44:45], 0, v[16:17]
	v_permlane16_swap_b32_e32 v6, v2
	v_permlane16_swap_b32_e32 v7, v3
	v_permlane16_swap_b32_e32 v8, v4
	v_permlane16_swap_b32_e32 v9, v5
	v_permlane32_swap_b32_e32 v6, v2
	v_permlane32_swap_b32_e32 v7, v3
	v_permlane32_swap_b32_e32 v8, v4
	v_permlane32_swap_b32_e32 v9, v5
	v_mov_b32_e32 v13, v6
	v_mov_b32_e32 v20, v7
	v_mov_b32_e32 v21, v8
	v_mov_b32_e32 v22, v9
	v_bfe_u32 v18, v227, 3, 1
	v_mul_i32_i24_e32 v18, 0xffff8040, v18
	v_ashrrev_i32_e32 v19, 31, v18
	v_lshl_add_u64 v[16:17], v[16:17], 0, v[18:19]
	v_mov_b32_e32 v18, 0x8000
	v_mov_b32_e32 v19, 0
	v_lshl_add_u64 v[18:19], v[16:17], 0, v[18:19]
	v_mov_b32_dpp v6, v2 row_ror:8 row_mask:0xf bank_mask:0xc
	v_mov_b32_dpp v7, v3 row_ror:8 row_mask:0xf bank_mask:0xc
	v_mov_b32_dpp v8, v4 row_ror:8 row_mask:0xf bank_mask:0xc
	v_mov_b32_dpp v9, v5 row_ror:8 row_mask:0xf bank_mask:0xc
	v_mov_b32_dpp v2, v13 row_ror:8 row_mask:0xf bank_mask:0x3
	v_mov_b32_dpp v3, v20 row_ror:8 row_mask:0xf bank_mask:0x3
	v_mov_b32_dpp v4, v21 row_ror:8 row_mask:0xf bank_mask:0x3
	v_mov_b32_dpp v5, v22 row_ror:8 row_mask:0xf bank_mask:0x3
	global_store_dwordx4 v[16:17], v[6:9], off offset:512
	global_store_dwordx4 v[18:19], v[2:5], off offset:512
	s_nop 1
	v_mov_b32_dpp v2, v6 row_ror:8 row_mask:0xf bank_mask:0x3
	v_mov_b32_dpp v3, v7 row_ror:8 row_mask:0xf bank_mask:0x3
	v_mov_b32_dpp v4, v8 row_ror:8 row_mask:0xf bank_mask:0x3
	v_mov_b32_dpp v5, v9 row_ror:8 row_mask:0xf bank_mask:0x3
	v_mov_b32_e32 v6, v13
	v_mov_b32_e32 v7, v20
	v_mov_b32_e32 v8, v21
	v_mov_b32_e32 v9, v22
	s_nop 1
	v_permlane32_swap_b32_e32 v6, v2
	v_permlane32_swap_b32_e32 v7, v3
	v_permlane32_swap_b32_e32 v8, v4
	v_permlane32_swap_b32_e32 v9, v5
	v_permlane16_swap_b32_e32 v6, v2
	v_permlane16_swap_b32_e32 v7, v3
	v_permlane16_swap_b32_e32 v8, v4
	v_permlane16_swap_b32_e32 v9, v5
	v_add_f32_e32 v11, v11, v12
	v_cvt_pk_bf16_f32 v6, v6, v7
	v_cvt_pk_bf16_f32 v7, v8, v9
	v_cvt_pk_bf16_f32 v8, v2, v3
	v_lshl_add_u64 v[2:3], v[76:77], 0, v[0:1]
	v_mov_b32_e32 v0, v10
	v_add_f32_e32 v11, v14, v11
	v_cvt_pk_bf16_f32 v9, v4, v5
	v_permlane16_swap_b32_e32 v10, v0
	global_store_dwordx4 v[2:3], v[6:9], off
	v_add_f32_e32 v2, v10, v0
	v_mov_b32_e32 v0, v11
	s_nop 1
	v_permlane16_swap_b32_e32 v11, v0
	v_add_f32_e32 v3, v11, v0
	v_mov_b32_e32 v4, v2
	v_mov_b32_e32 v5, v3
	s_nop 0
	v_permlane32_swap_b32_e32 v2, v4
	v_permlane32_swap_b32_e32 v3, v5
	s_and_saveexec_b64 s[24:25], s[40:41]
	s_cbranch_execz .LBB0_1719
	v_pk_add_f32 v[2:3], v[2:3], v[4:5]
	v_lshlrev_b64 v[4:5], 7, v[74:75]
	v_lshl_add_u64 v[4:5], s[8:9], 0, v[4:5]
	v_lshl_add_u64 v[4:5], s[38:39], 2, v[4:5]
	global_store_dwordx2 v[4:5], v[2:3], off
